# f32 to bf16 rounding: the v_bfe/v_add3 bit trick replaced by one v_cvt_pk_bf16_f32 where only the high half is consumed (754 sites; same RNE result)
# baseline (speedup 1.0000x reference)
.LBB0_436:
	s_mul_hi_i32 s12, s91, 0x2aaaaaab
	s_lshr_b32 s13, s12, 31
	s_ashr_i32 s12, s12, 2
	s_add_i32 s82, s12, s13
	s_mul_i32 s12, s82, 0xffffffe8
	s_add_i32 s76, s91, s12
	s_mov_b64 s[12:13], -1
	s_cmp_gt_i32 s76, 15
	v_lshl_add_u32 v103, s82, 5, v67
	s_cbranch_scc0 .LBB0_510
	v_mov_b32_e32 v155, v97
	s_add_i32 s12, s76, -16
	s_lshr_b32 s38, s12, 1
	s_and_b32 s28, s94, 2
	v_or_b32_e32 v146, s28, v63
	s_movk_i32 s26, 0x810
	v_cmp_gt_i32_e64 s[14:15], s26, v103
	s_mul_i32 s33, s38, 0x810
	s_nop 1
	v_cndmask_b32_e64 v140, 0, v103, s[14:15]
	v_add_u32_e32 v142, s33, v140
	v_mov_b64_e32 v[140:141], s[54:55]
	v_mad_i64_i32 v[144:145], s[16:17], v142, s44, v[140:141]
	v_lshlrev_b32_e32 v142, 1, v62
	v_lshl_or_b32 v142, v146, 7, v142
	v_or_b32_e32 v154, 0x2200, v142
	v_lshl_add_u64 v[146:147], v[144:145], 0, v[154:155]
	v_mov_b32_e32 v143, v155
	s_mov_b64 s[86:87], 0x2a00
	global_load_ushort v139, v[146:147], off
	v_lshl_add_u64 v[146:147], v[144:145], 0, v[142:143]
	v_lshl_add_u64 v[152:153], v[144:145], 0, s[86:87]
	v_add_co_u32_e32 v144, vcc, s74, v144
	s_nop 1
	v_addc_co_u32_e32 v145, vcc, 0, v145, vcc
	global_load_dwordx4 v[160:163], v[144:145], off offset:2560
	global_load_dwordx4 v[164:167], v[152:153], off offset:16
	v_or_b32_e32 v156, 2, v103
	v_cmp_gt_i32_e64 s[12:13], s26, v156
	v_or_b32_e32 v150, 3, v103
	v_or_b32_e32 v144, 1, v103
	v_cmp_gt_i32_e64 s[18:19], s26, v144
	v_cmp_gt_i32_e64 s[16:17], s26, v150
	s_nop 1
	v_cndmask_b32_e64 v144, 0, v144, s[18:19]
	v_add_u32_e32 v157, s33, v144
	v_mad_i64_i32 v[148:149], s[20:21], v157, s44, v[140:141]
	v_lshl_add_u64 v[144:145], v[148:149], 0, v[154:155]
	global_load_ushort v159, v[144:145], off
	v_lshl_add_u64 v[144:145], v[148:149], 0, v[142:143]
	v_lshl_add_u64 v[152:153], v[148:149], 0, s[86:87]
	v_add_co_u32_e32 v148, vcc, s74, v148
	s_nop 1
	v_addc_co_u32_e32 v149, vcc, 0, v149, vcc
	global_load_dwordx4 v[168:171], v[148:149], off offset:2560
	global_load_dwordx4 v[172:175], v[152:153], off offset:16
	v_cndmask_b32_e64 v148, 0, v156, s[12:13]
	v_add_u32_e32 v148, s33, v148
	v_mad_i64_i32 v[148:149], s[20:21], v148, s44, v[140:141]
	v_add_co_u32_e32 v146, vcc, s74, v146
	v_lshl_add_u64 v[152:153], v[148:149], 0, v[154:155]
	s_nop 1
	v_addc_co_u32_e32 v147, vcc, 0, v147, vcc
	global_load_ushort v176, v[152:153], off
	global_load_ushort v177, v[146:147], off offset:1024
	v_lshl_add_u64 v[152:153], v[148:149], 0, v[142:143]
	v_add_co_u32_e32 v146, vcc, s74, v152
	s_nop 1
	v_addc_co_u32_e32 v147, vcc, 0, v153, vcc
	global_load_ushort v178, v[146:147], off offset:1024
	v_lshl_add_u64 v[146:147], v[148:149], 0, s[86:87]
	v_add_co_u32_e32 v148, vcc, s74, v148
	s_nop 1
	v_addc_co_u32_e32 v149, vcc, 0, v149, vcc
	global_load_dwordx4 v[180:183], v[148:149], off offset:2560
	global_load_dwordx4 v[184:187], v[146:147], off offset:16
	v_cndmask_b32_e64 v146, 0, v150, s[16:17]
	v_add_u32_e32 v158, s33, v146
	v_mad_i64_i32 v[146:147], s[20:21], v158, s44, v[140:141]
	v_lshl_add_u64 v[150:151], v[146:147], 0, v[154:155]
	global_load_ushort v179, v[150:151], off
	v_lshl_add_u64 v[150:151], v[146:147], 0, v[142:143]
	v_add_co_u32_e32 v150, vcc, s74, v150
	s_nop 1
	v_addc_co_u32_e32 v151, vcc, 0, v151, vcc
	v_add_co_u32_e32 v144, vcc, s74, v144
	global_load_ushort v188, v[150:151], off offset:1024
	s_nop 1
	v_addc_co_u32_e32 v145, vcc, 0, v145, vcc
	global_load_ushort v189, v[144:145], off offset:1024
	v_lshl_add_u64 v[150:151], v[146:147], 0, s[86:87]
	v_add_co_u32_e32 v144, vcc, s74, v146
	s_nop 1
	v_addc_co_u32_e32 v145, vcc, 0, v147, vcc
	global_load_dwordx4 v[190:193], v[144:145], off offset:2560
	global_load_dwordx4 v[194:197], v[150:151], off offset:16
	s_add_i32 s12, s76, -16
	s_lshr_b32 s38, s12, 1
	s_and_b32 s28, s94, 2
	s_lshl_b32 s60, s38, 2
	v_or_b32_e32 v6, s28, v63
	s_add_i32 s60, s60, 32
	s_ashr_i32 s83, s82, 31
	v_or_b32_e32 v2, s60, v6
	v_mov_b64_e32 v[0:1], s[82:83]
	v_mad_u64_u32 v[0:1], s[12:13], v2, s79, v[0:1]
	v_mov_b64_e32 v[2:3], s[56:57]
	v_mad_u64_u32 v[38:39], s[12:13], v0, s44, v[2:3]
	v_lshlrev_b32_e32 v96, 8, v6
	v_mad_i32_i24 v39, v1, s44, v39
	v_lshl_add_u64 v[0:1], v[10:11], 0, v[96:97]
	global_load_dword v107, v[0:1], off
	v_lshl_add_u64 v[0:1], v[12:13], 0, v[96:97]
	s_movk_i32 s12, 0x1000
	v_add_co_u32_e32 v2, vcc, s12, v0
	global_load_dword v44, v[0:1], off
	global_load_dword v46, v[0:1], off offset:1024
	global_load_dword v42, v[0:1], off offset:2048
	global_load_dword v40, v[0:1], off offset:3072
	v_addc_co_u32_e32 v3, vcc, 0, v1, vcc
	v_add_co_u32_e32 v4, vcc, s74, v0
	s_movk_i32 s26, 0x810
	s_nop 0
	v_addc_co_u32_e32 v5, vcc, 0, v1, vcc
	v_add_co_u32_e32 v0, vcc, s44, v0
	v_cmp_gt_i32_e64 s[14:15], s26, v103
	s_nop 0
	v_addc_co_u32_e32 v1, vcc, 0, v1, vcc
	global_load_dword v54, v[4:5], off offset:-4096
	global_load_dword v52, v[2:3], off offset:1024
	global_load_dword v50, v[2:3], off offset:2048
	global_load_dword v48, v[2:3], off offset:3072
	global_load_dword v45, v[4:5], off
	global_load_dword v47, v[4:5], off offset:1024
	global_load_dword v43, v[4:5], off offset:2048
	global_load_dword v41, v[4:5], off offset:3072
	global_load_dword v55, v[0:1], off
	global_load_dword v53, v[0:1], off offset:1024
	global_load_dword v51, v[0:1], off offset:2048
	global_load_dword v49, v[0:1], off offset:3072
	s_mul_i32 s33, s38, 0x810
	v_cndmask_b32_e64 v0, 0, v103, s[14:15]
	v_add_u32_e32 v2, s33, v0
	v_mov_b64_e32 v[0:1], s[54:55]
	v_mad_i64_i32 v[4:5], s[16:17], v2, s44, v[0:1]
	v_lshlrev_b32_e32 v2, 1, v62
	v_lshl_or_b32 v2, v6, 7, v2
	v_or_b32_e32 v96, 0x2200, v2
	v_lshl_add_u64 v[6:7], v[4:5], 0, v[96:97]
	v_mov_b32_e32 v3, v97
	s_mov_b64 s[86:87], 0x2a00
	s_waitcnt vmcnt(0)
	v_mov_b32_e32 v106, v139
	v_lshl_add_u64 v[6:7], v[4:5], 0, v[2:3]
	v_lshl_add_u64 v[60:61], v[4:5], 0, s[86:87]
	v_add_co_u32_e32 v4, vcc, s74, v4
	s_mov_b32 s29, 0xbfb8aa3b
	s_nop 0
	v_addc_co_u32_e32 v5, vcc, 0, v5, vcc
	v_mov_b64_e32 v[56:57], v[160:161]
	v_mov_b64_e32 v[58:59], v[162:163]
	v_mov_b64_e32 v[108:109], v[164:165]
	v_mov_b64_e32 v[110:111], v[166:167]
	s_mov_b32 s49, 0x3f317217
	s_mov_b32 s61, 0x7f800000
	v_mov_b32_e32 v136, 0x41b17218
	v_or_b32_e32 v104, 2, v103
	v_cmp_gt_i32_e64 s[12:13], s26, v104
	s_waitcnt vmcnt(0)
	v_and_b32_e32 v60, 0xffff0000, v56
	v_and_b32_e32 v61, 0xffff0000, v108
	v_lshlrev_b32_e32 v4, 16, v56
	v_lshlrev_b32_e32 v5, 16, v108
	v_pk_mul_f32 v[60:61], v[46:47], v[60:61]
	v_lshlrev_b32_e32 v56, 16, v58
	v_pk_fma_f32 v[4:5], v[44:45], v[4:5], v[60:61]
	v_lshlrev_b32_e32 v60, 16, v57
	v_lshlrev_b32_e32 v61, 16, v109
	v_pk_fma_f32 v[4:5], v[42:43], v[60:61], v[4:5]
	v_and_b32_e32 v61, 0xffff0000, v109
	v_and_b32_e32 v60, 0xffff0000, v57
	v_pk_fma_f32 v[4:5], v[40:41], v[60:61], v[4:5]
	v_lshlrev_b32_e32 v57, 16, v110
	v_pk_fma_f32 v[4:5], v[54:55], v[56:57], v[4:5]
	v_and_b32_e32 v57, 0xffff0000, v110
	v_and_b32_e32 v56, 0xffff0000, v58
	v_pk_fma_f32 v[4:5], v[52:53], v[56:57], v[4:5]
	v_lshlrev_b32_e32 v56, 16, v59
	v_lshlrev_b32_e32 v57, 16, v111
	v_pk_fma_f32 v[4:5], v[50:51], v[56:57], v[4:5]
	v_and_b32_e32 v57, 0xffff0000, v111
	v_and_b32_e32 v56, 0xffff0000, v59
	v_pk_fma_f32 v[4:5], v[48:49], v[56:57], v[4:5]
	v_or_b32_e32 v58, 3, v103
	v_add_f32_e32 v4, v107, v4
	v_add_f32_e32 v4, v4, v5
	v_min_f32_e32 v5, 0, v4
	v_mul_f32_e64 v4, |v4|, s29
	v_exp_f32_e32 v4, v4
	s_nop 0
	v_add_f32_e32 v4, 1.0, v4
	v_cmp_gt_f32_e32 vcc, s45, v4
	s_nop 1
	v_cndmask_b32_e64 v56, 0, 32, vcc
	v_ldexp_f32 v4, v4, v56
	v_log_f32_e32 v4, v4
	s_nop 0
	v_mul_f32_e32 v56, 0x3f317217, v4
	v_fma_f32 v56, v4, s49, -v56
	v_fmac_f32_e32 v56, 0x3377d1cf, v4
	v_fmac_f32_e32 v56, 0x3f317217, v4
	v_cmp_lt_f32_e64 s[16:17], |v4|, s61
	s_nop 1
	v_cndmask_b32_e64 v4, v4, v56, s[16:17]
	v_cndmask_b32_e32 v56, 0, v136, vcc
	v_sub_f32_e32 v4, v4, v56
	v_sub_f32_e32 v4, v5, v4
	s_mov_b32 s16, 0x3d800000
	v_fma_f32 v4, v4, s16, 0
	v_cndmask_b32_e64 v108, 0, v4, s[14:15]
	v_or_b32_e32 v4, 1, v103
	v_cmp_gt_i32_e64 s[18:19], s26, v4
	v_cmp_gt_i32_e64 s[16:17], s26, v58
	s_nop 0
	v_cndmask_b32_e64 v4, 0, v4, s[18:19]
	v_add_u32_e32 v105, s33, v4
	v_mad_i64_i32 v[56:57], s[20:21], v105, s44, v[0:1]
	v_lshl_add_u64 v[4:5], v[56:57], 0, v[96:97]
	v_mov_b32_e32 v109, v159
	v_lshl_add_u64 v[4:5], v[56:57], 0, v[2:3]
	v_lshl_add_u64 v[60:61], v[56:57], 0, s[86:87]
	v_add_co_u32_e32 v56, vcc, s74, v56
	s_nop 1
	v_addc_co_u32_e32 v57, vcc, 0, v57, vcc
	v_mov_b64_e32 v[110:111], v[168:169]
	v_mov_b64_e32 v[112:113], v[170:171]
	v_mov_b64_e32 v[114:115], v[172:173]
	v_mov_b64_e32 v[116:117], v[174:175]
	s_waitcnt vmcnt(0)
	v_and_b32_e32 v60, 0xffff0000, v110
	s_waitcnt vmcnt(0)
	v_and_b32_e32 v61, 0xffff0000, v114
	v_lshlrev_b32_e32 v56, 16, v110
	v_lshlrev_b32_e32 v57, 16, v114
	v_pk_mul_f32 v[60:61], v[46:47], v[60:61]
	s_nop 0
	v_pk_fma_f32 v[56:57], v[44:45], v[56:57], v[60:61]
	v_lshlrev_b32_e32 v60, 16, v111
	v_lshlrev_b32_e32 v61, 16, v115
	v_pk_fma_f32 v[56:57], v[42:43], v[60:61], v[56:57]
	v_and_b32_e32 v61, 0xffff0000, v115
	v_and_b32_e32 v60, 0xffff0000, v111
	v_pk_fma_f32 v[56:57], v[40:41], v[60:61], v[56:57]
	v_lshlrev_b32_e32 v60, 16, v112
	v_lshlrev_b32_e32 v61, 16, v116
	v_pk_fma_f32 v[56:57], v[54:55], v[60:61], v[56:57]
	v_and_b32_e32 v61, 0xffff0000, v116
	v_and_b32_e32 v60, 0xffff0000, v112
	v_pk_fma_f32 v[56:57], v[52:53], v[60:61], v[56:57]
	v_lshlrev_b32_e32 v60, 16, v113
	v_lshlrev_b32_e32 v61, 16, v117
	v_pk_fma_f32 v[56:57], v[50:51], v[60:61], v[56:57]
	v_and_b32_e32 v61, 0xffff0000, v117
	v_and_b32_e32 v60, 0xffff0000, v113
	v_pk_fma_f32 v[56:57], v[48:49], v[60:61], v[56:57]
	s_nop 0
	v_add_f32_e32 v56, v107, v56
	v_add_f32_e32 v56, v56, v57
	v_min_f32_e32 v57, 0, v56
	v_mul_f32_e64 v56, |v56|, s29
	v_exp_f32_e32 v56, v56
	s_nop 0
	v_add_f32_e32 v56, 1.0, v56
	v_cmp_gt_f32_e32 vcc, s45, v56
	s_nop 1
	v_cndmask_b32_e64 v59, 0, 32, vcc
	v_ldexp_f32 v56, v56, v59
	v_log_f32_e32 v56, v56
	s_nop 0
	v_mul_f32_e32 v59, 0x3f317217, v56
	v_fma_f32 v59, v56, s49, -v59
	v_fmac_f32_e32 v59, 0x3377d1cf, v56
	v_fmac_f32_e32 v59, 0x3f317217, v56
	v_cmp_lt_f32_e64 s[20:21], |v56|, s61
	s_nop 1
	v_cndmask_b32_e64 v56, v56, v59, s[20:21]
	v_cndmask_b32_e32 v59, 0, v136, vcc
	v_sub_f32_e32 v56, v56, v59
	v_sub_f32_e32 v56, v57, v56
	v_mul_f32_e32 v56, 0x3d800000, v56
	v_cndmask_b32_e64 v56, 0, v56, s[18:19]
	v_add_f32_e32 v112, v108, v56
	v_cndmask_b32_e64 v56, 0, v104, s[12:13]
	v_add_u32_e32 v56, s33, v56
	v_mad_i64_i32 v[56:57], s[20:21], v56, s44, v[0:1]
	v_add_co_u32_e32 v6, vcc, s74, v6
	v_lshl_add_u64 v[60:61], v[56:57], 0, v[96:97]
	s_nop 0
	v_addc_co_u32_e32 v7, vcc, 0, v7, vcc
	v_mov_b32_e32 v113, v176
	v_mov_b32_e32 v59, v177
	v_lshl_add_u64 v[60:61], v[56:57], 0, v[2:3]
	v_add_co_u32_e32 v6, vcc, s74, v60
	s_waitcnt vmcnt(0)
	v_lshlrev_b32_e32 v59, 16, v59
	v_addc_co_u32_e32 v7, vcc, 0, v61, vcc
	v_mov_b32_e32 v6, v178
	s_waitcnt vmcnt(0)
	v_lshlrev_b32_e32 v60, 16, v6
	v_lshl_add_u64 v[6:7], v[56:57], 0, s[86:87]
	v_add_co_u32_e32 v56, vcc, s74, v56
	s_nop 1
	v_addc_co_u32_e32 v57, vcc, 0, v57, vcc
	v_mov_b64_e32 v[114:115], v[180:181]
	v_mov_b64_e32 v[116:117], v[182:183]
	v_mov_b64_e32 v[118:119], v[184:185]
	v_mov_b64_e32 v[120:121], v[186:187]
	s_waitcnt vmcnt(0)
	v_and_b32_e32 v56, 0xffff0000, v114
	s_waitcnt vmcnt(0)
	v_and_b32_e32 v57, 0xffff0000, v118
	v_lshlrev_b32_e32 v6, 16, v114
	v_lshlrev_b32_e32 v7, 16, v118
	v_pk_mul_f32 v[56:57], v[46:47], v[56:57]
	s_nop 0
	v_pk_fma_f32 v[6:7], v[44:45], v[6:7], v[56:57]
	v_lshlrev_b32_e32 v56, 16, v115
	v_lshlrev_b32_e32 v57, 16, v119
	v_pk_fma_f32 v[6:7], v[42:43], v[56:57], v[6:7]
	v_and_b32_e32 v57, 0xffff0000, v119
	v_and_b32_e32 v56, 0xffff0000, v115
	v_pk_fma_f32 v[6:7], v[40:41], v[56:57], v[6:7]
	v_lshlrev_b32_e32 v56, 16, v116
	v_lshlrev_b32_e32 v57, 16, v120
	v_pk_fma_f32 v[6:7], v[54:55], v[56:57], v[6:7]
	v_and_b32_e32 v57, 0xffff0000, v120
	v_and_b32_e32 v56, 0xffff0000, v116
	v_pk_fma_f32 v[6:7], v[52:53], v[56:57], v[6:7]
	v_lshlrev_b32_e32 v56, 16, v117
	v_lshlrev_b32_e32 v57, 16, v121
	v_pk_fma_f32 v[6:7], v[50:51], v[56:57], v[6:7]
	v_and_b32_e32 v57, 0xffff0000, v121
	v_and_b32_e32 v56, 0xffff0000, v117
	v_pk_fma_f32 v[6:7], v[48:49], v[56:57], v[6:7]
	v_cndmask_b32_e64 v57, 0, v60, s[12:13]
	v_add_f32_e32 v6, v107, v6
	v_add_f32_e32 v6, v6, v7
	v_min_f32_e32 v7, 0, v6
	v_mul_f32_e64 v6, |v6|, s29
	v_exp_f32_e32 v6, v6
	s_nop 0
	v_add_f32_e32 v6, 1.0, v6
	v_cmp_gt_f32_e32 vcc, s45, v6
	s_nop 1
	v_cndmask_b32_e64 v56, 0, 32, vcc
	v_ldexp_f32 v6, v6, v56
	v_log_f32_e32 v6, v6
	s_nop 0
	v_mul_f32_e32 v56, 0x3f317217, v6
	v_fma_f32 v56, v6, s49, -v56
	v_fmac_f32_e32 v56, 0x3377d1cf, v6
	v_fmac_f32_e32 v56, 0x3f317217, v6
	v_cmp_lt_f32_e64 s[20:21], |v6|, s61
	s_nop 1
	v_cndmask_b32_e64 v6, v6, v56, s[20:21]
	v_cndmask_b32_e32 v56, 0, v136, vcc
	v_sub_f32_e32 v6, v6, v56
	v_sub_f32_e32 v6, v7, v6
	v_mul_f32_e32 v6, 0x3d800000, v6
	v_cndmask_b32_e64 v6, 0, v6, s[12:13]
	v_add_f32_e32 v116, v112, v6
	v_cndmask_b32_e64 v6, 0, v58, s[16:17]
	v_add_u32_e32 v110, s33, v6
	v_mad_i64_i32 v[6:7], s[20:21], v110, s44, v[0:1]
	v_cndmask_b32_e64 v56, 0, v59, s[14:15]
	v_lshl_add_u64 v[58:59], v[6:7], 0, v[96:97]
	v_mov_b32_e32 v115, v179
	v_lshl_add_u64 v[58:59], v[6:7], 0, v[2:3]
	v_add_co_u32_e32 v58, vcc, s74, v58
	s_nop 1
	v_addc_co_u32_e32 v59, vcc, 0, v59, vcc
	v_add_co_u32_e32 v4, vcc, s74, v4
	v_mov_b32_e32 v58, v188
	s_nop 0
	v_addc_co_u32_e32 v5, vcc, 0, v5, vcc
	v_mov_b32_e32 v4, v189
	s_waitcnt vmcnt(0)
	v_lshlrev_b32_e32 v114, 16, v58
	v_lshl_add_u64 v[58:59], v[6:7], 0, s[86:87]
	s_waitcnt vmcnt(0)
	v_lshlrev_b32_e32 v111, 16, v4
	v_add_co_u32_e32 v4, vcc, s74, v6
	s_nop 1
	v_addc_co_u32_e32 v5, vcc, 0, v7, vcc
	v_mov_b64_e32 v[4:5], v[190:191]
	v_mov_b64_e32 v[6:7], v[192:193]
	s_nop 0
	v_mov_b64_e32 v[58:59], v[194:195]
	v_mov_b64_e32 v[60:61], v[196:197]
	v_mov_b32_e32 v140, v0
	v_mov_b32_e32 v141, v1
	v_mov_b32_e32 v142, v2
	v_mov_b32_e32 v143, v3
	v_or_b32_e32 v150, 4, v103
	v_cmp_gt_i32_e64 s[22:23], s26, v150
	v_or_b32_e32 v139, 6, v103
	s_nop 1
	v_cndmask_b32_e64 v144, 0, v150, s[22:23]
	v_add_u32_e32 v144, s33, v144
	v_mad_i64_i32 v[146:147], s[24:25], v144, s44, v[140:141]
	v_lshl_add_u64 v[144:145], v[146:147], 0, v[96:97]
	global_load_ushort v152, v[144:145], off
	v_lshl_add_u64 v[144:145], v[146:147], 0, v[142:143]
	v_lshl_add_u64 v[148:149], v[146:147], 0, s[86:87]
	v_add_co_u32_e32 v146, vcc, s74, v146
	v_cmp_gt_i32_e64 s[20:21], s26, v139
	s_nop 1
	v_addc_co_u32_e32 v147, vcc, 0, v147, vcc
	global_load_dwordx4 v[158:161], v[146:147], off offset:2560
	global_load_dwordx4 v[162:165], v[148:149], off offset:16
	v_or_b32_e32 v153, 7, v103
	v_or_b32_e32 v146, 5, v103
	v_cmp_gt_i32_e64 s[24:25], s26, v153
	v_cmp_gt_i32_e64 s[98:99], s26, v146
	s_nop 1
	v_cndmask_b32_e64 v146, 0, v146, s[98:99]
	v_add_u32_e32 v151, s33, v146
	v_mad_i64_i32 v[148:149], s[30:31], v151, s44, v[140:141]
	v_lshl_add_u64 v[146:147], v[148:149], 0, v[96:97]
	global_load_ushort v166, v[146:147], off
	v_lshl_add_u64 v[146:147], v[148:149], 0, v[142:143]
	v_lshl_add_u64 v[156:157], v[148:149], 0, s[86:87]
	v_add_co_u32_e32 v148, vcc, s74, v148
	s_nop 1
	v_addc_co_u32_e32 v149, vcc, 0, v149, vcc
	global_load_dwordx4 v[168:171], v[148:149], off offset:2560
	global_load_dwordx4 v[172:175], v[156:157], off offset:16
	v_cndmask_b32_e64 v148, 0, v139, s[20:21]
	v_add_u32_e32 v148, s33, v148
	v_mad_i64_i32 v[148:149], s[30:31], v148, s44, v[140:141]
	v_lshl_add_u64 v[154:155], v[148:149], 0, v[96:97]
	global_load_ushort v167, v[154:155], off
	v_lshl_add_u64 v[154:155], v[148:149], 0, v[142:143]
	v_add_co_u32_e32 v154, vcc, s74, v154
	s_nop 1
	v_addc_co_u32_e32 v155, vcc, 0, v155, vcc
	v_add_co_u32_e32 v144, vcc, s74, v144
	global_load_ushort v176, v[154:155], off offset:1024
	s_nop 1
	v_addc_co_u32_e32 v145, vcc, 0, v145, vcc
	global_load_ushort v177, v[144:145], off offset:1024
	v_lshl_add_u64 v[144:145], v[148:149], 0, s[86:87]
	v_add_co_u32_e32 v148, vcc, s74, v148
	s_nop 1
	v_addc_co_u32_e32 v149, vcc, 0, v149, vcc
	global_load_dwordx4 v[178:181], v[148:149], off offset:2560
	global_load_dwordx4 v[182:185], v[144:145], off offset:16
	v_cndmask_b32_e64 v144, 0, v153, s[24:25]
	v_add_u32_e32 v153, s33, v144
	v_mad_i64_i32 v[140:141], s[30:31], v153, s44, v[140:141]
	v_lshl_add_u64 v[142:143], v[140:141], 0, v[142:143]
	v_add_co_u32_e32 v142, vcc, s74, v142
	v_lshl_add_u64 v[144:145], v[140:141], 0, v[96:97]
	s_nop 1
	v_addc_co_u32_e32 v143, vcc, 0, v143, vcc
	global_load_ushort v186, v[144:145], off
	global_load_ushort v187, v[142:143], off offset:1024
	v_add_co_u32_e32 v142, vcc, s74, v146
	s_nop 1
	v_addc_co_u32_e32 v143, vcc, 0, v147, vcc
	global_load_ushort v188, v[142:143], off offset:1024
	v_lshl_add_u64 v[144:145], v[140:141], 0, s[86:87]
	v_add_co_u32_e32 v140, vcc, s74, v140
	s_nop 1
	v_addc_co_u32_e32 v141, vcc, 0, v141, vcc
	global_load_dwordx4 v[190:193], v[140:141], off offset:2560
	global_load_dwordx4 v[194:197], v[144:145], off offset:16
	s_waitcnt vmcnt(0)
	v_and_b32_e32 v120, 0xffff0000, v4
	s_waitcnt vmcnt(0)
	v_and_b32_e32 v121, 0xffff0000, v58
	v_lshlrev_b32_e32 v118, 16, v4
	v_lshlrev_b32_e32 v119, 16, v58
	v_pk_mul_f32 v[120:121], v[46:47], v[120:121]
	v_and_b32_e32 v58, 0xffff0000, v5
	v_pk_fma_f32 v[118:119], v[44:45], v[118:119], v[120:121]
	v_lshlrev_b32_e32 v120, 16, v5
	v_lshlrev_b32_e32 v121, 16, v59
	v_pk_fma_f32 v[118:119], v[42:43], v[120:121], v[118:119]
	v_and_b32_e32 v59, 0xffff0000, v59
	v_pk_fma_f32 v[4:5], v[40:41], v[58:59], v[118:119]
	v_lshlrev_b32_e32 v58, 16, v6
	v_lshlrev_b32_e32 v59, 16, v60
	v_pk_fma_f32 v[4:5], v[54:55], v[58:59], v[4:5]
	v_and_b32_e32 v59, 0xffff0000, v60
	v_and_b32_e32 v58, 0xffff0000, v6
	v_pk_fma_f32 v[4:5], v[52:53], v[58:59], v[4:5]
	v_lshlrev_b32_e32 v58, 16, v7
	v_lshlrev_b32_e32 v59, 16, v61
	v_pk_fma_f32 v[4:5], v[50:51], v[58:59], v[4:5]
	v_and_b32_e32 v59, 0xffff0000, v61
	v_and_b32_e32 v58, 0xffff0000, v7
	v_pk_fma_f32 v[4:5], v[48:49], v[58:59], v[4:5]
	v_cndmask_b32_e64 v59, 0, v114, s[16:17]
	v_add_f32_e32 v4, v107, v4
	v_add_f32_e32 v4, v4, v5
	v_min_f32_e32 v5, 0, v4
	v_mul_f32_e64 v4, |v4|, s29
	v_exp_f32_e32 v4, v4
	v_or_b32_e32 v114, 4, v103
	v_cmp_gt_i32_e64 s[22:23], s26, v114
	v_cndmask_b32_e64 v58, 0, v111, s[18:19]
	v_add_f32_e32 v4, 1.0, v4
	v_cmp_gt_f32_e32 vcc, s45, v4
	v_or_b32_e32 v111, 6, v103
	s_nop 0
	v_cndmask_b32_e64 v6, 0, 32, vcc
	v_ldexp_f32 v4, v4, v6
	v_log_f32_e32 v4, v4
	s_nop 0
	v_mul_f32_e32 v6, 0x3f317217, v4
	v_fma_f32 v6, v4, s49, -v6
	v_fmac_f32_e32 v6, 0x3377d1cf, v4
	v_fmac_f32_e32 v6, 0x3f317217, v4
	v_cmp_lt_f32_e64 s[20:21], |v4|, s61
	s_nop 1
	v_cndmask_b32_e64 v4, v4, v6, s[20:21]
	v_cndmask_b32_e32 v6, 0, v136, vcc
	v_sub_f32_e32 v4, v4, v6
	v_sub_f32_e32 v4, v5, v4
	v_mul_f32_e32 v4, 0x3d800000, v4
	v_cndmask_b32_e64 v4, 0, v4, s[16:17]
	v_add_f32_e32 v119, v116, v4
	v_cndmask_b32_e64 v4, 0, v114, s[22:23]
	v_add_u32_e32 v4, s33, v4
	v_mad_i64_i32 v[6:7], s[24:25], v4, s44, v[0:1]
	v_lshl_add_u64 v[4:5], v[6:7], 0, v[96:97]
	s_waitcnt vmcnt(0)
	v_mov_b32_e32 v118, v152
	v_lshl_add_u64 v[4:5], v[6:7], 0, v[2:3]
	v_lshl_add_u64 v[60:61], v[6:7], 0, s[86:87]
	v_add_co_u32_e32 v6, vcc, s74, v6
	v_cmp_gt_i32_e64 s[20:21], s26, v111
	s_nop 0
	v_addc_co_u32_e32 v7, vcc, 0, v7, vcc
	v_mov_b64_e32 v[120:121], v[158:159]
	v_mov_b64_e32 v[122:123], v[160:161]
	v_mov_b64_e32 v[124:125], v[162:163]
	v_mov_b64_e32 v[126:127], v[164:165]
	s_waitcnt vmcnt(0)
	v_and_b32_e32 v60, 0xffff0000, v120
	s_waitcnt vmcnt(0)
	v_and_b32_e32 v61, 0xffff0000, v124
	v_lshlrev_b32_e32 v6, 16, v120
	v_lshlrev_b32_e32 v7, 16, v124
	v_pk_mul_f32 v[60:61], v[46:47], v[60:61]
	s_nop 0
	v_pk_fma_f32 v[6:7], v[44:45], v[6:7], v[60:61]
	v_lshlrev_b32_e32 v60, 16, v121
	v_lshlrev_b32_e32 v61, 16, v125
	v_pk_fma_f32 v[6:7], v[42:43], v[60:61], v[6:7]
	v_and_b32_e32 v61, 0xffff0000, v125
	v_and_b32_e32 v60, 0xffff0000, v121
	v_pk_fma_f32 v[6:7], v[40:41], v[60:61], v[6:7]
	v_lshlrev_b32_e32 v60, 16, v122
	v_lshlrev_b32_e32 v61, 16, v126
	v_pk_fma_f32 v[6:7], v[54:55], v[60:61], v[6:7]
	v_and_b32_e32 v61, 0xffff0000, v126
	v_and_b32_e32 v60, 0xffff0000, v122
	v_pk_fma_f32 v[6:7], v[52:53], v[60:61], v[6:7]
	v_lshlrev_b32_e32 v60, 16, v123
	v_lshlrev_b32_e32 v61, 16, v127
	v_pk_fma_f32 v[6:7], v[50:51], v[60:61], v[6:7]
	v_and_b32_e32 v61, 0xffff0000, v127
	v_and_b32_e32 v60, 0xffff0000, v123
	v_pk_fma_f32 v[6:7], v[48:49], v[60:61], v[6:7]
	v_or_b32_e32 v123, 7, v103
	v_add_f32_e32 v6, v107, v6
	v_add_f32_e32 v6, v6, v7
	v_min_f32_e32 v7, 0, v6
	v_mul_f32_e64 v6, |v6|, s29
	v_exp_f32_e32 v6, v6
	s_nop 0
	v_add_f32_e32 v6, 1.0, v6
	v_cmp_gt_f32_e32 vcc, s45, v6
	s_nop 1
	v_cndmask_b32_e64 v60, 0, 32, vcc
	v_ldexp_f32 v6, v6, v60
	v_log_f32_e32 v6, v6
	s_nop 0
	v_mul_f32_e32 v60, 0x3f317217, v6
	v_fma_f32 v60, v6, s49, -v60
	v_fmac_f32_e32 v60, 0x3377d1cf, v6
	v_fmac_f32_e32 v60, 0x3f317217, v6
	v_cmp_lt_f32_e64 s[24:25], |v6|, s61
	s_nop 1
	v_cndmask_b32_e64 v6, v6, v60, s[24:25]
	v_cndmask_b32_e32 v60, 0, v136, vcc
	v_sub_f32_e32 v6, v6, v60
	v_sub_f32_e32 v6, v7, v6
	v_mul_f32_e32 v6, 0x3d800000, v6
	v_cndmask_b32_e64 v122, 0, v6, s[22:23]
	v_or_b32_e32 v6, 5, v103
	v_cmp_gt_i32_e64 s[24:25], s26, v123
	v_cmp_gt_i32_e64 s[26:27], s26, v6
	s_nop 1
	v_cndmask_b32_e64 v6, 0, v6, s[26:27]
	v_add_u32_e32 v117, s33, v6
	v_mad_i64_i32 v[60:61], s[30:31], v117, s44, v[0:1]
	v_lshl_add_u64 v[6:7], v[60:61], 0, v[96:97]
	v_mov_b32_e32 v120, v166
	v_lshl_add_u64 v[6:7], v[60:61], 0, v[2:3]
	v_lshl_add_u64 v[128:129], v[60:61], 0, s[86:87]
	v_add_co_u32_e32 v60, vcc, s74, v60
	s_nop 1
	v_addc_co_u32_e32 v61, vcc, 0, v61, vcc
	v_mov_b64_e32 v[124:125], v[168:169]
	v_mov_b64_e32 v[126:127], v[170:171]
	s_nop 0
	v_mov_b64_e32 v[128:129], v[172:173]
	v_mov_b64_e32 v[130:131], v[174:175]
	s_waitcnt vmcnt(0)
	v_and_b32_e32 v132, 0xffff0000, v124
	s_waitcnt vmcnt(0)
	v_and_b32_e32 v133, 0xffff0000, v128
	v_lshlrev_b32_e32 v60, 16, v124
	v_lshlrev_b32_e32 v61, 16, v128
	v_pk_mul_f32 v[132:133], v[46:47], v[132:133]
	v_and_b32_e32 v128, 0xffff0000, v125
	v_pk_fma_f32 v[60:61], v[44:45], v[60:61], v[132:133]
	v_lshlrev_b32_e32 v132, 16, v125
	v_lshlrev_b32_e32 v133, 16, v129
	v_pk_fma_f32 v[60:61], v[42:43], v[132:133], v[60:61]
	v_and_b32_e32 v129, 0xffff0000, v129
	v_pk_fma_f32 v[60:61], v[40:41], v[128:129], v[60:61]
	v_lshlrev_b32_e32 v124, 16, v126
	v_lshlrev_b32_e32 v125, 16, v130
	v_pk_fma_f32 v[60:61], v[54:55], v[124:125], v[60:61]
	v_and_b32_e32 v125, 0xffff0000, v130
	v_and_b32_e32 v124, 0xffff0000, v126
	v_pk_fma_f32 v[60:61], v[52:53], v[124:125], v[60:61]
	v_lshlrev_b32_e32 v124, 16, v127
	v_lshlrev_b32_e32 v125, 16, v131
	v_pk_fma_f32 v[60:61], v[50:51], v[124:125], v[60:61]
	v_and_b32_e32 v125, 0xffff0000, v131
	v_and_b32_e32 v124, 0xffff0000, v127
	v_pk_fma_f32 v[60:61], v[48:49], v[124:125], v[60:61]
	s_nop 0
	v_add_f32_e32 v60, v107, v60
	v_add_f32_e32 v60, v60, v61
	v_min_f32_e32 v61, 0, v60
	v_mul_f32_e64 v60, |v60|, s29
	v_exp_f32_e32 v60, v60
	s_nop 0
	v_add_f32_e32 v60, 1.0, v60
	v_cmp_gt_f32_e32 vcc, s45, v60
	s_nop 1
	v_cndmask_b32_e64 v121, 0, 32, vcc
	v_ldexp_f32 v60, v60, v121
	v_log_f32_e32 v60, v60
	s_nop 0
	v_mul_f32_e32 v121, 0x3f317217, v60
	v_fma_f32 v121, v60, s49, -v121
	v_fmac_f32_e32 v121, 0x3377d1cf, v60
	v_fmac_f32_e32 v121, 0x3f317217, v60
	v_cmp_lt_f32_e64 s[30:31], |v60|, s61
	s_nop 1
	v_cndmask_b32_e64 v60, v60, v121, s[30:31]
	v_cndmask_b32_e32 v121, 0, v136, vcc
	v_sub_f32_e32 v60, v60, v121
	v_sub_f32_e32 v60, v61, v60
	v_mul_f32_e32 v60, 0x3d800000, v60
	v_cndmask_b32_e64 v124, 0, v60, s[26:27]
	v_cndmask_b32_e64 v60, 0, v111, s[20:21]
	v_add_u32_e32 v60, s33, v60
	v_mad_i64_i32 v[60:61], s[30:31], v60, s44, v[0:1]
	v_lshl_add_u64 v[126:127], v[60:61], 0, v[96:97]
	v_mov_b32_e32 v121, v167
	v_lshl_add_u64 v[126:127], v[60:61], 0, v[2:3]
	v_add_co_u32_e32 v126, vcc, s74, v126
	s_nop 1
	v_addc_co_u32_e32 v127, vcc, 0, v127, vcc
	v_add_co_u32_e32 v4, vcc, s74, v4
	v_mov_b32_e32 v125, v176
	s_nop 0
	v_addc_co_u32_e32 v5, vcc, 0, v5, vcc
	v_mov_b32_e32 v4, v177
	s_waitcnt vmcnt(0)
	v_lshlrev_b32_e32 v135, 16, v125
	s_waitcnt vmcnt(0)
	v_lshlrev_b32_e32 v134, 16, v4
	v_lshl_add_u64 v[4:5], v[60:61], 0, s[86:87]
	v_add_co_u32_e32 v60, vcc, s74, v60
	s_nop 1
	v_addc_co_u32_e32 v61, vcc, 0, v61, vcc
	v_mov_b64_e32 v[126:127], v[178:179]
	v_mov_b64_e32 v[128:129], v[180:181]
	v_mov_b64_e32 v[130:131], v[182:183]
	v_mov_b64_e32 v[132:133], v[184:185]
	s_waitcnt vmcnt(0)
	v_and_b32_e32 v60, 0xffff0000, v126
	s_waitcnt vmcnt(0)
	v_and_b32_e32 v61, 0xffff0000, v130
	v_lshlrev_b32_e32 v4, 16, v126
	v_lshlrev_b32_e32 v5, 16, v130
	v_pk_mul_f32 v[60:61], v[46:47], v[60:61]
	s_nop 0
	v_pk_fma_f32 v[4:5], v[44:45], v[4:5], v[60:61]
	v_lshlrev_b32_e32 v60, 16, v127
	v_lshlrev_b32_e32 v61, 16, v131
	v_pk_fma_f32 v[4:5], v[42:43], v[60:61], v[4:5]
	v_and_b32_e32 v61, 0xffff0000, v131
	v_and_b32_e32 v60, 0xffff0000, v127
	v_pk_fma_f32 v[4:5], v[40:41], v[60:61], v[4:5]
	v_lshlrev_b32_e32 v60, 16, v128
	v_lshlrev_b32_e32 v61, 16, v132
	v_pk_fma_f32 v[4:5], v[54:55], v[60:61], v[4:5]
	v_and_b32_e32 v61, 0xffff0000, v132
	v_and_b32_e32 v60, 0xffff0000, v128
	v_pk_fma_f32 v[4:5], v[52:53], v[60:61], v[4:5]
	v_lshlrev_b32_e32 v60, 16, v129
	v_lshlrev_b32_e32 v61, 16, v133
	v_pk_fma_f32 v[4:5], v[50:51], v[60:61], v[4:5]
	v_and_b32_e32 v61, 0xffff0000, v133
	v_and_b32_e32 v60, 0xffff0000, v129
	v_pk_fma_f32 v[4:5], v[48:49], v[60:61], v[4:5]
	v_cndmask_b32_e64 v61, 0, v135, s[20:21]
	v_add_f32_e32 v4, v107, v4
	v_add_f32_e32 v4, v4, v5
	v_min_f32_e32 v5, 0, v4
	v_mul_f32_e64 v4, |v4|, s29
	v_exp_f32_e32 v4, v4
	s_nop 0
	v_add_f32_e32 v4, 1.0, v4
	v_cmp_gt_f32_e32 vcc, s45, v4
	s_nop 1
	v_cndmask_b32_e64 v60, 0, 32, vcc
	v_ldexp_f32 v4, v4, v60
	v_log_f32_e32 v4, v4
	s_nop 0
	v_mul_f32_e32 v60, 0x3f317217, v4
	v_fma_f32 v60, v4, s49, -v60
	v_fmac_f32_e32 v60, 0x3377d1cf, v4
	v_fmac_f32_e32 v60, 0x3f317217, v4
	v_cmp_lt_f32_e64 s[30:31], |v4|, s61
	s_nop 1
	v_cndmask_b32_e64 v4, v4, v60, s[30:31]
	v_cndmask_b32_e32 v60, 0, v136, vcc
	v_sub_f32_e32 v4, v4, v60
	v_sub_f32_e32 v4, v5, v4
	v_mul_f32_e32 v4, 0x3d800000, v4
	v_cndmask_b32_e64 v125, 0, v4, s[20:21]
	v_cndmask_b32_e64 v4, 0, v123, s[24:25]
	v_add_u32_e32 v123, s33, v4
	v_mad_i64_i32 v[0:1], s[30:31], v123, s44, v[0:1]
	v_lshl_add_u64 v[2:3], v[0:1], 0, v[2:3]
	v_add_co_u32_e32 v2, vcc, s74, v2
	v_lshl_add_u64 v[4:5], v[0:1], 0, v[96:97]
	s_nop 0
	v_addc_co_u32_e32 v3, vcc, 0, v3, vcc
	v_mov_b32_e32 v96, v186
	v_cndmask_b32_e64 v60, 0, v134, s[22:23]
	v_mov_b32_e32 v4, v187
	v_add_co_u32_e32 v2, vcc, s74, v6
	s_waitcnt vmcnt(0)
	v_lshlrev_b32_e32 v131, 16, v4
	v_addc_co_u32_e32 v3, vcc, 0, v7, vcc
	v_mov_b32_e32 v2, v188
	v_lshl_add_u64 v[4:5], v[0:1], 0, s[86:87]
	v_add_co_u32_e32 v0, vcc, s74, v0
	s_waitcnt vmcnt(0)
	v_lshlrev_b32_e32 v130, 16, v2
	v_addc_co_u32_e32 v1, vcc, 0, v1, vcc
	v_mov_b64_e32 v[0:1], v[190:191]
	v_mov_b64_e32 v[2:3], v[192:193]
	s_nop 0
	v_mov_b64_e32 v[4:5], v[194:195]
	v_mov_b64_e32 v[6:7], v[196:197]
	s_barrier
	s_waitcnt vmcnt(1)
	v_and_b32_e32 v128, 0xffff0000, v0
	s_waitcnt vmcnt(0)
	v_and_b32_e32 v129, 0xffff0000, v4
	v_lshlrev_b32_e32 v126, 16, v0
	v_lshlrev_b32_e32 v127, 16, v4
	v_pk_mul_f32 v[46:47], v[46:47], v[128:129]
	v_and_b32_e32 v4, 0xffff0000, v1
	v_pk_fma_f32 v[44:45], v[44:45], v[126:127], v[46:47]
	v_lshlrev_b32_e32 v46, 16, v1
	v_lshlrev_b32_e32 v47, 16, v5
	v_pk_fma_f32 v[42:43], v[42:43], v[46:47], v[44:45]
	v_and_b32_e32 v5, 0xffff0000, v5
	v_pk_fma_f32 v[0:1], v[40:41], v[4:5], v[42:43]
	v_lshlrev_b32_e32 v4, 16, v2
	v_lshlrev_b32_e32 v5, 16, v6
	v_pk_fma_f32 v[0:1], v[54:55], v[4:5], v[0:1]
	v_and_b32_e32 v5, 0xffff0000, v6
	v_and_b32_e32 v4, 0xffff0000, v2
	v_pk_fma_f32 v[0:1], v[52:53], v[4:5], v[0:1]
	v_lshlrev_b32_e32 v4, 16, v3
	v_lshlrev_b32_e32 v5, 16, v7
	v_pk_fma_f32 v[0:1], v[50:51], v[4:5], v[0:1]
	v_and_b32_e32 v5, 0xffff0000, v7
	v_and_b32_e32 v4, 0xffff0000, v3
	v_pk_fma_f32 v[0:1], v[48:49], v[4:5], v[0:1]
	v_add_f32_e32 v52, v119, v122
	v_add_f32_e32 v0, v107, v0
	v_add_f32_e32 v0, v0, v1
	v_min_f32_e32 v1, 0, v0
	v_mul_f32_e64 v0, |v0|, s29
	v_exp_f32_e32 v0, v0
	v_add_f32_e32 v53, v52, v124
	v_add_f32_e32 v54, v53, v125
	v_add_f32_e32 v0, 1.0, v0
	v_cmp_gt_f32_e32 vcc, s45, v0
	s_nop 1
	v_cndmask_b32_e64 v2, 0, 32, vcc
	v_ldexp_f32 v0, v0, v2
	v_log_f32_e32 v0, v0
	s_nop 0
	v_mul_f32_e32 v2, 0x3f317217, v0
	v_fma_f32 v2, v0, s49, -v2
	v_fmac_f32_e32 v2, 0x3377d1cf, v0
	v_fmac_f32_e32 v2, 0x3f317217, v0
	v_cmp_lt_f32_e64 s[30:31], |v0|, s61
	s_nop 1
	v_cndmask_b32_e64 v0, v0, v2, s[30:31]
	v_cndmask_b32_e32 v2, 0, v136, vcc
	v_sub_f32_e32 v0, v0, v2
	v_sub_f32_e32 v0, v1, v0
	v_mul_f32_e32 v0, 0x3d800000, v0
	v_cndmask_b32_e64 v2, 0, v0, s[24:25]
	v_add_f32_e32 v5, v54, v2
	ds_write_b32 v68, v5
	s_waitcnt lgkmcnt(0)
	s_barrier
	ds_read2st64_b32 v[6:7], v69 offset1:2
	ds_read2st64_b32 v[2:3], v69 offset0:4 offset1:6
	v_cndmask_b32_e64 v1, 0, v131, s[24:25]
	v_cndmask_b32_e64 v0, 0, v130, s[26:27]
	s_waitcnt lgkmcnt(1)
	v_add_f32_e32 v7, v6, v7
	s_waitcnt lgkmcnt(0)
	v_add_f32_e32 v4, v7, v2
	v_cndmask_b32_e64 v2, v4, v7, s[4:5]
	v_cndmask_b32_e64 v2, v2, v6, s[2:3]
	v_cndmask_b32_e64 v47, v2, 0, s[0:1]
	v_mov_b32_e32 v46, v3
	v_add_f32_e32 v45, v108, v47
	v_pk_add_f32 v[2:3], v[4:5], v[46:47]
	v_add_f32_e32 v44, v112, v47
	v_sub_f32_e32 v5, v2, v45
	v_mul_f32_e32 v5, 0x3fb8aa3b, v5
	v_exp_f32_e32 v40, v5
	v_sub_f32_e32 v5, v2, v44
	v_mul_f32_e32 v5, 0x3fb8aa3b, v5
	v_add_f32_e32 v43, v116, v47
	v_exp_f32_e32 v48, v5
	v_sub_f32_e32 v5, v2, v43
	v_mul_f32_e32 v5, 0x3fb8aa3b, v5
	v_exp_f32_e32 v41, v5
	v_add_f32_e32 v42, v119, v47
	v_sub_f32_e32 v5, v2, v42
	v_mul_f32_e32 v5, 0x3fb8aa3b, v5
	v_pk_mul_f32 v[50:51], v[56:57], v[40:41]
	v_add_f32_e32 v41, v52, v47
	v_exp_f32_e32 v49, v5
	v_sub_f32_e32 v5, v2, v41
	v_add_f32_e32 v40, v53, v47
	v_mul_f32_e32 v5, 0x3fb8aa3b, v5
	v_exp_f32_e32 v46, v5
	v_sub_f32_e32 v5, v2, v40
	v_mul_f32_e32 v5, 0x3fb8aa3b, v5
	v_exp_f32_e32 v52, v5
	v_add_f32_e32 v5, v47, v54
	v_sub_f32_e32 v53, v2, v3
	v_sub_f32_e32 v47, v2, v5
	v_mul_f32_e32 v53, 0x3fb8aa3b, v53
	v_mul_f32_e32 v47, 0x3fb8aa3b, v47
	v_exp_f32_e32 v53, v53
	v_exp_f32_e32 v47, v47
	v_pk_mul_f32 v[48:49], v[58:59], v[48:49]
	v_pk_mul_f32 v[52:53], v[0:1], v[52:53]
	v_pk_mul_f32 v[46:47], v[60:61], v[46:47]
	s_nop 0
	s_nop 0
	s_nop 0
	s_nop 0
	v_cvt_pk_bf16_f32 v52, v52, v52
	v_cvt_pk_bf16_f32 v53, v53, v53
	v_cvt_pk_bf16_f32 v54, v48, v48
	v_cvt_pk_bf16_f32 v55, v49, v49
	s_nop 0
	s_nop 0
	s_nop 0
	s_nop 0
	v_cvt_pk_bf16_f32 v47, v47, v47
	v_cvt_pk_bf16_f32 v46, v46, v46
	v_cvt_pk_bf16_f32 v48, v51, v51
	v_cvt_pk_bf16_f32 v49, v50, v50
	v_lshrrev_b32_e32 v46, 16, v46
	v_lshrrev_b32_e32 v47, 16, v47
	v_lshrrev_b32_e32 v50, 16, v49
	v_lshrrev_b32_e32 v51, 16, v48
	v_and_or_b32 v49, v53, s36, v47
	v_and_or_b32 v48, v52, s36, v46
	v_and_or_b32 v47, v55, s36, v51
	v_and_or_b32 v46, v54, s36, v50
	v_lshl_add_u64 v[50:51], v[38:39], 0, v[14:15]
	v_add_co_u32_e32 v50, vcc, 0x1000, v50
	s_nop 1
	v_addc_co_u32_e32 v51, vcc, 0, v51, vcc
	global_store_dwordx4 v[50:51], v[46:49], off
	s_and_saveexec_b64 s[30:31], s[8:9]
	s_cbranch_execz .LBB0_439
	v_mul_f32_e32 v2, 0x3fb8aa3b, v2
	v_exp_f32_e32 v2, v2
	v_lshl_add_u64 v[38:39], v[38:39], 0, v[8:9]
	v_add_co_u32_e32 v38, vcc, 0x2000, v38
	s_nop 1
	v_addc_co_u32_e32 v39, vcc, 0, v39, vcc
	global_store_dword v[38:39], v2, off offset:2048
.LBB0_439:
	s_or_b64 exec, exec, s[30:31]
	v_lshlrev_b32_e32 v2, 16, v106
	v_mul_f32_e32 v2, 0x3e000000, v2
	v_cndmask_b32_e64 v38, 0, v2, s[14:15]
	v_cndmask_b32_e64 v2, v4, v6, s[6:7]
	v_mul_f32_e32 v4, 0x3fb8aa3b, v45
	v_exp_f32_e32 v4, v4
	s_nop 0
	v_mul_f32_e32 v4, v38, v4
	s_nop 0
	v_cvt_pk_bf16_f32 v4, v4, v4
	v_add_u32_e32 v6, v71, v72
	ds_write_b16_d16_hi v6, v4 offset:2048
	v_sub_f32_e32 v4, v45, v2
	v_mul_f32_e32 v4, 0x3fb8aa3b, v4
	v_exp_f32_e32 v4, v4
	s_nop 0
	v_mul_f32_e32 v4, v38, v4
	s_nop 0
	v_cvt_pk_bf16_f32 v4, v4, v4
	ds_write_b16_d16_hi v73, v4 offset:10240
	v_sub_f32_e32 v4, v2, v45
	v_mul_f32_e32 v4, 0x3fb8aa3b, v4
	v_exp_f32_e32 v4, v4
	s_nop 0
	v_mul_f32_e32 v4, v56, v4
	s_nop 0
	v_cvt_pk_bf16_f32 v4, v4, v4
	ds_write_b16_d16_hi v73, v4 offset:18944
	s_and_saveexec_b64 s[30:31], s[6:7]
	s_xor_b64 s[30:31], exec, s[30:31]
	s_cbranch_execz .LBB0_441
	v_sub_f32_e32 v4, v7, v45
	v_mul_f32_e32 v4, 0x3fb8aa3b, v4
	v_exp_f32_e32 v4, v4
	s_nop 0
	v_mul_f32_e32 v4, v56, v4
	s_nop 0
	v_cvt_pk_bf16_f32 v4, v4, v4
	ds_write_b16_d16_hi v73, v4 offset:32000
.LBB0_441:
	s_andn2_saveexec_b64 s[30:31], s[30:31]
	s_cbranch_execz .LBB0_443
	v_sub_f32_e32 v4, v45, v7
	v_mul_f32_e32 v4, 0x3fb8aa3b, v4
	v_exp_f32_e32 v4, v4
	s_nop 0
	v_mul_f32_e32 v4, v38, v4
	s_nop 0
	v_cvt_pk_bf16_f32 v4, v4, v4
	ds_write_b16_d16_hi v74, v4 offset:23296
.LBB0_443:
	s_or_b64 exec, exec, s[30:31]
	v_mul_f32_e32 v6, 0x3fb8aa3b, v44
	v_exp_f32_e32 v6, v6
	v_lshlrev_b32_e32 v4, 16, v109
	v_mul_f32_e32 v4, 0x3e000000, v4
	v_cndmask_b32_e64 v4, 0, v4, s[18:19]
	v_mul_f32_e32 v6, v4, v6
	s_nop 0
	v_cvt_pk_bf16_f32 v6, v6, v6
	v_add_u32_e32 v38, v71, v75
	ds_write_b16_d16_hi v38, v6 offset:2048
	v_sub_f32_e32 v6, v44, v2
	v_mul_f32_e32 v6, 0x3fb8aa3b, v6
	v_exp_f32_e32 v6, v6
	s_nop 0
	v_mul_f32_e32 v6, v4, v6
	s_nop 0
	v_cvt_pk_bf16_f32 v6, v6, v6
	ds_write_b16_d16_hi v76, v6 offset:10240
	v_sub_f32_e32 v6, v2, v44
	v_mul_f32_e32 v6, 0x3fb8aa3b, v6
	v_exp_f32_e32 v6, v6
	s_nop 0
	v_mul_f32_e32 v6, v58, v6
	s_nop 0
	v_cvt_pk_bf16_f32 v6, v6, v6
	ds_write_b16_d16_hi v76, v6 offset:18944
	s_and_saveexec_b64 s[30:31], s[6:7]
	s_xor_b64 s[30:31], exec, s[30:31]
	s_cbranch_execz .LBB0_445
	v_sub_f32_e32 v4, v7, v44
	v_mul_f32_e32 v4, 0x3fb8aa3b, v4
	v_exp_f32_e32 v4, v4
	s_nop 0
	v_mul_f32_e32 v4, v58, v4
	v_bfe_u32 v6, v4, 16, 1
	v_add3_u32 v4, v4, v6, s48
	ds_write_b16_d16_hi v76, v4 offset:32000
.LBB0_445:
	s_andn2_saveexec_b64 s[30:31], s[30:31]
	s_cbranch_execz .LBB0_447
	v_sub_f32_e32 v6, v44, v7
	v_mul_f32_e32 v6, 0x3fb8aa3b, v6
	v_exp_f32_e32 v6, v6
	s_nop 0
	v_mul_f32_e32 v4, v4, v6
	s_nop 0
	v_cvt_pk_bf16_f32 v4, v4, v4
	ds_write_b16_d16_hi v77, v4 offset:23296
.LBB0_447:
	s_or_b64 exec, exec, s[30:31]
	v_mul_f32_e32 v6, 0x3fb8aa3b, v43
	v_exp_f32_e32 v6, v6
	v_lshlrev_b32_e32 v4, 16, v113
	v_mul_f32_e32 v4, 0x3e000000, v4
	v_cndmask_b32_e64 v4, 0, v4, s[12:13]
	v_mul_f32_e32 v6, v4, v6
	s_nop 0
	v_cvt_pk_bf16_f32 v6, v6, v6
	v_add_u32_e32 v38, v71, v78
	ds_write_b16_d16_hi v38, v6 offset:2048
	v_sub_f32_e32 v6, v43, v2
	v_mul_f32_e32 v6, 0x3fb8aa3b, v6
	v_exp_f32_e32 v6, v6
	s_nop 0
	v_mul_f32_e32 v6, v4, v6
	s_nop 0
	v_cvt_pk_bf16_f32 v6, v6, v6
	ds_write_b16_d16_hi v79, v6 offset:10240
	v_sub_f32_e32 v6, v2, v43
	v_mul_f32_e32 v6, 0x3fb8aa3b, v6
	v_exp_f32_e32 v6, v6
	s_nop 0
	v_mul_f32_e32 v6, v57, v6
	s_nop 0
	v_cvt_pk_bf16_f32 v6, v6, v6
	ds_write_b16_d16_hi v79, v6 offset:18944
	s_and_saveexec_b64 s[30:31], s[6:7]
	s_xor_b64 s[30:31], exec, s[30:31]
	s_cbranch_execz .LBB0_449
	v_sub_f32_e32 v4, v7, v43
	v_mul_f32_e32 v4, 0x3fb8aa3b, v4
	v_exp_f32_e32 v4, v4
	s_nop 0
	v_mul_f32_e32 v4, v57, v4
	v_bfe_u32 v6, v4, 16, 1
	v_add3_u32 v4, v4, v6, s48
	ds_write_b16_d16_hi v79, v4 offset:32000
.LBB0_449:
	s_andn2_saveexec_b64 s[30:31], s[30:31]
	s_cbranch_execz .LBB0_451
	v_sub_f32_e32 v6, v43, v7
	v_mul_f32_e32 v6, 0x3fb8aa3b, v6
	v_exp_f32_e32 v6, v6
	s_nop 0
	v_mul_f32_e32 v4, v4, v6
	s_nop 0
	v_cvt_pk_bf16_f32 v4, v4, v4
	ds_write_b16_d16_hi v80, v4 offset:23296
.LBB0_451:
	s_or_b64 exec, exec, s[30:31]
	v_mul_f32_e32 v6, 0x3fb8aa3b, v42
	v_exp_f32_e32 v6, v6
	v_lshlrev_b32_e32 v4, 16, v115
	v_mul_f32_e32 v4, 0x3e000000, v4
	v_cndmask_b32_e64 v4, 0, v4, s[16:17]
	v_mul_f32_e32 v6, v4, v6
	s_nop 0
	v_cvt_pk_bf16_f32 v6, v6, v6
	v_add_u32_e32 v38, v71, v81
	ds_write_b16_d16_hi v38, v6 offset:2048
	v_sub_f32_e32 v6, v42, v2
	v_mul_f32_e32 v6, 0x3fb8aa3b, v6
	v_exp_f32_e32 v6, v6
	s_nop 0
	v_mul_f32_e32 v6, v4, v6
	s_nop 0
	v_cvt_pk_bf16_f32 v6, v6, v6
	ds_write_b16_d16_hi v82, v6 offset:10240
	v_sub_f32_e32 v6, v2, v42
	v_mul_f32_e32 v6, 0x3fb8aa3b, v6
	v_exp_f32_e32 v6, v6
	s_nop 0
	v_mul_f32_e32 v6, v59, v6
	s_nop 0
	v_cvt_pk_bf16_f32 v6, v6, v6
	ds_write_b16_d16_hi v82, v6 offset:18944
	s_and_saveexec_b64 s[30:31], s[6:7]
	s_xor_b64 s[30:31], exec, s[30:31]
	s_cbranch_execz .LBB0_453
	v_sub_f32_e32 v4, v7, v42
	v_mul_f32_e32 v4, 0x3fb8aa3b, v4
	v_exp_f32_e32 v4, v4
	s_nop 0
	v_mul_f32_e32 v4, v59, v4
	v_bfe_u32 v6, v4, 16, 1
	v_add3_u32 v4, v4, v6, s48
	ds_write_b16_d16_hi v82, v4 offset:32000
.LBB0_453:
	s_andn2_saveexec_b64 s[30:31], s[30:31]
	s_cbranch_execz .LBB0_455
	v_sub_f32_e32 v6, v42, v7
	v_mul_f32_e32 v6, 0x3fb8aa3b, v6
	v_exp_f32_e32 v6, v6
	s_nop 0
	v_mul_f32_e32 v4, v4, v6
	s_nop 0
	v_cvt_pk_bf16_f32 v4, v4, v4
	ds_write_b16_d16_hi v83, v4 offset:23296
.LBB0_455:
	s_or_b64 exec, exec, s[30:31]
	v_mul_f32_e32 v6, 0x3fb8aa3b, v41
	v_exp_f32_e32 v6, v6
	v_lshlrev_b32_e32 v4, 16, v118
	v_mul_f32_e32 v4, 0x3e000000, v4
	v_cndmask_b32_e64 v4, 0, v4, s[22:23]
	v_mul_f32_e32 v6, v4, v6
	s_nop 0
	v_cvt_pk_bf16_f32 v6, v6, v6
	v_add_u32_e32 v38, v71, v84
	ds_write_b16_d16_hi v38, v6 offset:2048
	v_sub_f32_e32 v6, v41, v2
	v_mul_f32_e32 v6, 0x3fb8aa3b, v6
	v_exp_f32_e32 v6, v6
	s_nop 0
	v_mul_f32_e32 v6, v4, v6
	s_nop 0
	v_cvt_pk_bf16_f32 v6, v6, v6
	ds_write_b16_d16_hi v85, v6 offset:10240
	v_sub_f32_e32 v6, v2, v41
	v_mul_f32_e32 v6, 0x3fb8aa3b, v6
	v_exp_f32_e32 v6, v6
	s_nop 0
	v_mul_f32_e32 v6, v60, v6
	s_nop 0
	v_cvt_pk_bf16_f32 v6, v6, v6
	ds_write_b16_d16_hi v85, v6 offset:18944
	s_and_saveexec_b64 s[30:31], s[6:7]
	s_xor_b64 s[30:31], exec, s[30:31]
	s_cbranch_execz .LBB0_457
	v_sub_f32_e32 v4, v7, v41
	v_mul_f32_e32 v4, 0x3fb8aa3b, v4
	v_exp_f32_e32 v4, v4
	s_nop 0
	v_mul_f32_e32 v4, v60, v4
	v_bfe_u32 v6, v4, 16, 1
	v_add3_u32 v4, v4, v6, s48
	ds_write_b16_d16_hi v85, v4 offset:32000
.LBB0_457:
	s_andn2_saveexec_b64 s[30:31], s[30:31]
	s_cbranch_execz .LBB0_459
	v_sub_f32_e32 v6, v41, v7
	v_mul_f32_e32 v6, 0x3fb8aa3b, v6
	v_exp_f32_e32 v6, v6
	s_nop 0
	v_mul_f32_e32 v4, v4, v6
	s_nop 0
	v_cvt_pk_bf16_f32 v4, v4, v4
	ds_write_b16_d16_hi v86, v4 offset:23296
.LBB0_459:
	s_or_b64 exec, exec, s[30:31]
	v_mul_f32_e32 v6, 0x3fb8aa3b, v40
	v_exp_f32_e32 v6, v6
	v_lshlrev_b32_e32 v4, 16, v120
	v_mul_f32_e32 v4, 0x3e000000, v4
	v_cndmask_b32_e64 v4, 0, v4, s[26:27]
	v_mul_f32_e32 v6, v4, v6
	s_nop 0
	v_cvt_pk_bf16_f32 v6, v6, v6
	v_add_u32_e32 v38, v71, v87
	ds_write_b16_d16_hi v38, v6 offset:2048
	v_sub_f32_e32 v6, v40, v2
	v_mul_f32_e32 v6, 0x3fb8aa3b, v6
	v_exp_f32_e32 v6, v6
	s_nop 0
	v_mul_f32_e32 v6, v4, v6
	s_nop 0
	v_cvt_pk_bf16_f32 v6, v6, v6
	ds_write_b16_d16_hi v88, v6 offset:10240
	v_sub_f32_e32 v6, v2, v40
	v_mul_f32_e32 v6, 0x3fb8aa3b, v6
	v_exp_f32_e32 v6, v6
	s_nop 0
	v_mul_f32_e32 v6, v0, v6
	s_nop 0
	v_cvt_pk_bf16_f32 v6, v6, v6
	ds_write_b16_d16_hi v88, v6 offset:18944
	s_and_saveexec_b64 s[30:31], s[6:7]
	s_xor_b64 s[30:31], exec, s[30:31]
	s_cbranch_execz .LBB0_461
	v_sub_f32_e32 v4, v7, v40
	v_mul_f32_e32 v4, 0x3fb8aa3b, v4
	v_exp_f32_e32 v4, v4
	s_nop 0
	v_mul_f32_e32 v0, v0, v4
	s_nop 0
	v_cvt_pk_bf16_f32 v0, v0, v0
	ds_write_b16_d16_hi v88, v0 offset:32000
.LBB0_461:
	s_andn2_saveexec_b64 s[30:31], s[30:31]
	s_cbranch_execz .LBB0_463
	v_sub_f32_e32 v0, v40, v7
	v_mul_f32_e32 v0, 0x3fb8aa3b, v0
	v_exp_f32_e32 v0, v0
	s_nop 0
	v_mul_f32_e32 v0, v4, v0
	s_nop 0
	v_cvt_pk_bf16_f32 v0, v0, v0
	ds_write_b16_d16_hi v89, v0 offset:23296
.LBB0_463:
	s_or_b64 exec, exec, s[30:31]
	v_mul_f32_e32 v4, 0x3fb8aa3b, v5
	v_exp_f32_e32 v4, v4
	v_lshlrev_b32_e32 v0, 16, v121
	v_mul_f32_e32 v0, 0x3e000000, v0
	v_cndmask_b32_e64 v0, 0, v0, s[20:21]
	v_mul_f32_e32 v4, v0, v4
	s_nop 0
	v_cvt_pk_bf16_f32 v4, v4, v4
	v_add_u32_e32 v6, v71, v90
	ds_write_b16_d16_hi v6, v4 offset:2048
	v_sub_f32_e32 v4, v5, v2
	v_mul_f32_e32 v4, 0x3fb8aa3b, v4
	v_exp_f32_e32 v4, v4
	s_nop 0
	v_mul_f32_e32 v4, v0, v4
	s_nop 0
	v_cvt_pk_bf16_f32 v4, v4, v4
	ds_write_b16_d16_hi v91, v4 offset:10240
	v_sub_f32_e32 v4, v2, v5
	v_mul_f32_e32 v4, 0x3fb8aa3b, v4
	v_exp_f32_e32 v4, v4
	s_nop 0
	v_mul_f32_e32 v4, v61, v4
	s_nop 0
	v_cvt_pk_bf16_f32 v4, v4, v4
	ds_write_b16_d16_hi v91, v4 offset:18944
	s_and_saveexec_b64 s[30:31], s[6:7]
	s_xor_b64 s[30:31], exec, s[30:31]
	s_cbranch_execz .LBB0_465
	v_sub_f32_e32 v0, v7, v5
	v_mul_f32_e32 v0, 0x3fb8aa3b, v0
	v_exp_f32_e32 v0, v0
	s_nop 0
	v_mul_f32_e32 v0, v61, v0
	v_bfe_u32 v4, v0, 16, 1
	v_add3_u32 v0, v0, v4, s48
	ds_write_b16_d16_hi v91, v0 offset:32000
.LBB0_465:
	s_andn2_saveexec_b64 s[30:31], s[30:31]
	s_cbranch_execz .LBB0_467
	v_sub_f32_e32 v4, v5, v7
	v_mul_f32_e32 v4, 0x3fb8aa3b, v4
	v_exp_f32_e32 v4, v4
	s_nop 0
	v_mul_f32_e32 v0, v0, v4
	s_nop 0
	v_cvt_pk_bf16_f32 v0, v0, v0
	ds_write_b16_d16_hi v92, v0 offset:23296
.LBB0_467:
	s_or_b64 exec, exec, s[30:31]
	v_mul_f32_e32 v4, 0x3fb8aa3b, v3
	v_exp_f32_e32 v4, v4
	v_lshlrev_b32_e32 v0, 16, v96
	v_mul_f32_e32 v0, 0x3e000000, v0
	v_cndmask_b32_e64 v0, 0, v0, s[24:25]
	v_mul_f32_e32 v4, v0, v4
	s_nop 0
	v_cvt_pk_bf16_f32 v4, v4, v4
	v_add_u32_e32 v5, v71, v93
	ds_write_b16_d16_hi v5, v4 offset:2048
	v_sub_f32_e32 v4, v3, v2
	v_mul_f32_e32 v4, 0x3fb8aa3b, v4
	v_exp_f32_e32 v4, v4
	v_sub_f32_e32 v2, v2, v3
	v_mul_f32_e32 v2, 0x3fb8aa3b, v2
	v_exp_f32_e32 v2, v2
	v_mul_f32_e32 v4, v0, v4
	s_nop 0
	v_cvt_pk_bf16_f32 v4, v4, v4
	v_mul_f32_e32 v2, v1, v2
	ds_write_b16_d16_hi v94, v4 offset:10240
	s_nop 0
	v_cvt_pk_bf16_f32 v2, v2, v2
	ds_write_b16_d16_hi v94, v2 offset:18944
	s_and_saveexec_b64 s[30:31], s[6:7]
	s_xor_b64 s[30:31], exec, s[30:31]
	s_cbranch_execz .LBB0_469
	v_sub_f32_e32 v0, v7, v3
	v_mul_f32_e32 v0, 0x3fb8aa3b, v0
	v_exp_f32_e32 v0, v0
	s_nop 0
	v_mul_f32_e32 v0, v1, v0
	v_bfe_u32 v1, v0, 16, 1
	v_add3_u32 v0, v0, v1, s48
	ds_write_b16_d16_hi v94, v0 offset:32000
.LBB0_469:
	s_andn2_saveexec_b64 s[30:31], s[30:31]
	s_cbranch_execz .LBB0_471
	v_sub_f32_e32 v1, v3, v7
	v_mul_f32_e32 v1, 0x3fb8aa3b, v1
	v_exp_f32_e32 v1, v1
	s_nop 0
	v_mul_f32_e32 v0, v0, v1
	s_nop 0
	v_cvt_pk_bf16_f32 v0, v0, v0
	ds_write_b16_d16_hi v95, v0 offset:23296

.LBB0_503:
	s_or_b64 exec, exec, s[12:13]
	s_or_b32 s12, s30, s49
	s_mul_hi_u32 s13, s12, 0x41
	s_add_i32 s13, s13, s31
	s_mulk_i32 s12, 0x41
	s_add_u32 s12, s12, s33
	s_addc_u32 s13, s13, s38
	s_or_b32 s14, s60, s28
	s_waitcnt vmcnt(0)
	v_or_b32_e32 v41, v5, v4
	s_lshl_b64 s[12:13], s[12:13], 13
	v_add_u32_e32 v6, s14, v70
	v_mov_b64_e32 v[4:5], s[82:83]
	v_or_b32_e32 v39, v1, v0
	v_lshl_add_u64 v[0:1], v[16:17], 0, s[12:13]
	v_mad_i64_i32 v[4:5], s[12:13], v6, s79, v[4:5]
	v_mad_u64_u32 v[6:7], s[12:13], v4, s44, v[20:21]
	s_add_i32 s12, s14, s93
	s_mul_hi_i32 s13, s12, 0x41
	s_mulk_i32 s12, 0x41
	s_add_u32 s12, s12, s82
	v_or_b32_e32 v38, v49, v48
	v_or_b32_e32 v40, v3, v2
	s_addc_u32 s13, s13, s83
	global_store_dwordx4 v[0:1], v[38:41], off
	v_add_u32_e32 v0, v99, v18
	s_mulk_i32 s13, 0x3000
	s_mul_hi_u32 s14, s12, 0x3000
	s_waitcnt lgkmcnt(0)
	s_barrier
	ds_read_b128 v[0:3], v0 offset:2048
	s_add_i32 s14, s14, s13
	s_mulk_i32 s12, 0x3000
	s_add_u32 s12, s34, s12
	s_addc_u32 s13, s35, s14
	s_add_u32 s12, s12, 0x2e894000
	v_mad_i32_i24 v7, v5, s44, v7
	s_addc_u32 s13, s13, 0
	s_andn2_b64 vcc, exec, s[58:59]
	s_mov_b64 s[14:15], -1
	s_waitcnt lgkmcnt(0)
	global_store_dwordx4 v[6:7], v[0:3], off
	s_cbranch_vccnz .LBB0_505
	ds_read_b128 v[0:3], v100
	ds_read_b128 v[4:7], v102
	s_mov_b64 s[14:15], 0
	s_waitcnt lgkmcnt(0)
	v_mfma_f32_16x16x32_bf16 v[0:3], v[0:3], v[4:7], 0
	ds_read_b128 v[4:7], v100 offset:64
	ds_read_b128 v[38:41], v102 offset:64
	s_waitcnt lgkmcnt(0)
	v_mfma_f32_16x16x32_bf16 v[0:3], v[4:7], v[38:41], v[0:3]
	v_lshl_add_u64 v[4:5], s[12:13], 0, v[22:23]
	s_nop 6
	v_cndmask_b32_e64 v0, v0, 0, s[80:81]
	s_nop 0
	v_cvt_pk_bf16_f32 v0, v0, v0
	v_lshl_add_u64 v[6:7], v[4:5], 0, v[24:25]
	global_store_short_d16_hi v[6:7], v0, off
	v_cndmask_b32_e64 v0, v1, 0, s[62:63]
	v_bfe_u32 v1, v0, 16, 1
	v_add3_u32 v6, v0, v1, s48
	v_lshl_add_u64 v[0:1], v[4:5], 0, v[26:27]
	global_store_short_d16_hi v[0:1], v6, off
	v_cndmask_b32_e64 v0, v2, 0, s[64:65]
	s_nop 0
	v_cvt_pk_bf16_f32 v2, v0, v0
	v_lshl_add_u64 v[0:1], v[4:5], 0, v[28:29]
	global_store_short_d16_hi v[0:1], v2, off
	v_cndmask_b32_e64 v0, v3, 0, s[66:67]
	v_bfe_u32 v1, v0, 16, 1
	v_add3_u32 v2, v0, v1, s48
	v_lshl_add_u64 v[0:1], v[4:5], 0, v[30:31]
	global_store_short_d16_hi v[0:1], v2, off

.LBB0_510:
	s_and_b64 vcc, exec, s[12:13]
	s_cbranch_vccz .LBB0_435
	s_movk_i32 s29, 0x810
	v_or_b32_e32 v38, 1, v103
	s_ashr_i32 s33, s76, 2
	v_cmp_gt_i32_e64 s[12:13], s29, v103
	v_cmp_gt_i32_e64 s[16:17], s29, v38
	s_mul_i32 s60, s33, 0x810
	v_cndmask_b32_e64 v0, 0, v103, s[12:13]
	v_cndmask_b32_e64 v38, 0, v38, s[16:17]
	v_add_u32_e32 v0, s60, v0
	v_mov_b64_e32 v[2:3], s[54:55]
	v_add_u32_e32 v47, s60, v38
	v_or_b32_e32 v46, 2, v103
	v_mad_i64_i32 v[4:5], s[14:15], v0, s44, v[2:3]
	v_mad_i64_i32 v[38:39], s[14:15], v47, s44, v[2:3]
	s_and_b32 s28, s76, 3
	v_cmp_gt_i32_e64 s[14:15], s29, v46
	s_lshl_b32 s61, s28, 7
	v_add_lshl_u32 v0, s61, v65, 1
	v_cndmask_b32_e64 v42, 0, v46, s[14:15]
	v_mov_b32_e32 v1, v97
	v_add_u32_e32 v42, s60, v42
	v_lshl_add_u64 v[6:7], v[4:5], 0, v[0:1]
	v_mad_i64_i32 v[42:43], s[18:19], v42, s44, v[2:3]
	v_lshl_add_u64 v[40:41], v[38:39], 0, v[0:1]
	v_lshl_add_u64 v[44:45], v[42:43], 0, v[0:1]
	global_load_ushort v54, v[6:7], off
	global_load_ushort v55, v[40:41], off
	global_load_ushort v56, v[44:45], off
	s_lshl_b32 s38, s28, 9
	v_lshl_add_u64 v[6:7], v[34:35], 0, s[38:39]
	global_load_dword v58, v[6:7], off
	v_or_b32_e32 v40, 3, v103
	v_or_b32_e32 v48, 4, v103
	v_cmp_gt_i32_e64 s[20:21], s29, v40
	s_lshl_b32 s22, s28, 1
	s_lshl_b32 s76, s33, 3
	v_cndmask_b32_e64 v40, 0, v40, s[20:21]
	v_cmp_gt_i32_e64 s[18:19], s29, v48
	s_or_b32 s38, s22, s76
	v_add_u32_e32 v49, s60, v40
	v_cndmask_b32_e64 v41, 0, v48, s[18:19]
	v_add_lshl_u32 v96, s61, v64, 1
	v_add_u32_e32 v44, s60, v41
	v_or_b32_e32 v50, s38, v63
	v_mad_i64_i32 v[40:41], s[22:23], v49, s44, v[2:3]
	v_mad_i64_i32 v[44:45], s[22:23], v44, s44, v[2:3]
	v_lshl_add_u32 v57, v50, 6, v50
	v_lshl_add_u64 v[4:5], v[4:5], 0, v[96:97]
	v_lshl_add_u64 v[50:51], v[40:41], 0, v[96:97]
	v_lshl_add_u64 v[38:39], v[38:39], 0, v[96:97]
	v_lshl_add_u64 v[42:43], v[42:43], 0, v[96:97]
	v_lshl_add_u64 v[40:41], v[40:41], 0, v[0:1]
	v_lshl_add_u64 v[52:53], v[44:45], 0, v[0:1]
	v_add_u32_e32 v59, s82, v57
	global_load_ushort v57, v[50:51], off
	global_load_ushort v60, v[42:43], off
	global_load_ushort v104, v[38:39], off
	global_load_ushort v105, v[4:5], off
	global_load_ushort v61, v[40:41], off
	global_load_ushort v106, v[52:53], off
	v_mov_b64_e32 v[6:7], s[56:57]
	v_mad_i64_i32 v[40:41], s[22:23], v59, s44, v[6:7]
	s_mov_b32 s49, 0x3f317217
	v_mov_b32_e32 v114, 0x41b17218
	s_mov_b32 s78, 0x7f800000
	v_or_b32_e32 v50, 6, v103
	s_waitcnt vmcnt(0)
	v_lshlrev_b32_e32 v4, 16, v54
	v_mul_f32_e32 v4, 0x3fb8aa3b, v4
	v_exp_f32_e32 v4, v4
	v_lshlrev_b32_e32 v5, 16, v55
	v_mul_f32_e32 v5, 0x3fb8aa3b, v5
	v_exp_f32_e32 v5, v5
	v_add_f32_e32 v4, 1.0, v4
	v_rcp_f32_e32 v4, v4
	v_lshlrev_b32_e32 v6, 16, v56
	v_sub_f32_e32 v56, 1.0, v58
	v_add_f32_e32 v5, 1.0, v5
	v_mul_f32_e32 v4, v56, v4
	v_rcp_f32_e32 v5, v5
	v_min_f32_e32 v59, 0x3f7ff972, v4
	v_sub_f32_e32 v4, 1.0, v59
	v_cmp_gt_f32_e32 vcc, s45, v4
	v_mul_f32_e32 v5, v56, v5
	v_min_f32_e32 v107, 0x3f7ff972, v5
	v_cndmask_b32_e64 v7, 0, 32, vcc
	v_ldexp_f32 v4, v4, v7
	v_log_f32_e32 v4, v4
	v_mul_f32_e32 v6, 0x3fb8aa3b, v6
	v_sub_f32_e32 v5, 1.0, v107
	v_exp_f32_e32 v6, v6
	v_cmp_gt_f32_e64 s[22:23], s45, v5
	v_cndmask_b32_e32 v7, 0, v114, vcc
	v_cmp_lt_f32_e64 vcc, |v4|, s78
	v_cndmask_b32_e64 v38, 0, 32, s[22:23]
	v_ldexp_f32 v5, v5, v38
	v_mul_f32_e32 v38, 0x3f317217, v4
	v_fma_f32 v38, v4, s49, -v38
	v_add_f32_e32 v6, 1.0, v6
	v_log_f32_e32 v5, v5
	v_fmac_f32_e32 v38, 0x3377d1cf, v4
	v_rcp_f32_e32 v6, v6
	v_fmac_f32_e32 v38, 0x3f317217, v4
	v_cndmask_b32_e32 v4, v4, v38, vcc
	v_sub_f32_e32 v4, v4, v7
	v_mul_f32_e32 v39, 0x3f317217, v5
	v_add_f32_e32 v4, 0, v4
	v_fma_f32 v39, v5, s49, -v39
	v_cndmask_b32_e64 v108, 0, v4, s[12:13]
	v_mul_f32_e32 v4, v56, v6
	v_fmac_f32_e32 v39, 0x3377d1cf, v5
	v_min_f32_e32 v109, 0x3f7ff972, v4
	v_fmac_f32_e32 v39, 0x3f317217, v5
	v_cmp_lt_f32_e64 vcc, |v5|, s78
	v_sub_f32_e32 v4, 1.0, v109
	s_nop 0
	v_cndmask_b32_e32 v38, v5, v39, vcc
	v_cmp_gt_f32_e32 vcc, s45, v4
	v_cndmask_b32_e64 v39, 0, v114, s[22:23]
	s_nop 0
	v_cndmask_b32_e64 v5, 0, 32, vcc
	v_ldexp_f32 v42, v4, v5
	v_or_b32_e32 v4, 5, v103
	v_cmp_gt_i32_e64 s[22:23], s29, v4
	v_log_f32_e32 v111, v42
	s_nop 0
	v_cndmask_b32_e64 v4, 0, v4, s[22:23]
	v_add_u32_e32 v51, s60, v4
	v_mad_i64_i32 v[4:5], s[24:25], v51, s44, v[2:3]
	v_lshl_add_u64 v[6:7], v[4:5], 0, v[0:1]
	global_load_ushort v110, v[6:7], off
	v_cmp_gt_i32_e64 s[24:25], s29, v50
	v_sub_f32_e32 v6, v38, v39
	v_cndmask_b32_e64 v6, 0, v6, s[16:17]
	v_cndmask_b32_e64 v38, 0, v50, s[24:25]
	v_add_u32_e32 v38, s60, v38
	v_mad_i64_i32 v[38:39], s[26:27], v38, s44, v[2:3]
	v_add_f32_e32 v112, v108, v6
	v_mul_f32_e32 v6, 0x3f317217, v111
	v_lshl_add_u64 v[42:43], v[38:39], 0, v[0:1]
	v_fma_f32 v113, v111, s49, -v6
	v_lshl_add_u64 v[6:7], v[44:45], 0, v[96:97]
	global_load_ushort v45, v[42:43], off
	v_or_b32_e32 v44, 7, v103
	v_cmp_gt_i32_e64 s[26:27], s29, v44
	v_lshl_add_u64 v[4:5], v[4:5], 0, v[96:97]
	v_lshl_add_u64 v[38:39], v[38:39], 0, v[96:97]
	v_cndmask_b32_e64 v42, 0, v44, s[26:27]
	v_add_u32_e32 v52, s60, v42
	v_mad_i64_i32 v[2:3], s[30:31], v52, s44, v[2:3]
	v_lshl_add_u64 v[42:43], v[2:3], 0, v[96:97]
	v_lshl_add_u64 v[0:1], v[2:3], 0, v[0:1]
	global_load_ushort v53, v[42:43], off
	global_load_ushort v54, v[38:39], off
	global_load_ushort v55, v[4:5], off
	global_load_ushort v58, v[6:7], off
	v_lshlrev_b32_e32 v4, 16, v61
	global_load_ushort v0, v[0:1], off
	v_mul_f32_e32 v4, 0x3fb8aa3b, v4
	v_exp_f32_e32 v4, v4
	v_cndmask_b32_e32 v6, 0, v114, vcc
	v_fmac_f32_e32 v113, 0x3377d1cf, v111
	v_fmac_f32_e32 v113, 0x3f317217, v111
	v_add_f32_e32 v4, 1.0, v4
	v_rcp_f32_e32 v4, v4
	v_cmp_lt_f32_e64 s[30:31], |v111|, s78
	v_cndmask_b32_e64 v38, 0, v59, s[12:13]
	v_mul_f32_e32 v2, v56, v4
	v_min_f32_e32 v2, 0x3f7ff972, v2
	v_sub_f32_e32 v3, 1.0, v2
	v_cmp_gt_f32_e32 vcc, s45, v3
	v_cndmask_b32_e64 v5, v111, v113, s[30:31]
	v_sub_f32_e32 v1, v5, v6
	v_cndmask_b32_e64 v4, 0, 32, vcc
	v_ldexp_f32 v3, v3, v4
	v_log_f32_e32 v3, v3
	v_lshlrev_b32_e32 v4, 16, v106
	v_cndmask_b32_e64 v1, 0, v1, s[14:15]
	v_mul_f32_e32 v4, 0x3fb8aa3b, v4
	v_add_f32_e32 v59, v112, v1
	v_mul_f32_e32 v1, 0x3f317217, v3
	v_exp_f32_e32 v4, v4
	v_fma_f32 v1, v3, s49, -v1
	v_fmac_f32_e32 v1, 0x3377d1cf, v3
	v_fmac_f32_e32 v1, 0x3f317217, v3
	v_cmp_lt_f32_e64 s[30:31], |v3|, s78
	v_cndmask_b32_e64 v7, 0, v2, s[20:21]
	s_barrier
	v_cndmask_b32_e64 v1, v3, v1, s[30:31]
	v_add_f32_e32 v3, 1.0, v4
	v_rcp_f32_e32 v3, v3
	v_cndmask_b32_e32 v4, 0, v114, vcc
	v_sub_f32_e32 v1, v1, v4
	v_cndmask_b32_e64 v1, 0, v1, s[20:21]
	v_mul_f32_e32 v3, v56, v3
	v_min_f32_e32 v4, 0x3f7ff972, v3
	v_sub_f32_e32 v3, 1.0, v4
	v_cmp_gt_f32_e32 vcc, s45, v3
	v_add_f32_e32 v61, v59, v1
	s_nop 0
	v_cndmask_b32_e64 v5, 0, 32, vcc
	v_ldexp_f32 v3, v3, v5
	v_log_f32_e32 v3, v3
	v_cndmask_b32_e64 v39, 0, v109, s[14:15]
	v_cndmask_b32_e64 v6, 0, v107, s[16:17]
	v_cndmask_b32_e64 v4, 0, v4, s[18:19]
	v_mul_f32_e32 v1, 0x3f317217, v3
	v_fma_f32 v1, v3, s49, -v1
	v_fmac_f32_e32 v1, 0x3377d1cf, v3
	v_fmac_f32_e32 v1, 0x3f317217, v3
	s_waitcnt vmcnt(6)
	v_lshlrev_b32_e32 v2, 16, v110
	v_mul_f32_e32 v2, 0x3fb8aa3b, v2
	v_exp_f32_e32 v2, v2
	v_cmp_lt_f32_e64 s[30:31], |v3|, s78
	v_add_f32_e32 v2, 1.0, v2
	v_rcp_f32_e32 v2, v2
	v_cndmask_b32_e64 v1, v3, v1, s[30:31]
	v_cndmask_b32_e32 v3, 0, v114, vcc
	v_sub_f32_e32 v1, v1, v3
	v_mul_f32_e32 v2, v56, v2
	v_min_f32_e32 v42, 0x3f7ff972, v2
	v_sub_f32_e32 v2, 1.0, v42
	v_cmp_gt_f32_e32 vcc, s45, v2
	v_cndmask_b32_e64 v1, 0, v1, s[18:19]
	s_waitcnt vmcnt(0)
	v_lshlrev_b32_e32 v0, 16, v0
	v_cndmask_b32_e64 v3, 0, 32, vcc
	v_ldexp_f32 v2, v2, v3
	v_lshlrev_b32_e32 v3, 16, v45
	v_mul_f32_e32 v3, 0x3fb8aa3b, v3
	v_exp_f32_e32 v3, v3
	v_log_f32_e32 v2, v2
	v_mul_f32_e32 v0, 0x3fb8aa3b, v0
	v_exp_f32_e32 v0, v0
	v_add_f32_e32 v3, 1.0, v3
	v_rcp_f32_e32 v3, v3
	v_mul_f32_e32 v5, 0x3f317217, v2
	v_fma_f32 v5, v2, s49, -v5
	v_fmac_f32_e32 v5, 0x3377d1cf, v2
	v_mul_f32_e32 v3, v56, v3
	v_fmac_f32_e32 v5, 0x3f317217, v2
	v_cmp_lt_f32_e64 s[30:31], |v2|, s78
	v_min_f32_e32 v3, 0x3f7ff972, v3
	v_add_f32_e32 v0, 1.0, v0
	v_cndmask_b32_e64 v2, v2, v5, s[30:31]
	v_sub_f32_e32 v5, 1.0, v3
	v_cmp_gt_f32_e64 s[30:31], s45, v5
	v_rcp_f32_e32 v0, v0
	s_nop 0
	v_cndmask_b32_e64 v43, 0, 32, s[30:31]
	v_ldexp_f32 v5, v5, v43
	v_log_f32_e32 v5, v5
	v_cndmask_b32_e32 v43, 0, v114, vcc
	v_sub_f32_e32 v2, v2, v43
	v_mul_f32_e32 v0, v56, v0
	v_mul_f32_e32 v43, 0x3f317217, v5
	v_fma_f32 v43, v5, s49, -v43
	v_fmac_f32_e32 v43, 0x3377d1cf, v5
	v_min_f32_e32 v0, 0x3f7ff972, v0
	v_fmac_f32_e32 v43, 0x3f317217, v5
	v_cmp_lt_f32_e64 vcc, |v5|, s78
	v_sub_f32_e32 v44, 1.0, v0
	v_cndmask_b32_e64 v2, 0, v2, s[22:23]
	v_cndmask_b32_e32 v5, v5, v43, vcc
	v_cmp_gt_f32_e32 vcc, s45, v44
	v_cndmask_b32_e64 v43, 0, v114, s[30:31]
	v_sub_f32_e32 v5, v5, v43
	v_cndmask_b32_e64 v45, 0, 32, vcc
	v_ldexp_f32 v44, v44, v45
	v_log_f32_e32 v44, v44
	v_cndmask_b32_e64 v43, 0, v5, s[24:25]
	v_cndmask_b32_e64 v5, 0, v3, s[24:25]
	v_add_f32_e32 v56, v61, v1
	v_mul_f32_e32 v3, 0x3f317217, v44
	v_fma_f32 v3, v44, s49, -v3
	v_fmac_f32_e32 v3, 0x3377d1cf, v44
	v_fmac_f32_e32 v3, 0x3f317217, v44
	v_cmp_lt_f32_e64 s[30:31], |v44|, s78
	v_cndmask_b32_e64 v1, 0, v0, s[26:27]
	v_cndmask_b32_e64 v0, 0, v42, s[22:23]
	v_cndmask_b32_e64 v3, v44, v3, s[30:31]
	v_cndmask_b32_e32 v44, 0, v114, vcc
	v_sub_f32_e32 v3, v3, v44
	v_add_f32_e32 v114, v56, v2
	v_cndmask_b32_e64 v3, 0, v3, s[26:27]
	v_add_f32_e32 v115, v114, v43
	v_add_f32_e32 v43, v115, v3
	ds_write_b32 v68, v43
	s_waitcnt lgkmcnt(0)
	s_barrier
	ds_read2st64_b32 v[44:45], v69 offset1:2
	ds_read2st64_b32 v[2:3], v69 offset0:4 offset1:6
	s_waitcnt lgkmcnt(1)
	v_add_f32_e32 v45, v44, v45
	s_waitcnt lgkmcnt(0)
	v_add_f32_e32 v42, v45, v2
	v_cndmask_b32_e64 v2, v42, v45, s[4:5]
	v_cndmask_b32_e64 v2, v2, v44, s[2:3]
	v_cndmask_b32_e64 v109, v2, 0, s[0:1]
	v_add_f32_e32 v107, v108, v109
	v_mov_b32_e32 v108, v3
	v_pk_add_f32 v[2:3], v[42:43], v[108:109]
	v_add_f32_e32 v106, v112, v109
	v_sub_f32_e32 v43, v2, v107
	v_mul_f32_e32 v43, 0x3fb8aa3b, v43
	v_exp_f32_e32 v110, v43
	v_sub_f32_e32 v43, v2, v106
	v_mul_f32_e32 v43, 0x3fb8aa3b, v43
	v_add_f32_e32 v96, v59, v109
	v_exp_f32_e32 v112, v43
	v_sub_f32_e32 v43, v2, v96
	v_add_f32_e32 v61, v61, v109
	v_mul_f32_e32 v43, 0x3fb8aa3b, v43
	v_exp_f32_e32 v111, v43
	v_sub_f32_e32 v43, v2, v61
	v_mul_f32_e32 v43, 0x3fb8aa3b, v43
	v_add_f32_e32 v59, v56, v109
	v_exp_f32_e32 v113, v43
	v_sub_f32_e32 v43, v2, v59
	v_add_f32_e32 v56, v114, v109
	v_mul_f32_e32 v43, 0x3fb8aa3b, v43
	v_exp_f32_e32 v108, v43
	v_sub_f32_e32 v43, v2, v56
	v_mul_f32_e32 v43, 0x3fb8aa3b, v43
	v_exp_f32_e32 v114, v43
	v_add_f32_e32 v43, v115, v109
	v_sub_f32_e32 v115, v2, v3
	v_sub_f32_e32 v109, v2, v43
	v_mul_f32_e32 v115, 0x3fb8aa3b, v115
	v_mul_f32_e32 v109, 0x3fb8aa3b, v109
	v_exp_f32_e32 v115, v115
	v_exp_f32_e32 v109, v109
	v_pk_mul_f32 v[112:113], v[6:7], v[112:113]
	v_pk_mul_f32 v[110:111], v[38:39], v[110:111]
	v_pk_mul_f32 v[114:115], v[0:1], v[114:115]
	v_pk_mul_f32 v[108:109], v[4:5], v[108:109]
	s_nop 0
	s_nop 0
	s_nop 0
	s_nop 0
	v_cvt_pk_bf16_f32 v114, v114, v114
	v_cvt_pk_bf16_f32 v115, v115, v115
	v_cvt_pk_bf16_f32 v112, v112, v112
	v_cvt_pk_bf16_f32 v113, v113, v113
	s_nop 0
	s_nop 0
	s_nop 0
	s_nop 0
	v_cvt_pk_bf16_f32 v109, v109, v109
	v_cvt_pk_bf16_f32 v108, v108, v108
	v_cvt_pk_bf16_f32 v111, v111, v111
	v_cvt_pk_bf16_f32 v110, v110, v110
	v_lshrrev_b32_e32 v108, 16, v108
	v_lshrrev_b32_e32 v109, 16, v109
	v_lshrrev_b32_e32 v116, 16, v110
	v_lshrrev_b32_e32 v117, 16, v111
	v_and_or_b32 v111, v115, s36, v109
	v_and_or_b32 v110, v114, s36, v108
	v_and_or_b32 v109, v113, s36, v117
	v_and_or_b32 v108, v112, s36, v116
	v_lshl_add_u64 v[112:113], v[40:41], 0, v[14:15]
	v_add_co_u32_e32 v112, vcc, 0x1000, v112
	s_nop 1
	v_addc_co_u32_e32 v113, vcc, 0, v113, vcc
	global_store_dwordx4 v[112:113], v[108:111], off
	s_and_saveexec_b64 s[30:31], s[8:9]
	s_cbranch_execz .LBB0_513
	v_mul_f32_e32 v2, 0x3fb8aa3b, v2
	v_exp_f32_e32 v2, v2
	v_lshl_add_u64 v[40:41], v[40:41], 0, v[36:37]
	v_add_co_u32_e32 v40, vcc, 0x2000, v40
	s_nop 1
	v_addc_co_u32_e32 v41, vcc, 0, v41, vcc
	global_store_dword v[40:41], v2, off offset:2048
.LBB0_513:
	s_or_b64 exec, exec, s[30:31]
	v_lshlrev_b32_e32 v2, 16, v105
	v_mul_f32_e32 v40, 0xbfb8aa3b, v2
	v_exp_f32_e32 v40, v40
	v_mul_f32_e32 v41, 0x3fb8aa3b, v107
	v_exp_f32_e32 v41, v41
	v_add_f32_e32 v40, 1.0, v40
	v_rcp_f32_e32 v40, v40
	s_nop 0
	v_mul_f32_e32 v2, v40, v2
	v_cndmask_b32_e64 v40, 0, v2, s[12:13]
	v_mul_f32_e32 v41, v40, v41
	v_cndmask_b32_e64 v2, v42, v44, s[6:7]
	s_nop 0
	v_cvt_pk_bf16_f32 v41, v41, v41
	v_add_u32_e32 v42, v71, v72
	ds_write_b16_d16_hi v42, v41 offset:2048
	v_sub_f32_e32 v41, v107, v2
	v_mul_f32_e32 v41, 0x3fb8aa3b, v41
	v_exp_f32_e32 v41, v41
	s_nop 0
	v_mul_f32_e32 v41, v40, v41
	s_nop 0
	v_cvt_pk_bf16_f32 v41, v41, v41
	ds_write_b16_d16_hi v73, v41 offset:10240
	v_sub_f32_e32 v41, v2, v107
	v_mul_f32_e32 v41, 0x3fb8aa3b, v41
	v_exp_f32_e32 v41, v41
	s_nop 0
	v_mul_f32_e32 v41, v38, v41
	s_nop 0
	v_cvt_pk_bf16_f32 v41, v41, v41
	ds_write_b16_d16_hi v73, v41 offset:18944
	s_and_saveexec_b64 s[30:31], s[6:7]
	s_xor_b64 s[30:31], exec, s[30:31]
	s_cbranch_execz .LBB0_515
	v_sub_f32_e32 v40, v45, v107
	v_mul_f32_e32 v40, 0x3fb8aa3b, v40
	v_exp_f32_e32 v40, v40
	s_nop 0
	v_mul_f32_e32 v38, v38, v40
	s_nop 0
	v_cvt_pk_bf16_f32 v38, v38, v38
	ds_write_b16_d16_hi v73, v38 offset:32000
.LBB0_515:
	s_andn2_saveexec_b64 s[30:31], s[30:31]
	s_cbranch_execz .LBB0_517
	v_sub_f32_e32 v38, v107, v45
	v_mul_f32_e32 v38, 0x3fb8aa3b, v38
	v_exp_f32_e32 v38, v38
	s_nop 0
	v_mul_f32_e32 v38, v40, v38
	s_nop 0
	v_cvt_pk_bf16_f32 v38, v38, v38
	ds_write_b16_d16_hi v74, v38 offset:23296
.LBB0_517:
	s_or_b64 exec, exec, s[30:31]
	v_lshlrev_b32_e32 v38, 16, v104
	v_mul_f32_e32 v40, 0xbfb8aa3b, v38
	v_exp_f32_e32 v40, v40
	s_nop 0
	v_add_f32_e32 v40, 1.0, v40
	v_rcp_f32_e32 v40, v40
	s_nop 0
	v_mul_f32_e32 v38, v40, v38
	v_mul_f32_e32 v40, 0x3fb8aa3b, v106
	v_exp_f32_e32 v40, v40
	v_cndmask_b32_e64 v38, 0, v38, s[16:17]
	v_mul_f32_e32 v40, v38, v40
	s_nop 0
	v_cvt_pk_bf16_f32 v40, v40, v40
	v_add_u32_e32 v41, v71, v75
	ds_write_b16_d16_hi v41, v40 offset:2048
	v_sub_f32_e32 v40, v106, v2
	v_mul_f32_e32 v40, 0x3fb8aa3b, v40
	v_exp_f32_e32 v40, v40
	s_nop 0
	v_mul_f32_e32 v40, v38, v40
	s_nop 0
	v_cvt_pk_bf16_f32 v40, v40, v40
	ds_write_b16_d16_hi v76, v40 offset:10240
	v_sub_f32_e32 v40, v2, v106
	v_mul_f32_e32 v40, 0x3fb8aa3b, v40
	v_exp_f32_e32 v40, v40
	s_nop 0
	v_mul_f32_e32 v40, v6, v40
	s_nop 0
	v_cvt_pk_bf16_f32 v40, v40, v40
	ds_write_b16_d16_hi v76, v40 offset:18944
	s_and_saveexec_b64 s[30:31], s[6:7]
	s_xor_b64 s[30:31], exec, s[30:31]
	s_cbranch_execz .LBB0_519
	v_sub_f32_e32 v38, v45, v106
	v_mul_f32_e32 v38, 0x3fb8aa3b, v38
	v_exp_f32_e32 v38, v38
	s_nop 0
	v_mul_f32_e32 v6, v6, v38
	s_nop 0
	v_cvt_pk_bf16_f32 v6, v6, v6
	ds_write_b16_d16_hi v76, v6 offset:32000
.LBB0_519:
	s_andn2_saveexec_b64 s[30:31], s[30:31]
	s_cbranch_execz .LBB0_521
	v_sub_f32_e32 v6, v106, v45
	v_mul_f32_e32 v6, 0x3fb8aa3b, v6
	v_exp_f32_e32 v6, v6
	s_nop 0
	v_mul_f32_e32 v6, v38, v6
	s_nop 0
	v_cvt_pk_bf16_f32 v6, v6, v6
	ds_write_b16_d16_hi v77, v6 offset:23296
.LBB0_521:
	s_or_b64 exec, exec, s[30:31]
	v_lshlrev_b32_e32 v6, 16, v60
	v_mul_f32_e32 v38, 0xbfb8aa3b, v6
	v_exp_f32_e32 v38, v38
	s_nop 0
	v_add_f32_e32 v38, 1.0, v38
	v_rcp_f32_e32 v38, v38
	s_nop 0
	v_mul_f32_e32 v6, v38, v6
	v_mul_f32_e32 v38, 0x3fb8aa3b, v96
	v_exp_f32_e32 v38, v38
	v_cndmask_b32_e64 v6, 0, v6, s[14:15]
	v_mul_f32_e32 v38, v6, v38
	s_nop 0
	v_cvt_pk_bf16_f32 v38, v38, v38
	v_add_u32_e32 v40, v71, v78
	ds_write_b16_d16_hi v40, v38 offset:2048
	v_sub_f32_e32 v38, v96, v2
	v_mul_f32_e32 v38, 0x3fb8aa3b, v38
	v_exp_f32_e32 v38, v38
	s_nop 0
	v_mul_f32_e32 v38, v6, v38
	s_nop 0
	v_cvt_pk_bf16_f32 v38, v38, v38
	ds_write_b16_d16_hi v79, v38 offset:10240
	v_sub_f32_e32 v38, v2, v96
	v_mul_f32_e32 v38, 0x3fb8aa3b, v38
	v_exp_f32_e32 v38, v38
	s_nop 0
	v_mul_f32_e32 v38, v39, v38
	s_nop 0
	v_cvt_pk_bf16_f32 v38, v38, v38
	ds_write_b16_d16_hi v79, v38 offset:18944
	s_and_saveexec_b64 s[30:31], s[6:7]
	s_xor_b64 s[30:31], exec, s[30:31]
	s_cbranch_execz .LBB0_523
	v_sub_f32_e32 v6, v45, v96
	v_mul_f32_e32 v6, 0x3fb8aa3b, v6
	v_exp_f32_e32 v6, v6
	s_nop 0
	v_mul_f32_e32 v6, v39, v6
	v_bfe_u32 v38, v6, 16, 1
	v_add3_u32 v6, v6, v38, s48
	ds_write_b16_d16_hi v79, v6 offset:32000
.LBB0_523:
	s_andn2_saveexec_b64 s[30:31], s[30:31]
	s_cbranch_execz .LBB0_525
	v_sub_f32_e32 v38, v96, v45
	v_mul_f32_e32 v38, 0x3fb8aa3b, v38
	v_exp_f32_e32 v38, v38
	s_nop 0
	v_mul_f32_e32 v6, v6, v38
	s_nop 0
	v_cvt_pk_bf16_f32 v6, v6, v6
	ds_write_b16_d16_hi v80, v6 offset:23296
.LBB0_525:
	s_or_b64 exec, exec, s[30:31]
	v_lshlrev_b32_e32 v6, 16, v57
	v_mul_f32_e32 v38, 0xbfb8aa3b, v6
	v_exp_f32_e32 v38, v38
	s_nop 0
	v_add_f32_e32 v38, 1.0, v38
	v_rcp_f32_e32 v38, v38
	s_nop 0
	v_mul_f32_e32 v6, v38, v6
	v_mul_f32_e32 v38, 0x3fb8aa3b, v61
	v_exp_f32_e32 v38, v38
	v_cndmask_b32_e64 v6, 0, v6, s[20:21]
	v_mul_f32_e32 v38, v6, v38
	s_nop 0
	v_cvt_pk_bf16_f32 v38, v38, v38
	v_add_u32_e32 v39, v71, v81
	ds_write_b16_d16_hi v39, v38 offset:2048
	v_sub_f32_e32 v38, v61, v2
	v_mul_f32_e32 v38, 0x3fb8aa3b, v38
	v_exp_f32_e32 v38, v38
	s_nop 0
	v_mul_f32_e32 v38, v6, v38
	s_nop 0
	v_cvt_pk_bf16_f32 v38, v38, v38
	ds_write_b16_d16_hi v82, v38 offset:10240
	v_sub_f32_e32 v38, v2, v61
	v_mul_f32_e32 v38, 0x3fb8aa3b, v38
	v_exp_f32_e32 v38, v38
	s_nop 0
	v_mul_f32_e32 v38, v7, v38
	s_nop 0
	v_cvt_pk_bf16_f32 v38, v38, v38
	ds_write_b16_d16_hi v82, v38 offset:18944
	s_and_saveexec_b64 s[30:31], s[6:7]
	s_xor_b64 s[30:31], exec, s[30:31]
	s_cbranch_execz .LBB0_527
	v_sub_f32_e32 v6, v45, v61
	v_mul_f32_e32 v6, 0x3fb8aa3b, v6
	v_exp_f32_e32 v6, v6
	s_nop 0
	v_mul_f32_e32 v6, v7, v6
	v_bfe_u32 v7, v6, 16, 1
	v_add3_u32 v6, v6, v7, s48
	ds_write_b16_d16_hi v82, v6 offset:32000
.LBB0_527:
	s_andn2_saveexec_b64 s[30:31], s[30:31]
	s_cbranch_execz .LBB0_529
	v_sub_f32_e32 v7, v61, v45
	v_mul_f32_e32 v7, 0x3fb8aa3b, v7
	v_exp_f32_e32 v7, v7
	s_nop 0
	v_mul_f32_e32 v6, v6, v7
	s_nop 0
	v_cvt_pk_bf16_f32 v6, v6, v6
	ds_write_b16_d16_hi v83, v6 offset:23296
.LBB0_529:
	s_or_b64 exec, exec, s[30:31]
	v_lshlrev_b32_e32 v6, 16, v58
	v_mul_f32_e32 v7, 0xbfb8aa3b, v6
	v_exp_f32_e32 v7, v7
	s_nop 0
	v_add_f32_e32 v7, 1.0, v7
	v_rcp_f32_e32 v7, v7
	s_nop 0
	v_mul_f32_e32 v6, v7, v6
	v_mul_f32_e32 v7, 0x3fb8aa3b, v59
	v_exp_f32_e32 v7, v7
	v_cndmask_b32_e64 v6, 0, v6, s[18:19]
	v_mul_f32_e32 v7, v6, v7
	s_nop 0
	v_cvt_pk_bf16_f32 v7, v7, v7
	v_add_u32_e32 v38, v71, v84
	ds_write_b16_d16_hi v38, v7 offset:2048
	v_sub_f32_e32 v7, v59, v2
	v_mul_f32_e32 v7, 0x3fb8aa3b, v7
	v_exp_f32_e32 v7, v7
	s_nop 0
	v_mul_f32_e32 v7, v6, v7
	s_nop 0
	v_cvt_pk_bf16_f32 v7, v7, v7
	ds_write_b16_d16_hi v85, v7 offset:10240
	v_sub_f32_e32 v7, v2, v59
	v_mul_f32_e32 v7, 0x3fb8aa3b, v7
	v_exp_f32_e32 v7, v7
	s_nop 0
	v_mul_f32_e32 v7, v4, v7
	s_nop 0
	v_cvt_pk_bf16_f32 v7, v7, v7
	ds_write_b16_d16_hi v85, v7 offset:18944
	s_and_saveexec_b64 s[30:31], s[6:7]
	s_xor_b64 s[30:31], exec, s[30:31]
	s_cbranch_execz .LBB0_531
	v_sub_f32_e32 v6, v45, v59
	v_mul_f32_e32 v6, 0x3fb8aa3b, v6
	v_exp_f32_e32 v6, v6
	s_nop 0
	v_mul_f32_e32 v4, v4, v6
	s_nop 0
	v_cvt_pk_bf16_f32 v4, v4, v4
	ds_write_b16_d16_hi v85, v4 offset:32000
.LBB0_531:
	s_andn2_saveexec_b64 s[30:31], s[30:31]
	s_cbranch_execz .LBB0_533
	v_sub_f32_e32 v4, v59, v45
	v_mul_f32_e32 v4, 0x3fb8aa3b, v4
	v_exp_f32_e32 v4, v4
	s_nop 0
	v_mul_f32_e32 v4, v6, v4
	s_nop 0
	v_cvt_pk_bf16_f32 v4, v4, v4
	ds_write_b16_d16_hi v86, v4 offset:23296
.LBB0_533:
	s_or_b64 exec, exec, s[30:31]
	v_lshlrev_b32_e32 v4, 16, v55
	v_mul_f32_e32 v6, 0xbfb8aa3b, v4
	v_exp_f32_e32 v6, v6
	s_nop 0
	v_add_f32_e32 v6, 1.0, v6
	v_rcp_f32_e32 v6, v6
	s_nop 0
	v_mul_f32_e32 v4, v6, v4
	v_mul_f32_e32 v6, 0x3fb8aa3b, v56
	v_exp_f32_e32 v6, v6
	v_cndmask_b32_e64 v4, 0, v4, s[22:23]
	v_mul_f32_e32 v6, v4, v6
	s_nop 0
	v_cvt_pk_bf16_f32 v6, v6, v6
	v_add_u32_e32 v7, v71, v87
	ds_write_b16_d16_hi v7, v6 offset:2048
	v_sub_f32_e32 v6, v56, v2
	v_mul_f32_e32 v6, 0x3fb8aa3b, v6
	v_exp_f32_e32 v6, v6
	s_nop 0
	v_mul_f32_e32 v6, v4, v6
	s_nop 0
	v_cvt_pk_bf16_f32 v6, v6, v6
	ds_write_b16_d16_hi v88, v6 offset:10240
	v_sub_f32_e32 v6, v2, v56
	v_mul_f32_e32 v6, 0x3fb8aa3b, v6
	v_exp_f32_e32 v6, v6
	s_nop 0
	v_mul_f32_e32 v6, v0, v6
	s_nop 0
	v_cvt_pk_bf16_f32 v6, v6, v6
	ds_write_b16_d16_hi v88, v6 offset:18944
	s_and_saveexec_b64 s[30:31], s[6:7]
	s_xor_b64 s[30:31], exec, s[30:31]
	s_cbranch_execz .LBB0_535
	v_sub_f32_e32 v4, v45, v56
	v_mul_f32_e32 v4, 0x3fb8aa3b, v4
	v_exp_f32_e32 v4, v4
	s_nop 0
	v_mul_f32_e32 v0, v0, v4
	s_nop 0
	v_cvt_pk_bf16_f32 v0, v0, v0
	ds_write_b16_d16_hi v88, v0 offset:32000
.LBB0_535:
	s_andn2_saveexec_b64 s[30:31], s[30:31]
	s_cbranch_execz .LBB0_537
	v_sub_f32_e32 v0, v56, v45
	v_mul_f32_e32 v0, 0x3fb8aa3b, v0
	v_exp_f32_e32 v0, v0
	s_nop 0
	v_mul_f32_e32 v0, v4, v0
	s_nop 0
	v_cvt_pk_bf16_f32 v0, v0, v0
	ds_write_b16_d16_hi v89, v0 offset:23296
.LBB0_537:
	s_or_b64 exec, exec, s[30:31]
	v_lshlrev_b32_e32 v0, 16, v54
	v_mul_f32_e32 v4, 0xbfb8aa3b, v0
	v_exp_f32_e32 v4, v4
	s_nop 0
	v_add_f32_e32 v4, 1.0, v4
	v_rcp_f32_e32 v4, v4
	s_nop 0
	v_mul_f32_e32 v0, v4, v0
	v_mul_f32_e32 v4, 0x3fb8aa3b, v43
	v_exp_f32_e32 v4, v4
	v_cndmask_b32_e64 v0, 0, v0, s[24:25]
	v_mul_f32_e32 v4, v0, v4
	s_nop 0
	v_cvt_pk_bf16_f32 v4, v4, v4
	v_add_u32_e32 v6, v71, v90
	ds_write_b16_d16_hi v6, v4 offset:2048
	v_sub_f32_e32 v4, v43, v2
	v_mul_f32_e32 v4, 0x3fb8aa3b, v4
	v_exp_f32_e32 v4, v4
	s_nop 0
	v_mul_f32_e32 v4, v0, v4
	s_nop 0
	v_cvt_pk_bf16_f32 v4, v4, v4
	ds_write_b16_d16_hi v91, v4 offset:10240
	v_sub_f32_e32 v4, v2, v43
	v_mul_f32_e32 v4, 0x3fb8aa3b, v4
	v_exp_f32_e32 v4, v4
	s_nop 0
	v_mul_f32_e32 v4, v5, v4
	s_nop 0
	v_cvt_pk_bf16_f32 v4, v4, v4
	ds_write_b16_d16_hi v91, v4 offset:18944
	s_and_saveexec_b64 s[30:31], s[6:7]
	s_xor_b64 s[30:31], exec, s[30:31]
	s_cbranch_execz .LBB0_539
	v_sub_f32_e32 v0, v45, v43
	v_mul_f32_e32 v0, 0x3fb8aa3b, v0
	v_exp_f32_e32 v0, v0
	s_nop 0
	v_mul_f32_e32 v0, v5, v0
	v_bfe_u32 v4, v0, 16, 1
	v_add3_u32 v0, v0, v4, s48
	ds_write_b16_d16_hi v91, v0 offset:32000
.LBB0_539:
	s_andn2_saveexec_b64 s[30:31], s[30:31]
	s_cbranch_execz .LBB0_541
	v_sub_f32_e32 v4, v43, v45
	v_mul_f32_e32 v4, 0x3fb8aa3b, v4
	v_exp_f32_e32 v4, v4
	s_nop 0
	v_mul_f32_e32 v0, v0, v4
	s_nop 0
	v_cvt_pk_bf16_f32 v0, v0, v0
	ds_write_b16_d16_hi v92, v0 offset:23296
.LBB0_541:
	s_or_b64 exec, exec, s[30:31]
	v_lshlrev_b32_e32 v0, 16, v53
	v_mul_f32_e32 v4, 0xbfb8aa3b, v0
	v_exp_f32_e32 v4, v4
	s_nop 0
	v_add_f32_e32 v4, 1.0, v4
	v_rcp_f32_e32 v4, v4
	s_nop 0
	v_mul_f32_e32 v0, v4, v0
	v_mul_f32_e32 v4, 0x3fb8aa3b, v3
	v_exp_f32_e32 v4, v4
	v_cndmask_b32_e64 v0, 0, v0, s[26:27]
	v_mul_f32_e32 v4, v0, v4
	s_nop 0
	v_cvt_pk_bf16_f32 v4, v4, v4
	v_add_u32_e32 v5, v71, v93
	ds_write_b16_d16_hi v5, v4 offset:2048
	v_sub_f32_e32 v4, v3, v2
	v_mul_f32_e32 v4, 0x3fb8aa3b, v4
	v_exp_f32_e32 v4, v4
	v_sub_f32_e32 v2, v2, v3
	v_mul_f32_e32 v2, 0x3fb8aa3b, v2
	v_exp_f32_e32 v2, v2
	v_mul_f32_e32 v4, v0, v4
	s_nop 0
	v_cvt_pk_bf16_f32 v4, v4, v4
	v_mul_f32_e32 v2, v1, v2
	ds_write_b16_d16_hi v94, v4 offset:10240
	s_nop 0
	v_cvt_pk_bf16_f32 v2, v2, v2
	ds_write_b16_d16_hi v94, v2 offset:18944
	s_and_saveexec_b64 s[30:31], s[6:7]
	s_xor_b64 s[30:31], exec, s[30:31]
	s_cbranch_execz .LBB0_543
	v_sub_f32_e32 v0, v45, v3
	v_mul_f32_e32 v0, 0x3fb8aa3b, v0
	v_exp_f32_e32 v0, v0
	s_nop 0
	v_mul_f32_e32 v0, v1, v0
	v_bfe_u32 v1, v0, 16, 1
	v_add3_u32 v0, v0, v1, s48
	ds_write_b16_d16_hi v94, v0 offset:32000
.LBB0_543:
	s_andn2_saveexec_b64 s[30:31], s[30:31]
	s_cbranch_execz .LBB0_545
	v_sub_f32_e32 v1, v3, v45
	v_mul_f32_e32 v1, 0x3fb8aa3b, v1
	v_exp_f32_e32 v1, v1
	s_nop 0
	v_mul_f32_e32 v0, v0, v1
	s_nop 0
	v_cvt_pk_bf16_f32 v0, v0, v0
	ds_write_b16_d16_hi v95, v0 offset:23296

.LBB0_561:
	s_or_b64 exec, exec, s[12:13]
	s_ashr_i32 s12, s33, 31
	s_or_b32 s13, s76, s28
	s_mul_hi_u32 s14, s13, 0x41
	s_mulk_i32 s12, 0x41
	s_ashr_i32 s83, s82, 31
	s_add_i32 s14, s14, s12
	s_mulk_i32 s13, 0x41
	s_add_u32 s12, s13, s82
	s_addc_u32 s13, s14, s83
	s_lshl_b64 s[12:13], s[12:13], 13
	s_waitcnt vmcnt(0)
	v_or_b32_e32 v0, v3, v2
	v_or_b32_e32 v1, v5, v4
	v_or_b32_e32 v2, v7, v6
	v_or_b32_e32 v3, v39, v38
	v_lshl_add_u64 v[4:5], v[16:17], 0, s[12:13]
	global_store_dwordx4 v[4:5], v[0:3], off
	v_add_u32_e32 v4, s38, v70
	s_waitcnt lgkmcnt(0)
	v_add_u32_e32 v0, v99, v18
	s_barrier
	ds_read_b128 v[0:3], v0 offset:2048
	v_lshl_add_u32 v4, v4, 6, v4
	v_ashrrev_i32_e32 v5, 31, v4
	v_lshl_add_u64 v[4:5], v[4:5], 0, s[82:83]
	v_mad_u64_u32 v[6:7], s[12:13], v4, s44, v[20:21]
	v_mad_i32_i24 v7, v5, s44, v7
	s_andn2_b64 vcc, exec, s[70:71]
	s_waitcnt lgkmcnt(0)
	global_store_dwordx4 v[6:7], v[0:3], off
	s_cbranch_vccnz .LBB0_435
	s_mul_i32 s12, s38, 0x41
	s_add_i32 s12, s12, s82
	s_mul_hi_i32 s13, s12, 0x3000
	s_mulk_i32 s12, 0x3000
	s_add_u32 s12, s34, s12
	s_addc_u32 s13, s35, s13
	s_add_u32 s12, s12, 0x2e894000
	s_addc_u32 s13, s13, 0
	s_andn2_b64 vcc, exec, s[58:59]
	s_mov_b64 s[14:15], -1
	s_cbranch_vccnz .LBB0_564
	ds_read_b128 v[0:3], v19
	ds_read_b128 v[4:7], v101
	s_mov_b64 s[14:15], 0
	s_waitcnt lgkmcnt(0)
	v_mfma_f32_16x16x32_bf16 v[0:3], v[0:3], v[4:7], 0
	ds_read_b128 v[4:7], v19 offset:64
	ds_read_b128 v[38:41], v101 offset:64
	s_waitcnt lgkmcnt(0)
	v_mfma_f32_16x16x32_bf16 v[0:3], v[4:7], v[38:41], v[0:3]
	ds_read_b128 v[4:7], v19 offset:128
	ds_read_b128 v[38:41], v101 offset:128
	s_waitcnt lgkmcnt(0)
	v_mfma_f32_16x16x32_bf16 v[0:3], v[4:7], v[38:41], v[0:3]
	ds_read_b128 v[4:7], v19 offset:192
	ds_read_b128 v[38:41], v101 offset:192
	s_waitcnt lgkmcnt(0)
	v_mfma_f32_16x16x32_bf16 v[0:3], v[4:7], v[38:41], v[0:3]
	v_lshl_add_u64 v[4:5], s[12:13], 0, v[22:23]
	s_nop 6
	v_cndmask_b32_e64 v0, v0, 0, s[80:81]
	s_nop 0
	v_cvt_pk_bf16_f32 v0, v0, v0
	v_lshl_add_u64 v[6:7], v[4:5], 0, v[24:25]
	global_store_short_d16_hi v[6:7], v0, off
	v_cndmask_b32_e64 v0, v1, 0, s[62:63]
	v_bfe_u32 v1, v0, 16, 1
	v_add3_u32 v6, v0, v1, s48
	v_lshl_add_u64 v[0:1], v[4:5], 0, v[26:27]
	global_store_short_d16_hi v[0:1], v6, off
	v_cndmask_b32_e64 v0, v2, 0, s[64:65]
	s_nop 0
	v_cvt_pk_bf16_f32 v2, v0, v0
	v_lshl_add_u64 v[0:1], v[4:5], 0, v[28:29]
	global_store_short_d16_hi v[0:1], v2, off
	v_cndmask_b32_e64 v0, v3, 0, s[66:67]
	v_bfe_u32 v1, v0, 16, 1
	v_add3_u32 v2, v0, v1, s48
	v_lshl_add_u64 v[0:1], v[4:5], 0, v[30:31]
	global_store_short_d16_hi v[0:1], v2, off

.LBB0_665:
	s_mul_hi_i32 s12, s64, 0x2aaaaaab
	s_lshr_b32 s13, s12, 31
	s_ashr_i32 s12, s12, 2
	s_add_i32 s82, s12, s13
	s_mul_i32 s12, s82, 0xffffffe8
	s_add_i32 s92, s64, s12
	s_mov_b64 s[12:13], -1
	s_cmp_gt_i32 s92, 15
	v_lshl_add_u32 v103, s82, 5, v66
	s_cbranch_scc0 .LBB0_739
	v_mov_b32_e32 v155, v97
	s_add_i32 s12, s92, -16
	s_lshr_b32 s38, s12, 1
	s_and_b32 s28, s90, 2
	v_or_b32_e32 v146, s28, v62
	s_movk_i32 s26, 0x810
	v_cmp_gt_i32_e64 s[14:15], s26, v103
	s_mul_i32 s33, s38, 0x810
	s_nop 1
	v_cndmask_b32_e64 v140, 0, v103, s[14:15]
	v_add_u32_e32 v140, s33, v140
	v_mov_b64_e32 v[142:143], s[34:35]
	v_mad_i64_i32 v[144:145], s[16:17], v140, s44, v[142:143]
	v_lshl_or_b32 v140, v146, 7, v102
	v_or_b32_e32 v154, 0x2200, v140
	v_lshl_add_u64 v[146:147], v[144:145], 0, v[154:155]
	v_mov_b32_e32 v141, v155
	s_mov_b64 s[86:87], 0x2a00
	global_load_ushort v158, v[146:147], off
	v_lshl_add_u64 v[146:147], v[144:145], 0, v[140:141]
	v_lshl_add_u64 v[152:153], v[144:145], 0, s[86:87]
	v_add_co_u32_e32 v144, vcc, s74, v144
	s_nop 1
	v_addc_co_u32_e32 v145, vcc, 0, v145, vcc
	global_load_dwordx4 v[160:163], v[144:145], off offset:2560
	global_load_dwordx4 v[164:167], v[152:153], off offset:16
	v_or_b32_e32 v156, 2, v103
	v_cmp_gt_i32_e64 s[12:13], s26, v156
	v_or_b32_e32 v150, 3, v103
	v_or_b32_e32 v144, 1, v103
	v_cmp_gt_i32_e64 s[18:19], s26, v144
	v_cmp_gt_i32_e64 s[16:17], s26, v150
	s_nop 1
	v_cndmask_b32_e64 v144, 0, v144, s[18:19]
	v_add_u32_e32 v157, s33, v144
	v_mad_i64_i32 v[148:149], s[20:21], v157, s44, v[142:143]
	v_lshl_add_u64 v[144:145], v[148:149], 0, v[154:155]
	global_load_ushort v159, v[144:145], off
	v_lshl_add_u64 v[144:145], v[148:149], 0, v[140:141]
	v_lshl_add_u64 v[152:153], v[148:149], 0, s[86:87]
	v_add_co_u32_e32 v148, vcc, s74, v148
	s_nop 1
	v_addc_co_u32_e32 v149, vcc, 0, v149, vcc
	global_load_dwordx4 v[168:171], v[148:149], off offset:2560
	global_load_dwordx4 v[172:175], v[152:153], off offset:16
	v_cndmask_b32_e64 v148, 0, v156, s[12:13]
	v_add_u32_e32 v148, s33, v148
	v_mad_i64_i32 v[148:149], s[20:21], v148, s44, v[142:143]
	v_add_co_u32_e32 v146, vcc, s74, v146
	v_lshl_add_u64 v[152:153], v[148:149], 0, v[154:155]
	s_nop 1
	v_addc_co_u32_e32 v147, vcc, 0, v147, vcc
	global_load_ushort v176, v[152:153], off
	global_load_ushort v177, v[146:147], off offset:1024
	v_lshl_add_u64 v[152:153], v[148:149], 0, v[140:141]
	v_add_co_u32_e32 v146, vcc, s74, v152
	s_nop 1
	v_addc_co_u32_e32 v147, vcc, 0, v153, vcc
	global_load_ushort v178, v[146:147], off offset:1024
	v_lshl_add_u64 v[146:147], v[148:149], 0, s[86:87]
	v_add_co_u32_e32 v148, vcc, s74, v148
	s_nop 1
	v_addc_co_u32_e32 v149, vcc, 0, v149, vcc
	global_load_dwordx4 v[180:183], v[148:149], off offset:2560
	global_load_dwordx4 v[184:187], v[146:147], off offset:16
	v_cndmask_b32_e64 v146, 0, v150, s[16:17]
	v_add_u32_e32 v139, s33, v146
	v_mad_i64_i32 v[146:147], s[20:21], v139, s44, v[142:143]
	v_lshl_add_u64 v[150:151], v[146:147], 0, v[154:155]
	global_load_ushort v179, v[150:151], off
	v_lshl_add_u64 v[150:151], v[146:147], 0, v[140:141]
	v_add_co_u32_e32 v150, vcc, s74, v150
	s_nop 1
	v_addc_co_u32_e32 v151, vcc, 0, v151, vcc
	v_add_co_u32_e32 v144, vcc, s74, v144
	global_load_ushort v188, v[150:151], off offset:1024
	s_nop 1
	v_addc_co_u32_e32 v145, vcc, 0, v145, vcc
	global_load_ushort v189, v[144:145], off offset:1024
	v_lshl_add_u64 v[150:151], v[146:147], 0, s[86:87]
	v_add_co_u32_e32 v144, vcc, s74, v146
	s_nop 1
	v_addc_co_u32_e32 v145, vcc, 0, v147, vcc
	global_load_dwordx4 v[190:193], v[144:145], off offset:2560
	global_load_dwordx4 v[194:197], v[150:151], off offset:16
	s_add_i32 s12, s92, -16
	s_lshr_b32 s38, s12, 1
	s_and_b32 s28, s90, 2
	s_lshl_b32 s93, s38, 2
	v_or_b32_e32 v6, s28, v62
	s_add_i32 s93, s93, 32
	s_ashr_i32 s83, s82, 31
	v_or_b32_e32 v2, s93, v6
	v_mov_b64_e32 v[0:1], s[82:83]
	v_mad_u64_u32 v[0:1], s[12:13], v2, s79, v[0:1]
	v_mov_b64_e32 v[2:3], s[56:57]
	v_mad_u64_u32 v[38:39], s[12:13], v0, s44, v[2:3]
	v_lshlrev_b32_e32 v96, 8, v6
	v_mad_i32_i24 v39, v1, s44, v39
	v_lshl_add_u64 v[0:1], v[10:11], 0, v[96:97]
	global_load_dword v108, v[0:1], off
	v_lshl_add_u64 v[0:1], v[12:13], 0, v[96:97]
	s_movk_i32 s12, 0x1000
	v_add_co_u32_e32 v2, vcc, s12, v0
	global_load_dword v44, v[0:1], off
	global_load_dword v48, v[0:1], off offset:1024
	global_load_dword v42, v[0:1], off offset:2048
	global_load_dword v40, v[0:1], off offset:3072
	v_addc_co_u32_e32 v3, vcc, 0, v1, vcc
	v_add_co_u32_e32 v4, vcc, s74, v0
	s_movk_i32 s26, 0x810
	s_nop 0
	v_addc_co_u32_e32 v5, vcc, 0, v1, vcc
	v_add_co_u32_e32 v0, vcc, s44, v0
	v_cmp_gt_i32_e64 s[14:15], s26, v103
	s_nop 0
	v_addc_co_u32_e32 v1, vcc, 0, v1, vcc
	global_load_dword v54, v[4:5], off offset:-4096
	global_load_dword v52, v[2:3], off offset:1024
	global_load_dword v50, v[2:3], off offset:2048
	global_load_dword v46, v[2:3], off offset:3072
	global_load_dword v45, v[4:5], off
	global_load_dword v49, v[4:5], off offset:1024
	global_load_dword v43, v[4:5], off offset:2048
	global_load_dword v41, v[4:5], off offset:3072
	global_load_dword v55, v[0:1], off
	global_load_dword v53, v[0:1], off offset:1024
	global_load_dword v51, v[0:1], off offset:2048
	global_load_dword v47, v[0:1], off offset:3072
	s_mul_i32 s33, s38, 0x810
	v_cndmask_b32_e64 v0, 0, v103, s[14:15]
	v_add_u32_e32 v0, s33, v0
	v_mov_b64_e32 v[2:3], s[34:35]
	v_mad_i64_i32 v[4:5], s[16:17], v0, s44, v[2:3]
	v_lshl_or_b32 v0, v6, 7, v102
	v_or_b32_e32 v96, 0x2200, v0
	v_lshl_add_u64 v[6:7], v[4:5], 0, v[96:97]
	v_mov_b32_e32 v1, v97
	s_mov_b64 s[86:87], 0x2a00
	s_waitcnt vmcnt(0)
	v_mov_b32_e32 v107, v158
	v_lshl_add_u64 v[6:7], v[4:5], 0, v[0:1]
	v_lshl_add_u64 v[60:61], v[4:5], 0, s[86:87]
	v_add_co_u32_e32 v4, vcc, s74, v4
	s_mov_b32 s29, 0x3f317217
	s_nop 0
	v_addc_co_u32_e32 v5, vcc, 0, v5, vcc
	v_mov_b64_e32 v[56:57], v[160:161]
	v_mov_b64_e32 v[58:59], v[162:163]
	v_mov_b64_e32 v[110:111], v[164:165]
	v_mov_b64_e32 v[112:113], v[166:167]
	v_mov_b32_e32 v138, 0x41b17218
	v_or_b32_e32 v104, 2, v103
	v_cmp_gt_i32_e64 s[12:13], s26, v104
	s_waitcnt vmcnt(0)
	v_and_b32_e32 v60, 0xffff0000, v56
	v_and_b32_e32 v61, 0xffff0000, v110
	v_lshlrev_b32_e32 v4, 16, v56
	v_lshlrev_b32_e32 v5, 16, v110
	v_pk_mul_f32 v[60:61], v[48:49], v[60:61]
	v_lshlrev_b32_e32 v56, 16, v58
	v_pk_fma_f32 v[4:5], v[44:45], v[4:5], v[60:61]
	v_lshlrev_b32_e32 v60, 16, v57
	v_lshlrev_b32_e32 v61, 16, v111
	v_pk_fma_f32 v[4:5], v[42:43], v[60:61], v[4:5]
	v_and_b32_e32 v61, 0xffff0000, v111
	v_and_b32_e32 v60, 0xffff0000, v57
	v_pk_fma_f32 v[4:5], v[40:41], v[60:61], v[4:5]
	v_lshlrev_b32_e32 v57, 16, v112
	v_pk_fma_f32 v[4:5], v[54:55], v[56:57], v[4:5]
	v_and_b32_e32 v57, 0xffff0000, v112
	v_and_b32_e32 v56, 0xffff0000, v58
	v_pk_fma_f32 v[4:5], v[52:53], v[56:57], v[4:5]
	v_lshlrev_b32_e32 v56, 16, v59
	v_lshlrev_b32_e32 v57, 16, v113
	v_pk_fma_f32 v[4:5], v[50:51], v[56:57], v[4:5]
	v_and_b32_e32 v57, 0xffff0000, v113
	v_and_b32_e32 v56, 0xffff0000, v59
	v_pk_fma_f32 v[4:5], v[46:47], v[56:57], v[4:5]
	v_or_b32_e32 v58, 3, v103
	v_add_f32_e32 v4, v108, v4
	v_add_f32_e32 v4, v4, v5
	v_min_f32_e32 v5, 0, v4
	v_mul_f32_e64 v4, |v4|, s94
	v_exp_f32_e32 v4, v4
	s_nop 0
	v_add_f32_e32 v4, 1.0, v4
	v_cmp_gt_f32_e32 vcc, s45, v4
	s_nop 1
	v_cndmask_b32_e64 v56, 0, 32, vcc
	v_ldexp_f32 v4, v4, v56
	v_log_f32_e32 v4, v4
	s_nop 0
	v_mul_f32_e32 v56, 0x3f317217, v4
	v_fma_f32 v56, v4, s29, -v56
	v_fmac_f32_e32 v56, 0x3377d1cf, v4
	v_fmac_f32_e32 v56, 0x3f317217, v4
	v_cmp_lt_f32_e64 s[16:17], |v4|, s95
	s_nop 1
	v_cndmask_b32_e64 v4, v4, v56, s[16:17]
	v_cndmask_b32_e32 v56, 0, v138, vcc
	v_sub_f32_e32 v4, v4, v56
	v_sub_f32_e32 v4, v5, v4
	s_mov_b32 s16, 0x3d800000
	v_fma_f32 v4, v4, s16, 0
	v_cndmask_b32_e64 v109, 0, v4, s[14:15]
	v_or_b32_e32 v4, 1, v103
	v_cmp_gt_i32_e64 s[18:19], s26, v4
	v_cmp_gt_i32_e64 s[16:17], s26, v58
	s_nop 0
	v_cndmask_b32_e64 v4, 0, v4, s[18:19]
	v_add_u32_e32 v105, s33, v4
	v_mad_i64_i32 v[56:57], s[20:21], v105, s44, v[2:3]
	v_lshl_add_u64 v[4:5], v[56:57], 0, v[96:97]
	v_mov_b32_e32 v110, v159
	v_lshl_add_u64 v[4:5], v[56:57], 0, v[0:1]
	v_lshl_add_u64 v[60:61], v[56:57], 0, s[86:87]
	v_add_co_u32_e32 v56, vcc, s74, v56
	s_nop 1
	v_addc_co_u32_e32 v57, vcc, 0, v57, vcc
	v_mov_b64_e32 v[112:113], v[168:169]
	v_mov_b64_e32 v[114:115], v[170:171]
	v_mov_b64_e32 v[116:117], v[172:173]
	v_mov_b64_e32 v[118:119], v[174:175]
	s_waitcnt vmcnt(0)
	v_and_b32_e32 v60, 0xffff0000, v112
	s_waitcnt vmcnt(0)
	v_and_b32_e32 v61, 0xffff0000, v116
	v_lshlrev_b32_e32 v56, 16, v112
	v_lshlrev_b32_e32 v57, 16, v116
	v_pk_mul_f32 v[60:61], v[48:49], v[60:61]
	s_nop 0
	v_pk_fma_f32 v[56:57], v[44:45], v[56:57], v[60:61]
	v_lshlrev_b32_e32 v60, 16, v113
	v_lshlrev_b32_e32 v61, 16, v117
	v_pk_fma_f32 v[56:57], v[42:43], v[60:61], v[56:57]
	v_and_b32_e32 v61, 0xffff0000, v117
	v_and_b32_e32 v60, 0xffff0000, v113
	v_pk_fma_f32 v[56:57], v[40:41], v[60:61], v[56:57]
	v_lshlrev_b32_e32 v60, 16, v114
	v_lshlrev_b32_e32 v61, 16, v118
	v_pk_fma_f32 v[56:57], v[54:55], v[60:61], v[56:57]
	v_and_b32_e32 v61, 0xffff0000, v118
	v_and_b32_e32 v60, 0xffff0000, v114
	v_pk_fma_f32 v[56:57], v[52:53], v[60:61], v[56:57]
	v_lshlrev_b32_e32 v60, 16, v115
	v_lshlrev_b32_e32 v61, 16, v119
	v_pk_fma_f32 v[56:57], v[50:51], v[60:61], v[56:57]
	v_and_b32_e32 v61, 0xffff0000, v119
	v_and_b32_e32 v60, 0xffff0000, v115
	v_pk_fma_f32 v[56:57], v[46:47], v[60:61], v[56:57]
	s_nop 0
	v_add_f32_e32 v56, v108, v56
	v_add_f32_e32 v56, v56, v57
	v_min_f32_e32 v57, 0, v56
	v_mul_f32_e64 v56, |v56|, s94
	v_exp_f32_e32 v56, v56
	s_nop 0
	v_add_f32_e32 v56, 1.0, v56
	v_cmp_gt_f32_e32 vcc, s45, v56
	s_nop 1
	v_cndmask_b32_e64 v59, 0, 32, vcc
	v_ldexp_f32 v56, v56, v59
	v_log_f32_e32 v56, v56
	s_nop 0
	v_mul_f32_e32 v59, 0x3f317217, v56
	v_fma_f32 v59, v56, s29, -v59
	v_fmac_f32_e32 v59, 0x3377d1cf, v56
	v_fmac_f32_e32 v59, 0x3f317217, v56
	v_cmp_lt_f32_e64 s[20:21], |v56|, s95
	s_nop 1
	v_cndmask_b32_e64 v56, v56, v59, s[20:21]
	v_cndmask_b32_e32 v59, 0, v138, vcc
	v_sub_f32_e32 v56, v56, v59
	v_sub_f32_e32 v56, v57, v56
	v_mul_f32_e32 v56, 0x3d800000, v56
	v_cndmask_b32_e64 v56, 0, v56, s[18:19]
	v_add_f32_e32 v113, v109, v56
	v_cndmask_b32_e64 v56, 0, v104, s[12:13]
	v_add_u32_e32 v56, s33, v56
	v_mad_i64_i32 v[56:57], s[20:21], v56, s44, v[2:3]
	v_add_co_u32_e32 v6, vcc, s74, v6
	v_lshl_add_u64 v[60:61], v[56:57], 0, v[96:97]
	s_nop 0
	v_addc_co_u32_e32 v7, vcc, 0, v7, vcc
	v_mov_b32_e32 v114, v176
	v_mov_b32_e32 v59, v177
	v_lshl_add_u64 v[60:61], v[56:57], 0, v[0:1]
	v_add_co_u32_e32 v6, vcc, s74, v60
	s_waitcnt vmcnt(0)
	v_lshlrev_b32_e32 v59, 16, v59
	v_addc_co_u32_e32 v7, vcc, 0, v61, vcc
	v_mov_b32_e32 v6, v178
	s_waitcnt vmcnt(0)
	v_lshlrev_b32_e32 v60, 16, v6
	v_lshl_add_u64 v[6:7], v[56:57], 0, s[86:87]
	v_add_co_u32_e32 v56, vcc, s74, v56
	s_nop 1
	v_addc_co_u32_e32 v57, vcc, 0, v57, vcc
	v_mov_b64_e32 v[116:117], v[180:181]
	v_mov_b64_e32 v[118:119], v[182:183]
	v_mov_b64_e32 v[120:121], v[184:185]
	v_mov_b64_e32 v[122:123], v[186:187]
	s_waitcnt vmcnt(0)
	v_and_b32_e32 v56, 0xffff0000, v116
	s_waitcnt vmcnt(0)
	v_and_b32_e32 v57, 0xffff0000, v120
	v_lshlrev_b32_e32 v6, 16, v116
	v_lshlrev_b32_e32 v7, 16, v120
	v_pk_mul_f32 v[56:57], v[48:49], v[56:57]
	s_nop 0
	v_pk_fma_f32 v[6:7], v[44:45], v[6:7], v[56:57]
	v_lshlrev_b32_e32 v56, 16, v117
	v_lshlrev_b32_e32 v57, 16, v121
	v_pk_fma_f32 v[6:7], v[42:43], v[56:57], v[6:7]
	v_and_b32_e32 v57, 0xffff0000, v121
	v_and_b32_e32 v56, 0xffff0000, v117
	v_pk_fma_f32 v[6:7], v[40:41], v[56:57], v[6:7]
	v_lshlrev_b32_e32 v56, 16, v118
	v_lshlrev_b32_e32 v57, 16, v122
	v_pk_fma_f32 v[6:7], v[54:55], v[56:57], v[6:7]
	v_and_b32_e32 v57, 0xffff0000, v122
	v_and_b32_e32 v56, 0xffff0000, v118
	v_pk_fma_f32 v[6:7], v[52:53], v[56:57], v[6:7]
	v_lshlrev_b32_e32 v56, 16, v119
	v_lshlrev_b32_e32 v57, 16, v123
	v_pk_fma_f32 v[6:7], v[50:51], v[56:57], v[6:7]
	v_and_b32_e32 v57, 0xffff0000, v123
	v_and_b32_e32 v56, 0xffff0000, v119
	v_pk_fma_f32 v[6:7], v[46:47], v[56:57], v[6:7]
	v_cndmask_b32_e64 v57, 0, v60, s[12:13]
	v_add_f32_e32 v6, v108, v6
	v_add_f32_e32 v6, v6, v7
	v_min_f32_e32 v7, 0, v6
	v_mul_f32_e64 v6, |v6|, s94
	v_exp_f32_e32 v6, v6
	s_nop 0
	v_add_f32_e32 v6, 1.0, v6
	v_cmp_gt_f32_e32 vcc, s45, v6
	s_nop 1
	v_cndmask_b32_e64 v56, 0, 32, vcc
	v_ldexp_f32 v6, v6, v56
	v_log_f32_e32 v6, v6
	s_nop 0
	v_mul_f32_e32 v56, 0x3f317217, v6
	v_fma_f32 v56, v6, s29, -v56
	v_fmac_f32_e32 v56, 0x3377d1cf, v6
	v_fmac_f32_e32 v56, 0x3f317217, v6
	v_cmp_lt_f32_e64 s[20:21], |v6|, s95
	s_nop 1
	v_cndmask_b32_e64 v6, v6, v56, s[20:21]
	v_cndmask_b32_e32 v56, 0, v138, vcc
	v_sub_f32_e32 v6, v6, v56
	v_sub_f32_e32 v6, v7, v6
	v_mul_f32_e32 v6, 0x3d800000, v6
	v_cndmask_b32_e64 v6, 0, v6, s[12:13]
	v_add_f32_e32 v117, v113, v6
	v_cndmask_b32_e64 v6, 0, v58, s[16:17]
	v_add_u32_e32 v111, s33, v6
	v_mad_i64_i32 v[6:7], s[20:21], v111, s44, v[2:3]
	v_cndmask_b32_e64 v56, 0, v59, s[14:15]
	v_lshl_add_u64 v[58:59], v[6:7], 0, v[96:97]
	v_mov_b32_e32 v116, v179
	v_lshl_add_u64 v[58:59], v[6:7], 0, v[0:1]
	v_add_co_u32_e32 v58, vcc, s74, v58
	s_nop 1
	v_addc_co_u32_e32 v59, vcc, 0, v59, vcc
	v_add_co_u32_e32 v4, vcc, s74, v4
	v_mov_b32_e32 v58, v188
	s_nop 0
	v_addc_co_u32_e32 v5, vcc, 0, v5, vcc
	v_mov_b32_e32 v4, v189
	s_waitcnt vmcnt(0)
	v_lshlrev_b32_e32 v115, 16, v58
	v_lshl_add_u64 v[58:59], v[6:7], 0, s[86:87]
	s_waitcnt vmcnt(0)
	v_lshlrev_b32_e32 v112, 16, v4
	v_add_co_u32_e32 v4, vcc, s74, v6
	s_nop 1
	v_addc_co_u32_e32 v5, vcc, 0, v7, vcc
	v_mov_b64_e32 v[4:5], v[190:191]
	v_mov_b64_e32 v[6:7], v[192:193]
	s_nop 0
	v_mov_b64_e32 v[58:59], v[194:195]
	v_mov_b64_e32 v[60:61], v[196:197]
	v_mov_b32_e32 v142, v2
	v_mov_b32_e32 v143, v3
	v_mov_b32_e32 v140, v0
	v_mov_b32_e32 v141, v1
	v_or_b32_e32 v139, 4, v103
	v_cmp_gt_i32_e64 s[22:23], s26, v139
	v_or_b32_e32 v150, 6, v103
	s_nop 1
	v_cndmask_b32_e64 v144, 0, v139, s[22:23]
	v_add_u32_e32 v144, s33, v144
	v_mad_i64_i32 v[146:147], s[24:25], v144, s44, v[142:143]
	v_lshl_add_u64 v[144:145], v[146:147], 0, v[96:97]
	global_load_ushort v151, v[144:145], off
	v_lshl_add_u64 v[144:145], v[146:147], 0, v[140:141]
	v_lshl_add_u64 v[148:149], v[146:147], 0, s[86:87]
	v_add_co_u32_e32 v146, vcc, s74, v146
	v_cmp_gt_i32_e64 s[20:21], s26, v150
	s_nop 1
	v_addc_co_u32_e32 v147, vcc, 0, v147, vcc
	global_load_dwordx4 v[160:163], v[146:147], off offset:2560
	global_load_dwordx4 v[164:167], v[148:149], off offset:16
	v_or_b32_e32 v154, 7, v103
	v_or_b32_e32 v146, 5, v103
	v_cmp_gt_i32_e64 s[24:25], s26, v154
	v_cmp_gt_i32_e64 s[98:99], s26, v146
	s_nop 1
	v_cndmask_b32_e64 v146, 0, v146, s[98:99]
	v_add_u32_e32 v152, s33, v146
	v_mad_i64_i32 v[148:149], s[30:31], v152, s44, v[142:143]
	v_lshl_add_u64 v[146:147], v[148:149], 0, v[96:97]
	global_load_ushort v153, v[146:147], off
	v_lshl_add_u64 v[146:147], v[148:149], 0, v[140:141]
	v_lshl_add_u64 v[158:159], v[148:149], 0, s[86:87]
	v_add_co_u32_e32 v148, vcc, s74, v148
	s_nop 1
	v_addc_co_u32_e32 v149, vcc, 0, v149, vcc
	global_load_dwordx4 v[168:171], v[148:149], off offset:2560
	global_load_dwordx4 v[172:175], v[158:159], off offset:16
	v_cndmask_b32_e64 v148, 0, v150, s[20:21]
	v_add_u32_e32 v148, s33, v148
	v_mad_i64_i32 v[148:149], s[30:31], v148, s44, v[142:143]
	v_lshl_add_u64 v[156:157], v[148:149], 0, v[96:97]
	global_load_ushort v155, v[156:157], off
	v_lshl_add_u64 v[156:157], v[148:149], 0, v[140:141]
	v_add_co_u32_e32 v156, vcc, s74, v156
	s_nop 1
	v_addc_co_u32_e32 v157, vcc, 0, v157, vcc
	v_add_co_u32_e32 v144, vcc, s74, v144
	global_load_ushort v176, v[156:157], off offset:1024
	s_nop 1
	v_addc_co_u32_e32 v145, vcc, 0, v145, vcc
	global_load_ushort v177, v[144:145], off offset:1024
	v_lshl_add_u64 v[144:145], v[148:149], 0, s[86:87]
	v_add_co_u32_e32 v148, vcc, s74, v148
	s_nop 1
	v_addc_co_u32_e32 v149, vcc, 0, v149, vcc
	global_load_dwordx4 v[178:181], v[148:149], off offset:2560
	global_load_dwordx4 v[182:185], v[144:145], off offset:16
	v_cndmask_b32_e64 v144, 0, v154, s[24:25]
	v_add_u32_e32 v154, s33, v144
	v_mad_i64_i32 v[142:143], s[30:31], v154, s44, v[142:143]
	v_lshl_add_u64 v[140:141], v[142:143], 0, v[140:141]
	v_add_co_u32_e32 v140, vcc, s74, v140
	v_lshl_add_u64 v[144:145], v[142:143], 0, v[96:97]
	s_nop 1
	v_addc_co_u32_e32 v141, vcc, 0, v141, vcc
	global_load_ushort v186, v[144:145], off
	global_load_ushort v187, v[140:141], off offset:1024
	v_add_co_u32_e32 v140, vcc, s74, v146
	s_nop 1
	v_addc_co_u32_e32 v141, vcc, 0, v147, vcc
	global_load_ushort v188, v[140:141], off offset:1024
	v_lshl_add_u64 v[144:145], v[142:143], 0, s[86:87]
	v_add_co_u32_e32 v140, vcc, s74, v142
	s_nop 1
	v_addc_co_u32_e32 v141, vcc, 0, v143, vcc
	global_load_dwordx4 v[190:193], v[140:141], off offset:2560
	global_load_dwordx4 v[194:197], v[144:145], off offset:16
	s_waitcnt vmcnt(0)
	v_and_b32_e32 v120, 0xffff0000, v4
	s_waitcnt vmcnt(0)
	v_and_b32_e32 v121, 0xffff0000, v58
	v_lshlrev_b32_e32 v118, 16, v4
	v_lshlrev_b32_e32 v119, 16, v58
	v_pk_mul_f32 v[120:121], v[48:49], v[120:121]
	v_and_b32_e32 v58, 0xffff0000, v5
	v_pk_fma_f32 v[118:119], v[44:45], v[118:119], v[120:121]
	v_lshlrev_b32_e32 v120, 16, v5
	v_lshlrev_b32_e32 v121, 16, v59
	v_pk_fma_f32 v[118:119], v[42:43], v[120:121], v[118:119]
	v_and_b32_e32 v59, 0xffff0000, v59
	v_pk_fma_f32 v[4:5], v[40:41], v[58:59], v[118:119]
	v_lshlrev_b32_e32 v58, 16, v6
	v_lshlrev_b32_e32 v59, 16, v60
	v_pk_fma_f32 v[4:5], v[54:55], v[58:59], v[4:5]
	v_and_b32_e32 v59, 0xffff0000, v60
	v_and_b32_e32 v58, 0xffff0000, v6
	v_pk_fma_f32 v[4:5], v[52:53], v[58:59], v[4:5]
	v_lshlrev_b32_e32 v58, 16, v7
	v_lshlrev_b32_e32 v59, 16, v61
	v_pk_fma_f32 v[4:5], v[50:51], v[58:59], v[4:5]
	v_and_b32_e32 v59, 0xffff0000, v61
	v_and_b32_e32 v58, 0xffff0000, v7
	v_pk_fma_f32 v[4:5], v[46:47], v[58:59], v[4:5]
	v_cndmask_b32_e64 v59, 0, v115, s[16:17]
	v_add_f32_e32 v4, v108, v4
	v_add_f32_e32 v4, v4, v5
	v_min_f32_e32 v5, 0, v4
	v_mul_f32_e64 v4, |v4|, s94
	v_exp_f32_e32 v4, v4
	v_or_b32_e32 v115, 4, v103
	v_cmp_gt_i32_e64 s[22:23], s26, v115
	v_cndmask_b32_e64 v58, 0, v112, s[18:19]
	v_add_f32_e32 v4, 1.0, v4
	v_cmp_gt_f32_e32 vcc, s45, v4
	v_or_b32_e32 v112, 6, v103
	s_nop 0
	v_cndmask_b32_e64 v6, 0, 32, vcc
	v_ldexp_f32 v4, v4, v6
	v_log_f32_e32 v4, v4
	s_nop 0
	v_mul_f32_e32 v6, 0x3f317217, v4
	v_fma_f32 v6, v4, s29, -v6
	v_fmac_f32_e32 v6, 0x3377d1cf, v4
	v_fmac_f32_e32 v6, 0x3f317217, v4
	v_cmp_lt_f32_e64 s[20:21], |v4|, s95
	s_nop 1
	v_cndmask_b32_e64 v4, v4, v6, s[20:21]
	v_cndmask_b32_e32 v6, 0, v138, vcc
	v_sub_f32_e32 v4, v4, v6
	v_sub_f32_e32 v4, v5, v4
	v_mul_f32_e32 v4, 0x3d800000, v4
	v_cndmask_b32_e64 v4, 0, v4, s[16:17]
	v_add_f32_e32 v120, v117, v4
	v_cndmask_b32_e64 v4, 0, v115, s[22:23]
	v_add_u32_e32 v4, s33, v4
	v_mad_i64_i32 v[6:7], s[24:25], v4, s44, v[2:3]
	v_lshl_add_u64 v[4:5], v[6:7], 0, v[96:97]
	s_waitcnt vmcnt(0)
	v_mov_b32_e32 v119, v151
	v_lshl_add_u64 v[4:5], v[6:7], 0, v[0:1]
	v_lshl_add_u64 v[60:61], v[6:7], 0, s[86:87]
	v_add_co_u32_e32 v6, vcc, s74, v6
	v_cmp_gt_i32_e64 s[20:21], s26, v112
	s_nop 0
	v_addc_co_u32_e32 v7, vcc, 0, v7, vcc
	v_mov_b64_e32 v[122:123], v[160:161]
	v_mov_b64_e32 v[124:125], v[162:163]
	v_mov_b64_e32 v[126:127], v[164:165]
	v_mov_b64_e32 v[128:129], v[166:167]
	s_waitcnt vmcnt(0)
	v_and_b32_e32 v60, 0xffff0000, v122
	s_waitcnt vmcnt(0)
	v_and_b32_e32 v61, 0xffff0000, v126
	v_lshlrev_b32_e32 v6, 16, v122
	v_lshlrev_b32_e32 v7, 16, v126
	v_pk_mul_f32 v[60:61], v[48:49], v[60:61]
	s_nop 0
	v_pk_fma_f32 v[6:7], v[44:45], v[6:7], v[60:61]
	v_lshlrev_b32_e32 v60, 16, v123
	v_lshlrev_b32_e32 v61, 16, v127
	v_pk_fma_f32 v[6:7], v[42:43], v[60:61], v[6:7]
	v_and_b32_e32 v61, 0xffff0000, v127
	v_and_b32_e32 v60, 0xffff0000, v123
	v_pk_fma_f32 v[6:7], v[40:41], v[60:61], v[6:7]
	v_lshlrev_b32_e32 v60, 16, v124
	v_lshlrev_b32_e32 v61, 16, v128
	v_pk_fma_f32 v[6:7], v[54:55], v[60:61], v[6:7]
	v_and_b32_e32 v61, 0xffff0000, v128
	v_and_b32_e32 v60, 0xffff0000, v124
	v_pk_fma_f32 v[6:7], v[52:53], v[60:61], v[6:7]
	v_lshlrev_b32_e32 v60, 16, v125
	v_lshlrev_b32_e32 v61, 16, v129
	v_pk_fma_f32 v[6:7], v[50:51], v[60:61], v[6:7]
	v_and_b32_e32 v61, 0xffff0000, v129
	v_and_b32_e32 v60, 0xffff0000, v125
	v_pk_fma_f32 v[6:7], v[46:47], v[60:61], v[6:7]
	v_or_b32_e32 v124, 7, v103
	v_add_f32_e32 v6, v108, v6
	v_add_f32_e32 v6, v6, v7
	v_min_f32_e32 v7, 0, v6
	v_mul_f32_e64 v6, |v6|, s94
	v_exp_f32_e32 v6, v6
	s_nop 0
	v_add_f32_e32 v6, 1.0, v6
	v_cmp_gt_f32_e32 vcc, s45, v6
	s_nop 1
	v_cndmask_b32_e64 v60, 0, 32, vcc
	v_ldexp_f32 v6, v6, v60
	v_log_f32_e32 v6, v6
	s_nop 0
	v_mul_f32_e32 v60, 0x3f317217, v6
	v_fma_f32 v60, v6, s29, -v60
	v_fmac_f32_e32 v60, 0x3377d1cf, v6
	v_fmac_f32_e32 v60, 0x3f317217, v6
	v_cmp_lt_f32_e64 s[24:25], |v6|, s95
	s_nop 1
	v_cndmask_b32_e64 v6, v6, v60, s[24:25]
	v_cndmask_b32_e32 v60, 0, v138, vcc
	v_sub_f32_e32 v6, v6, v60
	v_sub_f32_e32 v6, v7, v6
	v_mul_f32_e32 v6, 0x3d800000, v6
	v_cndmask_b32_e64 v123, 0, v6, s[22:23]
	v_or_b32_e32 v6, 5, v103
	v_cmp_gt_i32_e64 s[24:25], s26, v124
	v_cmp_gt_i32_e64 s[26:27], s26, v6
	s_nop 1
	v_cndmask_b32_e64 v6, 0, v6, s[26:27]
	v_add_u32_e32 v118, s33, v6
	v_mad_i64_i32 v[60:61], s[30:31], v118, s44, v[2:3]
	v_lshl_add_u64 v[6:7], v[60:61], 0, v[96:97]
	v_mov_b32_e32 v121, v153
	v_lshl_add_u64 v[6:7], v[60:61], 0, v[0:1]
	v_lshl_add_u64 v[130:131], v[60:61], 0, s[86:87]
	v_add_co_u32_e32 v60, vcc, s74, v60
	s_nop 1
	v_addc_co_u32_e32 v61, vcc, 0, v61, vcc
	v_mov_b64_e32 v[126:127], v[168:169]
	v_mov_b64_e32 v[128:129], v[170:171]
	s_nop 0
	v_mov_b64_e32 v[130:131], v[172:173]
	v_mov_b64_e32 v[132:133], v[174:175]
	s_waitcnt vmcnt(0)
	v_and_b32_e32 v134, 0xffff0000, v126
	s_waitcnt vmcnt(0)
	v_and_b32_e32 v135, 0xffff0000, v130
	v_lshlrev_b32_e32 v60, 16, v126
	v_lshlrev_b32_e32 v61, 16, v130
	v_pk_mul_f32 v[134:135], v[48:49], v[134:135]
	v_and_b32_e32 v130, 0xffff0000, v127
	v_pk_fma_f32 v[60:61], v[44:45], v[60:61], v[134:135]
	v_lshlrev_b32_e32 v134, 16, v127
	v_lshlrev_b32_e32 v135, 16, v131
	v_pk_fma_f32 v[60:61], v[42:43], v[134:135], v[60:61]
	v_and_b32_e32 v131, 0xffff0000, v131
	v_pk_fma_f32 v[60:61], v[40:41], v[130:131], v[60:61]
	v_lshlrev_b32_e32 v126, 16, v128
	v_lshlrev_b32_e32 v127, 16, v132
	v_pk_fma_f32 v[60:61], v[54:55], v[126:127], v[60:61]
	v_and_b32_e32 v127, 0xffff0000, v132
	v_and_b32_e32 v126, 0xffff0000, v128
	v_pk_fma_f32 v[60:61], v[52:53], v[126:127], v[60:61]
	v_lshlrev_b32_e32 v126, 16, v129
	v_lshlrev_b32_e32 v127, 16, v133
	v_pk_fma_f32 v[60:61], v[50:51], v[126:127], v[60:61]
	v_and_b32_e32 v127, 0xffff0000, v133
	v_and_b32_e32 v126, 0xffff0000, v129
	v_pk_fma_f32 v[60:61], v[46:47], v[126:127], v[60:61]
	s_nop 0
	v_add_f32_e32 v60, v108, v60
	v_add_f32_e32 v60, v60, v61
	v_min_f32_e32 v61, 0, v60
	v_mul_f32_e64 v60, |v60|, s94
	v_exp_f32_e32 v60, v60
	s_nop 0
	v_add_f32_e32 v60, 1.0, v60
	v_cmp_gt_f32_e32 vcc, s45, v60
	s_nop 1
	v_cndmask_b32_e64 v122, 0, 32, vcc
	v_ldexp_f32 v60, v60, v122
	v_log_f32_e32 v60, v60
	s_nop 0
	v_mul_f32_e32 v122, 0x3f317217, v60
	v_fma_f32 v122, v60, s29, -v122
	v_fmac_f32_e32 v122, 0x3377d1cf, v60
	v_fmac_f32_e32 v122, 0x3f317217, v60
	v_cmp_lt_f32_e64 s[30:31], |v60|, s95
	s_nop 1
	v_cndmask_b32_e64 v60, v60, v122, s[30:31]
	v_cndmask_b32_e32 v122, 0, v138, vcc
	v_sub_f32_e32 v60, v60, v122
	v_sub_f32_e32 v60, v61, v60
	v_mul_f32_e32 v60, 0x3d800000, v60
	v_cndmask_b32_e64 v125, 0, v60, s[26:27]
	v_cndmask_b32_e64 v60, 0, v112, s[20:21]
	v_add_u32_e32 v60, s33, v60
	v_mad_i64_i32 v[60:61], s[30:31], v60, s44, v[2:3]
	v_lshl_add_u64 v[126:127], v[60:61], 0, v[96:97]
	v_mov_b32_e32 v122, v155
	v_lshl_add_u64 v[126:127], v[60:61], 0, v[0:1]
	v_add_co_u32_e32 v126, vcc, s74, v126
	s_nop 1
	v_addc_co_u32_e32 v127, vcc, 0, v127, vcc
	v_add_co_u32_e32 v4, vcc, s74, v4
	v_mov_b32_e32 v126, v176
	s_nop 0
	v_addc_co_u32_e32 v5, vcc, 0, v5, vcc
	v_mov_b32_e32 v4, v177
	s_waitcnt vmcnt(0)
	v_lshlrev_b32_e32 v135, 16, v126
	s_waitcnt vmcnt(0)
	v_lshlrev_b32_e32 v134, 16, v4
	v_lshl_add_u64 v[4:5], v[60:61], 0, s[86:87]
	v_add_co_u32_e32 v60, vcc, s74, v60
	s_nop 1
	v_addc_co_u32_e32 v61, vcc, 0, v61, vcc
	v_mov_b64_e32 v[126:127], v[178:179]
	v_mov_b64_e32 v[128:129], v[180:181]
	v_mov_b64_e32 v[130:131], v[182:183]
	v_mov_b64_e32 v[132:133], v[184:185]
	s_waitcnt vmcnt(0)
	v_and_b32_e32 v60, 0xffff0000, v126
	s_waitcnt vmcnt(0)
	v_and_b32_e32 v61, 0xffff0000, v130
	v_lshlrev_b32_e32 v4, 16, v126
	v_lshlrev_b32_e32 v5, 16, v130
	v_pk_mul_f32 v[60:61], v[48:49], v[60:61]
	s_nop 0
	v_pk_fma_f32 v[4:5], v[44:45], v[4:5], v[60:61]
	v_lshlrev_b32_e32 v60, 16, v127
	v_lshlrev_b32_e32 v61, 16, v131
	v_pk_fma_f32 v[4:5], v[42:43], v[60:61], v[4:5]
	v_and_b32_e32 v61, 0xffff0000, v131
	v_and_b32_e32 v60, 0xffff0000, v127
	v_pk_fma_f32 v[4:5], v[40:41], v[60:61], v[4:5]
	v_lshlrev_b32_e32 v60, 16, v128
	v_lshlrev_b32_e32 v61, 16, v132
	v_pk_fma_f32 v[4:5], v[54:55], v[60:61], v[4:5]
	v_and_b32_e32 v61, 0xffff0000, v132
	v_and_b32_e32 v60, 0xffff0000, v128
	v_pk_fma_f32 v[4:5], v[52:53], v[60:61], v[4:5]
	v_lshlrev_b32_e32 v60, 16, v129
	v_lshlrev_b32_e32 v61, 16, v133
	v_pk_fma_f32 v[4:5], v[50:51], v[60:61], v[4:5]
	v_and_b32_e32 v61, 0xffff0000, v133
	v_and_b32_e32 v60, 0xffff0000, v129
	v_pk_fma_f32 v[4:5], v[46:47], v[60:61], v[4:5]
	v_cndmask_b32_e64 v61, 0, v135, s[20:21]
	v_add_f32_e32 v4, v108, v4
	v_add_f32_e32 v4, v4, v5
	v_min_f32_e32 v5, 0, v4
	v_mul_f32_e64 v4, |v4|, s94
	v_exp_f32_e32 v4, v4
	s_nop 0
	v_add_f32_e32 v4, 1.0, v4
	v_cmp_gt_f32_e32 vcc, s45, v4
	s_nop 1
	v_cndmask_b32_e64 v60, 0, 32, vcc
	v_ldexp_f32 v4, v4, v60
	v_log_f32_e32 v4, v4
	s_nop 0
	v_mul_f32_e32 v60, 0x3f317217, v4
	v_fma_f32 v60, v4, s29, -v60
	v_fmac_f32_e32 v60, 0x3377d1cf, v4
	v_fmac_f32_e32 v60, 0x3f317217, v4
	v_cmp_lt_f32_e64 s[30:31], |v4|, s95
	s_nop 1
	v_cndmask_b32_e64 v4, v4, v60, s[30:31]
	v_cndmask_b32_e32 v60, 0, v138, vcc
	v_sub_f32_e32 v4, v4, v60
	v_sub_f32_e32 v4, v5, v4
	v_mul_f32_e32 v4, 0x3d800000, v4
	v_cndmask_b32_e64 v126, 0, v4, s[20:21]
	v_cndmask_b32_e64 v4, 0, v124, s[24:25]
	v_add_u32_e32 v124, s33, v4
	v_mad_i64_i32 v[2:3], s[30:31], v124, s44, v[2:3]
	v_lshl_add_u64 v[0:1], v[2:3], 0, v[0:1]
	v_add_co_u32_e32 v0, vcc, s74, v0
	v_lshl_add_u64 v[4:5], v[2:3], 0, v[96:97]
	s_nop 0
	v_addc_co_u32_e32 v1, vcc, 0, v1, vcc
	v_mov_b32_e32 v96, v186
	v_cndmask_b32_e64 v60, 0, v134, s[22:23]
	v_mov_b32_e32 v4, v187
	v_add_co_u32_e32 v0, vcc, s74, v6
	s_waitcnt vmcnt(0)
	v_lshlrev_b32_e32 v132, 16, v4
	v_addc_co_u32_e32 v1, vcc, 0, v7, vcc
	v_mov_b32_e32 v0, v188
	v_lshl_add_u64 v[4:5], v[2:3], 0, s[86:87]
	s_waitcnt vmcnt(0)
	v_lshlrev_b32_e32 v127, 16, v0
	v_add_co_u32_e32 v0, vcc, s74, v2
	s_nop 1
	v_addc_co_u32_e32 v1, vcc, 0, v3, vcc
	v_mov_b64_e32 v[0:1], v[190:191]
	v_mov_b64_e32 v[2:3], v[192:193]
	s_nop 0
	v_mov_b64_e32 v[4:5], v[194:195]
	v_mov_b64_e32 v[6:7], v[196:197]
	s_barrier
	s_waitcnt vmcnt(1)
	v_and_b32_e32 v130, 0xffff0000, v0
	s_waitcnt vmcnt(0)
	v_and_b32_e32 v131, 0xffff0000, v4
	v_lshlrev_b32_e32 v128, 16, v0
	v_lshlrev_b32_e32 v129, 16, v4
	v_pk_mul_f32 v[48:49], v[48:49], v[130:131]
	v_and_b32_e32 v4, 0xffff0000, v1
	v_pk_fma_f32 v[44:45], v[44:45], v[128:129], v[48:49]
	v_lshlrev_b32_e32 v48, 16, v1
	v_lshlrev_b32_e32 v49, 16, v5
	v_pk_fma_f32 v[42:43], v[42:43], v[48:49], v[44:45]
	v_and_b32_e32 v5, 0xffff0000, v5
	v_pk_fma_f32 v[0:1], v[40:41], v[4:5], v[42:43]
	v_lshlrev_b32_e32 v4, 16, v2
	v_lshlrev_b32_e32 v5, 16, v6
	v_pk_fma_f32 v[0:1], v[54:55], v[4:5], v[0:1]
	v_and_b32_e32 v5, 0xffff0000, v6
	v_and_b32_e32 v4, 0xffff0000, v2
	v_pk_fma_f32 v[0:1], v[52:53], v[4:5], v[0:1]
	v_lshlrev_b32_e32 v4, 16, v3
	v_lshlrev_b32_e32 v5, 16, v7
	v_pk_fma_f32 v[0:1], v[50:51], v[4:5], v[0:1]
	v_and_b32_e32 v5, 0xffff0000, v7
	v_and_b32_e32 v4, 0xffff0000, v3
	v_pk_fma_f32 v[0:1], v[46:47], v[4:5], v[0:1]
	v_add_f32_e32 v52, v120, v123
	v_add_f32_e32 v0, v108, v0
	v_add_f32_e32 v0, v0, v1
	v_min_f32_e32 v1, 0, v0
	v_mul_f32_e64 v0, |v0|, s94
	v_exp_f32_e32 v0, v0
	v_add_f32_e32 v53, v52, v125
	v_add_f32_e32 v54, v53, v126
	v_add_f32_e32 v0, 1.0, v0
	v_cmp_gt_f32_e32 vcc, s45, v0
	s_nop 1
	v_cndmask_b32_e64 v2, 0, 32, vcc
	v_ldexp_f32 v0, v0, v2
	v_log_f32_e32 v0, v0
	s_nop 0
	v_mul_f32_e32 v2, 0x3f317217, v0
	v_fma_f32 v2, v0, s29, -v2
	v_fmac_f32_e32 v2, 0x3377d1cf, v0
	v_fmac_f32_e32 v2, 0x3f317217, v0
	v_cmp_lt_f32_e64 s[30:31], |v0|, s95
	s_nop 1
	v_cndmask_b32_e64 v0, v0, v2, s[30:31]
	v_cndmask_b32_e32 v2, 0, v138, vcc
	v_sub_f32_e32 v0, v0, v2
	v_sub_f32_e32 v0, v1, v0
	v_mul_f32_e32 v0, 0x3d800000, v0
	v_cndmask_b32_e64 v2, 0, v0, s[24:25]
	v_add_f32_e32 v5, v54, v2
	ds_write_b32 v67, v5
	s_waitcnt lgkmcnt(0)
	s_barrier
	ds_read2st64_b32 v[6:7], v68 offset1:2
	ds_read2st64_b32 v[2:3], v68 offset0:4 offset1:6
	v_cndmask_b32_e64 v1, 0, v132, s[24:25]
	v_cndmask_b32_e64 v0, 0, v127, s[26:27]
	s_waitcnt lgkmcnt(1)
	v_add_f32_e32 v7, v6, v7
	s_waitcnt lgkmcnt(0)
	v_add_f32_e32 v4, v7, v2
	v_cndmask_b32_e64 v2, v4, v7, s[4:5]
	v_cndmask_b32_e64 v2, v2, v6, s[2:3]
	v_cndmask_b32_e64 v47, v2, 0, s[0:1]
	v_mov_b32_e32 v46, v3
	v_add_f32_e32 v45, v109, v47
	v_pk_add_f32 v[2:3], v[4:5], v[46:47]
	v_add_f32_e32 v44, v113, v47
	v_sub_f32_e32 v5, v2, v45
	v_mul_f32_e32 v5, 0x3fb8aa3b, v5
	v_exp_f32_e32 v40, v5
	v_sub_f32_e32 v5, v2, v44
	v_mul_f32_e32 v5, 0x3fb8aa3b, v5
	v_add_f32_e32 v43, v117, v47
	v_exp_f32_e32 v48, v5
	v_sub_f32_e32 v5, v2, v43
	v_mul_f32_e32 v5, 0x3fb8aa3b, v5
	v_exp_f32_e32 v41, v5
	v_add_f32_e32 v42, v120, v47
	v_sub_f32_e32 v5, v2, v42
	v_mul_f32_e32 v5, 0x3fb8aa3b, v5
	v_pk_mul_f32 v[50:51], v[56:57], v[40:41]
	v_add_f32_e32 v41, v52, v47
	v_exp_f32_e32 v49, v5
	v_sub_f32_e32 v5, v2, v41
	v_add_f32_e32 v40, v53, v47
	v_mul_f32_e32 v5, 0x3fb8aa3b, v5
	v_exp_f32_e32 v46, v5
	v_sub_f32_e32 v5, v2, v40
	v_mul_f32_e32 v5, 0x3fb8aa3b, v5
	v_exp_f32_e32 v52, v5
	v_add_f32_e32 v5, v47, v54
	v_sub_f32_e32 v53, v2, v3
	v_sub_f32_e32 v47, v2, v5
	v_mul_f32_e32 v53, 0x3fb8aa3b, v53
	v_mul_f32_e32 v47, 0x3fb8aa3b, v47
	v_exp_f32_e32 v53, v53
	v_exp_f32_e32 v47, v47
	v_pk_mul_f32 v[48:49], v[58:59], v[48:49]
	v_pk_mul_f32 v[52:53], v[0:1], v[52:53]
	v_pk_mul_f32 v[46:47], v[60:61], v[46:47]
	s_nop 0
	s_nop 0
	s_nop 0
	s_nop 0
	v_cvt_pk_bf16_f32 v52, v52, v52
	v_cvt_pk_bf16_f32 v53, v53, v53
	v_cvt_pk_bf16_f32 v54, v48, v48
	v_cvt_pk_bf16_f32 v55, v49, v49
	s_nop 0
	s_nop 0
	s_nop 0
	s_nop 0
	v_cvt_pk_bf16_f32 v47, v47, v47
	v_cvt_pk_bf16_f32 v46, v46, v46
	v_cvt_pk_bf16_f32 v48, v51, v51
	v_cvt_pk_bf16_f32 v49, v50, v50
	v_lshrrev_b32_e32 v46, 16, v46
	v_lshrrev_b32_e32 v47, 16, v47
	v_lshrrev_b32_e32 v50, 16, v49
	v_lshrrev_b32_e32 v51, 16, v48
	v_and_or_b32 v49, v53, s36, v47
	v_and_or_b32 v48, v52, s36, v46
	v_and_or_b32 v47, v55, s36, v51
	v_and_or_b32 v46, v54, s36, v50
	v_lshl_add_u64 v[50:51], v[38:39], 0, v[14:15]
	v_add_co_u32_e32 v50, vcc, 0x1000, v50
	s_nop 1
	v_addc_co_u32_e32 v51, vcc, 0, v51, vcc
	global_store_dwordx4 v[50:51], v[46:49], off
	s_and_saveexec_b64 s[30:31], s[8:9]
	s_cbranch_execz .LBB0_668
	v_mul_f32_e32 v2, 0x3fb8aa3b, v2
	v_exp_f32_e32 v2, v2
	v_lshl_add_u64 v[38:39], v[38:39], 0, v[8:9]
	v_add_co_u32_e32 v38, vcc, 0x2000, v38
	s_nop 1
	v_addc_co_u32_e32 v39, vcc, 0, v39, vcc
	global_store_dword v[38:39], v2, off offset:2048
.LBB0_668:
	s_or_b64 exec, exec, s[30:31]
	v_lshlrev_b32_e32 v2, 16, v107
	v_mul_f32_e32 v2, 0x3e000000, v2
	v_cndmask_b32_e64 v38, 0, v2, s[14:15]
	v_cndmask_b32_e64 v2, v4, v6, s[6:7]
	v_mul_f32_e32 v4, 0x3fb8aa3b, v45
	v_exp_f32_e32 v4, v4
	s_nop 0
	v_mul_f32_e32 v4, v38, v4
	s_nop 0
	v_cvt_pk_bf16_f32 v4, v4, v4
	v_add_u32_e32 v6, v70, v71
	ds_write_b16_d16_hi v6, v4 offset:2048
	v_sub_f32_e32 v4, v45, v2
	v_mul_f32_e32 v4, 0x3fb8aa3b, v4
	v_exp_f32_e32 v4, v4
	s_nop 0
	v_mul_f32_e32 v4, v38, v4
	s_nop 0
	v_cvt_pk_bf16_f32 v4, v4, v4
	ds_write_b16_d16_hi v72, v4 offset:10240
	v_sub_f32_e32 v4, v2, v45
	v_mul_f32_e32 v4, 0x3fb8aa3b, v4
	v_exp_f32_e32 v4, v4
	s_nop 0
	v_mul_f32_e32 v4, v56, v4
	s_nop 0
	v_cvt_pk_bf16_f32 v4, v4, v4
	ds_write_b16_d16_hi v72, v4 offset:18944
	s_and_saveexec_b64 s[30:31], s[6:7]
	s_xor_b64 s[30:31], exec, s[30:31]
	s_cbranch_execz .LBB0_670
	v_sub_f32_e32 v4, v7, v45
	v_mul_f32_e32 v4, 0x3fb8aa3b, v4
	v_exp_f32_e32 v4, v4
	s_nop 0
	v_mul_f32_e32 v4, v56, v4
	s_nop 0
	v_cvt_pk_bf16_f32 v4, v4, v4
	ds_write_b16_d16_hi v72, v4 offset:32000
.LBB0_670:
	s_andn2_saveexec_b64 s[30:31], s[30:31]
	s_cbranch_execz .LBB0_672
	v_sub_f32_e32 v4, v45, v7
	v_mul_f32_e32 v4, 0x3fb8aa3b, v4
	v_exp_f32_e32 v4, v4
	s_nop 0
	v_mul_f32_e32 v4, v38, v4
	s_nop 0
	v_cvt_pk_bf16_f32 v4, v4, v4
	ds_write_b16_d16_hi v73, v4 offset:23296
.LBB0_672:
	s_or_b64 exec, exec, s[30:31]
	v_mul_f32_e32 v6, 0x3fb8aa3b, v44
	v_exp_f32_e32 v6, v6
	v_lshlrev_b32_e32 v4, 16, v110
	v_mul_f32_e32 v4, 0x3e000000, v4
	v_cndmask_b32_e64 v4, 0, v4, s[18:19]
	v_mul_f32_e32 v6, v4, v6
	s_nop 0
	v_cvt_pk_bf16_f32 v6, v6, v6
	v_add_u32_e32 v38, v70, v74
	ds_write_b16_d16_hi v38, v6 offset:2048
	v_sub_f32_e32 v6, v44, v2
	v_mul_f32_e32 v6, 0x3fb8aa3b, v6
	v_exp_f32_e32 v6, v6
	s_nop 0
	v_mul_f32_e32 v6, v4, v6
	s_nop 0
	v_cvt_pk_bf16_f32 v6, v6, v6
	ds_write_b16_d16_hi v75, v6 offset:10240
	v_sub_f32_e32 v6, v2, v44
	v_mul_f32_e32 v6, 0x3fb8aa3b, v6
	v_exp_f32_e32 v6, v6
	s_nop 0
	v_mul_f32_e32 v6, v58, v6
	s_nop 0
	v_cvt_pk_bf16_f32 v6, v6, v6
	ds_write_b16_d16_hi v75, v6 offset:18944
	s_and_saveexec_b64 s[30:31], s[6:7]
	s_xor_b64 s[30:31], exec, s[30:31]
	s_cbranch_execz .LBB0_674
	v_sub_f32_e32 v4, v7, v44
	v_mul_f32_e32 v4, 0x3fb8aa3b, v4
	v_exp_f32_e32 v4, v4
	s_nop 0
	v_mul_f32_e32 v4, v58, v4
	v_bfe_u32 v6, v4, 16, 1
	v_add3_u32 v4, v4, v6, s48
	ds_write_b16_d16_hi v75, v4 offset:32000
.LBB0_674:
	s_andn2_saveexec_b64 s[30:31], s[30:31]
	s_cbranch_execz .LBB0_676
	v_sub_f32_e32 v6, v44, v7
	v_mul_f32_e32 v6, 0x3fb8aa3b, v6
	v_exp_f32_e32 v6, v6
	s_nop 0
	v_mul_f32_e32 v4, v4, v6
	s_nop 0
	v_cvt_pk_bf16_f32 v4, v4, v4
	ds_write_b16_d16_hi v76, v4 offset:23296
.LBB0_676:
	s_or_b64 exec, exec, s[30:31]
	v_mul_f32_e32 v6, 0x3fb8aa3b, v43
	v_exp_f32_e32 v6, v6
	v_lshlrev_b32_e32 v4, 16, v114
	v_mul_f32_e32 v4, 0x3e000000, v4
	v_cndmask_b32_e64 v4, 0, v4, s[12:13]
	v_mul_f32_e32 v6, v4, v6
	s_nop 0
	v_cvt_pk_bf16_f32 v6, v6, v6
	v_add_u32_e32 v38, v70, v77
	ds_write_b16_d16_hi v38, v6 offset:2048
	v_sub_f32_e32 v6, v43, v2
	v_mul_f32_e32 v6, 0x3fb8aa3b, v6
	v_exp_f32_e32 v6, v6
	s_nop 0
	v_mul_f32_e32 v6, v4, v6
	s_nop 0
	v_cvt_pk_bf16_f32 v6, v6, v6
	ds_write_b16_d16_hi v78, v6 offset:10240
	v_sub_f32_e32 v6, v2, v43
	v_mul_f32_e32 v6, 0x3fb8aa3b, v6
	v_exp_f32_e32 v6, v6
	s_nop 0
	v_mul_f32_e32 v6, v57, v6
	s_nop 0
	v_cvt_pk_bf16_f32 v6, v6, v6
	ds_write_b16_d16_hi v78, v6 offset:18944
	s_and_saveexec_b64 s[30:31], s[6:7]
	s_xor_b64 s[30:31], exec, s[30:31]
	s_cbranch_execz .LBB0_678
	v_sub_f32_e32 v4, v7, v43
	v_mul_f32_e32 v4, 0x3fb8aa3b, v4
	v_exp_f32_e32 v4, v4
	s_nop 0
	v_mul_f32_e32 v4, v57, v4
	v_bfe_u32 v6, v4, 16, 1
	v_add3_u32 v4, v4, v6, s48
	ds_write_b16_d16_hi v78, v4 offset:32000
.LBB0_678:
	s_andn2_saveexec_b64 s[30:31], s[30:31]
	s_cbranch_execz .LBB0_680
	v_sub_f32_e32 v6, v43, v7
	v_mul_f32_e32 v6, 0x3fb8aa3b, v6
	v_exp_f32_e32 v6, v6
	s_nop 0
	v_mul_f32_e32 v4, v4, v6
	s_nop 0
	v_cvt_pk_bf16_f32 v4, v4, v4
	ds_write_b16_d16_hi v79, v4 offset:23296
.LBB0_680:
	s_or_b64 exec, exec, s[30:31]
	v_mul_f32_e32 v6, 0x3fb8aa3b, v42
	v_exp_f32_e32 v6, v6
	v_lshlrev_b32_e32 v4, 16, v116
	v_mul_f32_e32 v4, 0x3e000000, v4
	v_cndmask_b32_e64 v4, 0, v4, s[16:17]
	v_mul_f32_e32 v6, v4, v6
	s_nop 0
	v_cvt_pk_bf16_f32 v6, v6, v6
	v_add_u32_e32 v38, v70, v80
	ds_write_b16_d16_hi v38, v6 offset:2048
	v_sub_f32_e32 v6, v42, v2
	v_mul_f32_e32 v6, 0x3fb8aa3b, v6
	v_exp_f32_e32 v6, v6
	s_nop 0
	v_mul_f32_e32 v6, v4, v6
	s_nop 0
	v_cvt_pk_bf16_f32 v6, v6, v6
	ds_write_b16_d16_hi v81, v6 offset:10240
	v_sub_f32_e32 v6, v2, v42
	v_mul_f32_e32 v6, 0x3fb8aa3b, v6
	v_exp_f32_e32 v6, v6
	s_nop 0
	v_mul_f32_e32 v6, v59, v6
	s_nop 0
	v_cvt_pk_bf16_f32 v6, v6, v6
	ds_write_b16_d16_hi v81, v6 offset:18944
	s_and_saveexec_b64 s[30:31], s[6:7]
	s_xor_b64 s[30:31], exec, s[30:31]
	s_cbranch_execz .LBB0_682
	v_sub_f32_e32 v4, v7, v42
	v_mul_f32_e32 v4, 0x3fb8aa3b, v4
	v_exp_f32_e32 v4, v4
	s_nop 0
	v_mul_f32_e32 v4, v59, v4
	v_bfe_u32 v6, v4, 16, 1
	v_add3_u32 v4, v4, v6, s48
	ds_write_b16_d16_hi v81, v4 offset:32000
.LBB0_682:
	s_andn2_saveexec_b64 s[30:31], s[30:31]
	s_cbranch_execz .LBB0_684
	v_sub_f32_e32 v6, v42, v7
	v_mul_f32_e32 v6, 0x3fb8aa3b, v6
	v_exp_f32_e32 v6, v6
	s_nop 0
	v_mul_f32_e32 v4, v4, v6
	s_nop 0
	v_cvt_pk_bf16_f32 v4, v4, v4
	ds_write_b16_d16_hi v82, v4 offset:23296
.LBB0_684:
	s_or_b64 exec, exec, s[30:31]
	v_mul_f32_e32 v6, 0x3fb8aa3b, v41
	v_exp_f32_e32 v6, v6
	v_lshlrev_b32_e32 v4, 16, v119
	v_mul_f32_e32 v4, 0x3e000000, v4
	v_cndmask_b32_e64 v4, 0, v4, s[22:23]
	v_mul_f32_e32 v6, v4, v6
	s_nop 0
	v_cvt_pk_bf16_f32 v6, v6, v6
	v_add_u32_e32 v38, v70, v83
	ds_write_b16_d16_hi v38, v6 offset:2048
	v_sub_f32_e32 v6, v41, v2
	v_mul_f32_e32 v6, 0x3fb8aa3b, v6
	v_exp_f32_e32 v6, v6
	s_nop 0
	v_mul_f32_e32 v6, v4, v6
	s_nop 0
	v_cvt_pk_bf16_f32 v6, v6, v6
	ds_write_b16_d16_hi v84, v6 offset:10240
	v_sub_f32_e32 v6, v2, v41
	v_mul_f32_e32 v6, 0x3fb8aa3b, v6
	v_exp_f32_e32 v6, v6
	s_nop 0
	v_mul_f32_e32 v6, v60, v6
	s_nop 0
	v_cvt_pk_bf16_f32 v6, v6, v6
	ds_write_b16_d16_hi v84, v6 offset:18944
	s_and_saveexec_b64 s[30:31], s[6:7]
	s_xor_b64 s[30:31], exec, s[30:31]
	s_cbranch_execz .LBB0_686
	v_sub_f32_e32 v4, v7, v41
	v_mul_f32_e32 v4, 0x3fb8aa3b, v4
	v_exp_f32_e32 v4, v4
	s_nop 0
	v_mul_f32_e32 v4, v60, v4
	v_bfe_u32 v6, v4, 16, 1
	v_add3_u32 v4, v4, v6, s48
	ds_write_b16_d16_hi v84, v4 offset:32000
.LBB0_686:
	s_andn2_saveexec_b64 s[30:31], s[30:31]
	s_cbranch_execz .LBB0_688
	v_sub_f32_e32 v6, v41, v7
	v_mul_f32_e32 v6, 0x3fb8aa3b, v6
	v_exp_f32_e32 v6, v6
	s_nop 0
	v_mul_f32_e32 v4, v4, v6
	s_nop 0
	v_cvt_pk_bf16_f32 v4, v4, v4
	ds_write_b16_d16_hi v85, v4 offset:23296
.LBB0_688:
	s_or_b64 exec, exec, s[30:31]
	v_mul_f32_e32 v6, 0x3fb8aa3b, v40
	v_exp_f32_e32 v6, v6
	v_lshlrev_b32_e32 v4, 16, v121
	v_mul_f32_e32 v4, 0x3e000000, v4
	v_cndmask_b32_e64 v4, 0, v4, s[26:27]
	v_mul_f32_e32 v6, v4, v6
	s_nop 0
	v_cvt_pk_bf16_f32 v6, v6, v6
	v_add_u32_e32 v38, v70, v86
	ds_write_b16_d16_hi v38, v6 offset:2048
	v_sub_f32_e32 v6, v40, v2
	v_mul_f32_e32 v6, 0x3fb8aa3b, v6
	v_exp_f32_e32 v6, v6
	s_nop 0
	v_mul_f32_e32 v6, v4, v6
	s_nop 0
	v_cvt_pk_bf16_f32 v6, v6, v6
	ds_write_b16_d16_hi v87, v6 offset:10240
	v_sub_f32_e32 v6, v2, v40
	v_mul_f32_e32 v6, 0x3fb8aa3b, v6
	v_exp_f32_e32 v6, v6
	s_nop 0
	v_mul_f32_e32 v6, v0, v6
	s_nop 0
	v_cvt_pk_bf16_f32 v6, v6, v6
	ds_write_b16_d16_hi v87, v6 offset:18944
	s_and_saveexec_b64 s[30:31], s[6:7]
	s_xor_b64 s[30:31], exec, s[30:31]
	s_cbranch_execz .LBB0_690
	v_sub_f32_e32 v4, v7, v40
	v_mul_f32_e32 v4, 0x3fb8aa3b, v4
	v_exp_f32_e32 v4, v4
	s_nop 0
	v_mul_f32_e32 v0, v0, v4
	s_nop 0
	v_cvt_pk_bf16_f32 v0, v0, v0
	ds_write_b16_d16_hi v87, v0 offset:32000
.LBB0_690:
	s_andn2_saveexec_b64 s[30:31], s[30:31]
	s_cbranch_execz .LBB0_692
	v_sub_f32_e32 v0, v40, v7
	v_mul_f32_e32 v0, 0x3fb8aa3b, v0
	v_exp_f32_e32 v0, v0
	s_nop 0
	v_mul_f32_e32 v0, v4, v0
	s_nop 0
	v_cvt_pk_bf16_f32 v0, v0, v0
	ds_write_b16_d16_hi v88, v0 offset:23296
.LBB0_692:
	s_or_b64 exec, exec, s[30:31]
	v_mul_f32_e32 v4, 0x3fb8aa3b, v5
	v_exp_f32_e32 v4, v4
	v_lshlrev_b32_e32 v0, 16, v122
	v_mul_f32_e32 v0, 0x3e000000, v0
	v_cndmask_b32_e64 v0, 0, v0, s[20:21]
	v_mul_f32_e32 v4, v0, v4
	s_nop 0
	v_cvt_pk_bf16_f32 v4, v4, v4
	v_add_u32_e32 v6, v70, v89
	ds_write_b16_d16_hi v6, v4 offset:2048
	v_sub_f32_e32 v4, v5, v2
	v_mul_f32_e32 v4, 0x3fb8aa3b, v4
	v_exp_f32_e32 v4, v4
	s_nop 0
	v_mul_f32_e32 v4, v0, v4
	s_nop 0
	v_cvt_pk_bf16_f32 v4, v4, v4
	ds_write_b16_d16_hi v90, v4 offset:10240
	v_sub_f32_e32 v4, v2, v5
	v_mul_f32_e32 v4, 0x3fb8aa3b, v4
	v_exp_f32_e32 v4, v4
	s_nop 0
	v_mul_f32_e32 v4, v61, v4
	s_nop 0
	v_cvt_pk_bf16_f32 v4, v4, v4
	ds_write_b16_d16_hi v90, v4 offset:18944
	s_and_saveexec_b64 s[30:31], s[6:7]
	s_xor_b64 s[30:31], exec, s[30:31]
	s_cbranch_execz .LBB0_694
	v_sub_f32_e32 v0, v7, v5
	v_mul_f32_e32 v0, 0x3fb8aa3b, v0
	v_exp_f32_e32 v0, v0
	s_nop 0
	v_mul_f32_e32 v0, v61, v0
	v_bfe_u32 v4, v0, 16, 1
	v_add3_u32 v0, v0, v4, s48
	ds_write_b16_d16_hi v90, v0 offset:32000
.LBB0_694:
	s_andn2_saveexec_b64 s[30:31], s[30:31]
	s_cbranch_execz .LBB0_696
	v_sub_f32_e32 v4, v5, v7
	v_mul_f32_e32 v4, 0x3fb8aa3b, v4
	v_exp_f32_e32 v4, v4
	s_nop 0
	v_mul_f32_e32 v0, v0, v4
	s_nop 0
	v_cvt_pk_bf16_f32 v0, v0, v0
	ds_write_b16_d16_hi v91, v0 offset:23296
.LBB0_696:
	s_or_b64 exec, exec, s[30:31]
	v_mul_f32_e32 v4, 0x3fb8aa3b, v3
	v_exp_f32_e32 v4, v4
	v_lshlrev_b32_e32 v0, 16, v96
	v_mul_f32_e32 v0, 0x3e000000, v0
	v_cndmask_b32_e64 v0, 0, v0, s[24:25]
	v_mul_f32_e32 v4, v0, v4
	s_nop 0
	v_cvt_pk_bf16_f32 v4, v4, v4
	v_add_u32_e32 v5, v70, v92
	ds_write_b16_d16_hi v5, v4 offset:2048
	v_sub_f32_e32 v4, v3, v2
	v_mul_f32_e32 v4, 0x3fb8aa3b, v4
	v_exp_f32_e32 v4, v4
	v_sub_f32_e32 v2, v2, v3
	v_mul_f32_e32 v2, 0x3fb8aa3b, v2
	v_exp_f32_e32 v2, v2
	v_mul_f32_e32 v4, v0, v4
	s_nop 0
	v_cvt_pk_bf16_f32 v4, v4, v4
	v_mul_f32_e32 v2, v1, v2
	ds_write_b16_d16_hi v93, v4 offset:10240
	s_nop 0
	v_cvt_pk_bf16_f32 v2, v2, v2
	ds_write_b16_d16_hi v93, v2 offset:18944
	s_and_saveexec_b64 s[30:31], s[6:7]
	s_xor_b64 s[30:31], exec, s[30:31]
	s_cbranch_execz .LBB0_698
	v_sub_f32_e32 v0, v7, v3
	v_mul_f32_e32 v0, 0x3fb8aa3b, v0
	v_exp_f32_e32 v0, v0
	s_nop 0
	v_mul_f32_e32 v0, v1, v0
	v_bfe_u32 v1, v0, 16, 1
	v_add3_u32 v0, v0, v1, s48
	ds_write_b16_d16_hi v93, v0 offset:32000
.LBB0_698:
	s_andn2_saveexec_b64 s[30:31], s[30:31]
	s_cbranch_execz .LBB0_700
	v_sub_f32_e32 v1, v3, v7
	v_mul_f32_e32 v1, 0x3fb8aa3b, v1
	v_exp_f32_e32 v1, v1
	s_nop 0
	v_mul_f32_e32 v0, v0, v1
	s_nop 0
	v_cvt_pk_bf16_f32 v0, v0, v0
	ds_write_b16_d16_hi v94, v0 offset:23296

.LBB0_732:
	s_or_b64 exec, exec, s[12:13]
	s_or_b32 s12, s30, s49
	s_mul_hi_u32 s13, s12, 0x41
	s_add_i32 s13, s13, s31
	s_mulk_i32 s12, 0x41
	s_add_u32 s12, s12, s33
	s_addc_u32 s13, s13, s38
	s_or_b32 s14, s93, s28
	s_waitcnt vmcnt(0)
	v_or_b32_e32 v41, v5, v4
	s_lshl_b64 s[12:13], s[12:13], 13
	v_add_u32_e32 v6, s14, v69
	v_mov_b64_e32 v[4:5], s[82:83]
	v_or_b32_e32 v39, v1, v0
	v_lshl_add_u64 v[0:1], v[16:17], 0, s[12:13]
	v_mad_i64_i32 v[4:5], s[12:13], v6, s79, v[4:5]
	v_mad_u64_u32 v[6:7], s[12:13], v4, s44, v[20:21]
	s_add_i32 s12, s14, s76
	s_mul_hi_i32 s13, s12, 0x41
	s_mulk_i32 s12, 0x41
	s_add_u32 s12, s12, s82
	v_or_b32_e32 v38, v49, v48
	v_or_b32_e32 v40, v3, v2
	s_addc_u32 s13, s13, s83
	global_store_dwordx4 v[0:1], v[38:41], off
	v_add_u32_e32 v0, v98, v18
	s_mulk_i32 s13, 0x3000
	s_mul_hi_u32 s14, s12, 0x3000
	s_waitcnt lgkmcnt(0)
	s_barrier
	ds_read_b128 v[0:3], v0 offset:2048
	s_add_i32 s14, s14, s13
	s_mulk_i32 s12, 0x3000
	s_add_u32 s12, s54, s12
	s_addc_u32 s13, s55, s14
	s_add_u32 s12, s12, 0x2e894000
	v_mad_i32_i24 v7, v5, s44, v7
	s_addc_u32 s13, s13, 0
	s_andn2_b64 vcc, exec, s[58:59]
	s_mov_b64 s[14:15], -1
	s_waitcnt lgkmcnt(0)
	global_store_dwordx4 v[6:7], v[0:3], off
	s_cbranch_vccnz .LBB0_734
	ds_read_b128 v[0:3], v99
	ds_read_b128 v[4:7], v101
	s_mov_b64 s[14:15], 0
	s_waitcnt lgkmcnt(0)
	v_mfma_f32_16x16x32_bf16 v[0:3], v[0:3], v[4:7], 0
	ds_read_b128 v[4:7], v99 offset:64
	ds_read_b128 v[38:41], v101 offset:64
	s_waitcnt lgkmcnt(0)
	v_mfma_f32_16x16x32_bf16 v[0:3], v[4:7], v[38:41], v[0:3]
	v_lshl_add_u64 v[4:5], s[12:13], 0, v[22:23]
	s_nop 6
	v_cndmask_b32_e64 v0, v0, 0, s[60:61]
	s_nop 0
	v_cvt_pk_bf16_f32 v0, v0, v0
	v_lshl_add_u64 v[6:7], v[4:5], 0, v[24:25]
	global_store_short_d16_hi v[6:7], v0, off
	v_cndmask_b32_e64 v0, v1, 0, s[62:63]
	v_bfe_u32 v1, v0, 16, 1
	v_add3_u32 v6, v0, v1, s48
	v_lshl_add_u64 v[0:1], v[4:5], 0, v[26:27]
	global_store_short_d16_hi v[0:1], v6, off
	v_cndmask_b32_e64 v0, v2, 0, s[88:89]
	s_nop 0
	v_cvt_pk_bf16_f32 v2, v0, v0
	v_lshl_add_u64 v[0:1], v[4:5], 0, v[28:29]
	global_store_short_d16_hi v[0:1], v2, off
	v_cndmask_b32_e64 v0, v3, 0, s[66:67]
	v_bfe_u32 v1, v0, 16, 1
	v_add3_u32 v2, v0, v1, s48
	v_lshl_add_u64 v[0:1], v[4:5], 0, v[30:31]
	global_store_short_d16_hi v[0:1], v2, off

.LBB0_739:
	s_and_b64 vcc, exec, s[12:13]
	s_cbranch_vccz .LBB0_664
	s_movk_i32 s29, 0x810
	v_or_b32_e32 v38, 1, v103
	s_ashr_i32 s33, s92, 2
	v_cmp_gt_i32_e64 s[12:13], s29, v103
	v_cmp_gt_i32_e64 s[16:17], s29, v38
	s_mul_i32 s83, s33, 0x810
	v_cndmask_b32_e64 v0, 0, v103, s[12:13]
	v_cndmask_b32_e64 v38, 0, v38, s[16:17]
	v_add_u32_e32 v0, s83, v0
	v_mov_b64_e32 v[2:3], s[34:35]
	v_add_u32_e32 v47, s83, v38
	v_or_b32_e32 v46, 2, v103
	v_mad_i64_i32 v[4:5], s[14:15], v0, s44, v[2:3]
	v_mad_i64_i32 v[38:39], s[14:15], v47, s44, v[2:3]
	s_and_b32 s28, s92, 3
	v_cmp_gt_i32_e64 s[14:15], s29, v46
	s_lshl_b32 s86, s28, 7
	v_add_lshl_u32 v0, s86, v64, 1
	v_cndmask_b32_e64 v42, 0, v46, s[14:15]
	v_mov_b32_e32 v1, v97
	v_add_u32_e32 v42, s83, v42
	v_lshl_add_u64 v[6:7], v[4:5], 0, v[0:1]
	v_mad_i64_i32 v[42:43], s[18:19], v42, s44, v[2:3]
	v_lshl_add_u64 v[40:41], v[38:39], 0, v[0:1]
	v_lshl_add_u64 v[44:45], v[42:43], 0, v[0:1]
	global_load_ushort v54, v[6:7], off
	global_load_ushort v55, v[40:41], off
	global_load_ushort v56, v[44:45], off
	s_lshl_b32 s38, s28, 9
	v_lshl_add_u64 v[6:7], v[34:35], 0, s[38:39]
	global_load_dword v58, v[6:7], off
	v_or_b32_e32 v40, 3, v103
	v_or_b32_e32 v48, 4, v103
	v_cmp_gt_i32_e64 s[20:21], s29, v40
	s_lshl_b32 s22, s28, 1
	s_lshl_b32 s87, s33, 3
	v_cndmask_b32_e64 v40, 0, v40, s[20:21]
	v_cmp_gt_i32_e64 s[18:19], s29, v48
	s_or_b32 s38, s22, s87
	v_add_u32_e32 v49, s83, v40
	v_cndmask_b32_e64 v41, 0, v48, s[18:19]
	v_add_lshl_u32 v96, s86, v63, 1
	v_add_u32_e32 v44, s83, v41
	v_or_b32_e32 v50, s38, v62
	v_mad_i64_i32 v[40:41], s[22:23], v49, s44, v[2:3]
	v_mad_i64_i32 v[44:45], s[22:23], v44, s44, v[2:3]
	v_lshl_add_u32 v57, v50, 6, v50
	v_lshl_add_u64 v[4:5], v[4:5], 0, v[96:97]
	v_lshl_add_u64 v[50:51], v[40:41], 0, v[96:97]
	v_lshl_add_u64 v[38:39], v[38:39], 0, v[96:97]
	v_lshl_add_u64 v[42:43], v[42:43], 0, v[96:97]
	v_lshl_add_u64 v[40:41], v[40:41], 0, v[0:1]
	v_lshl_add_u64 v[52:53], v[44:45], 0, v[0:1]
	v_add_u32_e32 v59, s82, v57
	global_load_ushort v57, v[50:51], off
	global_load_ushort v60, v[42:43], off
	global_load_ushort v104, v[38:39], off
	global_load_ushort v105, v[4:5], off
	global_load_ushort v61, v[40:41], off
	global_load_ushort v107, v[52:53], off
	v_mov_b64_e32 v[6:7], s[56:57]
	v_mad_i64_i32 v[40:41], s[22:23], v59, s44, v[6:7]
	s_mov_b32 s49, 0x3f317217
	v_mov_b32_e32 v115, 0x41b17218
	v_or_b32_e32 v50, 6, v103
	s_waitcnt vmcnt(0)
	v_lshlrev_b32_e32 v4, 16, v54
	v_mul_f32_e32 v4, 0x3fb8aa3b, v4
	v_exp_f32_e32 v4, v4
	v_lshlrev_b32_e32 v5, 16, v55
	v_mul_f32_e32 v5, 0x3fb8aa3b, v5
	v_exp_f32_e32 v5, v5
	v_add_f32_e32 v4, 1.0, v4
	v_rcp_f32_e32 v4, v4
	v_lshlrev_b32_e32 v6, 16, v56
	v_sub_f32_e32 v56, 1.0, v58
	v_add_f32_e32 v5, 1.0, v5
	v_mul_f32_e32 v4, v56, v4
	v_rcp_f32_e32 v5, v5
	v_min_f32_e32 v59, 0x3f7ff972, v4
	v_sub_f32_e32 v4, 1.0, v59
	v_cmp_gt_f32_e32 vcc, s45, v4
	v_mul_f32_e32 v5, v56, v5
	v_min_f32_e32 v108, 0x3f7ff972, v5
	v_cndmask_b32_e64 v7, 0, 32, vcc
	v_ldexp_f32 v4, v4, v7
	v_log_f32_e32 v4, v4
	v_mul_f32_e32 v6, 0x3fb8aa3b, v6
	v_sub_f32_e32 v5, 1.0, v108
	v_exp_f32_e32 v6, v6
	v_cmp_gt_f32_e64 s[22:23], s45, v5
	v_cndmask_b32_e32 v7, 0, v115, vcc
	v_cmp_lt_f32_e64 vcc, |v4|, s95
	v_cndmask_b32_e64 v38, 0, 32, s[22:23]
	v_ldexp_f32 v5, v5, v38
	v_mul_f32_e32 v38, 0x3f317217, v4
	v_fma_f32 v38, v4, s49, -v38
	v_add_f32_e32 v6, 1.0, v6
	v_log_f32_e32 v5, v5
	v_fmac_f32_e32 v38, 0x3377d1cf, v4
	v_rcp_f32_e32 v6, v6
	v_fmac_f32_e32 v38, 0x3f317217, v4
	v_cndmask_b32_e32 v4, v4, v38, vcc
	v_sub_f32_e32 v4, v4, v7
	v_mul_f32_e32 v39, 0x3f317217, v5
	v_add_f32_e32 v4, 0, v4
	v_fma_f32 v39, v5, s49, -v39
	v_cndmask_b32_e64 v109, 0, v4, s[12:13]
	v_mul_f32_e32 v4, v56, v6
	v_fmac_f32_e32 v39, 0x3377d1cf, v5
	v_min_f32_e32 v110, 0x3f7ff972, v4
	v_fmac_f32_e32 v39, 0x3f317217, v5
	v_cmp_lt_f32_e64 vcc, |v5|, s95
	v_sub_f32_e32 v4, 1.0, v110
	s_nop 0
	v_cndmask_b32_e32 v38, v5, v39, vcc
	v_cmp_gt_f32_e32 vcc, s45, v4
	v_cndmask_b32_e64 v39, 0, v115, s[22:23]
	s_nop 0
	v_cndmask_b32_e64 v5, 0, 32, vcc
	v_ldexp_f32 v42, v4, v5
	v_or_b32_e32 v4, 5, v103
	v_cmp_gt_i32_e64 s[22:23], s29, v4
	v_log_f32_e32 v112, v42
	s_nop 0
	v_cndmask_b32_e64 v4, 0, v4, s[22:23]
	v_add_u32_e32 v51, s83, v4
	v_mad_i64_i32 v[4:5], s[24:25], v51, s44, v[2:3]
	v_lshl_add_u64 v[6:7], v[4:5], 0, v[0:1]
	global_load_ushort v111, v[6:7], off
	v_cmp_gt_i32_e64 s[24:25], s29, v50
	v_sub_f32_e32 v6, v38, v39
	v_cndmask_b32_e64 v6, 0, v6, s[16:17]
	v_cndmask_b32_e64 v38, 0, v50, s[24:25]
	v_add_u32_e32 v38, s83, v38
	v_mad_i64_i32 v[38:39], s[26:27], v38, s44, v[2:3]
	v_add_f32_e32 v113, v109, v6
	v_mul_f32_e32 v6, 0x3f317217, v112
	v_lshl_add_u64 v[42:43], v[38:39], 0, v[0:1]
	v_fma_f32 v114, v112, s49, -v6
	v_lshl_add_u64 v[6:7], v[44:45], 0, v[96:97]
	global_load_ushort v45, v[42:43], off
	v_or_b32_e32 v44, 7, v103
	v_cmp_gt_i32_e64 s[26:27], s29, v44
	v_lshl_add_u64 v[4:5], v[4:5], 0, v[96:97]
	v_lshl_add_u64 v[38:39], v[38:39], 0, v[96:97]
	v_cndmask_b32_e64 v42, 0, v44, s[26:27]
	v_add_u32_e32 v52, s83, v42
	v_mad_i64_i32 v[2:3], s[30:31], v52, s44, v[2:3]
	v_lshl_add_u64 v[42:43], v[2:3], 0, v[96:97]
	v_lshl_add_u64 v[0:1], v[2:3], 0, v[0:1]
	global_load_ushort v53, v[42:43], off
	global_load_ushort v54, v[38:39], off
	global_load_ushort v55, v[4:5], off
	global_load_ushort v58, v[6:7], off
	v_lshlrev_b32_e32 v4, 16, v61
	global_load_ushort v0, v[0:1], off
	v_mul_f32_e32 v4, 0x3fb8aa3b, v4
	v_exp_f32_e32 v4, v4
	v_cndmask_b32_e32 v6, 0, v115, vcc
	v_fmac_f32_e32 v114, 0x3377d1cf, v112
	v_fmac_f32_e32 v114, 0x3f317217, v112
	v_add_f32_e32 v4, 1.0, v4
	v_rcp_f32_e32 v4, v4
	v_cmp_lt_f32_e64 s[30:31], |v112|, s95
	v_cndmask_b32_e64 v38, 0, v59, s[12:13]
	v_mul_f32_e32 v2, v56, v4
	v_min_f32_e32 v2, 0x3f7ff972, v2
	v_sub_f32_e32 v3, 1.0, v2
	v_cmp_gt_f32_e32 vcc, s45, v3
	v_cndmask_b32_e64 v5, v112, v114, s[30:31]
	v_sub_f32_e32 v1, v5, v6
	v_cndmask_b32_e64 v4, 0, 32, vcc
	v_ldexp_f32 v3, v3, v4
	v_log_f32_e32 v3, v3
	v_lshlrev_b32_e32 v4, 16, v107
	v_cndmask_b32_e64 v1, 0, v1, s[14:15]
	v_mul_f32_e32 v4, 0x3fb8aa3b, v4
	v_add_f32_e32 v59, v113, v1
	v_mul_f32_e32 v1, 0x3f317217, v3
	v_exp_f32_e32 v4, v4
	v_fma_f32 v1, v3, s49, -v1
	v_fmac_f32_e32 v1, 0x3377d1cf, v3
	v_fmac_f32_e32 v1, 0x3f317217, v3
	v_cmp_lt_f32_e64 s[30:31], |v3|, s95
	v_cndmask_b32_e64 v7, 0, v2, s[20:21]
	s_barrier
	v_cndmask_b32_e64 v1, v3, v1, s[30:31]
	v_add_f32_e32 v3, 1.0, v4
	v_rcp_f32_e32 v3, v3
	v_cndmask_b32_e32 v4, 0, v115, vcc
	v_sub_f32_e32 v1, v1, v4
	v_cndmask_b32_e64 v1, 0, v1, s[20:21]
	v_mul_f32_e32 v3, v56, v3
	v_min_f32_e32 v4, 0x3f7ff972, v3
	v_sub_f32_e32 v3, 1.0, v4
	v_cmp_gt_f32_e32 vcc, s45, v3
	v_add_f32_e32 v61, v59, v1
	s_nop 0
	v_cndmask_b32_e64 v5, 0, 32, vcc
	v_ldexp_f32 v3, v3, v5
	v_log_f32_e32 v3, v3
	v_cndmask_b32_e64 v39, 0, v110, s[14:15]
	v_cndmask_b32_e64 v6, 0, v108, s[16:17]
	v_cndmask_b32_e64 v4, 0, v4, s[18:19]
	v_mul_f32_e32 v1, 0x3f317217, v3
	v_fma_f32 v1, v3, s49, -v1
	v_fmac_f32_e32 v1, 0x3377d1cf, v3
	v_fmac_f32_e32 v1, 0x3f317217, v3
	s_waitcnt vmcnt(6)
	v_lshlrev_b32_e32 v2, 16, v111
	v_mul_f32_e32 v2, 0x3fb8aa3b, v2
	v_exp_f32_e32 v2, v2
	v_cmp_lt_f32_e64 s[30:31], |v3|, s95
	v_add_f32_e32 v2, 1.0, v2
	v_rcp_f32_e32 v2, v2
	v_cndmask_b32_e64 v1, v3, v1, s[30:31]
	v_cndmask_b32_e32 v3, 0, v115, vcc
	v_sub_f32_e32 v1, v1, v3
	v_mul_f32_e32 v2, v56, v2
	v_min_f32_e32 v42, 0x3f7ff972, v2
	v_sub_f32_e32 v2, 1.0, v42
	v_cmp_gt_f32_e32 vcc, s45, v2
	v_cndmask_b32_e64 v1, 0, v1, s[18:19]
	s_waitcnt vmcnt(0)
	v_lshlrev_b32_e32 v0, 16, v0
	v_cndmask_b32_e64 v3, 0, 32, vcc
	v_ldexp_f32 v2, v2, v3
	v_lshlrev_b32_e32 v3, 16, v45
	v_mul_f32_e32 v3, 0x3fb8aa3b, v3
	v_exp_f32_e32 v3, v3
	v_log_f32_e32 v2, v2
	v_mul_f32_e32 v0, 0x3fb8aa3b, v0
	v_exp_f32_e32 v0, v0
	v_add_f32_e32 v3, 1.0, v3
	v_rcp_f32_e32 v3, v3
	v_mul_f32_e32 v5, 0x3f317217, v2
	v_fma_f32 v5, v2, s49, -v5
	v_fmac_f32_e32 v5, 0x3377d1cf, v2
	v_mul_f32_e32 v3, v56, v3
	v_fmac_f32_e32 v5, 0x3f317217, v2
	v_cmp_lt_f32_e64 s[30:31], |v2|, s95
	v_min_f32_e32 v3, 0x3f7ff972, v3
	v_add_f32_e32 v0, 1.0, v0
	v_cndmask_b32_e64 v2, v2, v5, s[30:31]
	v_sub_f32_e32 v5, 1.0, v3
	v_cmp_gt_f32_e64 s[30:31], s45, v5
	v_rcp_f32_e32 v0, v0
	s_nop 0
	v_cndmask_b32_e64 v43, 0, 32, s[30:31]
	v_ldexp_f32 v5, v5, v43
	v_log_f32_e32 v5, v5
	v_cndmask_b32_e32 v43, 0, v115, vcc
	v_sub_f32_e32 v2, v2, v43
	v_mul_f32_e32 v0, v56, v0
	v_mul_f32_e32 v43, 0x3f317217, v5
	v_fma_f32 v43, v5, s49, -v43
	v_fmac_f32_e32 v43, 0x3377d1cf, v5
	v_min_f32_e32 v0, 0x3f7ff972, v0
	v_fmac_f32_e32 v43, 0x3f317217, v5
	v_cmp_lt_f32_e64 vcc, |v5|, s95
	v_sub_f32_e32 v44, 1.0, v0
	v_cndmask_b32_e64 v2, 0, v2, s[22:23]
	v_cndmask_b32_e32 v5, v5, v43, vcc
	v_cmp_gt_f32_e32 vcc, s45, v44
	v_cndmask_b32_e64 v43, 0, v115, s[30:31]
	v_sub_f32_e32 v5, v5, v43
	v_cndmask_b32_e64 v45, 0, 32, vcc
	v_ldexp_f32 v44, v44, v45
	v_log_f32_e32 v44, v44
	v_cndmask_b32_e64 v43, 0, v5, s[24:25]
	v_cndmask_b32_e64 v5, 0, v3, s[24:25]
	v_add_f32_e32 v56, v61, v1
	v_mul_f32_e32 v3, 0x3f317217, v44
	v_fma_f32 v3, v44, s49, -v3
	v_fmac_f32_e32 v3, 0x3377d1cf, v44
	v_fmac_f32_e32 v3, 0x3f317217, v44
	v_cmp_lt_f32_e64 s[30:31], |v44|, s95
	v_add_f32_e32 v116, v56, v2
	v_add_f32_e32 v117, v116, v43
	v_cndmask_b32_e64 v3, v44, v3, s[30:31]
	v_cndmask_b32_e32 v44, 0, v115, vcc
	v_sub_f32_e32 v3, v3, v44
	v_cndmask_b32_e64 v3, 0, v3, s[26:27]
	v_add_f32_e32 v43, v117, v3
	ds_write_b32 v67, v43
	s_waitcnt lgkmcnt(0)
	s_barrier
	ds_read2st64_b32 v[44:45], v68 offset1:2
	ds_read2st64_b32 v[2:3], v68 offset0:4 offset1:6
	v_cndmask_b32_e64 v1, 0, v0, s[26:27]
	v_cndmask_b32_e64 v0, 0, v42, s[22:23]
	s_waitcnt lgkmcnt(1)
	v_add_f32_e32 v45, v44, v45
	s_waitcnt lgkmcnt(0)
	v_add_f32_e32 v42, v45, v2
	v_cndmask_b32_e64 v2, v42, v45, s[4:5]
	v_cndmask_b32_e64 v2, v2, v44, s[2:3]
	v_cndmask_b32_e64 v111, v2, 0, s[0:1]
	v_mov_b32_e32 v110, v3
	v_add_f32_e32 v108, v109, v111
	v_pk_add_f32 v[2:3], v[42:43], v[110:111]
	v_add_f32_e32 v107, v113, v111
	v_sub_f32_e32 v43, v2, v108
	v_mul_f32_e32 v43, 0x3fb8aa3b, v43
	v_exp_f32_e32 v112, v43
	v_sub_f32_e32 v43, v2, v107
	v_mul_f32_e32 v43, 0x3fb8aa3b, v43
	v_add_f32_e32 v96, v59, v111
	v_exp_f32_e32 v114, v43
	v_sub_f32_e32 v43, v2, v96
	v_add_f32_e32 v61, v61, v111
	v_mul_f32_e32 v43, 0x3fb8aa3b, v43
	v_exp_f32_e32 v113, v43
	v_sub_f32_e32 v43, v2, v61
	v_mul_f32_e32 v43, 0x3fb8aa3b, v43
	v_add_f32_e32 v59, v56, v111
	v_exp_f32_e32 v115, v43
	v_sub_f32_e32 v43, v2, v59
	v_add_f32_e32 v56, v116, v111
	v_mul_f32_e32 v43, 0x3fb8aa3b, v43
	v_exp_f32_e32 v110, v43
	v_sub_f32_e32 v43, v2, v56
	v_mul_f32_e32 v43, 0x3fb8aa3b, v43
	v_exp_f32_e32 v116, v43
	v_add_f32_e32 v43, v117, v111
	v_sub_f32_e32 v109, v2, v43
	v_mul_f32_e32 v109, 0x3fb8aa3b, v109
	v_exp_f32_e32 v111, v109
	v_sub_f32_e32 v109, v2, v3
	v_mul_f32_e32 v109, 0x3fb8aa3b, v109
	v_exp_f32_e32 v117, v109
	v_pk_mul_f32 v[114:115], v[6:7], v[114:115]
	v_pk_mul_f32 v[112:113], v[38:39], v[112:113]
	v_pk_mul_f32 v[110:111], v[4:5], v[110:111]
	v_pk_mul_f32 v[116:117], v[0:1], v[116:117]
	s_nop 0
	s_nop 0
	s_nop 0
	s_nop 0
	v_cvt_pk_bf16_f32 v116, v116, v116
	v_cvt_pk_bf16_f32 v109, v117, v117
	v_cvt_pk_bf16_f32 v114, v114, v114
	v_cvt_pk_bf16_f32 v115, v115, v115
	s_nop 0
	s_nop 0
	s_nop 0
	s_nop 0
	v_cvt_pk_bf16_f32 v111, v111, v111
	v_cvt_pk_bf16_f32 v110, v110, v110
	v_cvt_pk_bf16_f32 v113, v113, v113
	v_cvt_pk_bf16_f32 v112, v112, v112
	v_lshrrev_b32_e32 v110, 16, v110
	v_lshrrev_b32_e32 v111, 16, v111
	v_lshrrev_b32_e32 v117, 16, v112
	v_lshrrev_b32_e32 v118, 16, v113
	v_and_or_b32 v113, v109, s36, v111
	v_and_or_b32 v112, v116, s36, v110
	v_and_or_b32 v111, v115, s36, v118
	v_and_or_b32 v110, v114, s36, v117
	v_lshl_add_u64 v[114:115], v[40:41], 0, v[14:15]
	v_add_co_u32_e32 v114, vcc, 0x1000, v114
	s_nop 1
	v_addc_co_u32_e32 v115, vcc, 0, v115, vcc
	global_store_dwordx4 v[114:115], v[110:113], off
	s_and_saveexec_b64 s[30:31], s[8:9]
	s_cbranch_execz .LBB0_742
	v_mul_f32_e32 v2, 0x3fb8aa3b, v2
	v_exp_f32_e32 v2, v2
	v_lshl_add_u64 v[40:41], v[40:41], 0, v[36:37]
	v_add_co_u32_e32 v40, vcc, 0x2000, v40
	s_nop 1
	v_addc_co_u32_e32 v41, vcc, 0, v41, vcc
	global_store_dword v[40:41], v2, off offset:2048
.LBB0_742:
	s_or_b64 exec, exec, s[30:31]
	v_lshlrev_b32_e32 v2, 16, v105
	v_mul_f32_e32 v40, 0xbfb8aa3b, v2
	v_exp_f32_e32 v40, v40
	v_mul_f32_e32 v41, 0x3fb8aa3b, v108
	v_exp_f32_e32 v41, v41
	v_add_f32_e32 v40, 1.0, v40
	v_rcp_f32_e32 v40, v40
	s_nop 0
	v_mul_f32_e32 v2, v40, v2
	v_cndmask_b32_e64 v40, 0, v2, s[12:13]
	v_mul_f32_e32 v41, v40, v41
	v_cndmask_b32_e64 v2, v42, v44, s[6:7]
	s_nop 0
	v_cvt_pk_bf16_f32 v41, v41, v41
	v_add_u32_e32 v42, v70, v71
	ds_write_b16_d16_hi v42, v41 offset:2048
	v_sub_f32_e32 v41, v108, v2
	v_mul_f32_e32 v41, 0x3fb8aa3b, v41
	v_exp_f32_e32 v41, v41
	s_nop 0
	v_mul_f32_e32 v41, v40, v41
	s_nop 0
	v_cvt_pk_bf16_f32 v41, v41, v41
	ds_write_b16_d16_hi v72, v41 offset:10240
	v_sub_f32_e32 v41, v2, v108
	v_mul_f32_e32 v41, 0x3fb8aa3b, v41
	v_exp_f32_e32 v41, v41
	s_nop 0
	v_mul_f32_e32 v41, v38, v41
	s_nop 0
	v_cvt_pk_bf16_f32 v41, v41, v41
	ds_write_b16_d16_hi v72, v41 offset:18944
	s_and_saveexec_b64 s[30:31], s[6:7]
	s_xor_b64 s[30:31], exec, s[30:31]
	s_cbranch_execz .LBB0_744
	v_sub_f32_e32 v40, v45, v108
	v_mul_f32_e32 v40, 0x3fb8aa3b, v40
	v_exp_f32_e32 v40, v40
	s_nop 0
	v_mul_f32_e32 v38, v38, v40
	s_nop 0
	v_cvt_pk_bf16_f32 v38, v38, v38
	ds_write_b16_d16_hi v72, v38 offset:32000
.LBB0_744:
	s_andn2_saveexec_b64 s[30:31], s[30:31]
	s_cbranch_execz .LBB0_746
	v_sub_f32_e32 v38, v108, v45
	v_mul_f32_e32 v38, 0x3fb8aa3b, v38
	v_exp_f32_e32 v38, v38
	s_nop 0
	v_mul_f32_e32 v38, v40, v38
	s_nop 0
	v_cvt_pk_bf16_f32 v38, v38, v38
	ds_write_b16_d16_hi v73, v38 offset:23296
.LBB0_746:
	s_or_b64 exec, exec, s[30:31]
	v_lshlrev_b32_e32 v38, 16, v104
	v_mul_f32_e32 v40, 0xbfb8aa3b, v38
	v_exp_f32_e32 v40, v40
	s_nop 0
	v_add_f32_e32 v40, 1.0, v40
	v_rcp_f32_e32 v40, v40
	s_nop 0
	v_mul_f32_e32 v38, v40, v38
	v_mul_f32_e32 v40, 0x3fb8aa3b, v107
	v_exp_f32_e32 v40, v40
	v_cndmask_b32_e64 v38, 0, v38, s[16:17]
	v_mul_f32_e32 v40, v38, v40
	s_nop 0
	v_cvt_pk_bf16_f32 v40, v40, v40
	v_add_u32_e32 v41, v70, v74
	ds_write_b16_d16_hi v41, v40 offset:2048
	v_sub_f32_e32 v40, v107, v2
	v_mul_f32_e32 v40, 0x3fb8aa3b, v40
	v_exp_f32_e32 v40, v40
	s_nop 0
	v_mul_f32_e32 v40, v38, v40
	s_nop 0
	v_cvt_pk_bf16_f32 v40, v40, v40
	ds_write_b16_d16_hi v75, v40 offset:10240
	v_sub_f32_e32 v40, v2, v107
	v_mul_f32_e32 v40, 0x3fb8aa3b, v40
	v_exp_f32_e32 v40, v40
	s_nop 0
	v_mul_f32_e32 v40, v6, v40
	s_nop 0
	v_cvt_pk_bf16_f32 v40, v40, v40
	ds_write_b16_d16_hi v75, v40 offset:18944
	s_and_saveexec_b64 s[30:31], s[6:7]
	s_xor_b64 s[30:31], exec, s[30:31]
	s_cbranch_execz .LBB0_748
	v_sub_f32_e32 v38, v45, v107
	v_mul_f32_e32 v38, 0x3fb8aa3b, v38
	v_exp_f32_e32 v38, v38
	s_nop 0
	v_mul_f32_e32 v6, v6, v38
	s_nop 0
	v_cvt_pk_bf16_f32 v6, v6, v6
	ds_write_b16_d16_hi v75, v6 offset:32000
.LBB0_748:
	s_andn2_saveexec_b64 s[30:31], s[30:31]
	s_cbranch_execz .LBB0_750
	v_sub_f32_e32 v6, v107, v45
	v_mul_f32_e32 v6, 0x3fb8aa3b, v6
	v_exp_f32_e32 v6, v6
	s_nop 0
	v_mul_f32_e32 v6, v38, v6
	s_nop 0
	v_cvt_pk_bf16_f32 v6, v6, v6
	ds_write_b16_d16_hi v76, v6 offset:23296
.LBB0_750:
	s_or_b64 exec, exec, s[30:31]
	v_lshlrev_b32_e32 v6, 16, v60
	v_mul_f32_e32 v38, 0xbfb8aa3b, v6
	v_exp_f32_e32 v38, v38
	s_nop 0
	v_add_f32_e32 v38, 1.0, v38
	v_rcp_f32_e32 v38, v38
	s_nop 0
	v_mul_f32_e32 v6, v38, v6
	v_mul_f32_e32 v38, 0x3fb8aa3b, v96
	v_exp_f32_e32 v38, v38
	v_cndmask_b32_e64 v6, 0, v6, s[14:15]
	v_mul_f32_e32 v38, v6, v38
	s_nop 0
	v_cvt_pk_bf16_f32 v38, v38, v38
	v_add_u32_e32 v40, v70, v77
	ds_write_b16_d16_hi v40, v38 offset:2048
	v_sub_f32_e32 v38, v96, v2
	v_mul_f32_e32 v38, 0x3fb8aa3b, v38
	v_exp_f32_e32 v38, v38
	s_nop 0
	v_mul_f32_e32 v38, v6, v38
	s_nop 0
	v_cvt_pk_bf16_f32 v38, v38, v38
	ds_write_b16_d16_hi v78, v38 offset:10240
	v_sub_f32_e32 v38, v2, v96
	v_mul_f32_e32 v38, 0x3fb8aa3b, v38
	v_exp_f32_e32 v38, v38
	s_nop 0
	v_mul_f32_e32 v38, v39, v38
	s_nop 0
	v_cvt_pk_bf16_f32 v38, v38, v38
	ds_write_b16_d16_hi v78, v38 offset:18944
	s_and_saveexec_b64 s[30:31], s[6:7]
	s_xor_b64 s[30:31], exec, s[30:31]
	s_cbranch_execz .LBB0_752
	v_sub_f32_e32 v6, v45, v96
	v_mul_f32_e32 v6, 0x3fb8aa3b, v6
	v_exp_f32_e32 v6, v6
	s_nop 0
	v_mul_f32_e32 v6, v39, v6
	v_bfe_u32 v38, v6, 16, 1
	v_add3_u32 v6, v6, v38, s48
	ds_write_b16_d16_hi v78, v6 offset:32000
.LBB0_752:
	s_andn2_saveexec_b64 s[30:31], s[30:31]
	s_cbranch_execz .LBB0_754
	v_sub_f32_e32 v38, v96, v45
	v_mul_f32_e32 v38, 0x3fb8aa3b, v38
	v_exp_f32_e32 v38, v38
	s_nop 0
	v_mul_f32_e32 v6, v6, v38
	s_nop 0
	v_cvt_pk_bf16_f32 v6, v6, v6
	ds_write_b16_d16_hi v79, v6 offset:23296
.LBB0_754:
	s_or_b64 exec, exec, s[30:31]
	v_lshlrev_b32_e32 v6, 16, v57
	v_mul_f32_e32 v38, 0xbfb8aa3b, v6
	v_exp_f32_e32 v38, v38
	s_nop 0
	v_add_f32_e32 v38, 1.0, v38
	v_rcp_f32_e32 v38, v38
	s_nop 0
	v_mul_f32_e32 v6, v38, v6
	v_mul_f32_e32 v38, 0x3fb8aa3b, v61
	v_exp_f32_e32 v38, v38
	v_cndmask_b32_e64 v6, 0, v6, s[20:21]
	v_mul_f32_e32 v38, v6, v38
	s_nop 0
	v_cvt_pk_bf16_f32 v38, v38, v38
	v_add_u32_e32 v39, v70, v80
	ds_write_b16_d16_hi v39, v38 offset:2048
	v_sub_f32_e32 v38, v61, v2
	v_mul_f32_e32 v38, 0x3fb8aa3b, v38
	v_exp_f32_e32 v38, v38
	s_nop 0
	v_mul_f32_e32 v38, v6, v38
	s_nop 0
	v_cvt_pk_bf16_f32 v38, v38, v38
	ds_write_b16_d16_hi v81, v38 offset:10240
	v_sub_f32_e32 v38, v2, v61
	v_mul_f32_e32 v38, 0x3fb8aa3b, v38
	v_exp_f32_e32 v38, v38
	s_nop 0
	v_mul_f32_e32 v38, v7, v38
	s_nop 0
	v_cvt_pk_bf16_f32 v38, v38, v38
	ds_write_b16_d16_hi v81, v38 offset:18944
	s_and_saveexec_b64 s[30:31], s[6:7]
	s_xor_b64 s[30:31], exec, s[30:31]
	s_cbranch_execz .LBB0_756
	v_sub_f32_e32 v6, v45, v61
	v_mul_f32_e32 v6, 0x3fb8aa3b, v6
	v_exp_f32_e32 v6, v6
	s_nop 0
	v_mul_f32_e32 v6, v7, v6
	v_bfe_u32 v7, v6, 16, 1
	v_add3_u32 v6, v6, v7, s48
	ds_write_b16_d16_hi v81, v6 offset:32000
.LBB0_756:
	s_andn2_saveexec_b64 s[30:31], s[30:31]
	s_cbranch_execz .LBB0_758
	v_sub_f32_e32 v7, v61, v45
	v_mul_f32_e32 v7, 0x3fb8aa3b, v7
	v_exp_f32_e32 v7, v7
	s_nop 0
	v_mul_f32_e32 v6, v6, v7
	s_nop 0
	v_cvt_pk_bf16_f32 v6, v6, v6
	ds_write_b16_d16_hi v82, v6 offset:23296
.LBB0_758:
	s_or_b64 exec, exec, s[30:31]
	v_lshlrev_b32_e32 v6, 16, v58
	v_mul_f32_e32 v7, 0xbfb8aa3b, v6
	v_exp_f32_e32 v7, v7
	s_nop 0
	v_add_f32_e32 v7, 1.0, v7
	v_rcp_f32_e32 v7, v7
	s_nop 0
	v_mul_f32_e32 v6, v7, v6
	v_mul_f32_e32 v7, 0x3fb8aa3b, v59
	v_exp_f32_e32 v7, v7
	v_cndmask_b32_e64 v6, 0, v6, s[18:19]
	v_mul_f32_e32 v7, v6, v7
	s_nop 0
	v_cvt_pk_bf16_f32 v7, v7, v7
	v_add_u32_e32 v38, v70, v83
	ds_write_b16_d16_hi v38, v7 offset:2048
	v_sub_f32_e32 v7, v59, v2
	v_mul_f32_e32 v7, 0x3fb8aa3b, v7
	v_exp_f32_e32 v7, v7
	s_nop 0
	v_mul_f32_e32 v7, v6, v7
	s_nop 0
	v_cvt_pk_bf16_f32 v7, v7, v7
	ds_write_b16_d16_hi v84, v7 offset:10240
	v_sub_f32_e32 v7, v2, v59
	v_mul_f32_e32 v7, 0x3fb8aa3b, v7
	v_exp_f32_e32 v7, v7
	s_nop 0
	v_mul_f32_e32 v7, v4, v7
	s_nop 0
	v_cvt_pk_bf16_f32 v7, v7, v7
	ds_write_b16_d16_hi v84, v7 offset:18944
	s_and_saveexec_b64 s[30:31], s[6:7]
	s_xor_b64 s[30:31], exec, s[30:31]
	s_cbranch_execz .LBB0_760
	v_sub_f32_e32 v6, v45, v59
	v_mul_f32_e32 v6, 0x3fb8aa3b, v6
	v_exp_f32_e32 v6, v6
	s_nop 0
	v_mul_f32_e32 v4, v4, v6
	s_nop 0
	v_cvt_pk_bf16_f32 v4, v4, v4
	ds_write_b16_d16_hi v84, v4 offset:32000
.LBB0_760:
	s_andn2_saveexec_b64 s[30:31], s[30:31]
	s_cbranch_execz .LBB0_762
	v_sub_f32_e32 v4, v59, v45
	v_mul_f32_e32 v4, 0x3fb8aa3b, v4
	v_exp_f32_e32 v4, v4
	s_nop 0
	v_mul_f32_e32 v4, v6, v4
	s_nop 0
	v_cvt_pk_bf16_f32 v4, v4, v4
	ds_write_b16_d16_hi v85, v4 offset:23296
.LBB0_762:
	s_or_b64 exec, exec, s[30:31]
	v_lshlrev_b32_e32 v4, 16, v55
	v_mul_f32_e32 v6, 0xbfb8aa3b, v4
	v_exp_f32_e32 v6, v6
	s_nop 0
	v_add_f32_e32 v6, 1.0, v6
	v_rcp_f32_e32 v6, v6
	s_nop 0
	v_mul_f32_e32 v4, v6, v4
	v_mul_f32_e32 v6, 0x3fb8aa3b, v56
	v_exp_f32_e32 v6, v6
	v_cndmask_b32_e64 v4, 0, v4, s[22:23]
	v_mul_f32_e32 v6, v4, v6
	s_nop 0
	v_cvt_pk_bf16_f32 v6, v6, v6
	v_add_u32_e32 v7, v70, v86
	ds_write_b16_d16_hi v7, v6 offset:2048
	v_sub_f32_e32 v6, v56, v2
	v_mul_f32_e32 v6, 0x3fb8aa3b, v6
	v_exp_f32_e32 v6, v6
	s_nop 0
	v_mul_f32_e32 v6, v4, v6
	s_nop 0
	v_cvt_pk_bf16_f32 v6, v6, v6
	ds_write_b16_d16_hi v87, v6 offset:10240
	v_sub_f32_e32 v6, v2, v56
	v_mul_f32_e32 v6, 0x3fb8aa3b, v6
	v_exp_f32_e32 v6, v6
	s_nop 0
	v_mul_f32_e32 v6, v0, v6
	s_nop 0
	v_cvt_pk_bf16_f32 v6, v6, v6
	ds_write_b16_d16_hi v87, v6 offset:18944
	s_and_saveexec_b64 s[30:31], s[6:7]
	s_xor_b64 s[30:31], exec, s[30:31]
	s_cbranch_execz .LBB0_764
	v_sub_f32_e32 v4, v45, v56
	v_mul_f32_e32 v4, 0x3fb8aa3b, v4
	v_exp_f32_e32 v4, v4
	s_nop 0
	v_mul_f32_e32 v0, v0, v4
	s_nop 0
	v_cvt_pk_bf16_f32 v0, v0, v0
	ds_write_b16_d16_hi v87, v0 offset:32000
.LBB0_764:
	s_andn2_saveexec_b64 s[30:31], s[30:31]
	s_cbranch_execz .LBB0_766
	v_sub_f32_e32 v0, v56, v45
	v_mul_f32_e32 v0, 0x3fb8aa3b, v0
	v_exp_f32_e32 v0, v0
	s_nop 0
	v_mul_f32_e32 v0, v4, v0
	s_nop 0
	v_cvt_pk_bf16_f32 v0, v0, v0
	ds_write_b16_d16_hi v88, v0 offset:23296
.LBB0_766:
	s_or_b64 exec, exec, s[30:31]
	v_lshlrev_b32_e32 v0, 16, v54
	v_mul_f32_e32 v4, 0xbfb8aa3b, v0
	v_exp_f32_e32 v4, v4
	s_nop 0
	v_add_f32_e32 v4, 1.0, v4
	v_rcp_f32_e32 v4, v4
	s_nop 0
	v_mul_f32_e32 v0, v4, v0
	v_mul_f32_e32 v4, 0x3fb8aa3b, v43
	v_exp_f32_e32 v4, v4
	v_cndmask_b32_e64 v0, 0, v0, s[24:25]
	v_mul_f32_e32 v4, v0, v4
	s_nop 0
	v_cvt_pk_bf16_f32 v4, v4, v4
	v_add_u32_e32 v6, v70, v89
	ds_write_b16_d16_hi v6, v4 offset:2048
	v_sub_f32_e32 v4, v43, v2
	v_mul_f32_e32 v4, 0x3fb8aa3b, v4
	v_exp_f32_e32 v4, v4
	s_nop 0
	v_mul_f32_e32 v4, v0, v4
	s_nop 0
	v_cvt_pk_bf16_f32 v4, v4, v4
	ds_write_b16_d16_hi v90, v4 offset:10240
	v_sub_f32_e32 v4, v2, v43
	v_mul_f32_e32 v4, 0x3fb8aa3b, v4
	v_exp_f32_e32 v4, v4
	s_nop 0
	v_mul_f32_e32 v4, v5, v4
	s_nop 0
	v_cvt_pk_bf16_f32 v4, v4, v4
	ds_write_b16_d16_hi v90, v4 offset:18944
	s_and_saveexec_b64 s[30:31], s[6:7]
	s_xor_b64 s[30:31], exec, s[30:31]
	s_cbranch_execz .LBB0_768
	v_sub_f32_e32 v0, v45, v43
	v_mul_f32_e32 v0, 0x3fb8aa3b, v0
	v_exp_f32_e32 v0, v0
	s_nop 0
	v_mul_f32_e32 v0, v5, v0
	v_bfe_u32 v4, v0, 16, 1
	v_add3_u32 v0, v0, v4, s48
	ds_write_b16_d16_hi v90, v0 offset:32000
.LBB0_768:
	s_andn2_saveexec_b64 s[30:31], s[30:31]
	s_cbranch_execz .LBB0_770
	v_sub_f32_e32 v4, v43, v45
	v_mul_f32_e32 v4, 0x3fb8aa3b, v4
	v_exp_f32_e32 v4, v4
	s_nop 0
	v_mul_f32_e32 v0, v0, v4
	s_nop 0
	v_cvt_pk_bf16_f32 v0, v0, v0
	ds_write_b16_d16_hi v91, v0 offset:23296
.LBB0_770:
	s_or_b64 exec, exec, s[30:31]
	v_lshlrev_b32_e32 v0, 16, v53
	v_mul_f32_e32 v4, 0xbfb8aa3b, v0
	v_exp_f32_e32 v4, v4
	s_nop 0
	v_add_f32_e32 v4, 1.0, v4
	v_rcp_f32_e32 v4, v4
	s_nop 0
	v_mul_f32_e32 v0, v4, v0
	v_mul_f32_e32 v4, 0x3fb8aa3b, v3
	v_exp_f32_e32 v4, v4
	v_cndmask_b32_e64 v0, 0, v0, s[26:27]
	v_mul_f32_e32 v4, v0, v4
	s_nop 0
	v_cvt_pk_bf16_f32 v4, v4, v4
	v_add_u32_e32 v5, v70, v92
	ds_write_b16_d16_hi v5, v4 offset:2048
	v_sub_f32_e32 v4, v3, v2
	v_mul_f32_e32 v4, 0x3fb8aa3b, v4
	v_exp_f32_e32 v4, v4
	v_sub_f32_e32 v2, v2, v3
	v_mul_f32_e32 v2, 0x3fb8aa3b, v2
	v_exp_f32_e32 v2, v2
	v_mul_f32_e32 v4, v0, v4
	s_nop 0
	v_cvt_pk_bf16_f32 v4, v4, v4
	v_mul_f32_e32 v2, v1, v2
	ds_write_b16_d16_hi v93, v4 offset:10240
	s_nop 0
	v_cvt_pk_bf16_f32 v2, v2, v2
	ds_write_b16_d16_hi v93, v2 offset:18944
	s_and_saveexec_b64 s[30:31], s[6:7]
	s_xor_b64 s[30:31], exec, s[30:31]
	s_cbranch_execz .LBB0_772
	v_sub_f32_e32 v0, v45, v3
	v_mul_f32_e32 v0, 0x3fb8aa3b, v0
	v_exp_f32_e32 v0, v0
	s_nop 0
	v_mul_f32_e32 v0, v1, v0
	v_bfe_u32 v1, v0, 16, 1
	v_add3_u32 v0, v0, v1, s48
	ds_write_b16_d16_hi v93, v0 offset:32000
.LBB0_772:
	s_andn2_saveexec_b64 s[30:31], s[30:31]
	s_cbranch_execz .LBB0_774
	v_sub_f32_e32 v1, v3, v45
	v_mul_f32_e32 v1, 0x3fb8aa3b, v1
	v_exp_f32_e32 v1, v1
	s_nop 0
	v_mul_f32_e32 v0, v0, v1
	s_nop 0
	v_cvt_pk_bf16_f32 v0, v0, v0
	ds_write_b16_d16_hi v94, v0 offset:23296

.LBB0_790:
	s_or_b64 exec, exec, s[12:13]
	s_ashr_i32 s12, s33, 31
	s_or_b32 s13, s87, s28
	s_mul_hi_u32 s14, s13, 0x41
	s_mulk_i32 s12, 0x41
	s_ashr_i32 s83, s82, 31
	s_add_i32 s14, s14, s12
	s_mulk_i32 s13, 0x41
	s_add_u32 s12, s13, s82
	s_addc_u32 s13, s14, s83
	s_lshl_b64 s[12:13], s[12:13], 13
	s_waitcnt vmcnt(0)
	v_or_b32_e32 v0, v3, v2
	v_or_b32_e32 v1, v5, v4
	v_or_b32_e32 v2, v7, v6
	v_or_b32_e32 v3, v39, v38
	v_lshl_add_u64 v[4:5], v[16:17], 0, s[12:13]
	global_store_dwordx4 v[4:5], v[0:3], off
	v_add_u32_e32 v4, s38, v69
	s_waitcnt lgkmcnt(0)
	v_add_u32_e32 v0, v98, v18
	s_barrier
	ds_read_b128 v[0:3], v0 offset:2048
	v_lshl_add_u32 v4, v4, 6, v4
	v_ashrrev_i32_e32 v5, 31, v4
	v_lshl_add_u64 v[4:5], v[4:5], 0, s[82:83]
	v_mad_u64_u32 v[6:7], s[12:13], v4, s44, v[20:21]
	v_mad_i32_i24 v7, v5, s44, v7
	s_andn2_b64 vcc, exec, s[70:71]
	s_waitcnt lgkmcnt(0)
	global_store_dwordx4 v[6:7], v[0:3], off
	s_cbranch_vccnz .LBB0_664
	s_mul_i32 s12, s38, 0x41
	s_add_i32 s12, s12, s82
	s_mul_hi_i32 s13, s12, 0x3000
	s_mulk_i32 s12, 0x3000
	s_add_u32 s12, s54, s12
	s_addc_u32 s13, s55, s13
	s_add_u32 s12, s12, 0x2e894000
	s_addc_u32 s13, s13, 0
	s_andn2_b64 vcc, exec, s[58:59]
	s_mov_b64 s[14:15], -1
	s_cbranch_vccnz .LBB0_793
	ds_read_b128 v[0:3], v19
	ds_read_b128 v[4:7], v100
	s_mov_b64 s[14:15], 0
	s_waitcnt lgkmcnt(0)
	v_mfma_f32_16x16x32_bf16 v[0:3], v[0:3], v[4:7], 0
	ds_read_b128 v[4:7], v19 offset:64
	ds_read_b128 v[38:41], v100 offset:64
	s_waitcnt lgkmcnt(0)
	v_mfma_f32_16x16x32_bf16 v[0:3], v[4:7], v[38:41], v[0:3]
	ds_read_b128 v[4:7], v19 offset:128
	ds_read_b128 v[38:41], v100 offset:128
	s_waitcnt lgkmcnt(0)
	v_mfma_f32_16x16x32_bf16 v[0:3], v[4:7], v[38:41], v[0:3]
	ds_read_b128 v[4:7], v19 offset:192
	ds_read_b128 v[38:41], v100 offset:192
	s_waitcnt lgkmcnt(0)
	v_mfma_f32_16x16x32_bf16 v[0:3], v[4:7], v[38:41], v[0:3]
	v_lshl_add_u64 v[4:5], s[12:13], 0, v[22:23]
	s_nop 6
	v_cndmask_b32_e64 v0, v0, 0, s[60:61]
	s_nop 0
	v_cvt_pk_bf16_f32 v0, v0, v0
	v_lshl_add_u64 v[6:7], v[4:5], 0, v[24:25]
	global_store_short_d16_hi v[6:7], v0, off
	v_cndmask_b32_e64 v0, v1, 0, s[62:63]
	v_bfe_u32 v1, v0, 16, 1
	v_add3_u32 v6, v0, v1, s48
	v_lshl_add_u64 v[0:1], v[4:5], 0, v[26:27]
	global_store_short_d16_hi v[0:1], v6, off
	v_cndmask_b32_e64 v0, v2, 0, s[88:89]
	s_nop 0
	v_cvt_pk_bf16_f32 v2, v0, v0
	v_lshl_add_u64 v[0:1], v[4:5], 0, v[28:29]
	global_store_short_d16_hi v[0:1], v2, off
	v_cndmask_b32_e64 v0, v3, 0, s[66:67]
	v_bfe_u32 v1, v0, 16, 1
	v_add3_u32 v2, v0, v1, s48
	v_lshl_add_u64 v[0:1], v[4:5], 0, v[30:31]
	global_store_short_d16_hi v[0:1], v2, off

.LBB0_800:
	s_mul_hi_i32 s0, s66, 0x7e07e07f
	s_lshr_b32 s1, s0, 31
	s_ashr_i32 s8, s0, 5
	s_add_i32 s8, s8, s1
	s_mul_i32 s0, s8, 0x41
	s_sub_i32 s12, s66, s0
	s_ashr_i32 s13, s8, 3
	s_lshl_b32 s10, s12, 5
	s_cmp_lg_u32 s12, 64
	v_and_b32_e32 v107, 31, v136
	s_cselect_b64 s[0:1], -1, 0
	v_or_b32_e32 v4, s10, v107
	v_cmp_gt_u32_e32 vcc, 16, v107
	v_ashrrev_i32_e32 v0, 31, v4
	s_or_b64 s[2:3], s[0:1], vcc
	v_cndmask_b32_e64 v1, 0, v0, s[2:3]
	v_cndmask_b32_e64 v0, 0, v4, s[2:3]
	v_mov_b32_e32 v2, 0x810
	v_ashrrev_i32_e32 v138, 5, v136
	v_mad_i64_i32 v[0:1], s[4:5], s13, v2, v[0:1]
	v_mov_b64_e32 v[2:3], s[56:57]
	v_mad_u64_u32 v[2:3], s[4:5], v0, s44, v[2:3]
	v_lshlrev_b32_e32 v68, 3, v138
	v_mad_i32_i24 v3, v1, s44, v3
	v_ashrrev_i32_e32 v69, 31, v68
	v_lshl_add_u64 v[102:103], v[68:69], 1, v[2:3]
	v_cmp_lt_i32_e64 s[4:5], 0, v4
	s_and_b32 s14, s8, 7
	s_lshl_b32 s11, s14, 6
	s_mul_hi_i32 s7, s13, 0x810
	s_mul_i32 s6, s13, 0x810
	v_or_b32_e32 v134, s34, v107
	v_or_b32_e32 v134, s11, v134
	v_mov_b32_e32 v135, s35
	v_lshlrev_b64 v[110:111], 7, v[134:135]
	v_lshlrev_b64 v[114:115], 8, v[134:135]
	v_lshl_add_u64 v[110:111], s[92:93], 0, v[110:111]
	v_lshl_add_u64 v[114:115], s[92:93], 0, v[114:115]
	v_lshl_add_u64 v[110:111], v[68:69], 1, v[110:111]
	v_lshl_add_u64 v[114:115], v[68:69], 1, v[114:115]
	s_mov_b64 s[100:101], 0x800
	v_lshl_add_u64 v[110:111], v[110:111], 0, s[100:101]
	s_mov_b64 s[100:101], 0x40000
	v_lshl_add_u64 v[112:113], v[110:111], 0, s[100:101]
	s_mov_b64 s[100:101], 0x80000
	v_lshl_add_u64 v[114:115], v[114:115], 0, s[100:101]
	s_mov_b64 s[100:101], 0x2000
	v_lshl_add_u64 v[116:117], v[114:115], 0, s[100:101]
	v_lshl_add_u64 v[108:109], v[68:69], 2, s[60:61]
	s_mov_b64 s[100:101], 0x1800
	v_lshl_add_u64 v[108:109], v[108:109], 0, s[100:101]
	s_mov_b32 s100, 0xffffdc00
	s_mov_b32 s101, -1
	v_lshl_add_u64 v[104:105], v[102:103], 0, s[100:101]
	s_mov_b64 s[100:101], 0xc00
	v_lshl_add_u64 v[134:135], v[102:103], 0, s[100:101]
	v_cndmask_b32_e64 v104, v134, v104, s[4:5]
	v_cndmask_b32_e64 v105, v135, v105, s[4:5]
	global_load_dwordx4 v[192:195], v[110:111], off offset:-2048
	global_load_dwordx4 v[196:199], v[110:111], off offset:2048
	global_load_dwordx4 v[144:147], v[102:103], off offset:3072
	global_load_dwordx4 v[148:151], v[104:105], off
	global_load_dwordx4 v[152:155], v[108:109], off
	global_load_dwordx4 v[156:159], v[108:109], off offset:16
	global_load_dword v212, v[102:103], off offset:3200
	global_load_dword v213, v[102:103], off offset:3328
	global_load_dword v214, v[102:103], off offset:3456
	global_load_dword v139, v[104:105], off offset:128
	global_load_dword v244, v[104:105], off offset:256
	global_load_dword v245, v[104:105], off offset:384
	global_load_dwordx4 v[200:203], v[110:111], off offset:-2016
	global_load_dwordx4 v[204:207], v[110:111], off offset:2080
	global_load_dwordx4 v[160:163], v[102:103], off offset:3104
	global_load_dwordx4 v[164:167], v[104:105], off offset:32
	global_load_dwordx4 v[168:171], v[108:109], off offset:64
	global_load_dwordx4 v[172:175], v[108:109], off offset:80
	global_load_dwordx4 v[208:211], v[110:111], off offset:-1984
	global_load_dwordx4 v[222:225], v[110:111], off offset:2112
	global_load_dwordx4 v[176:179], v[102:103], off offset:3136
	global_load_dwordx4 v[180:183], v[104:105], off offset:64
	global_load_dwordx4 v[184:187], v[108:109], off offset:128
	global_load_dwordx4 v[188:191], v[108:109], off offset:144
	global_load_dwordx4 v[226:229], v[110:111], off offset:-1952
	global_load_dwordx4 v[238:241], v[110:111], off offset:2144
	s_waitcnt vmcnt(20)
	v_lshlrev_b32_e32 v118, 16, v144
	v_and_b32_e32 v119, 0xffff0000, v144
	v_lshlrev_b32_e32 v120, 16, v145
	v_and_b32_e32 v121, 0xffff0000, v145
	v_lshlrev_b32_e32 v122, 16, v146
	v_and_b32_e32 v123, 0xffff0000, v146
	v_lshlrev_b32_e32 v124, 16, v147
	v_and_b32_e32 v125, 0xffff0000, v147
	v_cndmask_b32_e64 v148, 0, v148, s[4:5]
	v_cndmask_b32_e64 v149, 0, v149, s[4:5]
	v_cndmask_b32_e64 v150, 0, v150, s[4:5]
	v_cndmask_b32_e64 v151, 0, v151, s[4:5]
	v_lshlrev_b32_e32 v126, 16, v148
	v_and_b32_e32 v127, 0xffff0000, v148
	v_lshlrev_b32_e32 v128, 16, v149
	v_and_b32_e32 v129, 0xffff0000, v149
	v_lshlrev_b32_e32 v130, 16, v150
	v_and_b32_e32 v131, 0xffff0000, v150
	v_lshlrev_b32_e32 v132, 16, v151
	v_and_b32_e32 v133, 0xffff0000, v151
	global_load_dwordx4 v[144:147], v[102:103], off offset:3168
	global_load_dwordx4 v[148:151], v[104:105], off offset:96
	v_sub_f32_e32 v126, v126, v118
	v_sub_f32_e32 v127, v127, v119
	v_sub_f32_e32 v128, v128, v120
	v_sub_f32_e32 v129, v129, v121
	v_sub_f32_e32 v130, v130, v122
	v_sub_f32_e32 v131, v131, v123
	v_sub_f32_e32 v132, v132, v124
	v_sub_f32_e32 v133, v133, v125
	v_fmac_f32_e32 v118, v126, v152
	v_fmac_f32_e32 v119, v127, v153
	v_fmac_f32_e32 v120, v128, v154
	v_fmac_f32_e32 v121, v129, v155
	v_fmac_f32_e32 v122, v130, v156
	v_fmac_f32_e32 v123, v131, v157
	v_fmac_f32_e32 v124, v132, v158
	v_fmac_f32_e32 v125, v133, v159
	global_load_dwordx4 v[152:155], v[108:109], off offset:192
	global_load_dwordx4 v[156:159], v[108:109], off offset:208
	v_add_f32_e32 v126, v118, v118
	v_add_f32_e32 v127, v119, v119
	v_add_f32_e32 v128, v120, v120
	v_add_f32_e32 v129, v121, v121
	v_add_f32_e32 v130, v122, v122
	v_add_f32_e32 v131, v123, v123
	v_add_f32_e32 v132, v124, v124
	v_add_f32_e32 v133, v125, v125
	v_mul_f32_e32 v126, 0x3fb8aa3b, v126
	v_mul_f32_e32 v127, 0x3fb8aa3b, v127
	v_mul_f32_e32 v128, 0x3fb8aa3b, v128
	v_mul_f32_e32 v129, 0x3fb8aa3b, v129
	v_mul_f32_e32 v130, 0x3fb8aa3b, v130
	v_mul_f32_e32 v131, 0x3fb8aa3b, v131
	v_mul_f32_e32 v132, 0x3fb8aa3b, v132
	v_mul_f32_e32 v133, 0x3fb8aa3b, v133
	v_exp_f32_e32 v126, v126
	v_exp_f32_e32 v127, v127
	v_exp_f32_e32 v128, v128
	v_exp_f32_e32 v129, v129
	v_exp_f32_e32 v130, v130
	v_exp_f32_e32 v131, v131
	v_exp_f32_e32 v132, v132
	v_exp_f32_e32 v133, v133
	v_add_f32_e32 v126, 1.0, v126
	v_add_f32_e32 v127, 1.0, v127
	v_add_f32_e32 v128, 1.0, v128
	v_add_f32_e32 v129, 1.0, v129
	v_add_f32_e32 v130, 1.0, v130
	v_add_f32_e32 v131, 1.0, v131
	v_add_f32_e32 v132, 1.0, v132
	v_add_f32_e32 v133, 1.0, v133
	v_rcp_f32_e32 v126, v126
	v_rcp_f32_e32 v127, v127
	v_rcp_f32_e32 v128, v128
	v_rcp_f32_e32 v129, v129
	v_rcp_f32_e32 v130, v130
	v_rcp_f32_e32 v131, v131
	v_rcp_f32_e32 v132, v132
	v_rcp_f32_e32 v133, v133
	v_fma_f32 v118, v126, -2.0, 1.0
	v_fma_f32 v119, v127, -2.0, 1.0
	v_fma_f32 v120, v128, -2.0, 1.0
	v_fma_f32 v121, v129, -2.0, 1.0
	v_fma_f32 v122, v130, -2.0, 1.0
	v_fma_f32 v123, v131, -2.0, 1.0
	v_fma_f32 v124, v132, -2.0, 1.0
	v_fma_f32 v125, v133, -2.0, 1.0
	s_nop 0
	v_cvt_pk_bf16_f32 v98, v118, v119
	v_cvt_pk_bf16_f32 v99, v120, v121
	v_cvt_pk_bf16_f32 v100, v122, v123
	v_cvt_pk_bf16_f32 v101, v124, v125
	v_cndmask_b32_e64 v98, 0, v98, s[2:3]
	v_cndmask_b32_e64 v99, 0, v99, s[2:3]
	v_cndmask_b32_e64 v100, 0, v100, s[2:3]
	v_cndmask_b32_e64 v101, 0, v101, s[2:3]
	s_nop 1
	v_mfma_f32_32x32x16_bf16 v[32:47], v[98:101], v[192:195], 0
	v_mfma_f32_32x32x16_bf16 v[48:63], v[98:101], v[196:199], 0
	global_load_dwordx4 v[192:195], v[112:113], off offset:-2048
	global_load_dwordx4 v[196:199], v[112:113], off offset:2048
	s_waitcnt vmcnt(14)
	v_lshlrev_b32_e32 v118, 16, v160
	v_and_b32_e32 v119, 0xffff0000, v160
	v_lshlrev_b32_e32 v120, 16, v161
	v_and_b32_e32 v121, 0xffff0000, v161
	v_lshlrev_b32_e32 v122, 16, v162
	v_and_b32_e32 v123, 0xffff0000, v162
	v_lshlrev_b32_e32 v124, 16, v163
	v_and_b32_e32 v125, 0xffff0000, v163
	v_cndmask_b32_e64 v164, 0, v164, s[4:5]
	v_cndmask_b32_e64 v165, 0, v165, s[4:5]
	v_cndmask_b32_e64 v166, 0, v166, s[4:5]
	v_cndmask_b32_e64 v167, 0, v167, s[4:5]
	v_lshlrev_b32_e32 v126, 16, v164
	v_and_b32_e32 v127, 0xffff0000, v164
	v_lshlrev_b32_e32 v128, 16, v165
	v_and_b32_e32 v129, 0xffff0000, v165
	v_lshlrev_b32_e32 v130, 16, v166
	v_and_b32_e32 v131, 0xffff0000, v166
	v_lshlrev_b32_e32 v132, 16, v167
	v_and_b32_e32 v133, 0xffff0000, v167
	global_load_dwordx4 v[160:163], v[102:103], off offset:3200
	global_load_dwordx4 v[164:167], v[104:105], off offset:128
	v_sub_f32_e32 v126, v126, v118
	v_sub_f32_e32 v127, v127, v119
	v_sub_f32_e32 v128, v128, v120
	v_sub_f32_e32 v129, v129, v121
	v_sub_f32_e32 v130, v130, v122
	v_sub_f32_e32 v131, v131, v123
	v_sub_f32_e32 v132, v132, v124
	v_sub_f32_e32 v133, v133, v125
	v_fmac_f32_e32 v118, v126, v168
	v_fmac_f32_e32 v119, v127, v169
	v_fmac_f32_e32 v120, v128, v170
	v_fmac_f32_e32 v121, v129, v171
	v_fmac_f32_e32 v122, v130, v172
	v_fmac_f32_e32 v123, v131, v173
	v_fmac_f32_e32 v124, v132, v174
	v_fmac_f32_e32 v125, v133, v175
	global_load_dwordx4 v[168:171], v[108:109], off offset:256
	global_load_dwordx4 v[172:175], v[108:109], off offset:272
	v_add_f32_e32 v126, v118, v118
	v_add_f32_e32 v127, v119, v119
	v_add_f32_e32 v128, v120, v120
	v_add_f32_e32 v129, v121, v121
	v_add_f32_e32 v130, v122, v122
	v_add_f32_e32 v131, v123, v123
	v_add_f32_e32 v132, v124, v124
	v_add_f32_e32 v133, v125, v125
	v_mul_f32_e32 v126, 0x3fb8aa3b, v126
	v_mul_f32_e32 v127, 0x3fb8aa3b, v127
	v_mul_f32_e32 v128, 0x3fb8aa3b, v128
	v_mul_f32_e32 v129, 0x3fb8aa3b, v129
	v_mul_f32_e32 v130, 0x3fb8aa3b, v130
	v_mul_f32_e32 v131, 0x3fb8aa3b, v131
	v_mul_f32_e32 v132, 0x3fb8aa3b, v132
	v_mul_f32_e32 v133, 0x3fb8aa3b, v133
	v_exp_f32_e32 v126, v126
	v_exp_f32_e32 v127, v127
	v_exp_f32_e32 v128, v128
	v_exp_f32_e32 v129, v129
	v_exp_f32_e32 v130, v130
	v_exp_f32_e32 v131, v131
	v_exp_f32_e32 v132, v132
	v_exp_f32_e32 v133, v133
	v_add_f32_e32 v126, 1.0, v126
	v_add_f32_e32 v127, 1.0, v127
	v_add_f32_e32 v128, 1.0, v128
	v_add_f32_e32 v129, 1.0, v129
	v_add_f32_e32 v130, 1.0, v130
	v_add_f32_e32 v131, 1.0, v131
	v_add_f32_e32 v132, 1.0, v132
	v_add_f32_e32 v133, 1.0, v133
	v_rcp_f32_e32 v126, v126
	v_rcp_f32_e32 v127, v127
	v_rcp_f32_e32 v128, v128
	v_rcp_f32_e32 v129, v129
	v_rcp_f32_e32 v130, v130
	v_rcp_f32_e32 v131, v131
	v_rcp_f32_e32 v132, v132
	v_rcp_f32_e32 v133, v133
	v_fma_f32 v118, v126, -2.0, 1.0
	v_fma_f32 v119, v127, -2.0, 1.0
	v_fma_f32 v120, v128, -2.0, 1.0
	v_fma_f32 v121, v129, -2.0, 1.0
	v_fma_f32 v122, v130, -2.0, 1.0
	v_fma_f32 v123, v131, -2.0, 1.0
	v_fma_f32 v124, v132, -2.0, 1.0
	v_fma_f32 v125, v133, -2.0, 1.0
	s_nop 0
	v_cvt_pk_bf16_f32 v98, v118, v119
	v_cvt_pk_bf16_f32 v99, v120, v121
	v_cvt_pk_bf16_f32 v100, v122, v123
	v_cvt_pk_bf16_f32 v101, v124, v125
	v_cndmask_b32_e64 v98, 0, v98, s[2:3]
	v_cndmask_b32_e64 v99, 0, v99, s[2:3]
	v_cndmask_b32_e64 v100, 0, v100, s[2:3]
	v_cndmask_b32_e64 v101, 0, v101, s[2:3]
	s_nop 1
	v_mfma_f32_32x32x16_bf16 v[32:47], v[98:101], v[200:203], v[32:47]
	v_mfma_f32_32x32x16_bf16 v[48:63], v[98:101], v[204:207], v[48:63]
	global_load_dwordx4 v[200:203], v[112:113], off offset:-2016
	global_load_dwordx4 v[204:207], v[112:113], off offset:2080
	s_waitcnt vmcnt(14)
	v_lshlrev_b32_e32 v118, 16, v176
	v_and_b32_e32 v119, 0xffff0000, v176
	v_lshlrev_b32_e32 v120, 16, v177
	v_and_b32_e32 v121, 0xffff0000, v177
	v_lshlrev_b32_e32 v122, 16, v178
	v_and_b32_e32 v123, 0xffff0000, v178
	v_lshlrev_b32_e32 v124, 16, v179
	v_and_b32_e32 v125, 0xffff0000, v179
	v_cndmask_b32_e64 v180, 0, v180, s[4:5]
	v_cndmask_b32_e64 v181, 0, v181, s[4:5]
	v_cndmask_b32_e64 v182, 0, v182, s[4:5]
	v_cndmask_b32_e64 v183, 0, v183, s[4:5]
	v_lshlrev_b32_e32 v126, 16, v180
	v_and_b32_e32 v127, 0xffff0000, v180
	v_lshlrev_b32_e32 v128, 16, v181
	v_and_b32_e32 v129, 0xffff0000, v181
	v_lshlrev_b32_e32 v130, 16, v182
	v_and_b32_e32 v131, 0xffff0000, v182
	v_lshlrev_b32_e32 v132, 16, v183
	v_and_b32_e32 v133, 0xffff0000, v183
	global_load_dwordx4 v[176:179], v[102:103], off offset:3232
	global_load_dwordx4 v[180:183], v[104:105], off offset:160
	v_sub_f32_e32 v126, v126, v118
	v_sub_f32_e32 v127, v127, v119
	v_sub_f32_e32 v128, v128, v120
	v_sub_f32_e32 v129, v129, v121
	v_sub_f32_e32 v130, v130, v122
	v_sub_f32_e32 v131, v131, v123
	v_sub_f32_e32 v132, v132, v124
	v_sub_f32_e32 v133, v133, v125
	v_fmac_f32_e32 v118, v126, v184
	v_fmac_f32_e32 v119, v127, v185
	v_fmac_f32_e32 v120, v128, v186
	v_fmac_f32_e32 v121, v129, v187
	v_fmac_f32_e32 v122, v130, v188
	v_fmac_f32_e32 v123, v131, v189
	v_fmac_f32_e32 v124, v132, v190
	v_fmac_f32_e32 v125, v133, v191
	global_load_dwordx4 v[184:187], v[108:109], off offset:320
	global_load_dwordx4 v[188:191], v[108:109], off offset:336
	v_add_f32_e32 v126, v118, v118
	v_add_f32_e32 v127, v119, v119
	v_add_f32_e32 v128, v120, v120
	v_add_f32_e32 v129, v121, v121
	v_add_f32_e32 v130, v122, v122
	v_add_f32_e32 v131, v123, v123
	v_add_f32_e32 v132, v124, v124
	v_add_f32_e32 v133, v125, v125
	v_mul_f32_e32 v126, 0x3fb8aa3b, v126
	v_mul_f32_e32 v127, 0x3fb8aa3b, v127
	v_mul_f32_e32 v128, 0x3fb8aa3b, v128
	v_mul_f32_e32 v129, 0x3fb8aa3b, v129
	v_mul_f32_e32 v130, 0x3fb8aa3b, v130
	v_mul_f32_e32 v131, 0x3fb8aa3b, v131
	v_mul_f32_e32 v132, 0x3fb8aa3b, v132
	v_mul_f32_e32 v133, 0x3fb8aa3b, v133
	v_exp_f32_e32 v126, v126
	v_exp_f32_e32 v127, v127
	v_exp_f32_e32 v128, v128
	v_exp_f32_e32 v129, v129
	v_exp_f32_e32 v130, v130
	v_exp_f32_e32 v131, v131
	v_exp_f32_e32 v132, v132
	v_exp_f32_e32 v133, v133
	v_add_f32_e32 v126, 1.0, v126
	v_add_f32_e32 v127, 1.0, v127
	v_add_f32_e32 v128, 1.0, v128
	v_add_f32_e32 v129, 1.0, v129
	v_add_f32_e32 v130, 1.0, v130
	v_add_f32_e32 v131, 1.0, v131
	v_add_f32_e32 v132, 1.0, v132
	v_add_f32_e32 v133, 1.0, v133
	v_rcp_f32_e32 v126, v126
	v_rcp_f32_e32 v127, v127
	v_rcp_f32_e32 v128, v128
	v_rcp_f32_e32 v129, v129
	v_rcp_f32_e32 v130, v130
	v_rcp_f32_e32 v131, v131
	v_rcp_f32_e32 v132, v132
	v_rcp_f32_e32 v133, v133
	v_fma_f32 v118, v126, -2.0, 1.0
	v_fma_f32 v119, v127, -2.0, 1.0
	v_fma_f32 v120, v128, -2.0, 1.0
	v_fma_f32 v121, v129, -2.0, 1.0
	v_fma_f32 v122, v130, -2.0, 1.0
	v_fma_f32 v123, v131, -2.0, 1.0
	v_fma_f32 v124, v132, -2.0, 1.0
	v_fma_f32 v125, v133, -2.0, 1.0
	s_nop 0
	v_cvt_pk_bf16_f32 v98, v118, v119
	v_cvt_pk_bf16_f32 v99, v120, v121
	v_cvt_pk_bf16_f32 v100, v122, v123
	v_cvt_pk_bf16_f32 v101, v124, v125
	v_cndmask_b32_e64 v98, 0, v98, s[2:3]
	v_cndmask_b32_e64 v99, 0, v99, s[2:3]
	v_cndmask_b32_e64 v100, 0, v100, s[2:3]
	v_cndmask_b32_e64 v101, 0, v101, s[2:3]
	s_nop 1
	v_mfma_f32_32x32x16_bf16 v[32:47], v[98:101], v[208:211], v[32:47]
	v_mfma_f32_32x32x16_bf16 v[48:63], v[98:101], v[222:225], v[48:63]
	global_load_dwordx4 v[208:211], v[112:113], off offset:-1984
	global_load_dwordx4 v[222:225], v[112:113], off offset:2112
	s_waitcnt vmcnt(14)
	v_lshlrev_b32_e32 v118, 16, v144
	v_and_b32_e32 v119, 0xffff0000, v144
	v_lshlrev_b32_e32 v120, 16, v145
	v_and_b32_e32 v121, 0xffff0000, v145
	v_lshlrev_b32_e32 v122, 16, v146
	v_and_b32_e32 v123, 0xffff0000, v146
	v_lshlrev_b32_e32 v124, 16, v147
	v_and_b32_e32 v125, 0xffff0000, v147
	v_cndmask_b32_e64 v148, 0, v148, s[4:5]
	v_cndmask_b32_e64 v149, 0, v149, s[4:5]
	v_cndmask_b32_e64 v150, 0, v150, s[4:5]
	v_cndmask_b32_e64 v151, 0, v151, s[4:5]
	v_lshlrev_b32_e32 v126, 16, v148
	v_and_b32_e32 v127, 0xffff0000, v148
	v_lshlrev_b32_e32 v128, 16, v149
	v_and_b32_e32 v129, 0xffff0000, v149
	v_lshlrev_b32_e32 v130, 16, v150
	v_and_b32_e32 v131, 0xffff0000, v150
	v_lshlrev_b32_e32 v132, 16, v151
	v_and_b32_e32 v133, 0xffff0000, v151
	global_load_dwordx4 v[144:147], v[102:103], off offset:3264
	global_load_dwordx4 v[148:151], v[104:105], off offset:192
	v_sub_f32_e32 v126, v126, v118
	v_sub_f32_e32 v127, v127, v119
	v_sub_f32_e32 v128, v128, v120
	v_sub_f32_e32 v129, v129, v121
	v_sub_f32_e32 v130, v130, v122
	v_sub_f32_e32 v131, v131, v123
	v_sub_f32_e32 v132, v132, v124
	v_sub_f32_e32 v133, v133, v125
	v_fmac_f32_e32 v118, v126, v152
	v_fmac_f32_e32 v119, v127, v153
	v_fmac_f32_e32 v120, v128, v154
	v_fmac_f32_e32 v121, v129, v155
	v_fmac_f32_e32 v122, v130, v156
	v_fmac_f32_e32 v123, v131, v157
	v_fmac_f32_e32 v124, v132, v158
	v_fmac_f32_e32 v125, v133, v159
	global_load_dwordx4 v[152:155], v[108:109], off offset:384
	global_load_dwordx4 v[156:159], v[108:109], off offset:400
	v_add_f32_e32 v126, v118, v118
	v_add_f32_e32 v127, v119, v119
	v_add_f32_e32 v128, v120, v120
	v_add_f32_e32 v129, v121, v121
	v_add_f32_e32 v130, v122, v122
	v_add_f32_e32 v131, v123, v123
	v_add_f32_e32 v132, v124, v124
	v_add_f32_e32 v133, v125, v125
	v_mul_f32_e32 v126, 0x3fb8aa3b, v126
	v_mul_f32_e32 v127, 0x3fb8aa3b, v127
	v_mul_f32_e32 v128, 0x3fb8aa3b, v128
	v_mul_f32_e32 v129, 0x3fb8aa3b, v129
	v_mul_f32_e32 v130, 0x3fb8aa3b, v130
	v_mul_f32_e32 v131, 0x3fb8aa3b, v131
	v_mul_f32_e32 v132, 0x3fb8aa3b, v132
	v_mul_f32_e32 v133, 0x3fb8aa3b, v133
	v_exp_f32_e32 v126, v126
	v_exp_f32_e32 v127, v127
	v_exp_f32_e32 v128, v128
	v_exp_f32_e32 v129, v129
	v_exp_f32_e32 v130, v130
	v_exp_f32_e32 v131, v131
	v_exp_f32_e32 v132, v132
	v_exp_f32_e32 v133, v133
	v_add_f32_e32 v126, 1.0, v126
	v_add_f32_e32 v127, 1.0, v127
	v_add_f32_e32 v128, 1.0, v128
	v_add_f32_e32 v129, 1.0, v129
	v_add_f32_e32 v130, 1.0, v130
	v_add_f32_e32 v131, 1.0, v131
	v_add_f32_e32 v132, 1.0, v132
	v_add_f32_e32 v133, 1.0, v133
	v_rcp_f32_e32 v126, v126
	v_rcp_f32_e32 v127, v127
	v_rcp_f32_e32 v128, v128
	v_rcp_f32_e32 v129, v129
	v_rcp_f32_e32 v130, v130
	v_rcp_f32_e32 v131, v131
	v_rcp_f32_e32 v132, v132
	v_rcp_f32_e32 v133, v133
	v_fma_f32 v118, v126, -2.0, 1.0
	v_fma_f32 v119, v127, -2.0, 1.0
	v_fma_f32 v120, v128, -2.0, 1.0
	v_fma_f32 v121, v129, -2.0, 1.0
	v_fma_f32 v122, v130, -2.0, 1.0
	v_fma_f32 v123, v131, -2.0, 1.0
	v_fma_f32 v124, v132, -2.0, 1.0
	v_fma_f32 v125, v133, -2.0, 1.0
	s_nop 0
	v_cvt_pk_bf16_f32 v98, v118, v119
	v_cvt_pk_bf16_f32 v99, v120, v121
	v_cvt_pk_bf16_f32 v100, v122, v123
	v_cvt_pk_bf16_f32 v101, v124, v125
	v_cndmask_b32_e64 v98, 0, v98, s[2:3]
	v_cndmask_b32_e64 v99, 0, v99, s[2:3]
	v_cndmask_b32_e64 v100, 0, v100, s[2:3]
	v_cndmask_b32_e64 v101, 0, v101, s[2:3]
	s_nop 1
	v_mfma_f32_32x32x16_bf16 v[32:47], v[98:101], v[226:229], v[32:47]
	v_mfma_f32_32x32x16_bf16 v[48:63], v[98:101], v[238:241], v[48:63]
	global_load_dwordx4 v[226:229], v[112:113], off offset:-1952
	global_load_dwordx4 v[238:241], v[112:113], off offset:2144
	s_waitcnt vmcnt(14)
	v_lshlrev_b32_e32 v118, 16, v160
	v_and_b32_e32 v119, 0xffff0000, v160
	v_lshlrev_b32_e32 v120, 16, v161
	v_and_b32_e32 v121, 0xffff0000, v161
	v_lshlrev_b32_e32 v122, 16, v162
	v_and_b32_e32 v123, 0xffff0000, v162
	v_lshlrev_b32_e32 v124, 16, v163
	v_and_b32_e32 v125, 0xffff0000, v163
	v_cndmask_b32_e64 v164, 0, v164, s[4:5]
	v_cndmask_b32_e64 v165, 0, v165, s[4:5]
	v_cndmask_b32_e64 v166, 0, v166, s[4:5]
	v_cndmask_b32_e64 v167, 0, v167, s[4:5]
	v_lshlrev_b32_e32 v126, 16, v164
	v_and_b32_e32 v127, 0xffff0000, v164
	v_lshlrev_b32_e32 v128, 16, v165
	v_and_b32_e32 v129, 0xffff0000, v165
	v_lshlrev_b32_e32 v130, 16, v166
	v_and_b32_e32 v131, 0xffff0000, v166
	v_lshlrev_b32_e32 v132, 16, v167
	v_and_b32_e32 v133, 0xffff0000, v167
	global_load_dwordx4 v[160:163], v[102:103], off offset:3296
	global_load_dwordx4 v[164:167], v[104:105], off offset:224
	v_sub_f32_e32 v126, v126, v118
	v_sub_f32_e32 v127, v127, v119
	v_sub_f32_e32 v128, v128, v120
	v_sub_f32_e32 v129, v129, v121
	v_sub_f32_e32 v130, v130, v122
	v_sub_f32_e32 v131, v131, v123
	v_sub_f32_e32 v132, v132, v124
	v_sub_f32_e32 v133, v133, v125
	v_fmac_f32_e32 v118, v126, v168
	v_fmac_f32_e32 v119, v127, v169
	v_fmac_f32_e32 v120, v128, v170
	v_fmac_f32_e32 v121, v129, v171
	v_fmac_f32_e32 v122, v130, v172
	v_fmac_f32_e32 v123, v131, v173
	v_fmac_f32_e32 v124, v132, v174
	v_fmac_f32_e32 v125, v133, v175
	global_load_dwordx4 v[168:171], v[108:109], off offset:448
	global_load_dwordx4 v[172:175], v[108:109], off offset:464
	v_cvt_pk_bf16_f32 v98, v118, v119
	v_cvt_pk_bf16_f32 v99, v120, v121
	v_cvt_pk_bf16_f32 v100, v122, v123
	v_cvt_pk_bf16_f32 v101, v124, v125
	v_cndmask_b32_e64 v98, 0, v98, s[2:3]
	v_cndmask_b32_e64 v99, 0, v99, s[2:3]
	v_cndmask_b32_e64 v100, 0, v100, s[2:3]
	v_cndmask_b32_e64 v101, 0, v101, s[2:3]
	s_nop 1
	v_mfma_f32_32x32x16_bf16 v[0:15], v[98:101], v[192:195], 0
	v_mfma_f32_32x32x16_bf16 v[16:31], v[98:101], v[196:199], 0
	global_load_dwordx4 v[192:195], v[114:115], off
	global_load_dwordx4 v[196:199], v[116:117], off
	s_waitcnt vmcnt(14)
	v_lshlrev_b32_e32 v118, 16, v176
	v_and_b32_e32 v119, 0xffff0000, v176
	v_lshlrev_b32_e32 v120, 16, v177
	v_and_b32_e32 v121, 0xffff0000, v177
	v_lshlrev_b32_e32 v122, 16, v178
	v_and_b32_e32 v123, 0xffff0000, v178
	v_lshlrev_b32_e32 v124, 16, v179
	v_and_b32_e32 v125, 0xffff0000, v179
	v_cndmask_b32_e64 v180, 0, v180, s[4:5]
	v_cndmask_b32_e64 v181, 0, v181, s[4:5]
	v_cndmask_b32_e64 v182, 0, v182, s[4:5]
	v_cndmask_b32_e64 v183, 0, v183, s[4:5]
	v_lshlrev_b32_e32 v126, 16, v180
	v_and_b32_e32 v127, 0xffff0000, v180
	v_lshlrev_b32_e32 v128, 16, v181
	v_and_b32_e32 v129, 0xffff0000, v181
	v_lshlrev_b32_e32 v130, 16, v182
	v_and_b32_e32 v131, 0xffff0000, v182
	v_lshlrev_b32_e32 v132, 16, v183
	v_and_b32_e32 v133, 0xffff0000, v183
	global_load_dwordx4 v[176:179], v[102:103], off offset:3328
	global_load_dwordx4 v[180:183], v[104:105], off offset:256
	v_sub_f32_e32 v126, v126, v118
	v_sub_f32_e32 v127, v127, v119
	v_sub_f32_e32 v128, v128, v120
	v_sub_f32_e32 v129, v129, v121
	v_sub_f32_e32 v130, v130, v122
	v_sub_f32_e32 v131, v131, v123
	v_sub_f32_e32 v132, v132, v124
	v_sub_f32_e32 v133, v133, v125
	v_fmac_f32_e32 v118, v126, v184
	v_fmac_f32_e32 v119, v127, v185
	v_fmac_f32_e32 v120, v128, v186
	v_fmac_f32_e32 v121, v129, v187
	v_fmac_f32_e32 v122, v130, v188
	v_fmac_f32_e32 v123, v131, v189
	v_fmac_f32_e32 v124, v132, v190
	v_fmac_f32_e32 v125, v133, v191
	global_load_dwordx4 v[184:187], v[108:109], off offset:512
	global_load_dwordx4 v[188:191], v[108:109], off offset:528
	v_cvt_pk_bf16_f32 v98, v118, v119
	v_cvt_pk_bf16_f32 v99, v120, v121
	v_cvt_pk_bf16_f32 v100, v122, v123
	v_cvt_pk_bf16_f32 v101, v124, v125
	v_cndmask_b32_e64 v98, 0, v98, s[2:3]
	v_cndmask_b32_e64 v99, 0, v99, s[2:3]
	v_cndmask_b32_e64 v100, 0, v100, s[2:3]
	v_cndmask_b32_e64 v101, 0, v101, s[2:3]
	s_nop 1
	v_mfma_f32_32x32x16_bf16 v[0:15], v[98:101], v[200:203], v[0:15]
	v_mfma_f32_32x32x16_bf16 v[16:31], v[98:101], v[204:207], v[16:31]
	global_load_dwordx4 v[200:203], v[114:115], off offset:32
	global_load_dwordx4 v[204:207], v[116:117], off offset:32
	s_waitcnt vmcnt(14)
	v_lshlrev_b32_e32 v118, 16, v144
	v_and_b32_e32 v119, 0xffff0000, v144
	v_lshlrev_b32_e32 v120, 16, v145
	v_and_b32_e32 v121, 0xffff0000, v145
	v_lshlrev_b32_e32 v122, 16, v146
	v_and_b32_e32 v123, 0xffff0000, v146
	v_lshlrev_b32_e32 v124, 16, v147
	v_and_b32_e32 v125, 0xffff0000, v147
	v_cndmask_b32_e64 v148, 0, v148, s[4:5]
	v_cndmask_b32_e64 v149, 0, v149, s[4:5]
	v_cndmask_b32_e64 v150, 0, v150, s[4:5]
	v_cndmask_b32_e64 v151, 0, v151, s[4:5]
	v_lshlrev_b32_e32 v126, 16, v148
	v_and_b32_e32 v127, 0xffff0000, v148
	v_lshlrev_b32_e32 v128, 16, v149
	v_and_b32_e32 v129, 0xffff0000, v149
	v_lshlrev_b32_e32 v130, 16, v150
	v_and_b32_e32 v131, 0xffff0000, v150
	v_lshlrev_b32_e32 v132, 16, v151
	v_and_b32_e32 v133, 0xffff0000, v151
	global_load_dwordx4 v[144:147], v[102:103], off offset:3360
	global_load_dwordx4 v[148:151], v[104:105], off offset:288
	v_sub_f32_e32 v126, v126, v118
	v_sub_f32_e32 v127, v127, v119
	v_sub_f32_e32 v128, v128, v120
	v_sub_f32_e32 v129, v129, v121
	v_sub_f32_e32 v130, v130, v122
	v_sub_f32_e32 v131, v131, v123
	v_sub_f32_e32 v132, v132, v124
	v_sub_f32_e32 v133, v133, v125
	v_fmac_f32_e32 v118, v126, v152
	v_fmac_f32_e32 v119, v127, v153
	v_fmac_f32_e32 v120, v128, v154
	v_fmac_f32_e32 v121, v129, v155
	v_fmac_f32_e32 v122, v130, v156
	v_fmac_f32_e32 v123, v131, v157
	v_fmac_f32_e32 v124, v132, v158
	v_fmac_f32_e32 v125, v133, v159
	global_load_dwordx4 v[152:155], v[108:109], off offset:576
	global_load_dwordx4 v[156:159], v[108:109], off offset:592
	v_cvt_pk_bf16_f32 v98, v118, v119
	v_cvt_pk_bf16_f32 v99, v120, v121
	v_cvt_pk_bf16_f32 v100, v122, v123
	v_cvt_pk_bf16_f32 v101, v124, v125
	v_cndmask_b32_e64 v98, 0, v98, s[2:3]
	v_cndmask_b32_e64 v99, 0, v99, s[2:3]
	v_cndmask_b32_e64 v100, 0, v100, s[2:3]
	v_cndmask_b32_e64 v101, 0, v101, s[2:3]
	s_nop 1
	v_mfma_f32_32x32x16_bf16 v[0:15], v[98:101], v[208:211], v[0:15]
	v_mfma_f32_32x32x16_bf16 v[16:31], v[98:101], v[222:225], v[16:31]
	global_load_dwordx4 v[208:211], v[114:115], off offset:64
	global_load_dwordx4 v[222:225], v[116:117], off offset:64
	s_waitcnt vmcnt(14)
	v_lshlrev_b32_e32 v118, 16, v160
	v_and_b32_e32 v119, 0xffff0000, v160
	v_lshlrev_b32_e32 v120, 16, v161
	v_and_b32_e32 v121, 0xffff0000, v161
	v_lshlrev_b32_e32 v122, 16, v162
	v_and_b32_e32 v123, 0xffff0000, v162
	v_lshlrev_b32_e32 v124, 16, v163
	v_and_b32_e32 v125, 0xffff0000, v163
	v_cndmask_b32_e64 v164, 0, v164, s[4:5]
	v_cndmask_b32_e64 v165, 0, v165, s[4:5]
	v_cndmask_b32_e64 v166, 0, v166, s[4:5]
	v_cndmask_b32_e64 v167, 0, v167, s[4:5]
	v_lshlrev_b32_e32 v126, 16, v164
	v_and_b32_e32 v127, 0xffff0000, v164
	v_lshlrev_b32_e32 v128, 16, v165
	v_and_b32_e32 v129, 0xffff0000, v165
	v_lshlrev_b32_e32 v130, 16, v166
	v_and_b32_e32 v131, 0xffff0000, v166
	v_lshlrev_b32_e32 v132, 16, v167
	v_and_b32_e32 v133, 0xffff0000, v167
	global_load_dwordx4 v[160:163], v[102:103], off offset:3392
	global_load_dwordx4 v[164:167], v[104:105], off offset:320
	v_sub_f32_e32 v126, v126, v118
	v_sub_f32_e32 v127, v127, v119
	v_sub_f32_e32 v128, v128, v120
	v_sub_f32_e32 v129, v129, v121
	v_sub_f32_e32 v130, v130, v122
	v_sub_f32_e32 v131, v131, v123
	v_sub_f32_e32 v132, v132, v124
	v_sub_f32_e32 v133, v133, v125
	v_fmac_f32_e32 v118, v126, v168
	v_fmac_f32_e32 v119, v127, v169
	v_fmac_f32_e32 v120, v128, v170
	v_fmac_f32_e32 v121, v129, v171
	v_fmac_f32_e32 v122, v130, v172
	v_fmac_f32_e32 v123, v131, v173
	v_fmac_f32_e32 v124, v132, v174
	v_fmac_f32_e32 v125, v133, v175
	global_load_dwordx4 v[168:171], v[108:109], off offset:640
	global_load_dwordx4 v[172:175], v[108:109], off offset:656
	v_cvt_pk_bf16_f32 v98, v118, v119
	v_cvt_pk_bf16_f32 v99, v120, v121
	v_cvt_pk_bf16_f32 v100, v122, v123
	v_cvt_pk_bf16_f32 v101, v124, v125
	v_cndmask_b32_e64 v98, 0, v98, s[2:3]
	v_cndmask_b32_e64 v99, 0, v99, s[2:3]
	v_cndmask_b32_e64 v100, 0, v100, s[2:3]
	v_cndmask_b32_e64 v101, 0, v101, s[2:3]
	s_nop 1
	v_mfma_f32_32x32x16_bf16 v[0:15], v[98:101], v[226:229], v[0:15]
	v_mfma_f32_32x32x16_bf16 v[16:31], v[98:101], v[238:241], v[16:31]
	global_load_dwordx4 v[226:229], v[114:115], off offset:96
	global_load_dwordx4 v[238:241], v[116:117], off offset:96
	s_waitcnt vmcnt(14)
	v_lshlrev_b32_e32 v118, 16, v176
	v_and_b32_e32 v119, 0xffff0000, v176
	v_lshlrev_b32_e32 v120, 16, v177
	v_and_b32_e32 v121, 0xffff0000, v177
	v_lshlrev_b32_e32 v122, 16, v178
	v_and_b32_e32 v123, 0xffff0000, v178
	v_lshlrev_b32_e32 v124, 16, v179
	v_and_b32_e32 v125, 0xffff0000, v179
	v_cndmask_b32_e64 v180, 0, v180, s[4:5]
	v_cndmask_b32_e64 v181, 0, v181, s[4:5]
	v_cndmask_b32_e64 v182, 0, v182, s[4:5]
	v_cndmask_b32_e64 v183, 0, v183, s[4:5]
	v_lshlrev_b32_e32 v126, 16, v180
	v_and_b32_e32 v127, 0xffff0000, v180
	v_lshlrev_b32_e32 v128, 16, v181
	v_and_b32_e32 v129, 0xffff0000, v181
	v_lshlrev_b32_e32 v130, 16, v182
	v_and_b32_e32 v131, 0xffff0000, v182
	v_lshlrev_b32_e32 v132, 16, v183
	v_and_b32_e32 v133, 0xffff0000, v183
	global_load_dwordx4 v[176:179], v[102:103], off offset:3424
	global_load_dwordx4 v[180:183], v[104:105], off offset:352
	v_sub_f32_e32 v126, v126, v118
	v_sub_f32_e32 v127, v127, v119
	v_sub_f32_e32 v128, v128, v120
	v_sub_f32_e32 v129, v129, v121
	v_sub_f32_e32 v130, v130, v122
	v_sub_f32_e32 v131, v131, v123
	v_sub_f32_e32 v132, v132, v124
	v_sub_f32_e32 v133, v133, v125
	v_fmac_f32_e32 v118, v126, v184
	v_fmac_f32_e32 v119, v127, v185
	v_fmac_f32_e32 v120, v128, v186
	v_fmac_f32_e32 v121, v129, v187
	v_fmac_f32_e32 v122, v130, v188
	v_fmac_f32_e32 v123, v131, v189
	v_fmac_f32_e32 v124, v132, v190
	v_fmac_f32_e32 v125, v133, v191
	global_load_dwordx4 v[184:187], v[108:109], off offset:704
	global_load_dwordx4 v[188:191], v[108:109], off offset:720
	v_mul_f32_e32 v126, 0xbfb8aa3b, v118
	v_mul_f32_e32 v127, 0xbfb8aa3b, v119
	v_mul_f32_e32 v128, 0xbfb8aa3b, v120
	v_mul_f32_e32 v129, 0xbfb8aa3b, v121
	v_mul_f32_e32 v130, 0xbfb8aa3b, v122
	v_mul_f32_e32 v131, 0xbfb8aa3b, v123
	v_mul_f32_e32 v132, 0xbfb8aa3b, v124
	v_mul_f32_e32 v133, 0xbfb8aa3b, v125
	v_exp_f32_e32 v126, v126
	v_exp_f32_e32 v127, v127
	v_exp_f32_e32 v128, v128
	v_exp_f32_e32 v129, v129
	v_exp_f32_e32 v130, v130
	v_exp_f32_e32 v131, v131
	v_exp_f32_e32 v132, v132
	v_exp_f32_e32 v133, v133
	v_add_f32_e32 v126, 1.0, v126
	v_add_f32_e32 v127, 1.0, v127
	v_add_f32_e32 v128, 1.0, v128
	v_add_f32_e32 v129, 1.0, v129
	v_add_f32_e32 v130, 1.0, v130
	v_add_f32_e32 v131, 1.0, v131
	v_add_f32_e32 v132, 1.0, v132
	v_add_f32_e32 v133, 1.0, v133
	v_rcp_f32_e32 v126, v126
	v_rcp_f32_e32 v127, v127
	v_rcp_f32_e32 v128, v128
	v_rcp_f32_e32 v129, v129
	v_rcp_f32_e32 v130, v130
	v_rcp_f32_e32 v131, v131
	v_rcp_f32_e32 v132, v132
	v_rcp_f32_e32 v133, v133
	s_nop 0
	v_cvt_pk_bf16_f32 v98, v126, v127
	v_cvt_pk_bf16_f32 v99, v128, v129
	v_cvt_pk_bf16_f32 v100, v130, v131
	v_cvt_pk_bf16_f32 v101, v132, v133
	v_cndmask_b32_e64 v98, 0, v98, s[2:3]
	v_cndmask_b32_e64 v99, 0, v99, s[2:3]
	v_cndmask_b32_e64 v100, 0, v100, s[2:3]
	v_cndmask_b32_e64 v101, 0, v101, s[2:3]
	s_nop 1
	v_mfma_f32_32x32x16_bf16 v[80:95], v[98:101], v[192:195], 0
	v_mfma_f32_32x32x16_bf16 v[64:79], v[98:101], v[196:199], 0
	global_load_dwordx4 v[192:195], v[114:115], off offset:128
	global_load_dwordx4 v[196:199], v[116:117], off offset:128
	s_waitcnt vmcnt(14)
	v_lshlrev_b32_e32 v118, 16, v144
	v_and_b32_e32 v119, 0xffff0000, v144
	v_lshlrev_b32_e32 v120, 16, v145
	v_and_b32_e32 v121, 0xffff0000, v145
	v_lshlrev_b32_e32 v122, 16, v146
	v_and_b32_e32 v123, 0xffff0000, v146
	v_lshlrev_b32_e32 v124, 16, v147
	v_and_b32_e32 v125, 0xffff0000, v147
	v_cndmask_b32_e64 v148, 0, v148, s[4:5]
	v_cndmask_b32_e64 v149, 0, v149, s[4:5]
	v_cndmask_b32_e64 v150, 0, v150, s[4:5]
	v_cndmask_b32_e64 v151, 0, v151, s[4:5]
	v_lshlrev_b32_e32 v126, 16, v148
	v_and_b32_e32 v127, 0xffff0000, v148
	v_lshlrev_b32_e32 v128, 16, v149
	v_and_b32_e32 v129, 0xffff0000, v149
	v_lshlrev_b32_e32 v130, 16, v150
	v_and_b32_e32 v131, 0xffff0000, v150
	v_lshlrev_b32_e32 v132, 16, v151
	v_and_b32_e32 v133, 0xffff0000, v151
	global_load_dwordx4 v[144:147], v[102:103], off offset:3456
	global_load_dwordx4 v[148:151], v[104:105], off offset:384
	v_sub_f32_e32 v126, v126, v118
	v_sub_f32_e32 v127, v127, v119
	v_sub_f32_e32 v128, v128, v120
	v_sub_f32_e32 v129, v129, v121
	v_sub_f32_e32 v130, v130, v122
	v_sub_f32_e32 v131, v131, v123
	v_sub_f32_e32 v132, v132, v124
	v_sub_f32_e32 v133, v133, v125
	v_fmac_f32_e32 v118, v126, v152
	v_fmac_f32_e32 v119, v127, v153
	v_fmac_f32_e32 v120, v128, v154
	v_fmac_f32_e32 v121, v129, v155
	v_fmac_f32_e32 v122, v130, v156
	v_fmac_f32_e32 v123, v131, v157
	v_fmac_f32_e32 v124, v132, v158
	v_fmac_f32_e32 v125, v133, v159
	global_load_dwordx4 v[152:155], v[108:109], off offset:768
	global_load_dwordx4 v[156:159], v[108:109], off offset:784
	v_mul_f32_e32 v126, 0xbfb8aa3b, v118
	v_mul_f32_e32 v127, 0xbfb8aa3b, v119
	v_mul_f32_e32 v128, 0xbfb8aa3b, v120
	v_mul_f32_e32 v129, 0xbfb8aa3b, v121
	v_mul_f32_e32 v130, 0xbfb8aa3b, v122
	v_mul_f32_e32 v131, 0xbfb8aa3b, v123
	v_mul_f32_e32 v132, 0xbfb8aa3b, v124
	v_mul_f32_e32 v133, 0xbfb8aa3b, v125
	v_exp_f32_e32 v126, v126
	v_exp_f32_e32 v127, v127
	v_exp_f32_e32 v128, v128
	v_exp_f32_e32 v129, v129
	v_exp_f32_e32 v130, v130
	v_exp_f32_e32 v131, v131
	v_exp_f32_e32 v132, v132
	v_exp_f32_e32 v133, v133
	v_add_f32_e32 v126, 1.0, v126
	v_add_f32_e32 v127, 1.0, v127
	v_add_f32_e32 v128, 1.0, v128
	v_add_f32_e32 v129, 1.0, v129
	v_add_f32_e32 v130, 1.0, v130
	v_add_f32_e32 v131, 1.0, v131
	v_add_f32_e32 v132, 1.0, v132
	v_add_f32_e32 v133, 1.0, v133
	v_rcp_f32_e32 v126, v126
	v_rcp_f32_e32 v127, v127
	v_rcp_f32_e32 v128, v128
	v_rcp_f32_e32 v129, v129
	v_rcp_f32_e32 v130, v130
	v_rcp_f32_e32 v131, v131
	v_rcp_f32_e32 v132, v132
	v_rcp_f32_e32 v133, v133
	s_nop 0
	v_cvt_pk_bf16_f32 v98, v126, v127
	v_cvt_pk_bf16_f32 v99, v128, v129
	v_cvt_pk_bf16_f32 v100, v130, v131
	v_cvt_pk_bf16_f32 v101, v132, v133
	v_cndmask_b32_e64 v98, 0, v98, s[2:3]
	v_cndmask_b32_e64 v99, 0, v99, s[2:3]
	v_cndmask_b32_e64 v100, 0, v100, s[2:3]
	v_cndmask_b32_e64 v101, 0, v101, s[2:3]
	s_nop 1
	v_mfma_f32_32x32x16_bf16 v[80:95], v[98:101], v[200:203], v[80:95]
	v_mfma_f32_32x32x16_bf16 v[64:79], v[98:101], v[204:207], v[64:79]
	global_load_dwordx4 v[200:203], v[114:115], off offset:160
	global_load_dwordx4 v[204:207], v[116:117], off offset:160
	s_waitcnt vmcnt(14)
	v_lshlrev_b32_e32 v118, 16, v160
	v_and_b32_e32 v119, 0xffff0000, v160
	v_lshlrev_b32_e32 v120, 16, v161
	v_and_b32_e32 v121, 0xffff0000, v161
	v_lshlrev_b32_e32 v122, 16, v162
	v_and_b32_e32 v123, 0xffff0000, v162
	v_lshlrev_b32_e32 v124, 16, v163
	v_and_b32_e32 v125, 0xffff0000, v163
	v_cndmask_b32_e64 v164, 0, v164, s[4:5]
	v_cndmask_b32_e64 v165, 0, v165, s[4:5]
	v_cndmask_b32_e64 v166, 0, v166, s[4:5]
	v_cndmask_b32_e64 v167, 0, v167, s[4:5]
	v_lshlrev_b32_e32 v126, 16, v164
	v_and_b32_e32 v127, 0xffff0000, v164
	v_lshlrev_b32_e32 v128, 16, v165
	v_and_b32_e32 v129, 0xffff0000, v165
	v_lshlrev_b32_e32 v130, 16, v166
	v_and_b32_e32 v131, 0xffff0000, v166
	v_lshlrev_b32_e32 v132, 16, v167
	v_and_b32_e32 v133, 0xffff0000, v167
	global_load_dwordx4 v[160:163], v[102:103], off offset:3488
	global_load_dwordx4 v[164:167], v[104:105], off offset:416
	v_sub_f32_e32 v126, v126, v118
	v_sub_f32_e32 v127, v127, v119
	v_sub_f32_e32 v128, v128, v120
	v_sub_f32_e32 v129, v129, v121
	v_sub_f32_e32 v130, v130, v122
	v_sub_f32_e32 v131, v131, v123
	v_sub_f32_e32 v132, v132, v124
	v_sub_f32_e32 v133, v133, v125
	v_fmac_f32_e32 v118, v126, v168
	v_fmac_f32_e32 v119, v127, v169
	v_fmac_f32_e32 v120, v128, v170
	v_fmac_f32_e32 v121, v129, v171
	v_fmac_f32_e32 v122, v130, v172
	v_fmac_f32_e32 v123, v131, v173
	v_fmac_f32_e32 v124, v132, v174
	v_fmac_f32_e32 v125, v133, v175
	global_load_dwordx4 v[168:171], v[108:109], off offset:832
	global_load_dwordx4 v[172:175], v[108:109], off offset:848
	v_mul_f32_e32 v126, 0xbfb8aa3b, v118
	v_mul_f32_e32 v127, 0xbfb8aa3b, v119
	v_mul_f32_e32 v128, 0xbfb8aa3b, v120
	v_mul_f32_e32 v129, 0xbfb8aa3b, v121
	v_mul_f32_e32 v130, 0xbfb8aa3b, v122
	v_mul_f32_e32 v131, 0xbfb8aa3b, v123
	v_mul_f32_e32 v132, 0xbfb8aa3b, v124
	v_mul_f32_e32 v133, 0xbfb8aa3b, v125
	v_exp_f32_e32 v126, v126
	v_exp_f32_e32 v127, v127
	v_exp_f32_e32 v128, v128
	v_exp_f32_e32 v129, v129
	v_exp_f32_e32 v130, v130
	v_exp_f32_e32 v131, v131
	v_exp_f32_e32 v132, v132
	v_exp_f32_e32 v133, v133
	v_add_f32_e32 v126, 1.0, v126
	v_add_f32_e32 v127, 1.0, v127
	v_add_f32_e32 v128, 1.0, v128
	v_add_f32_e32 v129, 1.0, v129
	v_add_f32_e32 v130, 1.0, v130
	v_add_f32_e32 v131, 1.0, v131
	v_add_f32_e32 v132, 1.0, v132
	v_add_f32_e32 v133, 1.0, v133
	v_rcp_f32_e32 v126, v126
	v_rcp_f32_e32 v127, v127
	v_rcp_f32_e32 v128, v128
	v_rcp_f32_e32 v129, v129
	v_rcp_f32_e32 v130, v130
	v_rcp_f32_e32 v131, v131
	v_rcp_f32_e32 v132, v132
	v_rcp_f32_e32 v133, v133
	s_nop 0
	v_cvt_pk_bf16_f32 v98, v126, v127
	v_cvt_pk_bf16_f32 v99, v128, v129
	v_cvt_pk_bf16_f32 v100, v130, v131
	v_cvt_pk_bf16_f32 v101, v132, v133
	v_cndmask_b32_e64 v98, 0, v98, s[2:3]
	v_cndmask_b32_e64 v99, 0, v99, s[2:3]
	v_cndmask_b32_e64 v100, 0, v100, s[2:3]
	v_cndmask_b32_e64 v101, 0, v101, s[2:3]
	s_nop 1
	v_mfma_f32_32x32x16_bf16 v[80:95], v[98:101], v[208:211], v[80:95]
	v_mfma_f32_32x32x16_bf16 v[64:79], v[98:101], v[222:225], v[64:79]
	global_load_dwordx4 v[208:211], v[114:115], off offset:192
	global_load_dwordx4 v[222:225], v[116:117], off offset:192
	s_waitcnt vmcnt(14)
	v_lshlrev_b32_e32 v118, 16, v176
	v_and_b32_e32 v119, 0xffff0000, v176
	v_lshlrev_b32_e32 v120, 16, v177
	v_and_b32_e32 v121, 0xffff0000, v177
	v_lshlrev_b32_e32 v122, 16, v178
	v_and_b32_e32 v123, 0xffff0000, v178
	v_lshlrev_b32_e32 v124, 16, v179
	v_and_b32_e32 v125, 0xffff0000, v179
	v_cndmask_b32_e64 v180, 0, v180, s[4:5]
	v_cndmask_b32_e64 v181, 0, v181, s[4:5]
	v_cndmask_b32_e64 v182, 0, v182, s[4:5]
	v_cndmask_b32_e64 v183, 0, v183, s[4:5]
	v_lshlrev_b32_e32 v126, 16, v180
	v_and_b32_e32 v127, 0xffff0000, v180
	v_lshlrev_b32_e32 v128, 16, v181
	v_and_b32_e32 v129, 0xffff0000, v181
	v_lshlrev_b32_e32 v130, 16, v182
	v_and_b32_e32 v131, 0xffff0000, v182
	v_lshlrev_b32_e32 v132, 16, v183
	v_and_b32_e32 v133, 0xffff0000, v183
	global_load_dwordx4 v[176:179], v[102:103], off offset:3520
	global_load_dwordx4 v[180:183], v[104:105], off offset:448
	v_sub_f32_e32 v126, v126, v118
	v_sub_f32_e32 v127, v127, v119
	v_sub_f32_e32 v128, v128, v120
	v_sub_f32_e32 v129, v129, v121
	v_sub_f32_e32 v130, v130, v122
	v_sub_f32_e32 v131, v131, v123
	v_sub_f32_e32 v132, v132, v124
	v_sub_f32_e32 v133, v133, v125
	v_fmac_f32_e32 v118, v126, v184
	v_fmac_f32_e32 v119, v127, v185
	v_fmac_f32_e32 v120, v128, v186
	v_fmac_f32_e32 v121, v129, v187
	v_fmac_f32_e32 v122, v130, v188
	v_fmac_f32_e32 v123, v131, v189
	v_fmac_f32_e32 v124, v132, v190
	v_fmac_f32_e32 v125, v133, v191
	global_load_dwordx4 v[184:187], v[108:109], off offset:896
	global_load_dwordx4 v[188:191], v[108:109], off offset:912
	v_mul_f32_e32 v126, 0xbfb8aa3b, v118
	v_mul_f32_e32 v127, 0xbfb8aa3b, v119
	v_mul_f32_e32 v128, 0xbfb8aa3b, v120
	v_mul_f32_e32 v129, 0xbfb8aa3b, v121
	v_mul_f32_e32 v130, 0xbfb8aa3b, v122
	v_mul_f32_e32 v131, 0xbfb8aa3b, v123
	v_mul_f32_e32 v132, 0xbfb8aa3b, v124
	v_mul_f32_e32 v133, 0xbfb8aa3b, v125
	v_exp_f32_e32 v126, v126
	v_exp_f32_e32 v127, v127
	v_exp_f32_e32 v128, v128
	v_exp_f32_e32 v129, v129
	v_exp_f32_e32 v130, v130
	v_exp_f32_e32 v131, v131
	v_exp_f32_e32 v132, v132
	v_exp_f32_e32 v133, v133
	v_add_f32_e32 v126, 1.0, v126
	v_add_f32_e32 v127, 1.0, v127
	v_add_f32_e32 v128, 1.0, v128
	v_add_f32_e32 v129, 1.0, v129
	v_add_f32_e32 v130, 1.0, v130
	v_add_f32_e32 v131, 1.0, v131
	v_add_f32_e32 v132, 1.0, v132
	v_add_f32_e32 v133, 1.0, v133
	v_rcp_f32_e32 v126, v126
	v_rcp_f32_e32 v127, v127
	v_rcp_f32_e32 v128, v128
	v_rcp_f32_e32 v129, v129
	v_rcp_f32_e32 v130, v130
	v_rcp_f32_e32 v131, v131
	v_rcp_f32_e32 v132, v132
	v_rcp_f32_e32 v133, v133
	s_nop 0
	v_cvt_pk_bf16_f32 v98, v126, v127
	v_cvt_pk_bf16_f32 v99, v128, v129
	v_cvt_pk_bf16_f32 v100, v130, v131
	v_cvt_pk_bf16_f32 v101, v132, v133
	v_cndmask_b32_e64 v98, 0, v98, s[2:3]
	v_cndmask_b32_e64 v99, 0, v99, s[2:3]
	v_cndmask_b32_e64 v100, 0, v100, s[2:3]
	v_cndmask_b32_e64 v101, 0, v101, s[2:3]
	s_nop 1
	v_mfma_f32_32x32x16_bf16 v[80:95], v[98:101], v[226:229], v[80:95]
	v_mfma_f32_32x32x16_bf16 v[64:79], v[98:101], v[238:241], v[64:79]
	global_load_dwordx4 v[226:229], v[114:115], off offset:224
	global_load_dwordx4 v[238:241], v[116:117], off offset:224
	s_waitcnt vmcnt(14)
	v_lshlrev_b32_e32 v118, 16, v144
	v_and_b32_e32 v119, 0xffff0000, v144
	v_lshlrev_b32_e32 v120, 16, v145
	v_and_b32_e32 v121, 0xffff0000, v145
	v_lshlrev_b32_e32 v122, 16, v146
	v_and_b32_e32 v123, 0xffff0000, v146
	v_lshlrev_b32_e32 v124, 16, v147
	v_and_b32_e32 v125, 0xffff0000, v147
	v_cndmask_b32_e64 v148, 0, v148, s[4:5]
	v_cndmask_b32_e64 v149, 0, v149, s[4:5]
	v_cndmask_b32_e64 v150, 0, v150, s[4:5]
	v_cndmask_b32_e64 v151, 0, v151, s[4:5]
	v_lshlrev_b32_e32 v126, 16, v148
	v_and_b32_e32 v127, 0xffff0000, v148
	v_lshlrev_b32_e32 v128, 16, v149
	v_and_b32_e32 v129, 0xffff0000, v149
	v_lshlrev_b32_e32 v130, 16, v150
	v_and_b32_e32 v131, 0xffff0000, v150
	v_lshlrev_b32_e32 v132, 16, v151
	v_and_b32_e32 v133, 0xffff0000, v151
	global_load_dwordx4 v[144:147], v[102:103], off offset:3552
	global_load_dwordx4 v[148:151], v[104:105], off offset:480
	v_sub_f32_e32 v126, v126, v118
	v_sub_f32_e32 v127, v127, v119
	v_sub_f32_e32 v128, v128, v120
	v_sub_f32_e32 v129, v129, v121
	v_sub_f32_e32 v130, v130, v122
	v_sub_f32_e32 v131, v131, v123
	v_sub_f32_e32 v132, v132, v124
	v_sub_f32_e32 v133, v133, v125
	v_fmac_f32_e32 v118, v126, v152
	v_fmac_f32_e32 v119, v127, v153
	v_fmac_f32_e32 v120, v128, v154
	v_fmac_f32_e32 v121, v129, v155
	v_fmac_f32_e32 v122, v130, v156
	v_fmac_f32_e32 v123, v131, v157
	v_fmac_f32_e32 v124, v132, v158
	v_fmac_f32_e32 v125, v133, v159
	global_load_dwordx4 v[152:155], v[108:109], off offset:960
	global_load_dwordx4 v[156:159], v[108:109], off offset:976
	v_mul_f32_e32 v126, 0xbfb8aa3b, v118
	v_mul_f32_e32 v127, 0xbfb8aa3b, v119
	v_mul_f32_e32 v128, 0xbfb8aa3b, v120
	v_mul_f32_e32 v129, 0xbfb8aa3b, v121
	v_mul_f32_e32 v130, 0xbfb8aa3b, v122
	v_mul_f32_e32 v131, 0xbfb8aa3b, v123
	v_mul_f32_e32 v132, 0xbfb8aa3b, v124
	v_mul_f32_e32 v133, 0xbfb8aa3b, v125
	v_exp_f32_e32 v126, v126
	v_exp_f32_e32 v127, v127
	v_exp_f32_e32 v128, v128
	v_exp_f32_e32 v129, v129
	v_exp_f32_e32 v130, v130
	v_exp_f32_e32 v131, v131
	v_exp_f32_e32 v132, v132
	v_exp_f32_e32 v133, v133
	v_add_f32_e32 v126, 1.0, v126
	v_add_f32_e32 v127, 1.0, v127
	v_add_f32_e32 v128, 1.0, v128
	v_add_f32_e32 v129, 1.0, v129
	v_add_f32_e32 v130, 1.0, v130
	v_add_f32_e32 v131, 1.0, v131
	v_add_f32_e32 v132, 1.0, v132
	v_add_f32_e32 v133, 1.0, v133
	v_rcp_f32_e32 v126, v126
	v_rcp_f32_e32 v127, v127
	v_rcp_f32_e32 v128, v128
	v_rcp_f32_e32 v129, v129
	v_rcp_f32_e32 v130, v130
	v_rcp_f32_e32 v131, v131
	v_rcp_f32_e32 v132, v132
	v_rcp_f32_e32 v133, v133
	s_nop 0
	v_cvt_pk_bf16_f32 v98, v126, v127
	v_cvt_pk_bf16_f32 v99, v128, v129
	v_cvt_pk_bf16_f32 v100, v130, v131
	v_cvt_pk_bf16_f32 v101, v132, v133
	v_cndmask_b32_e64 v98, 0, v98, s[2:3]
	v_cndmask_b32_e64 v99, 0, v99, s[2:3]
	v_cndmask_b32_e64 v100, 0, v100, s[2:3]
	v_cndmask_b32_e64 v101, 0, v101, s[2:3]
	s_nop 1
	v_mfma_f32_32x32x16_bf16 v[80:95], v[98:101], v[192:195], v[80:95]
	v_mfma_f32_32x32x16_bf16 v[64:79], v[98:101], v[196:199], v[64:79]
	s_waitcnt vmcnt(12)
	v_lshlrev_b32_e32 v118, 16, v160
	v_and_b32_e32 v119, 0xffff0000, v160
	v_lshlrev_b32_e32 v120, 16, v161
	v_and_b32_e32 v121, 0xffff0000, v161
	v_lshlrev_b32_e32 v122, 16, v162
	v_and_b32_e32 v123, 0xffff0000, v162
	v_lshlrev_b32_e32 v124, 16, v163
	v_and_b32_e32 v125, 0xffff0000, v163
	v_cndmask_b32_e64 v164, 0, v164, s[4:5]
	v_cndmask_b32_e64 v165, 0, v165, s[4:5]
	v_cndmask_b32_e64 v166, 0, v166, s[4:5]
	v_cndmask_b32_e64 v167, 0, v167, s[4:5]
	v_lshlrev_b32_e32 v126, 16, v164
	v_and_b32_e32 v127, 0xffff0000, v164
	v_lshlrev_b32_e32 v128, 16, v165
	v_and_b32_e32 v129, 0xffff0000, v165
	v_lshlrev_b32_e32 v130, 16, v166
	v_and_b32_e32 v131, 0xffff0000, v166
	v_lshlrev_b32_e32 v132, 16, v167
	v_and_b32_e32 v133, 0xffff0000, v167
	v_sub_f32_e32 v126, v126, v118
	v_sub_f32_e32 v127, v127, v119
	v_sub_f32_e32 v128, v128, v120
	v_sub_f32_e32 v129, v129, v121
	v_sub_f32_e32 v130, v130, v122
	v_sub_f32_e32 v131, v131, v123
	v_sub_f32_e32 v132, v132, v124
	v_sub_f32_e32 v133, v133, v125
	v_fmac_f32_e32 v118, v126, v168
	v_fmac_f32_e32 v119, v127, v169
	v_fmac_f32_e32 v120, v128, v170
	v_fmac_f32_e32 v121, v129, v171
	v_fmac_f32_e32 v122, v130, v172
	v_fmac_f32_e32 v123, v131, v173
	v_fmac_f32_e32 v124, v132, v174
	v_fmac_f32_e32 v125, v133, v175
	v_mul_f32_e32 v126, 0xbfb8aa3b, v118
	v_mul_f32_e32 v127, 0xbfb8aa3b, v119
	v_mul_f32_e32 v128, 0xbfb8aa3b, v120
	v_mul_f32_e32 v129, 0xbfb8aa3b, v121
	v_mul_f32_e32 v130, 0xbfb8aa3b, v122
	v_mul_f32_e32 v131, 0xbfb8aa3b, v123
	v_mul_f32_e32 v132, 0xbfb8aa3b, v124
	v_mul_f32_e32 v133, 0xbfb8aa3b, v125
	v_exp_f32_e32 v126, v126
	v_exp_f32_e32 v127, v127
	v_exp_f32_e32 v128, v128
	v_exp_f32_e32 v129, v129
	v_exp_f32_e32 v130, v130
	v_exp_f32_e32 v131, v131
	v_exp_f32_e32 v132, v132
	v_exp_f32_e32 v133, v133
	v_add_f32_e32 v126, 1.0, v126
	v_add_f32_e32 v127, 1.0, v127
	v_add_f32_e32 v128, 1.0, v128
	v_add_f32_e32 v129, 1.0, v129
	v_add_f32_e32 v130, 1.0, v130
	v_add_f32_e32 v131, 1.0, v131
	v_add_f32_e32 v132, 1.0, v132
	v_add_f32_e32 v133, 1.0, v133
	v_rcp_f32_e32 v126, v126
	v_rcp_f32_e32 v127, v127
	v_rcp_f32_e32 v128, v128
	v_rcp_f32_e32 v129, v129
	v_rcp_f32_e32 v130, v130
	v_rcp_f32_e32 v131, v131
	v_rcp_f32_e32 v132, v132
	v_rcp_f32_e32 v133, v133
	s_nop 0
	v_cvt_pk_bf16_f32 v98, v126, v127
	v_cvt_pk_bf16_f32 v99, v128, v129
	v_cvt_pk_bf16_f32 v100, v130, v131
	v_cvt_pk_bf16_f32 v101, v132, v133
	v_cndmask_b32_e64 v98, 0, v98, s[2:3]
	v_cndmask_b32_e64 v99, 0, v99, s[2:3]
	v_cndmask_b32_e64 v100, 0, v100, s[2:3]
	v_cndmask_b32_e64 v101, 0, v101, s[2:3]
	s_nop 1
	v_mfma_f32_32x32x16_bf16 v[80:95], v[98:101], v[200:203], v[80:95]
	v_mfma_f32_32x32x16_bf16 v[64:79], v[98:101], v[204:207], v[64:79]
	s_waitcnt vmcnt(6)
	v_lshlrev_b32_e32 v118, 16, v176
	v_and_b32_e32 v119, 0xffff0000, v176
	v_lshlrev_b32_e32 v120, 16, v177
	v_and_b32_e32 v121, 0xffff0000, v177
	v_lshlrev_b32_e32 v122, 16, v178
	v_and_b32_e32 v123, 0xffff0000, v178
	v_lshlrev_b32_e32 v124, 16, v179
	v_and_b32_e32 v125, 0xffff0000, v179
	v_cndmask_b32_e64 v180, 0, v180, s[4:5]
	v_cndmask_b32_e64 v181, 0, v181, s[4:5]
	v_cndmask_b32_e64 v182, 0, v182, s[4:5]
	v_cndmask_b32_e64 v183, 0, v183, s[4:5]
	v_lshlrev_b32_e32 v126, 16, v180
	v_and_b32_e32 v127, 0xffff0000, v180
	v_lshlrev_b32_e32 v128, 16, v181
	v_and_b32_e32 v129, 0xffff0000, v181
	v_lshlrev_b32_e32 v130, 16, v182
	v_and_b32_e32 v131, 0xffff0000, v182
	v_lshlrev_b32_e32 v132, 16, v183
	v_and_b32_e32 v133, 0xffff0000, v183
	v_sub_f32_e32 v126, v126, v118
	v_sub_f32_e32 v127, v127, v119
	v_sub_f32_e32 v128, v128, v120
	v_sub_f32_e32 v129, v129, v121
	v_sub_f32_e32 v130, v130, v122
	v_sub_f32_e32 v131, v131, v123
	v_sub_f32_e32 v132, v132, v124
	v_sub_f32_e32 v133, v133, v125
	v_fmac_f32_e32 v118, v126, v184
	v_fmac_f32_e32 v119, v127, v185
	v_fmac_f32_e32 v120, v128, v186
	v_fmac_f32_e32 v121, v129, v187
	v_fmac_f32_e32 v122, v130, v188
	v_fmac_f32_e32 v123, v131, v189
	v_fmac_f32_e32 v124, v132, v190
	v_fmac_f32_e32 v125, v133, v191
	v_mul_f32_e32 v126, 0xbfb8aa3b, v118
	v_mul_f32_e32 v127, 0xbfb8aa3b, v119
	v_mul_f32_e32 v128, 0xbfb8aa3b, v120
	v_mul_f32_e32 v129, 0xbfb8aa3b, v121
	v_mul_f32_e32 v130, 0xbfb8aa3b, v122
	v_mul_f32_e32 v131, 0xbfb8aa3b, v123
	v_mul_f32_e32 v132, 0xbfb8aa3b, v124
	v_mul_f32_e32 v133, 0xbfb8aa3b, v125
	v_exp_f32_e32 v126, v126
	v_exp_f32_e32 v127, v127
	v_exp_f32_e32 v128, v128
	v_exp_f32_e32 v129, v129
	v_exp_f32_e32 v130, v130
	v_exp_f32_e32 v131, v131
	v_exp_f32_e32 v132, v132
	v_exp_f32_e32 v133, v133
	v_add_f32_e32 v126, 1.0, v126
	v_add_f32_e32 v127, 1.0, v127
	v_add_f32_e32 v128, 1.0, v128
	v_add_f32_e32 v129, 1.0, v129
	v_add_f32_e32 v130, 1.0, v130
	v_add_f32_e32 v131, 1.0, v131
	v_add_f32_e32 v132, 1.0, v132
	v_add_f32_e32 v133, 1.0, v133
	v_rcp_f32_e32 v126, v126
	v_rcp_f32_e32 v127, v127
	v_rcp_f32_e32 v128, v128
	v_rcp_f32_e32 v129, v129
	v_rcp_f32_e32 v130, v130
	v_rcp_f32_e32 v131, v131
	v_rcp_f32_e32 v132, v132
	v_rcp_f32_e32 v133, v133
	s_nop 0
	v_cvt_pk_bf16_f32 v98, v126, v127
	v_cvt_pk_bf16_f32 v99, v128, v129
	v_cvt_pk_bf16_f32 v100, v130, v131
	v_cvt_pk_bf16_f32 v101, v132, v133
	v_cndmask_b32_e64 v98, 0, v98, s[2:3]
	v_cndmask_b32_e64 v99, 0, v99, s[2:3]
	v_cndmask_b32_e64 v100, 0, v100, s[2:3]
	v_cndmask_b32_e64 v101, 0, v101, s[2:3]
	s_nop 1
	v_mfma_f32_32x32x16_bf16 v[80:95], v[98:101], v[208:211], v[80:95]
	v_mfma_f32_32x32x16_bf16 v[64:79], v[98:101], v[222:225], v[64:79]
	s_waitcnt vmcnt(0)
	v_lshlrev_b32_e32 v118, 16, v144
	v_and_b32_e32 v119, 0xffff0000, v144
	v_lshlrev_b32_e32 v120, 16, v145
	v_and_b32_e32 v121, 0xffff0000, v145
	v_lshlrev_b32_e32 v122, 16, v146
	v_and_b32_e32 v123, 0xffff0000, v146
	v_lshlrev_b32_e32 v124, 16, v147
	v_and_b32_e32 v125, 0xffff0000, v147
	v_cndmask_b32_e64 v148, 0, v148, s[4:5]
	v_cndmask_b32_e64 v149, 0, v149, s[4:5]
	v_cndmask_b32_e64 v150, 0, v150, s[4:5]
	v_cndmask_b32_e64 v151, 0, v151, s[4:5]
	v_lshlrev_b32_e32 v126, 16, v148
	v_and_b32_e32 v127, 0xffff0000, v148
	v_lshlrev_b32_e32 v128, 16, v149
	v_and_b32_e32 v129, 0xffff0000, v149
	v_lshlrev_b32_e32 v130, 16, v150
	v_and_b32_e32 v131, 0xffff0000, v150
	v_lshlrev_b32_e32 v132, 16, v151
	v_and_b32_e32 v133, 0xffff0000, v151
	v_sub_f32_e32 v126, v126, v118
	v_sub_f32_e32 v127, v127, v119
	v_sub_f32_e32 v128, v128, v120
	v_sub_f32_e32 v129, v129, v121
	v_sub_f32_e32 v130, v130, v122
	v_sub_f32_e32 v131, v131, v123
	v_sub_f32_e32 v132, v132, v124
	v_sub_f32_e32 v133, v133, v125
	v_fmac_f32_e32 v118, v126, v152
	v_fmac_f32_e32 v119, v127, v153
	v_fmac_f32_e32 v120, v128, v154
	v_fmac_f32_e32 v121, v129, v155
	v_fmac_f32_e32 v122, v130, v156
	v_fmac_f32_e32 v123, v131, v157
	v_fmac_f32_e32 v124, v132, v158
	v_fmac_f32_e32 v125, v133, v159
	v_mul_f32_e32 v126, 0xbfb8aa3b, v118
	v_mul_f32_e32 v127, 0xbfb8aa3b, v119
	v_mul_f32_e32 v128, 0xbfb8aa3b, v120
	v_mul_f32_e32 v129, 0xbfb8aa3b, v121
	v_mul_f32_e32 v130, 0xbfb8aa3b, v122
	v_mul_f32_e32 v131, 0xbfb8aa3b, v123
	v_mul_f32_e32 v132, 0xbfb8aa3b, v124
	v_mul_f32_e32 v133, 0xbfb8aa3b, v125
	v_exp_f32_e32 v126, v126
	v_exp_f32_e32 v127, v127
	v_exp_f32_e32 v128, v128
	v_exp_f32_e32 v129, v129
	v_exp_f32_e32 v130, v130
	v_exp_f32_e32 v131, v131
	v_exp_f32_e32 v132, v132
	v_exp_f32_e32 v133, v133
	v_add_f32_e32 v126, 1.0, v126
	v_add_f32_e32 v127, 1.0, v127
	v_add_f32_e32 v128, 1.0, v128
	v_add_f32_e32 v129, 1.0, v129
	v_add_f32_e32 v130, 1.0, v130
	v_add_f32_e32 v131, 1.0, v131
	v_add_f32_e32 v132, 1.0, v132
	v_add_f32_e32 v133, 1.0, v133
	v_rcp_f32_e32 v126, v126
	v_rcp_f32_e32 v127, v127
	v_rcp_f32_e32 v128, v128
	v_rcp_f32_e32 v129, v129
	v_rcp_f32_e32 v130, v130
	v_rcp_f32_e32 v131, v131
	v_rcp_f32_e32 v132, v132
	v_rcp_f32_e32 v133, v133
	s_nop 0
	v_cvt_pk_bf16_f32 v98, v126, v127
	v_cvt_pk_bf16_f32 v99, v128, v129
	v_cvt_pk_bf16_f32 v100, v130, v131
	v_cvt_pk_bf16_f32 v101, v132, v133
	v_cndmask_b32_e64 v98, 0, v98, s[2:3]
	v_cndmask_b32_e64 v99, 0, v99, s[2:3]
	v_cndmask_b32_e64 v100, 0, v100, s[2:3]
	v_cndmask_b32_e64 v101, 0, v101, s[2:3]
	s_nop 1
	v_mfma_f32_32x32x16_bf16 v[80:95], v[98:101], v[226:229], v[80:95]
	v_mfma_f32_32x32x16_bf16 v[64:79], v[98:101], v[238:241], v[64:79]
	s_ashr_i32 s3, s10, 31
	s_add_u32 s2, s6, s10
	v_lshlrev_b32_e32 v108, 2, v138
	s_addc_u32 s3, s7, s3
	v_ashrrev_i32_e32 v109, 31, v108
	v_lshl_add_u64 v[102:103], s[2:3], 0, v[108:109]
	v_lshlrev_b64 v[98:99], 10, v[102:103]
	v_lshl_add_u64 v[98:99], s[86:87], 0, v[98:99]
	s_lshl_b32 s38, s11, 1
	v_lshl_add_u64 v[100:101], v[98:99], 0, s[38:39]
	v_lshlrev_b32_e32 v98, 1, v107
	v_mov_b32_e32 v99, v97
	v_or_b32_e32 v104, s11, v107
	v_lshl_add_u64 v[110:111], v[100:101], 0, v[98:99]
	v_or_b32_e32 v100, s34, v104
	v_mov_b32_e32 v101, s35
	v_readlane_b32 s16, v254, 50
	v_lshlrev_b64 v[100:101], 2, v[100:101]
	v_readlane_b32 s17, v254, 51
	v_readlane_b32 s18, v254, 52
	v_readlane_b32 s19, v254, 53
	v_readlane_b32 s20, v254, 54
	v_readlane_b32 s21, v254, 55
	v_readlane_b32 s22, v254, 56
	v_readlane_b32 s23, v254, 57
	v_readlane_b32 s24, v254, 58
	v_readlane_b32 s25, v254, 59
	v_readlane_b32 s26, v254, 60
	v_readlane_b32 s27, v254, 61
	v_readlane_b32 s28, v254, 62
	v_readlane_b32 s29, v254, 63
	v_readlane_b32 s30, v255, 0
	v_readlane_b32 s31, v255, 1
	v_lshl_add_u64 v[112:113], s[28:29], 0, v[100:101]
	v_readlane_b32 s16, v253, 34
	v_readlane_b32 s17, v253, 35
	global_load_dword v96, v[112:113], off
	s_nop 0
	v_lshl_add_u64 v[112:113], s[16:17], 0, v[100:101]
	global_load_dword v112, v[112:113], off
	v_cvt_pk_bf16_f32 v80, v80, v80
	global_store_short_d16_hi v[110:111], v80, off
	s_nop 0
	v_cvt_pk_bf16_f32 v80, v81, v81
	global_store_short_d16_hi v[110:111], v80, off offset:1024
	s_nop 0
	v_cvt_pk_bf16_f32 v80, v82, v82
	global_store_short_d16_hi v[110:111], v80, off offset:2048
	s_nop 0
	v_cvt_pk_bf16_f32 v80, v83, v83
	global_store_short_d16_hi v[110:111], v80, off offset:3072
	s_nop 0
	v_cvt_pk_bf16_f32 v82, v84, v84
	v_add_co_u32_e32 v80, vcc, s74, v110
	v_readlane_b32 s18, v253, 36
	s_nop 0
	v_addc_co_u32_e32 v81, vcc, 0, v111, vcc
	global_store_short_d16_hi v[80:81], v82, off
	s_nop 0
	v_cvt_pk_bf16_f32 v82, v85, v85
	global_store_short_d16_hi v[80:81], v82, off offset:1024
	s_nop 0
	v_cvt_pk_bf16_f32 v82, v86, v86
	global_store_short_d16_hi v[80:81], v82, off offset:2048
	s_nop 0
	v_cvt_pk_bf16_f32 v82, v87, v87
	global_store_short_d16_hi v[80:81], v82, off offset:3072
	v_cndmask_b32_e64 v82, 0, 1, s[0:1]
	v_cmp_ne_u32_e64 s[2:3], 1, v82
	s_andn2_b64 vcc, exec, s[0:1]
	v_readlane_b32 s19, v253, 37
	v_readlane_b32 s20, v253, 38
	v_readlane_b32 s21, v253, 39
	v_readlane_b32 s22, v253, 40
	v_readlane_b32 s23, v253, 41
	v_readlane_b32 s24, v253, 42
	v_readlane_b32 s25, v253, 43
	v_readlane_b32 s26, v253, 44
	v_readlane_b32 s27, v253, 45
	v_readlane_b32 s28, v253, 46
	v_readlane_b32 s29, v253, 47
	v_readlane_b32 s30, v253, 48
	v_readlane_b32 s31, v253, 49
	s_cbranch_vccnz .LBB0_904
	s_nop 0
	v_cvt_pk_bf16_f32 v84, v88, v88
	v_add_co_u32_e32 v82, vcc, 0x4000, v110
	s_nop 1
	v_addc_co_u32_e32 v83, vcc, 0, v111, vcc
	global_store_short_d16_hi v[82:83], v84, off
	s_and_b64 vcc, exec, s[2:3]
	s_cbranch_vccz .LBB0_905

.LBB0_899:
	s_nop 0
	v_cvt_pk_bf16_f32 v84, v90, v90
	v_add_co_u32_e32 v82, vcc, 0x4000, v110
	s_nop 1
	v_addc_co_u32_e32 v83, vcc, 0, v111, vcc
	global_store_short_d16_hi v[82:83], v84, off offset:2048
	s_and_b64 vcc, exec, s[2:3]
	s_cbranch_vccz .LBB0_907

.LBB0_901:
	s_nop 0
	v_cvt_pk_bf16_f32 v84, v92, v92
	v_add_co_u32_e32 v82, vcc, 0x6000, v110
	s_nop 1
	v_addc_co_u32_e32 v83, vcc, 0, v111, vcc
	global_store_short_d16_hi v[82:83], v84, off
	s_and_b64 vcc, exec, s[2:3]
	s_cbranch_vccz .LBB0_909

.LBB0_903:
	s_nop 0
	v_cvt_pk_bf16_f32 v84, v94, v94
	v_add_co_u32_e32 v82, vcc, 0x6000, v110
	s_nop 1
	v_addc_co_u32_e32 v83, vcc, 0, v111, vcc
	global_store_short_d16_hi v[82:83], v84, off offset:2048
	s_and_b64 vcc, exec, s[2:3]
	s_cbranch_vccz .LBB0_911
	s_branch .LBB0_912

.LBB0_905:
	s_nop 0
	v_cvt_pk_bf16_f32 v84, v89, v89
	v_add_co_u32_e32 v82, vcc, 0x4000, v110
	s_nop 1
	v_addc_co_u32_e32 v83, vcc, 0, v111, vcc
	global_store_short_d16_hi v[82:83], v84, off offset:1024
	s_and_b64 vcc, exec, s[2:3]
	s_cbranch_vccz .LBB0_899

.LBB0_907:
	s_nop 0
	v_cvt_pk_bf16_f32 v84, v91, v91
	v_add_co_u32_e32 v82, vcc, 0x4000, v110
	s_nop 1
	v_addc_co_u32_e32 v83, vcc, 0, v111, vcc
	global_store_short_d16_hi v[82:83], v84, off offset:3072
	s_and_b64 vcc, exec, s[2:3]
	s_cbranch_vccz .LBB0_901

.LBB0_909:
	s_nop 0
	v_cvt_pk_bf16_f32 v84, v93, v93
	v_add_co_u32_e32 v82, vcc, 0x6000, v110
	s_nop 1
	v_addc_co_u32_e32 v83, vcc, 0, v111, vcc
	global_store_short_d16_hi v[82:83], v84, off offset:1024
	s_and_b64 vcc, exec, s[2:3]
	s_cbranch_vccz .LBB0_903

.LBB0_911:
	s_nop 0
	v_cvt_pk_bf16_f32 v84, v95, v95
	v_add_co_u32_e32 v82, vcc, 0x6000, v110
	s_nop 1
	v_addc_co_u32_e32 v83, vcc, 0, v111, vcc
	global_store_short_d16_hi v[82:83], v84, off offset:3072
.LBB0_912:
	v_lshlrev_b32_e32 v82, 2, v104
	global_load_dword v83, v82, s[94:95] offset:128
	global_load_dword v84, v82, s[58:59] offset:128
	s_nop 0
	v_cvt_pk_bf16_f32 v64, v64, v64
	global_store_short_d16_hi v[110:111], v64, off offset:64
	s_nop 0
	v_cvt_pk_bf16_f32 v64, v65, v65
	global_store_short_d16_hi v[110:111], v64, off offset:1088
	s_nop 0
	v_cvt_pk_bf16_f32 v64, v66, v66
	global_store_short_d16_hi v[110:111], v64, off offset:2112
	s_nop 0
	v_cvt_pk_bf16_f32 v64, v67, v67
	global_store_short_d16_hi v[110:111], v64, off offset:3136
	s_nop 0
	v_cvt_pk_bf16_f32 v64, v68, v68
	global_store_short_d16_hi v[80:81], v64, off offset:64
	s_nop 0
	v_cvt_pk_bf16_f32 v64, v69, v69
	global_store_short_d16_hi v[80:81], v64, off offset:1088
	s_nop 0
	v_cvt_pk_bf16_f32 v64, v70, v70
	global_store_short_d16_hi v[80:81], v64, off offset:2112
	s_nop 0
	v_mov_b32_e32 v105, v97
	v_cvt_pk_bf16_f32 v64, v71, v71
	s_and_b64 vcc, exec, s[2:3]
	global_store_short_d16_hi v[80:81], v64, off offset:3136
	s_cbranch_vccnz .LBB0_920
	s_nop 0
	v_cvt_pk_bf16_f32 v66, v72, v72
	v_add_co_u32_e32 v64, vcc, 0x4000, v110
	s_nop 1
	v_addc_co_u32_e32 v65, vcc, 0, v111, vcc
	global_store_short_d16_hi v[64:65], v66, off offset:64
	s_and_b64 vcc, exec, s[2:3]
	s_cbranch_vccz .LBB0_921

.LBB0_915:
	s_nop 0
	v_cvt_pk_bf16_f32 v66, v74, v74
	v_add_co_u32_e32 v64, vcc, 0x4000, v110
	s_nop 1
	v_addc_co_u32_e32 v65, vcc, 0, v111, vcc
	global_store_short_d16_hi v[64:65], v66, off offset:2112
	s_and_b64 vcc, exec, s[2:3]
	s_cbranch_vccz .LBB0_923

.LBB0_917:
	s_nop 0
	v_cvt_pk_bf16_f32 v66, v76, v76
	v_add_co_u32_e32 v64, vcc, 0x6000, v110
	s_nop 1
	v_addc_co_u32_e32 v65, vcc, 0, v111, vcc
	global_store_short_d16_hi v[64:65], v66, off offset:64
	s_and_b64 vcc, exec, s[2:3]
	s_cbranch_vccz .LBB0_925

.LBB0_919:
	s_nop 0
	v_cvt_pk_bf16_f32 v66, v78, v78
	v_add_co_u32_e32 v64, vcc, 0x6000, v110
	s_nop 1
	v_addc_co_u32_e32 v65, vcc, 0, v111, vcc
	global_store_short_d16_hi v[64:65], v66, off offset:2112
	s_and_b64 vcc, exec, s[2:3]
	s_cbranch_vccz .LBB0_927
	s_branch .LBB0_928

.LBB0_921:
	s_nop 0
	v_cvt_pk_bf16_f32 v66, v73, v73
	v_add_co_u32_e32 v64, vcc, 0x4000, v110
	s_nop 1
	v_addc_co_u32_e32 v65, vcc, 0, v111, vcc
	global_store_short_d16_hi v[64:65], v66, off offset:1088
	s_and_b64 vcc, exec, s[2:3]
	s_cbranch_vccz .LBB0_915

.LBB0_923:
	s_nop 0
	v_cvt_pk_bf16_f32 v66, v75, v75
	v_add_co_u32_e32 v64, vcc, 0x4000, v110
	s_nop 1
	v_addc_co_u32_e32 v65, vcc, 0, v111, vcc
	global_store_short_d16_hi v[64:65], v66, off offset:3136
	s_and_b64 vcc, exec, s[2:3]
	s_cbranch_vccz .LBB0_917

.LBB0_925:
	s_nop 0
	v_cvt_pk_bf16_f32 v66, v77, v77
	v_add_co_u32_e32 v64, vcc, 0x6000, v110
	s_nop 1
	v_addc_co_u32_e32 v65, vcc, 0, v111, vcc
	global_store_short_d16_hi v[64:65], v66, off offset:1088
	s_and_b64 vcc, exec, s[2:3]
	s_cbranch_vccz .LBB0_919

.LBB0_927:
	s_nop 0
	v_cvt_pk_bf16_f32 v66, v79, v79
	v_add_co_u32_e32 v64, vcc, 0x6000, v110
	s_nop 1
	v_addc_co_u32_e32 v65, vcc, 0, v111, vcc
	global_store_short_d16_hi v[64:65], v66, off offset:3136

.LBB0_935:
	s_or_b64 exec, exec, s[4:5]
	s_waitcnt vmcnt(8)
	v_add_f32_e32 v16, v16, v84
	v_mul_f32_e32 v16, 0xbfb8aa3b, v16
	v_add_f32_e32 v17, v17, v84
	v_exp_f32_e32 v16, v16
	v_mul_f32_e32 v17, 0xbfb8aa3b, v17
	v_add_f32_e32 v18, v18, v84
	v_exp_f32_e32 v17, v17
	v_mul_f32_e32 v18, 0xbfb8aa3b, v18
	v_exp_f32_e32 v18, v18
	v_add_f32_e32 v16, 1.0, v16
	v_cndmask_b32_e64 v126, v79, v52, s[0:1]
	v_rcp_f32_e32 v52, v16
	v_add_f32_e32 v16, 1.0, v17
	v_add_f32_e32 v17, v19, v84
	v_cndmask_b32_e64 v124, v85, v65, s[0:1]
	v_cndmask_b32_e64 v85, v70, v53, s[0:1]
	v_rcp_f32_e32 v53, v16
	v_add_f32_e32 v16, 1.0, v18
	v_mul_f32_e32 v17, 0xbfb8aa3b, v17
	v_add_f32_e32 v18, v20, v84
	v_exp_f32_e32 v17, v17
	v_mul_f32_e32 v18, 0xbfb8aa3b, v18
	v_exp_f32_e32 v18, v18
	v_cndmask_b32_e64 v118, v73, v46, s[0:1]
	v_rcp_f32_e32 v46, v16
	v_add_f32_e32 v16, 1.0, v17
	v_add_f32_e32 v17, v21, v84
	v_add_f32_e32 v2, v2, v112
	v_cndmask_b32_e64 v127, v78, v47, s[0:1]
	v_rcp_f32_e32 v47, v16
	v_add_f32_e32 v16, 1.0, v18
	v_mul_f32_e32 v17, 0xbfb8aa3b, v17
	v_add_f32_e32 v18, v22, v84
	v_mul_f32_e32 v2, 0xbfb8aa3b, v2
	v_add_f32_e32 v3, v3, v112
	v_exp_f32_e32 v17, v17
	v_mul_f32_e32 v18, 0xbfb8aa3b, v18
	v_exp_f32_e32 v2, v2
	v_mul_f32_e32 v3, 0xbfb8aa3b, v3
	v_exp_f32_e32 v18, v18
	v_exp_f32_e32 v3, v3
	v_add_f32_e32 v4, v4, v112
	v_mul_f32_e32 v4, 0xbfb8aa3b, v4
	v_cndmask_b32_e64 v116, v77, v44, s[0:1]
	v_rcp_f32_e32 v44, v16
	v_add_f32_e32 v16, 1.0, v17
	v_add_f32_e32 v2, 1.0, v2
	v_exp_f32_e32 v4, v4
	v_readlane_b32 s16, v253, 34
	v_cndmask_b32_e64 v117, v76, v45, s[0:1]
	v_rcp_f32_e32 v45, v16
	v_add_f32_e32 v16, 1.0, v18
	v_rcp_f32_e32 v18, v2
	v_add_f32_e32 v2, 1.0, v3
	s_waitcnt lgkmcnt(0)
	v_readlane_b32 s22, v253, 40
	v_readlane_b32 s23, v253, 41
	v_rcp_f32_e32 v19, v2
	v_cndmask_b32_e64 v125, v83, v66, s[0:1]
	v_lshl_add_u64 v[2:3], s[22:23], 0, v[100:101]
	v_cndmask_b32_e64 v119, v72, v42, s[0:1]
	global_load_dword v66, v82, s[60:61] offset:2048
	global_load_dword v72, v82, s[60:61]
	global_load_dword v214, v[2:3], off
	v_add_f32_e32 v2, v5, v112
	v_add_f32_e32 v4, 1.0, v4
	v_mul_f32_e32 v2, 0xbfb8aa3b, v2
	v_exp_f32_e32 v3, v2
	global_load_dword v38, v82, s[60:61] offset:2176
	global_load_dword v42, v82, s[60:61] offset:128
	v_rcp_f32_e32 v2, v4
	v_add_f32_e32 v4, v6, v112
	v_readlane_b32 s24, v253, 42
	v_readlane_b32 s25, v253, 43
	v_mul_f32_e32 v4, 0xbfb8aa3b, v4
	v_exp_f32_e32 v6, v4
	v_lshl_add_u64 v[4:5], s[24:25], 0, v[100:101]
	v_cndmask_b32_e64 v65, v68, v62, s[0:1]
	global_load_dword v32, v82, s[82:83] offset:128
	global_load_dword v62, v[4:5], off
	v_readlane_b32 s26, v253, 44
	v_readlane_b32 s27, v253, 45
	v_cndmask_b32_e64 v35, v89, v63, s[0:1]
	v_cndmask_b32_e64 v67, v67, v57, s[0:1]
	v_lshl_add_u64 v[4:5], s[26:27], 0, v[100:101]
	global_load_dword v22, v[4:5], off
	global_load_dword v34, v82, s[70:71] offset:128
	v_cndmask_b32_e64 v89, v69, v56, s[0:1]
	v_lshl_add_u64 v[56:57], s[34:35], 0, v[104:105]
	v_lshl_add_u64 v[4:5], v[56:57], 2, s[26:27]
	global_load_dword v20, v[4:5], off offset:128
	v_add_f32_e32 v7, v7, v112
	v_mul_f32_e32 v7, 0xbfb8aa3b, v7
	v_exp_f32_e32 v7, v7
	v_add_f32_e32 v4, 1.0, v6
	v_rcp_f32_e32 v78, v4
	v_mov_b32_e32 v83, v97
	v_add_f32_e32 v4, 1.0, v7
	v_rcp_f32_e32 v79, v4
	v_add_f32_e32 v4, v8, v112
	v_mul_f32_e32 v4, 0xbfb8aa3b, v4
	v_exp_f32_e32 v6, v4
	v_lshl_add_u64 v[4:5], s[60:61], 0, v[82:83]
	s_movk_i32 s5, 0x1000
	v_add_co_u32_e32 v4, vcc, s5, v4
	v_cndmask_b32_e64 v63, v88, v64, s[0:1]
	s_nop 0
	v_addc_co_u32_e32 v5, vcc, 0, v5, vcc
	global_load_dword v64, v[4:5], off
	global_load_dword v36, v[4:5], off offset:128
	v_add_f32_e32 v17, v23, v84
	v_mul_f32_e32 v17, 0xbfb8aa3b, v17
	v_exp_f32_e32 v17, v17
	v_lshlrev_b64 v[54:55], 9, v[102:103]
	v_lshl_add_u64 v[4:5], v[54:55], 1, s[88:89]
	v_rcp_f32_e32 v40, v16
	v_add_f32_e32 v16, 1.0, v17
	v_lshl_add_u64 v[4:5], v[4:5], 0, s[38:39]
	v_mov_b32_e32 v99, v97
	v_cmp_lt_i32_e32 vcc, v246, v252
	v_rcp_f32_e32 v41, v16
	v_lshl_add_u64 v[16:17], v[4:5], 0, v[98:99]
	v_cndmask_b32_e32 v4, v217, v246, vcc
	v_cmp_lt_i32_e32 vcc, v247, v252
	v_lshlrev_b32_e32 v94, 2, v4
	s_movk_i32 s5, 0x640
	v_cndmask_b32_e32 v4, v217, v247, vcc
	v_cmp_lt_i32_e32 vcc, v248, v252
	v_lshlrev_b32_e32 v90, 2, v4
	v_add_f32_e32 v0, v0, v112
	v_cndmask_b32_e32 v4, v217, v248, vcc
	v_cmp_lt_i32_e32 vcc, v221, v252
	v_lshlrev_b32_e32 v88, 2, v4
	v_add_f32_e32 v1, v1, v112
	v_cndmask_b32_e32 v4, v217, v221, vcc
	v_lshlrev_b32_e32 v82, 2, v4
	v_mul_lo_u32 v4, v138, s5
	v_mul_f32_e32 v0, 0xbfb8aa3b, v0
	v_mul_f32_e32 v1, 0xbfb8aa3b, v1
	v_add_f32_e32 v6, 1.0, v6
	v_add3_u32 v33, s76, v4, v98
	v_cndmask_b32_e64 v140, v71, v43, s[0:1]
	v_exp_f32_e32 v0, v0
	v_exp_f32_e32 v1, v1
	v_rcp_f32_e32 v83, v6
	ds_read_u16 v21, v33 offset:256
	ds_read_u16 v4, v33 offset:128
	ds_read_u16 v5, v33
	ds_read_u16 v6, v33 offset:400
	ds_read_u16 v7, v33 offset:464
	ds_read_u16 v23, v33 offset:320
	ds_read_u16 v43, v33 offset:192
	ds_read_u16 v54, v33 offset:64
	ds_read_u16 v55, v33 offset:528
	ds_read_u16 v57, v33 offset:656
	ds_read_u16 v68, v33 offset:720
	ds_read_u16 v69, v33 offset:592
	s_waitcnt lgkmcnt(9)
	v_lshlrev_b32_e32 v56, 16, v5
	s_waitcnt lgkmcnt(8)
	v_lshlrev_b32_e32 v70, 16, v6
	v_add_f32_e32 v0, 1.0, v0
	v_add_f32_e32 v1, 1.0, v1
	v_sub_f32_e32 v6, v56, v70
	v_rcp_f32_e32 v0, v0
	v_rcp_f32_e32 v1, v1
	s_waitcnt vmcnt(10)
	v_fmac_f32_e32 v70, v72, v6
	s_waitcnt lgkmcnt(4)
	v_lshlrev_b32_e32 v6, 16, v54
	v_lshlrev_b32_e32 v56, 16, v7
	v_sub_f32_e32 v6, v6, v56
	v_lshlrev_b32_e32 v4, 16, v4
	s_waitcnt lgkmcnt(3)
	v_lshlrev_b32_e32 v55, 16, v55
	s_waitcnt vmcnt(7)
	v_fmac_f32_e32 v56, v42, v6
	v_lshlrev_b32_e32 v6, 16, v43
	s_waitcnt lgkmcnt(0)
	v_lshlrev_b32_e32 v43, 16, v69
	v_sub_f32_e32 v4, v4, v55
	v_sub_f32_e32 v6, v6, v43
	v_fmac_f32_e32 v55, v66, v4
	v_pk_add_f32 v[4:5], v[0:1], -1.0 op_sel_hi:[1,0]
	v_fmac_f32_e32 v43, v38, v6
	s_waitcnt vmcnt(6)
	v_mul_f32_e32 v54, v32, v43
	s_waitcnt vmcnt(5)
	v_pk_fma_f32 v[4:5], v[4:5], v[62:63], 1.0 op_sel_hi:[1,0,0]
	v_mul_f32_e32 v69, v54, v54
	v_mul_f32_e32 v54, v4, v55
	v_pk_add_f32 v[6:7], v[52:53], -1.0 op_sel_hi:[1,0]
	v_mul_f32_e32 v54, v70, v54
	v_mul_f32_e32 v71, v214, v55
	s_waitcnt vmcnt(4)
	v_fma_f32 v70, v22, v54, 0
	s_waitcnt vmcnt(3)
	v_pk_fma_f32 v[54:55], v[6:7], v[34:35], 1.0 op_sel_hi:[1,0,0]
	v_fmac_f32_e32 v69, v71, v71
	v_mul_f32_e32 v6, v54, v43
	v_mul_f32_e32 v6, v56, v6
	s_waitcnt vmcnt(2)
	v_fmac_f32_e32 v70, v20, v6
	ds_bpermute_b32 v6, v94, v70
	ds_bpermute_b32 v71, v94, v69
	v_cmp_lt_i32_e32 vcc, v216, v252
	v_lshlrev_b32_e32 v7, 16, v57
	v_lshlrev_b32_e32 v21, 16, v21
	s_waitcnt lgkmcnt(1)
	v_add_f32_e32 v6, v70, v6
	ds_bpermute_b32 v56, v90, v6
	v_cndmask_b32_e32 v8, v217, v216, vcc
	v_lshlrev_b32_e32 v101, 2, v8
	s_waitcnt lgkmcnt(1)
	v_add_f32_e32 v8, v69, v71
	ds_bpermute_b32 v43, v90, v8
	s_waitcnt lgkmcnt(1)
	v_add_f32_e32 v6, v6, v56
	ds_bpermute_b32 v56, v88, v6
	v_sub_f32_e32 v21, v21, v7
	s_waitcnt vmcnt(1)
	v_fmac_f32_e32 v7, v64, v21
	s_waitcnt lgkmcnt(1)
	v_add_f32_e32 v8, v8, v43
	ds_bpermute_b32 v43, v88, v8
	s_waitcnt lgkmcnt(1)
	v_add_f32_e32 v6, v6, v56
	ds_bpermute_b32 v56, v82, v6
	v_lshlrev_b32_e32 v21, 16, v68
	v_lshlrev_b32_e32 v23, 16, v23
	s_waitcnt lgkmcnt(1)
	v_add_f32_e32 v8, v8, v43
	v_sub_f32_e32 v23, v23, v21
	s_waitcnt lgkmcnt(0)
	v_add_f32_e32 v6, v6, v56
	ds_bpermute_b32 v43, v82, v8
	s_waitcnt vmcnt(0)
	v_fmac_f32_e32 v21, v36, v23
	ds_bpermute_b32 v23, v101, v6
	v_add_f32_e32 v3, 1.0, v3
	v_rcp_f32_e32 v3, v3
	s_waitcnt lgkmcnt(1)
	v_add_f32_e32 v99, v8, v43
	ds_bpermute_b32 v100, v101, v99
	s_waitcnt lgkmcnt(1)
	v_add_f32_e32 v6, v6, v23
	v_mul_f32_e32 v7, v7, v6
	s_nop 0
	v_or_b32_e32 v109, 1, v108
	s_movk_i32 s5, 0x190
	v_cvt_pk_bf16_f32 v7, v7, v7
	v_mul_f32_e32 v6, v21, v6
	v_mul_lo_u32 v8, v109, s5
	global_store_short_d16_hi v[16:17], v7, off
	s_nop 0
	s_ashr_i32 s4, s13, 31
	v_add3_u32 v135, s76, v8, v98
	v_cvt_pk_bf16_f32 v6, v6, v6
	v_readlane_b32 s17, v253, 35
	v_readlane_b32 s18, v253, 36
	v_readlane_b32 s19, v253, 37
	v_readlane_b32 s20, v253, 38
	v_readlane_b32 s21, v253, 39
	v_readlane_b32 s28, v253, 46
	v_readlane_b32 s29, v253, 47
	v_readlane_b32 s30, v253, 48
	v_readlane_b32 s31, v253, 49
	global_store_short_d16_hi v[16:17], v6, off offset:64
	ds_read_u16 v6, v135 offset:656
	ds_read_u16 v7, v135 offset:256
	ds_read_u16 v23, v135 offset:528
	ds_read_u16 v43, v135 offset:400
	ds_read_u16 v21, v135
	s_waitcnt lgkmcnt(4)
	v_lshlrev_b32_e32 v6, 16, v6
	s_waitcnt lgkmcnt(3)
	v_lshlrev_b32_e32 v7, 16, v7
	v_sub_f32_e32 v7, v7, v6
	v_fmac_f32_e32 v6, v64, v7
	ds_read_u16 v7, v135 offset:128
	s_waitcnt lgkmcnt(3)
	v_lshlrev_b32_e32 v23, 16, v23
	s_waitcnt lgkmcnt(1)
	v_lshlrev_b32_e32 v21, 16, v21
	v_lshlrev_b32_e32 v43, 16, v43
	v_sub_f32_e32 v21, v21, v43
	s_waitcnt lgkmcnt(0)
	v_lshlrev_b32_e32 v7, 16, v7
	v_sub_f32_e32 v7, v7, v23
	v_fmac_f32_e32 v23, v66, v7
	v_mul_f32_e32 v7, v5, v23
	v_fmac_f32_e32 v43, v72, v21
	v_mul_f32_e32 v7, v43, v7
	ds_read_u16 v21, v135 offset:720
	ds_read_u16 v43, v135 offset:320
	v_fma_f32 v7, v22, v7, 0
	ds_read_u16 v56, v135 offset:464
	v_mul_f32_e32 v23, v214, v23
	s_waitcnt lgkmcnt(2)
	v_lshlrev_b32_e32 v21, 16, v21
	s_waitcnt lgkmcnt(1)
	v_lshlrev_b32_e32 v43, 16, v43
	v_sub_f32_e32 v43, v43, v21
	v_fmac_f32_e32 v21, v36, v43
	ds_read_u16 v43, v135 offset:64
	s_waitcnt lgkmcnt(1)
	v_lshlrev_b32_e32 v56, 16, v56
	ds_read_u16 v57, v135 offset:592
	s_waitcnt lgkmcnt(1)
	v_lshlrev_b32_e32 v43, 16, v43
	v_sub_f32_e32 v43, v43, v56
	v_fmac_f32_e32 v56, v42, v43
	ds_read_u16 v43, v135 offset:192
	s_waitcnt lgkmcnt(1)
	v_lshlrev_b32_e32 v57, 16, v57
	s_waitcnt lgkmcnt(0)
	v_lshlrev_b32_e32 v43, 16, v43
	v_sub_f32_e32 v43, v43, v57
	v_fmac_f32_e32 v57, v38, v43
	v_mul_f32_e32 v43, v55, v57
	v_mul_f32_e32 v43, v56, v43
	v_fmac_f32_e32 v7, v20, v43
	v_mul_f32_e32 v43, v32, v57
	v_mul_f32_e32 v43, v43, v43
	v_fmac_f32_e32 v43, v23, v23
	ds_bpermute_b32 v23, v94, v43
	s_waitcnt lgkmcnt(0)
	v_add_f32_e32 v23, v43, v23
	ds_bpermute_b32 v43, v90, v23
	s_waitcnt lgkmcnt(0)
	v_add_f32_e32 v23, v23, v43
	ds_bpermute_b32 v43, v88, v23
	s_waitcnt lgkmcnt(0)
	v_add_f32_e32 v23, v23, v43
	ds_bpermute_b32 v43, v82, v23
	s_waitcnt lgkmcnt(0)
	v_add_f32_e32 v102, v23, v43
	ds_bpermute_b32 v23, v94, v7
	ds_bpermute_b32 v103, v101, v102
	s_waitcnt lgkmcnt(1)
	v_add_f32_e32 v7, v7, v23
	ds_bpermute_b32 v23, v90, v7
	s_waitcnt lgkmcnt(0)
	v_add_f32_e32 v7, v7, v23
	ds_bpermute_b32 v23, v88, v7
	s_waitcnt lgkmcnt(0)
	v_add_f32_e32 v7, v7, v23
	ds_bpermute_b32 v23, v82, v7
	s_waitcnt lgkmcnt(0)
	v_add_f32_e32 v7, v7, v23
	ds_bpermute_b32 v23, v101, v7
	s_waitcnt lgkmcnt(0)
	v_add_f32_e32 v7, v7, v23
	v_mul_f32_e32 v6, v6, v7
	s_nop 0
	v_cvt_pk_bf16_f32 v6, v6, v6
	global_store_short_d16_hi v[16:17], v6, off offset:1024
	v_mul_f32_e32 v6, v21, v7
	s_nop 0
	v_cvt_pk_bf16_f32 v6, v6, v6
	global_store_short_d16_hi v[16:17], v6, off offset:1088
	ds_read_u16 v6, v135 offset:1056
	ds_read_u16 v7, v135 offset:656
	ds_read_u16 v21, v135 offset:528
	ds_read_u16 v23, v135 offset:400
	ds_read_u16 v43, v135 offset:928
	s_waitcnt lgkmcnt(4)
	v_lshlrev_b32_e32 v68, 16, v6
	ds_read_u16 v6, v135 offset:800
	ds_read_u16 v57, v135 offset:864
	ds_read_u16 v56, v135 offset:464
	s_waitcnt lgkmcnt(6)
	v_lshlrev_b32_e32 v69, 16, v7
	s_waitcnt lgkmcnt(5)
	v_lshlrev_b32_e32 v7, 16, v21
	s_waitcnt lgkmcnt(4)
	v_lshlrev_b32_e32 v21, 16, v23
	s_waitcnt lgkmcnt(3)
	v_lshlrev_b32_e32 v23, 16, v43
	s_waitcnt lgkmcnt(2)
	v_lshlrev_b32_e32 v43, 16, v6
	v_sub_f32_e32 v21, v21, v43
	v_fmac_f32_e32 v43, v72, v21
	s_waitcnt lgkmcnt(0)
	v_lshlrev_b32_e32 v21, 16, v56
	ds_read_u16 v56, v135 offset:592
	ds_read_u16 v71, v135 offset:992
	v_lshlrev_b32_e32 v73, 16, v57
	v_sub_f32_e32 v6, v7, v23
	v_sub_f32_e32 v21, v21, v73
	v_fmac_f32_e32 v23, v66, v6
	v_pk_add_f32 v[6:7], v[18:19], -1.0 op_sel_hi:[1,0]
	v_fmac_f32_e32 v73, v42, v21
	s_waitcnt lgkmcnt(1)
	v_lshlrev_b32_e32 v21, 16, v56
	s_waitcnt lgkmcnt(0)
	v_lshlrev_b32_e32 v71, 16, v71
	v_sub_f32_e32 v21, v21, v71
	v_pk_add_f32 v[56:57], v[46:47], -1.0 op_sel_hi:[1,0]
	v_pk_fma_f32 v[6:7], v[6:7], v[62:63], 1.0 op_sel_hi:[1,0,0]
	v_fmac_f32_e32 v71, v38, v21
	v_mul_f32_e32 v21, v6, v23
	v_pk_fma_f32 v[56:57], v[56:57], v[34:35], 1.0 op_sel_hi:[1,0,0]
	v_mul_f32_e32 v70, v214, v23
	v_mul_f32_e32 v21, v43, v21
	v_mul_f32_e32 v23, v56, v71
	v_fma_f32 v21, v22, v21, 0
	v_mul_f32_e32 v23, v73, v23
	v_fmac_f32_e32 v21, v20, v23
	ds_bpermute_b32 v23, v94, v21
	v_mul_f32_e32 v43, v32, v71
	v_mul_f32_e32 v43, v43, v43
	v_fmac_f32_e32 v43, v70, v70
	ds_bpermute_b32 v70, v94, v43
	s_waitcnt lgkmcnt(1)
	v_add_f32_e32 v21, v21, v23
	ds_bpermute_b32 v23, v90, v21
	v_sub_f32_e32 v69, v69, v68
	v_fmac_f32_e32 v68, v64, v69
	s_waitcnt lgkmcnt(1)
	v_add_f32_e32 v43, v43, v70
	ds_bpermute_b32 v69, v90, v43
	s_waitcnt lgkmcnt(1)
	v_add_f32_e32 v21, v21, v23
	ds_bpermute_b32 v23, v88, v21
	ds_read_u16 v70, v135 offset:1120
	ds_read_u16 v71, v135 offset:720
	s_waitcnt lgkmcnt(3)
	v_add_f32_e32 v43, v43, v69
	ds_bpermute_b32 v69, v88, v43
	s_waitcnt lgkmcnt(3)
	v_add_f32_e32 v21, v21, v23
	ds_bpermute_b32 v23, v82, v21
	s_waitcnt lgkmcnt(3)
	v_lshlrev_b32_e32 v70, 16, v70
	s_waitcnt lgkmcnt(2)
	v_lshlrev_b32_e32 v71, 16, v71
	s_waitcnt lgkmcnt(1)
	v_add_f32_e32 v43, v43, v69
	ds_bpermute_b32 v69, v82, v43
	s_waitcnt lgkmcnt(1)
	v_add_f32_e32 v21, v21, v23
	ds_bpermute_b32 v23, v101, v21
	v_sub_f32_e32 v71, v71, v70
	v_fmac_f32_e32 v70, v36, v71
	s_waitcnt lgkmcnt(1)
	v_add_f32_e32 v120, v43, v69
	ds_bpermute_b32 v121, v101, v120
	s_waitcnt lgkmcnt(1)
	v_add_f32_e32 v21, v21, v23
	v_mul_f32_e32 v23, v68, v21
	s_nop 0
	v_cvt_pk_bf16_f32 v23, v23, v23
	v_mul_f32_e32 v21, v70, v21
	global_store_short_d16_hi v[16:17], v23, off offset:2048
	s_nop 0
	v_cvt_pk_bf16_f32 v21, v21, v21
	global_store_short_d16_hi v[16:17], v21, off offset:2112
	ds_read_u16 v21, v135 offset:1456
	ds_read_u16 v23, v135 offset:1056
	ds_read_u16 v68, v135 offset:1328
	ds_read_u16 v69, v135 offset:1200
	ds_read_u16 v43, v135 offset:800
	s_waitcnt lgkmcnt(4)
	v_lshlrev_b32_e32 v21, 16, v21
	s_waitcnt lgkmcnt(3)
	v_lshlrev_b32_e32 v23, 16, v23
	v_sub_f32_e32 v23, v23, v21
	v_fmac_f32_e32 v21, v64, v23
	ds_read_u16 v23, v135 offset:928
	s_waitcnt lgkmcnt(3)
	v_lshlrev_b32_e32 v68, 16, v68
	s_waitcnt lgkmcnt(1)
	v_lshlrev_b32_e32 v43, 16, v43
	v_lshlrev_b32_e32 v69, 16, v69
	v_sub_f32_e32 v43, v43, v69
	s_waitcnt lgkmcnt(0)
	v_lshlrev_b32_e32 v23, 16, v23
	v_sub_f32_e32 v23, v23, v68
	v_fmac_f32_e32 v68, v66, v23
	v_mul_f32_e32 v23, v7, v68
	v_fmac_f32_e32 v69, v72, v43
	v_mul_f32_e32 v23, v69, v23
	ds_read_u16 v43, v135 offset:1520
	ds_read_u16 v69, v135 offset:1120
	v_fma_f32 v23, v22, v23, 0
	ds_read_u16 v70, v135 offset:1264
	v_mul_f32_e32 v68, v214, v68
	s_waitcnt lgkmcnt(2)
	v_lshlrev_b32_e32 v43, 16, v43
	s_waitcnt lgkmcnt(1)
	v_lshlrev_b32_e32 v69, 16, v69
	v_sub_f32_e32 v69, v69, v43
	v_fmac_f32_e32 v43, v36, v69
	ds_read_u16 v69, v135 offset:864
	s_waitcnt lgkmcnt(1)
	v_lshlrev_b32_e32 v70, 16, v70
	ds_read_u16 v71, v135 offset:1392
	s_waitcnt lgkmcnt(1)
	v_lshlrev_b32_e32 v69, 16, v69
	v_sub_f32_e32 v69, v69, v70
	v_fmac_f32_e32 v70, v42, v69
	ds_read_u16 v69, v135 offset:992
	s_waitcnt lgkmcnt(1)
	v_lshlrev_b32_e32 v71, 16, v71
	s_waitcnt lgkmcnt(0)
	v_lshlrev_b32_e32 v69, 16, v69
	v_sub_f32_e32 v69, v69, v71
	v_fmac_f32_e32 v71, v38, v69
	v_mul_f32_e32 v69, v57, v71
	v_mul_f32_e32 v69, v70, v69
	v_fmac_f32_e32 v23, v20, v69
	v_mul_f32_e32 v69, v32, v71
	v_mul_f32_e32 v69, v69, v69
	v_fmac_f32_e32 v69, v68, v68
	ds_bpermute_b32 v68, v94, v69
	s_waitcnt lgkmcnt(0)
	v_add_f32_e32 v68, v69, v68
	ds_bpermute_b32 v69, v90, v68
	s_waitcnt lgkmcnt(0)
	v_add_f32_e32 v68, v68, v69
	ds_bpermute_b32 v69, v88, v68
	s_waitcnt lgkmcnt(0)
	v_add_f32_e32 v68, v68, v69
	ds_bpermute_b32 v69, v82, v68
	s_waitcnt lgkmcnt(0)
	v_add_f32_e32 v164, v68, v69
	ds_bpermute_b32 v68, v94, v23
	ds_bpermute_b32 v165, v101, v164
	s_waitcnt lgkmcnt(1)
	v_add_f32_e32 v23, v23, v68
	ds_bpermute_b32 v68, v90, v23
	s_waitcnt lgkmcnt(0)
	v_add_f32_e32 v23, v23, v68
	ds_bpermute_b32 v68, v88, v23
	s_waitcnt lgkmcnt(0)
	v_add_f32_e32 v23, v23, v68
	ds_bpermute_b32 v68, v82, v23
	s_waitcnt lgkmcnt(0)
	v_add_f32_e32 v23, v23, v68
	ds_bpermute_b32 v68, v101, v23
	s_waitcnt lgkmcnt(0)
	v_add_f32_e32 v23, v23, v68
	v_mul_f32_e32 v21, v21, v23
	s_nop 0
	v_cvt_pk_bf16_f32 v21, v21, v21
	global_store_short_d16_hi v[16:17], v21, off offset:3072
	v_mul_f32_e32 v21, v43, v23
	s_nop 0
	v_cvt_pk_bf16_f32 v21, v21, v21
	global_store_short_d16_hi v[16:17], v21, off offset:3136
	ds_read_u16 v21, v135 offset:3456
	ds_read_u16 v23, v135 offset:3056
	ds_read_u16 v43, v135 offset:2928
	ds_read_u16 v68, v135 offset:2800
	ds_read_u16 v69, v135 offset:3328
	ds_read_u16 v70, v135 offset:3200
	s_waitcnt lgkmcnt(5)
	v_lshlrev_b32_e32 v21, 16, v21
	s_waitcnt lgkmcnt(3)
	v_lshlrev_b32_e32 v43, 16, v43
	s_waitcnt lgkmcnt(2)
	v_lshlrev_b32_e32 v71, 16, v68
	s_waitcnt lgkmcnt(1)
	v_lshlrev_b32_e32 v73, 16, v69
	v_sub_f32_e32 v43, v43, v73
	v_fmac_f32_e32 v73, v66, v43
	ds_read_u16 v43, v135 offset:2864
	s_waitcnt lgkmcnt(1)
	v_lshlrev_b32_e32 v76, 16, v70
	v_sub_f32_e32 v70, v71, v76
	ds_read_u16 v71, v135 offset:3264
	v_fmac_f32_e32 v76, v72, v70
	ds_read_u16 v70, v135 offset:2992
	ds_read_u16 v96, v135 offset:3392
	s_waitcnt lgkmcnt(3)
	v_lshlrev_b32_e32 v43, 16, v43
	v_pk_add_f32 v[68:69], v[2:3], -1.0 op_sel_hi:[1,0]
	s_waitcnt lgkmcnt(2)
	v_lshlrev_b32_e32 v114, 16, v71
	v_sub_f32_e32 v43, v43, v114
	v_fmac_f32_e32 v114, v42, v43
	s_waitcnt lgkmcnt(1)
	v_lshlrev_b32_e32 v43, 16, v70
	s_waitcnt lgkmcnt(0)
	v_lshlrev_b32_e32 v96, 16, v96
	v_sub_f32_e32 v43, v43, v96
	v_pk_add_f32 v[70:71], v[44:45], -1.0 op_sel_hi:[1,0]
	v_pk_fma_f32 v[104:105], v[68:69], v[62:63], 1.0 op_sel_hi:[1,0,0]
	v_fmac_f32_e32 v96, v38, v43
	v_mul_f32_e32 v43, v104, v73
	v_pk_fma_f32 v[68:69], v[70:71], v[34:35], 1.0 op_sel_hi:[1,0,0]
	v_mul_f32_e32 v43, v76, v43
	v_mul_f32_e32 v70, v68, v96
	v_fma_f32 v43, v22, v43, 0
	v_mul_f32_e32 v70, v114, v70
	v_fmac_f32_e32 v43, v20, v70
	ds_bpermute_b32 v70, v94, v43
	v_mul_f32_e32 v71, v32, v96
	v_mul_f32_e32 v77, v214, v73
	v_mul_f32_e32 v71, v71, v71
	v_fmac_f32_e32 v71, v77, v77
	s_waitcnt lgkmcnt(0)
	v_add_f32_e32 v43, v43, v70
	ds_bpermute_b32 v73, v94, v71
	ds_bpermute_b32 v70, v90, v43
	v_lshlrev_b32_e32 v23, 16, v23
	v_sub_f32_e32 v23, v23, v21
	v_fmac_f32_e32 v21, v64, v23
	s_waitcnt lgkmcnt(1)
	v_add_f32_e32 v23, v71, v73
	s_waitcnt lgkmcnt(0)
	v_add_f32_e32 v43, v43, v70
	ds_bpermute_b32 v71, v90, v23
	ds_bpermute_b32 v70, v88, v43
	ds_read_u16 v73, v135 offset:3520
	ds_read_u16 v76, v135 offset:3120
	s_waitcnt lgkmcnt(3)
	v_add_f32_e32 v23, v23, v71
	s_waitcnt lgkmcnt(2)
	v_add_f32_e32 v43, v43, v70
	ds_bpermute_b32 v71, v88, v23
	ds_bpermute_b32 v70, v82, v43
	s_waitcnt lgkmcnt(3)
	v_lshlrev_b32_e32 v73, 16, v73
	s_waitcnt lgkmcnt(2)
	v_lshlrev_b32_e32 v76, 16, v76
	v_sub_f32_e32 v76, v76, v73
	s_waitcnt lgkmcnt(1)
	v_add_f32_e32 v23, v23, v71
	s_waitcnt lgkmcnt(0)
	v_add_f32_e32 v43, v43, v70
	ds_bpermute_b32 v71, v82, v23
	ds_bpermute_b32 v70, v101, v43
	v_fmac_f32_e32 v73, v36, v76
	v_add_co_u32_e32 v76, vcc, s74, v16
	s_waitcnt lgkmcnt(1)
	v_add_f32_e32 v178, v23, v71
	s_waitcnt lgkmcnt(0)
	v_add_f32_e32 v23, v43, v70
	v_mul_f32_e32 v21, v21, v23
	ds_bpermute_b32 v179, v101, v178
	s_nop 0
	v_cvt_pk_bf16_f32 v21, v21, v21
	v_addc_co_u32_e32 v77, vcc, 0, v17, vcc
	global_store_short_d16_hi v[76:77], v21, off
	v_mul_f32_e32 v21, v73, v23
	s_nop 0
	v_cvt_pk_bf16_f32 v21, v21, v21
	global_store_short_d16_hi v[76:77], v21, off offset:64
	ds_read_u16 v21, v135 offset:3856
	ds_read_u16 v23, v135 offset:3456
	ds_read_u16 v70, v135 offset:3728
	ds_read_u16 v71, v135 offset:3600
	ds_read_u16 v43, v135 offset:3200
	s_waitcnt lgkmcnt(4)
	v_lshlrev_b32_e32 v21, 16, v21
	s_waitcnt lgkmcnt(3)
	v_lshlrev_b32_e32 v23, 16, v23
	v_sub_f32_e32 v23, v23, v21
	v_fmac_f32_e32 v21, v64, v23
	ds_read_u16 v23, v135 offset:3328
	s_waitcnt lgkmcnt(3)
	v_lshlrev_b32_e32 v70, 16, v70
	s_waitcnt lgkmcnt(1)
	v_lshlrev_b32_e32 v43, 16, v43
	v_lshlrev_b32_e32 v71, 16, v71
	v_sub_f32_e32 v43, v43, v71
	s_waitcnt lgkmcnt(0)
	v_lshlrev_b32_e32 v23, 16, v23
	v_sub_f32_e32 v23, v23, v70
	v_fmac_f32_e32 v70, v66, v23
	v_mul_f32_e32 v23, v105, v70
	v_fmac_f32_e32 v71, v72, v43
	v_mul_f32_e32 v23, v71, v23
	ds_read_u16 v43, v135 offset:3920
	ds_read_u16 v71, v135 offset:3520
	v_fma_f32 v23, v22, v23, 0
	ds_read_u16 v73, v135 offset:3664
	v_mul_f32_e32 v70, v214, v70
	s_waitcnt lgkmcnt(2)
	v_lshlrev_b32_e32 v43, 16, v43
	s_waitcnt lgkmcnt(1)
	v_lshlrev_b32_e32 v71, 16, v71
	v_sub_f32_e32 v71, v71, v43
	v_fmac_f32_e32 v43, v36, v71
	ds_read_u16 v71, v135 offset:3264
	s_waitcnt lgkmcnt(1)
	v_lshlrev_b32_e32 v73, 16, v73
	ds_read_u16 v96, v135 offset:3792
	s_waitcnt lgkmcnt(1)
	v_lshlrev_b32_e32 v71, 16, v71
	v_sub_f32_e32 v71, v71, v73
	v_fmac_f32_e32 v73, v42, v71
	ds_read_u16 v71, v135 offset:3392
	s_waitcnt lgkmcnt(1)
	v_lshlrev_b32_e32 v96, 16, v96
	s_waitcnt lgkmcnt(0)
	v_lshlrev_b32_e32 v71, 16, v71
	v_sub_f32_e32 v71, v71, v96
	v_fmac_f32_e32 v96, v38, v71
	v_mul_f32_e32 v71, v69, v96
	v_mul_f32_e32 v71, v73, v71
	v_fmac_f32_e32 v23, v20, v71
	v_mul_f32_e32 v71, v32, v96
	v_mul_f32_e32 v71, v71, v71
	v_fmac_f32_e32 v71, v70, v70
	ds_bpermute_b32 v70, v94, v71
	s_waitcnt lgkmcnt(0)
	v_add_f32_e32 v70, v71, v70
	ds_bpermute_b32 v71, v90, v70
	s_waitcnt lgkmcnt(0)
	v_add_f32_e32 v70, v70, v71
	ds_bpermute_b32 v71, v88, v70
	s_waitcnt lgkmcnt(0)
	v_add_f32_e32 v70, v70, v71
	ds_bpermute_b32 v71, v82, v70
	s_waitcnt lgkmcnt(0)
	v_add_f32_e32 v180, v70, v71
	ds_bpermute_b32 v70, v94, v23
	ds_bpermute_b32 v181, v101, v180
	s_waitcnt lgkmcnt(1)
	v_add_f32_e32 v23, v23, v70
	ds_bpermute_b32 v70, v90, v23
	s_waitcnt lgkmcnt(0)
	v_add_f32_e32 v23, v23, v70
	ds_bpermute_b32 v70, v88, v23
	s_waitcnt lgkmcnt(0)
	v_add_f32_e32 v23, v23, v70
	ds_bpermute_b32 v70, v82, v23
	s_waitcnt lgkmcnt(0)
	v_add_f32_e32 v23, v23, v70
	ds_bpermute_b32 v70, v101, v23
	s_waitcnt lgkmcnt(0)
	v_add_f32_e32 v23, v23, v70
	v_mul_f32_e32 v21, v21, v23
	s_nop 0
	v_cvt_pk_bf16_f32 v21, v21, v21
	global_store_short_d16_hi v[76:77], v21, off offset:1024
	v_mul_f32_e32 v21, v43, v23
	s_nop 0
	v_cvt_pk_bf16_f32 v21, v21, v21
	global_store_short_d16_hi v[76:77], v21, off offset:1088
	ds_read_u16 v21, v135 offset:4256
	ds_read_u16 v23, v135 offset:3856
	ds_read_u16 v43, v135 offset:3728
	ds_read_u16 v70, v135 offset:3600
	ds_read_u16 v71, v135 offset:4128
	ds_read_u16 v73, v135 offset:4000
	ds_read_u16 v114, v135 offset:4064
	s_waitcnt lgkmcnt(4)
	v_lshlrev_b32_e32 v43, 16, v43
	s_waitcnt lgkmcnt(3)
	v_lshlrev_b32_e32 v96, 16, v70
	s_waitcnt lgkmcnt(2)
	v_lshlrev_b32_e32 v139, 16, v71
	v_sub_f32_e32 v43, v43, v139
	v_fmac_f32_e32 v139, v66, v43
	ds_read_u16 v43, v135 offset:3664
	s_waitcnt lgkmcnt(2)
	v_lshlrev_b32_e32 v73, 16, v73
	v_sub_f32_e32 v96, v96, v73
	v_fmac_f32_e32 v73, v72, v96
	ds_read_u16 v96, v135 offset:3792
	ds_read_u16 v115, v135 offset:4192
	s_waitcnt lgkmcnt(2)
	v_lshlrev_b32_e32 v43, 16, v43
	v_lshlrev_b32_e32 v142, 16, v114
	v_sub_f32_e32 v43, v43, v142
	v_pk_add_f32 v[70:71], v[78:79], -1.0 op_sel_hi:[1,0]
	v_fmac_f32_e32 v142, v42, v43
	s_waitcnt lgkmcnt(1)
	v_lshlrev_b32_e32 v43, 16, v96
	s_waitcnt lgkmcnt(0)
	v_lshlrev_b32_e32 v96, 16, v115
	v_sub_f32_e32 v43, v43, v96
	v_pk_add_f32 v[122:123], v[40:41], -1.0 op_sel_hi:[1,0]
	v_pk_fma_f32 v[114:115], v[70:71], v[62:63], 1.0 op_sel_hi:[1,0,0]
	v_fmac_f32_e32 v96, v38, v43
	v_mul_f32_e32 v43, v114, v139
	v_pk_fma_f32 v[70:71], v[122:123], v[34:35], 1.0 op_sel_hi:[1,0,0]
	v_mul_f32_e32 v43, v73, v43
	v_mul_f32_e32 v73, v70, v96
	v_fma_f32 v43, v22, v43, 0
	v_mul_f32_e32 v73, v142, v73
	v_fmac_f32_e32 v43, v20, v73
	ds_bpermute_b32 v73, v94, v43
	v_mul_f32_e32 v96, v32, v96
	v_mul_f32_e32 v141, v214, v139
	v_mul_f32_e32 v96, v96, v96
	v_fmac_f32_e32 v96, v141, v141
	s_waitcnt lgkmcnt(0)
	v_add_f32_e32 v43, v43, v73
	ds_bpermute_b32 v122, v94, v96
	ds_bpermute_b32 v73, v90, v43
	v_lshlrev_b32_e32 v21, 16, v21
	v_lshlrev_b32_e32 v23, 16, v23
	v_sub_f32_e32 v23, v23, v21
	v_fmac_f32_e32 v21, v64, v23
	s_waitcnt lgkmcnt(1)
	v_add_f32_e32 v23, v96, v122
	s_waitcnt lgkmcnt(0)
	v_add_f32_e32 v43, v43, v73
	ds_bpermute_b32 v96, v90, v23
	ds_bpermute_b32 v73, v88, v43
	ds_read_u16 v122, v135 offset:4320
	ds_read_u16 v123, v135 offset:3920
	s_waitcnt lgkmcnt(3)
	v_add_f32_e32 v23, v23, v96
	s_waitcnt lgkmcnt(2)
	v_add_f32_e32 v43, v43, v73
	ds_bpermute_b32 v96, v88, v23
	ds_bpermute_b32 v73, v82, v43
	s_waitcnt lgkmcnt(3)
	v_lshlrev_b32_e32 v122, 16, v122
	s_waitcnt lgkmcnt(2)
	v_lshlrev_b32_e32 v123, 16, v123
	v_sub_f32_e32 v123, v123, v122
	s_waitcnt lgkmcnt(1)
	v_add_f32_e32 v23, v23, v96
	s_waitcnt lgkmcnt(0)
	v_add_f32_e32 v43, v43, v73
	ds_bpermute_b32 v96, v82, v23
	ds_bpermute_b32 v73, v101, v43
	v_fmac_f32_e32 v122, v36, v123
	s_waitcnt lgkmcnt(1)
	v_add_f32_e32 v182, v23, v96
	s_waitcnt lgkmcnt(0)
	v_add_f32_e32 v23, v43, v73
	v_mul_f32_e32 v21, v21, v23
	ds_bpermute_b32 v183, v101, v182
	s_nop 0
	v_cvt_pk_bf16_f32 v21, v21, v21
	global_store_short_d16_hi v[76:77], v21, off offset:2048
	v_mul_f32_e32 v21, v122, v23
	s_nop 0
	v_cvt_pk_bf16_f32 v21, v21, v21
	global_store_short_d16_hi v[76:77], v21, off offset:2112
	ds_read_u16 v21, v135 offset:4656
	ds_read_u16 v23, v135 offset:4256
	ds_read_u16 v73, v135 offset:4528
	ds_read_u16 v96, v135 offset:4400
	ds_read_u16 v43, v135 offset:4000
	s_waitcnt lgkmcnt(4)
	v_lshlrev_b32_e32 v21, 16, v21
	s_waitcnt lgkmcnt(3)
	v_lshlrev_b32_e32 v23, 16, v23
	v_sub_f32_e32 v23, v23, v21
	v_fmac_f32_e32 v21, v64, v23
	ds_read_u16 v23, v135 offset:4128
	s_waitcnt lgkmcnt(3)
	v_lshlrev_b32_e32 v73, 16, v73
	s_waitcnt lgkmcnt(1)
	v_lshlrev_b32_e32 v43, 16, v43
	v_lshlrev_b32_e32 v96, 16, v96
	v_sub_f32_e32 v43, v43, v96
	s_waitcnt lgkmcnt(0)
	v_lshlrev_b32_e32 v23, 16, v23
	v_sub_f32_e32 v23, v23, v73
	v_fmac_f32_e32 v73, v66, v23
	v_mul_f32_e32 v23, v115, v73
	v_fmac_f32_e32 v96, v72, v43
	v_mul_f32_e32 v23, v96, v23
	ds_read_u16 v43, v135 offset:4720
	ds_read_u16 v96, v135 offset:4320
	v_fma_f32 v23, v22, v23, 0
	ds_read_u16 v122, v135 offset:4464
	v_mul_f32_e32 v73, v214, v73
	s_waitcnt lgkmcnt(2)
	v_lshlrev_b32_e32 v43, 16, v43
	s_waitcnt lgkmcnt(1)
	v_lshlrev_b32_e32 v96, 16, v96
	v_sub_f32_e32 v96, v96, v43
	v_fmac_f32_e32 v43, v36, v96
	ds_read_u16 v96, v135 offset:4064
	s_waitcnt lgkmcnt(1)
	v_lshlrev_b32_e32 v122, 16, v122
	ds_read_u16 v123, v135 offset:4592
	s_waitcnt lgkmcnt(1)
	v_lshlrev_b32_e32 v96, 16, v96
	v_sub_f32_e32 v96, v96, v122
	v_fmac_f32_e32 v122, v42, v96
	ds_read_u16 v96, v135 offset:4192
	s_waitcnt lgkmcnt(1)
	v_lshlrev_b32_e32 v123, 16, v123
	s_waitcnt lgkmcnt(0)
	v_lshlrev_b32_e32 v96, 16, v96
	v_sub_f32_e32 v96, v96, v123
	v_fmac_f32_e32 v123, v38, v96
	v_mul_f32_e32 v96, v71, v123
	v_mul_f32_e32 v96, v122, v96
	v_fmac_f32_e32 v23, v20, v96
	v_mul_f32_e32 v96, v32, v123
	v_mul_f32_e32 v96, v96, v96
	v_fmac_f32_e32 v96, v73, v73
	ds_bpermute_b32 v73, v94, v96
	s_waitcnt lgkmcnt(0)
	v_add_f32_e32 v73, v96, v73
	ds_bpermute_b32 v96, v90, v73
	s_waitcnt lgkmcnt(0)
	v_add_f32_e32 v73, v73, v96
	ds_bpermute_b32 v96, v88, v73
	s_waitcnt lgkmcnt(0)
	v_add_f32_e32 v73, v73, v96
	ds_bpermute_b32 v96, v82, v73
	s_waitcnt lgkmcnt(0)
	v_add_f32_e32 v184, v73, v96
	ds_bpermute_b32 v73, v94, v23
	ds_bpermute_b32 v185, v101, v184
	s_waitcnt lgkmcnt(1)
	v_add_f32_e32 v23, v23, v73
	ds_bpermute_b32 v73, v90, v23
	s_waitcnt lgkmcnt(0)
	v_add_f32_e32 v23, v23, v73
	ds_bpermute_b32 v73, v88, v23
	s_waitcnt lgkmcnt(0)
	v_add_f32_e32 v23, v23, v73
	ds_bpermute_b32 v73, v82, v23
	s_waitcnt lgkmcnt(0)
	v_add_f32_e32 v23, v23, v73
	ds_bpermute_b32 v73, v101, v23
	s_waitcnt lgkmcnt(0)
	v_add_f32_e32 v23, v23, v73
	v_mul_f32_e32 v21, v21, v23
	s_nop 0
	v_cvt_pk_bf16_f32 v21, v21, v21
	global_store_short_d16_hi v[76:77], v21, off offset:3072
	v_mul_f32_e32 v21, v43, v23
	s_nop 0
	v_cvt_pk_bf16_f32 v21, v21, v21
	global_store_short_d16_hi v[76:77], v21, off offset:3136
	v_add_u32_e32 v8, 0x1770, v8
	v_add3_u32 v155, s76, v8, v98
	ds_read_u16 v123, v155 offset:656
	ds_read_u16 v139, v155 offset:256
	s_and_b64 vcc, exec, s[0:1]
	v_add_f32_e32 v168, -1.0, v83
	s_cbranch_vccz .LBB0_937
	ds_read_u16 v21, v155 offset:528
	ds_read_u16 v23, v155 offset:128
	ds_read_u16 v43, v155 offset:400
	ds_read_u16 v73, v155
	s_waitcnt lgkmcnt(3)
	v_lshlrev_b32_e32 v77, 16, v21
	s_waitcnt lgkmcnt(2)
	v_lshlrev_b32_e32 v21, 16, v23
	s_waitcnt lgkmcnt(1)
	v_lshlrev_b32_e32 v143, 16, v43
	s_waitcnt lgkmcnt(0)
	v_lshlrev_b32_e32 v142, 16, v73
	v_mov_b32_e32 v76, v143
	v_pk_add_f32 v[144:145], v[142:143], v[76:77] neg_lo:[0,1] neg_hi:[0,1]
	v_sub_f32_e32 v21, v21, v77
	v_mov_b32_e32 v73, v62
	v_mov_b32_e32 v145, v168
	v_mov_b32_e32 v142, v143
	v_mov_b32_e32 v143, v215
	v_pk_fma_f32 v[142:143], v[72:73], v[144:145], v[142:143]
	v_fmac_f32_e32 v77, v66, v21
	v_mul_f32_e32 v21, v143, v77
	v_mul_f32_e32 v76, v142, v21
	v_mov_b32_e32 v23, v214
	v_pk_mul_f32 v[142:143], v[22:23], v[76:77]
	v_mov_b32_e32 v144, v97
	v_mov_b32_e32 v145, v143
	v_pk_fma_f32 v[76:77], v[22:23], v[76:77], v[144:145]
	v_pk_mul_f32 v[142:143], v[142:143], v[142:143]
	s_nop 0
	v_mov_b32_e32 v77, v143
	s_branch .LBB0_938

.LBB0_940:
	ds_bpermute_b32 v21, v94, v77
	ds_bpermute_b32 v24, v94, v76
	s_and_b64 vcc, exec, s[2:3]
	s_waitcnt lgkmcnt(1)
	v_add_f32_e32 v21, v77, v21
	s_waitcnt lgkmcnt(0)
	v_add_f32_e32 v24, v76, v24
	ds_bpermute_b32 v43, v90, v21
	ds_bpermute_b32 v76, v90, v24
	s_waitcnt lgkmcnt(1)
	v_add_f32_e32 v21, v21, v43
	s_waitcnt lgkmcnt(0)
	v_add_f32_e32 v24, v24, v76
	ds_bpermute_b32 v43, v88, v21
	ds_bpermute_b32 v76, v88, v24
	s_waitcnt lgkmcnt(1)
	v_add_f32_e32 v21, v21, v43
	s_waitcnt lgkmcnt(0)
	v_add_f32_e32 v43, v24, v76
	ds_bpermute_b32 v24, v82, v21
	ds_bpermute_b32 v76, v82, v43
	s_waitcnt lgkmcnt(1)
	v_add_f32_e32 v24, v21, v24
	s_waitcnt lgkmcnt(0)
	v_add_f32_e32 v21, v43, v76
	ds_bpermute_b32 v122, v101, v24
	ds_bpermute_b32 v43, v101, v21
	s_cbranch_vccnz .LBB0_942
	v_lshlrev_b32_e32 v23, 16, v23
	v_lshlrev_b32_e32 v73, 16, v73
	v_sub_f32_e32 v73, v73, v23
	v_fmac_f32_e32 v23, v36, v73
	v_lshlrev_b32_e32 v73, 16, v123
	v_lshlrev_b32_e32 v76, 16, v139
	v_sub_f32_e32 v76, v76, v73
	v_fmac_f32_e32 v73, v64, v76
	s_waitcnt lgkmcnt(0)
	v_add_f32_e32 v21, v21, v43
	v_mul_f32_e32 v43, v73, v21
	v_mul_f32_e32 v21, v23, v21
	s_nop 0
	v_add_co_u32_e32 v76, vcc, 0x4000, v16
	s_nop 0
	v_cvt_pk_bf16_f32 v43, v43, v43
	v_addc_co_u32_e32 v77, vcc, 0, v17, vcc
	v_cvt_pk_bf16_f32 v21, v21, v21
	global_store_short_d16_hi v[76:77], v43, off
	global_store_short_d16_hi v[76:77], v21, off offset:64

.LBB0_947:
	ds_bpermute_b32 v21, v94, v9
	ds_bpermute_b32 v25, v94, v8
	s_and_b64 vcc, exec, s[2:3]
	s_waitcnt lgkmcnt(1)
	v_add_f32_e32 v9, v9, v21
	s_waitcnt lgkmcnt(0)
	v_add_f32_e32 v8, v8, v25
	ds_bpermute_b32 v21, v90, v9
	ds_bpermute_b32 v25, v90, v8
	s_waitcnt lgkmcnt(1)
	v_add_f32_e32 v9, v9, v21
	s_waitcnt lgkmcnt(0)
	v_add_f32_e32 v8, v8, v25
	ds_bpermute_b32 v21, v88, v9
	ds_bpermute_b32 v25, v88, v8
	s_waitcnt lgkmcnt(1)
	v_add_f32_e32 v9, v9, v21
	s_waitcnt lgkmcnt(0)
	v_add_f32_e32 v8, v8, v25
	ds_bpermute_b32 v21, v82, v9
	ds_bpermute_b32 v43, v82, v8
	s_waitcnt lgkmcnt(1)
	v_add_f32_e32 v25, v9, v21
	s_waitcnt lgkmcnt(0)
	v_add_f32_e32 v8, v8, v43
	ds_bpermute_b32 v123, v101, v25
	ds_bpermute_b32 v9, v101, v8
	s_cbranch_vccnz .LBB0_949
	v_lshlrev_b32_e32 v21, 16, v23
	v_lshlrev_b32_e32 v23, 16, v73
	v_sub_f32_e32 v23, v23, v21
	v_fmac_f32_e32 v21, v36, v23
	v_lshlrev_b32_e32 v23, 16, v77
	v_lshlrev_b32_e32 v43, 16, v139
	v_sub_f32_e32 v43, v43, v23
	v_fmac_f32_e32 v23, v64, v43
	s_waitcnt lgkmcnt(0)
	v_add_f32_e32 v43, v8, v9
	v_mul_f32_e32 v8, v23, v43
	s_nop 0
	v_cvt_pk_bf16_f32 v23, v8, v8
	v_add_co_u32_e32 v8, vcc, 0x4000, v16
	v_mul_f32_e32 v21, v21, v43
	s_nop 0
	v_addc_co_u32_e32 v9, vcc, 0, v17, vcc
	global_store_short_d16_hi v[8:9], v23, off offset:1024
	s_nop 0
	v_cvt_pk_bf16_f32 v21, v21, v21
	global_store_short_d16_hi v[8:9], v21, off offset:1088

.LBB0_954:
	ds_bpermute_b32 v10, v94, v9
	ds_bpermute_b32 v21, v94, v8
	s_and_b64 vcc, exec, s[2:3]
	s_waitcnt lgkmcnt(1)
	v_add_f32_e32 v9, v9, v10
	s_waitcnt lgkmcnt(0)
	v_add_f32_e32 v8, v8, v21
	ds_bpermute_b32 v10, v90, v9
	ds_bpermute_b32 v21, v90, v8
	s_waitcnt lgkmcnt(1)
	v_add_f32_e32 v9, v9, v10
	s_waitcnt lgkmcnt(0)
	v_add_f32_e32 v8, v8, v21
	ds_bpermute_b32 v10, v88, v9
	ds_bpermute_b32 v21, v88, v8
	s_waitcnt lgkmcnt(1)
	v_add_f32_e32 v9, v9, v10
	s_waitcnt lgkmcnt(0)
	v_add_f32_e32 v8, v8, v21
	ds_bpermute_b32 v10, v82, v9
	ds_bpermute_b32 v21, v82, v8
	s_waitcnt lgkmcnt(1)
	v_add_f32_e32 v10, v9, v10
	s_waitcnt lgkmcnt(0)
	v_add_f32_e32 v8, v8, v21
	ds_bpermute_b32 v26, v101, v10
	ds_bpermute_b32 v9, v101, v8
	s_cbranch_vccnz .LBB0_956
	v_lshlrev_b32_e32 v21, 16, v23
	v_lshlrev_b32_e32 v23, 16, v73
	v_sub_f32_e32 v23, v23, v21
	v_fmac_f32_e32 v21, v36, v23
	v_lshlrev_b32_e32 v23, 16, v77
	v_lshlrev_b32_e32 v43, 16, v139
	v_sub_f32_e32 v43, v43, v23
	v_fmac_f32_e32 v23, v64, v43
	s_waitcnt lgkmcnt(0)
	v_add_f32_e32 v43, v8, v9
	v_mul_f32_e32 v8, v23, v43
	s_nop 0
	v_cvt_pk_bf16_f32 v23, v8, v8
	v_add_co_u32_e32 v8, vcc, 0x4000, v16
	v_mul_f32_e32 v21, v21, v43
	s_nop 0
	v_addc_co_u32_e32 v9, vcc, 0, v17, vcc
	global_store_short_d16_hi v[8:9], v23, off offset:2048
	s_nop 0
	v_cvt_pk_bf16_f32 v21, v21, v21
	global_store_short_d16_hi v[8:9], v21, off offset:2112

.LBB0_961:
	ds_bpermute_b32 v11, v94, v9
	ds_bpermute_b32 v21, v94, v8
	s_and_b64 vcc, exec, s[2:3]
	s_waitcnt lgkmcnt(1)
	v_add_f32_e32 v9, v9, v11
	s_waitcnt lgkmcnt(0)
	v_add_f32_e32 v8, v8, v21
	ds_bpermute_b32 v11, v90, v9
	ds_bpermute_b32 v21, v90, v8
	s_waitcnt lgkmcnt(1)
	v_add_f32_e32 v9, v9, v11
	s_waitcnt lgkmcnt(0)
	v_add_f32_e32 v8, v8, v21
	ds_bpermute_b32 v11, v88, v9
	ds_bpermute_b32 v21, v88, v8
	s_waitcnt lgkmcnt(1)
	v_add_f32_e32 v9, v9, v11
	s_waitcnt lgkmcnt(0)
	v_add_f32_e32 v8, v8, v21
	ds_bpermute_b32 v11, v82, v9
	ds_bpermute_b32 v21, v82, v8
	s_waitcnt lgkmcnt(1)
	v_add_f32_e32 v11, v9, v11
	s_waitcnt lgkmcnt(0)
	v_add_f32_e32 v8, v8, v21
	ds_bpermute_b32 v27, v101, v11
	ds_bpermute_b32 v9, v101, v8
	s_cbranch_vccnz .LBB0_963
	v_lshlrev_b32_e32 v21, 16, v23
	v_lshlrev_b32_e32 v23, 16, v73
	v_sub_f32_e32 v23, v23, v21
	v_fmac_f32_e32 v21, v36, v23
	v_lshlrev_b32_e32 v23, 16, v77
	v_lshlrev_b32_e32 v43, 16, v139
	v_sub_f32_e32 v43, v43, v23
	v_fmac_f32_e32 v23, v64, v43
	s_waitcnt lgkmcnt(0)
	v_add_f32_e32 v43, v8, v9
	v_mul_f32_e32 v8, v23, v43
	s_nop 0
	v_cvt_pk_bf16_f32 v23, v8, v8
	v_add_co_u32_e32 v8, vcc, 0x4000, v16
	v_mul_f32_e32 v21, v21, v43
	s_nop 0
	v_addc_co_u32_e32 v9, vcc, 0, v17, vcc
	global_store_short_d16_hi v[8:9], v23, off offset:3072
	s_nop 0
	v_cvt_pk_bf16_f32 v21, v21, v21
	global_store_short_d16_hi v[8:9], v21, off offset:3136

.LBB0_968:
	ds_bpermute_b32 v12, v94, v9
	ds_bpermute_b32 v21, v94, v8
	s_and_b64 vcc, exec, s[2:3]
	s_waitcnt lgkmcnt(1)
	v_add_f32_e32 v9, v9, v12
	s_waitcnt lgkmcnt(0)
	v_add_f32_e32 v8, v8, v21
	ds_bpermute_b32 v12, v90, v9
	ds_bpermute_b32 v21, v90, v8
	s_waitcnt lgkmcnt(1)
	v_add_f32_e32 v9, v9, v12
	s_waitcnt lgkmcnt(0)
	v_add_f32_e32 v8, v8, v21
	ds_bpermute_b32 v12, v88, v9
	ds_bpermute_b32 v21, v88, v8
	s_waitcnt lgkmcnt(1)
	v_add_f32_e32 v9, v9, v12
	s_waitcnt lgkmcnt(0)
	v_add_f32_e32 v8, v8, v21
	ds_bpermute_b32 v12, v82, v9
	ds_bpermute_b32 v21, v82, v8
	s_waitcnt lgkmcnt(1)
	v_add_f32_e32 v12, v9, v12
	s_waitcnt lgkmcnt(0)
	v_add_f32_e32 v8, v8, v21
	ds_bpermute_b32 v186, v101, v12
	ds_bpermute_b32 v9, v101, v8
	s_cbranch_vccnz .LBB0_970
	v_lshlrev_b32_e32 v21, 16, v23
	v_lshlrev_b32_e32 v23, 16, v28
	v_sub_f32_e32 v23, v23, v21
	v_fmac_f32_e32 v21, v36, v23
	v_lshlrev_b32_e32 v23, 16, v77
	v_lshlrev_b32_e32 v28, 16, v141
	v_sub_f32_e32 v28, v28, v23
	v_fmac_f32_e32 v23, v64, v28
	s_waitcnt lgkmcnt(0)
	v_add_f32_e32 v28, v8, v9
	v_mul_f32_e32 v8, v23, v28
	s_nop 0
	v_cvt_pk_bf16_f32 v23, v8, v8
	v_add_co_u32_e32 v8, vcc, 0x6000, v16
	v_mul_f32_e32 v21, v21, v28
	s_nop 0
	v_addc_co_u32_e32 v9, vcc, 0, v17, vcc
	global_store_short_d16_hi v[8:9], v23, off
	s_nop 0
	v_cvt_pk_bf16_f32 v21, v21, v21
	global_store_short_d16_hi v[8:9], v21, off offset:64

.LBB0_975:
	ds_bpermute_b32 v13, v94, v9
	ds_bpermute_b32 v21, v94, v8
	s_and_b64 vcc, exec, s[2:3]
	s_waitcnt lgkmcnt(1)
	v_add_f32_e32 v9, v9, v13
	s_waitcnt lgkmcnt(0)
	v_add_f32_e32 v8, v8, v21
	ds_bpermute_b32 v13, v90, v9
	ds_bpermute_b32 v21, v90, v8
	s_waitcnt lgkmcnt(1)
	v_add_f32_e32 v9, v9, v13
	s_waitcnt lgkmcnt(0)
	v_add_f32_e32 v8, v8, v21
	ds_bpermute_b32 v13, v88, v9
	ds_bpermute_b32 v21, v88, v8
	s_waitcnt lgkmcnt(1)
	v_add_f32_e32 v9, v9, v13
	s_waitcnt lgkmcnt(0)
	v_add_f32_e32 v8, v8, v21
	ds_bpermute_b32 v13, v82, v9
	ds_bpermute_b32 v21, v82, v8
	s_waitcnt lgkmcnt(1)
	v_add_f32_e32 v13, v9, v13
	s_waitcnt lgkmcnt(0)
	v_add_f32_e32 v8, v8, v21
	ds_bpermute_b32 v76, v101, v13
	ds_bpermute_b32 v9, v101, v8
	s_cbranch_vccnz .LBB0_977
	v_lshlrev_b32_e32 v21, 16, v23
	v_lshlrev_b32_e32 v23, 16, v29
	v_sub_f32_e32 v23, v23, v21
	v_fmac_f32_e32 v21, v36, v23
	v_lshlrev_b32_e32 v23, 16, v28
	v_lshlrev_b32_e32 v28, 16, v141
	v_sub_f32_e32 v28, v28, v23
	v_fmac_f32_e32 v23, v64, v28
	s_waitcnt lgkmcnt(0)
	v_add_f32_e32 v28, v8, v9
	v_mul_f32_e32 v8, v23, v28
	s_nop 0
	v_cvt_pk_bf16_f32 v23, v8, v8
	v_add_co_u32_e32 v8, vcc, 0x6000, v16
	v_mul_f32_e32 v21, v21, v28
	s_nop 0
	v_addc_co_u32_e32 v9, vcc, 0, v17, vcc
	global_store_short_d16_hi v[8:9], v23, off offset:1024
	s_nop 0
	v_cvt_pk_bf16_f32 v21, v21, v21
	global_store_short_d16_hi v[8:9], v21, off offset:1088

.LBB0_982:
	ds_bpermute_b32 v14, v94, v9
	ds_bpermute_b32 v21, v94, v8
	s_and_b64 vcc, exec, s[2:3]
	s_waitcnt lgkmcnt(1)
	v_add_f32_e32 v9, v9, v14
	s_waitcnt lgkmcnt(0)
	v_add_f32_e32 v8, v8, v21
	ds_bpermute_b32 v14, v90, v9
	ds_bpermute_b32 v21, v90, v8
	s_waitcnt lgkmcnt(1)
	v_add_f32_e32 v9, v9, v14
	s_waitcnt lgkmcnt(0)
	v_add_f32_e32 v8, v8, v21
	ds_bpermute_b32 v14, v88, v9
	ds_bpermute_b32 v21, v88, v8
	s_waitcnt lgkmcnt(1)
	v_add_f32_e32 v9, v9, v14
	s_waitcnt lgkmcnt(0)
	v_add_f32_e32 v8, v8, v21
	ds_bpermute_b32 v14, v82, v9
	ds_bpermute_b32 v21, v82, v8
	s_waitcnt lgkmcnt(1)
	v_add_f32_e32 v14, v9, v14
	s_waitcnt lgkmcnt(0)
	v_add_f32_e32 v8, v8, v21
	ds_bpermute_b32 v30, v101, v14
	ds_bpermute_b32 v9, v101, v8
	s_cbranch_vccnz .LBB0_984
	v_lshlrev_b32_e32 v21, 16, v23
	v_lshlrev_b32_e32 v23, 16, v73
	v_sub_f32_e32 v23, v23, v21
	v_fmac_f32_e32 v21, v36, v23
	v_lshlrev_b32_e32 v23, 16, v28
	v_lshlrev_b32_e32 v28, 16, v29
	v_sub_f32_e32 v28, v28, v23
	v_fmac_f32_e32 v23, v64, v28
	s_waitcnt lgkmcnt(0)
	v_add_f32_e32 v28, v8, v9
	v_mul_f32_e32 v8, v23, v28
	s_nop 0
	v_cvt_pk_bf16_f32 v23, v8, v8
	v_add_co_u32_e32 v8, vcc, 0x6000, v16
	v_mul_f32_e32 v21, v21, v28
	s_nop 0
	v_addc_co_u32_e32 v9, vcc, 0, v17, vcc
	global_store_short_d16_hi v[8:9], v23, off offset:2048
	s_nop 0
	v_cvt_pk_bf16_f32 v21, v21, v21
	global_store_short_d16_hi v[8:9], v21, off offset:2112

.LBB0_989:
	ds_bpermute_b32 v20, v94, v9
	ds_bpermute_b32 v21, v94, v8
	s_and_b64 vcc, exec, s[2:3]
	s_waitcnt lgkmcnt(1)
	v_add_f32_e32 v9, v9, v20
	s_waitcnt lgkmcnt(0)
	v_add_f32_e32 v8, v8, v21
	ds_bpermute_b32 v20, v90, v9
	ds_bpermute_b32 v21, v90, v8
	s_waitcnt lgkmcnt(1)
	v_add_f32_e32 v9, v9, v20
	s_waitcnt lgkmcnt(0)
	v_add_f32_e32 v8, v8, v21
	ds_bpermute_b32 v20, v88, v9
	ds_bpermute_b32 v21, v88, v8
	s_waitcnt lgkmcnt(1)
	v_add_f32_e32 v9, v9, v20
	s_waitcnt lgkmcnt(0)
	v_add_f32_e32 v20, v8, v21
	ds_bpermute_b32 v8, v82, v9
	ds_bpermute_b32 v21, v82, v20
	s_waitcnt lgkmcnt(1)
	v_add_f32_e32 v8, v9, v8
	s_waitcnt lgkmcnt(0)
	v_add_f32_e32 v20, v20, v21
	ds_bpermute_b32 v9, v101, v8
	ds_bpermute_b32 v21, v101, v20
	s_cbranch_vccnz .LBB0_991
	v_lshlrev_b32_e32 v22, 16, v22
	v_lshlrev_b32_e32 v23, 16, v23
	v_sub_f32_e32 v23, v23, v22
	v_fmac_f32_e32 v22, v36, v23
	v_lshlrev_b32_e32 v15, 16, v15
	v_lshlrev_b32_e32 v23, 16, v28
	v_sub_f32_e32 v23, v23, v15
	v_fmac_f32_e32 v15, v64, v23
	s_waitcnt lgkmcnt(0)
	v_add_f32_e32 v20, v20, v21
	v_mul_f32_e32 v15, v15, v20
	s_nop 0
	v_add_co_u32_e32 v16, vcc, 0x6000, v16
	v_cvt_pk_bf16_f32 v15, v15, v15
	s_nop 0
	v_addc_co_u32_e32 v17, vcc, 0, v17, vcc
	global_store_short_d16_hi v[16:17], v15, off offset:3072
	v_mul_f32_e32 v15, v22, v20
	s_nop 0
	v_cvt_pk_bf16_f32 v15, v15, v15
	global_store_short_d16_hi v[16:17], v15, off offset:3136

.LBB0_1136:
	v_readlane_b32 s2, v255, 40
	s_add_i32 s0, s2, 1
	v_readlane_b32 s3, v255, 41
	v_writelane_b32 v255, s0, 42
	s_waitcnt lgkmcnt(0)
	s_barrier
	v_writelane_b32 v255, s1, 43
	s_mov_b32 s0, s1
	s_mov_b32 s1, -1
	v_readlane_b32 s3, v255, 5
	s_mul_i32 s2, s3, s0
	v_mbcnt_lo_u32_b32 v0, s1, 0
	v_readlane_b32 s4, v253, 2
	s_lshl_b32 s0, s0, 14
	v_mbcnt_hi_u32_b32 v0, s1, v0
	s_add_i32 s87, s2, s46
	v_readlane_b32 s5, v253, 3
	v_readlane_b32 s6, v253, 4
	v_readlane_b32 s7, v253, 5
	s_add_i32 s86, s0, 0
	v_and_b32_e32 v224, 63, v0
	s_mov_b64 s[12:13], s[6:7]
	s_mov_b64 s[10:11], s[4:5]
	s_cmpk_gt_i32 s87, 0xff
	s_mov_b64 s[0:1], -1
	s_cbranch_scc0 .LBB0_1315
	s_add_i32 s95, s87, 0xffffff00
	s_cmpk_gt_u32 s87, 0x17f
	s_cbranch_scc1 .LBB0_1147
	s_lshr_b32 s38, s95, 5
	s_and_b32 s0, s87, 31
	v_readlane_b32 s4, v255, 52
	v_readlane_b32 s5, v255, 53
	s_add_u32 s1, s12, s4
	s_addc_u32 s5, s13, s5
	s_lshl_b32 s4, s0, 9
	s_add_u32 s4, s1, s4
	v_lshlrev_b32_e32 v0, 1, v224
	s_addc_u32 s5, s5, 0
	v_ashrrev_i32_e32 v1, 31, v0
	v_lshl_add_u64 v[0:1], v[0:1], 2, s[4:5]
	s_mov_b32 s1, 0x399f2000
	v_add_co_u32_e32 v0, vcc, s1, v0
	s_mul_i32 s4, s38, 0x280000
	s_nop 0
	v_addc_co_u32_e32 v1, vcc, 0, v1, vcc
	global_load_dwordx2 v[0:1], v[0:1], off
	s_mul_i32 s5, s0, 0x14000
	s_mul_hi_u32 s1, s38, 0x280000
	s_add_u32 s4, s4, s5
	s_addc_u32 s1, s1, 0
	s_add_u32 s4, s12, s4
	v_ashrrev_i32_e32 v225, 31, v224
	s_addc_u32 s5, s13, s1
	v_lshl_add_u64 v[4:5], v[224:225], 2, s[4:5]
	s_mov_b64 s[4:5], 0x39a02400
	v_lshl_add_u64 v[4:5], v[4:5], 0, s[4:5]
	s_mul_i32 s4, s38, 0x140000
	s_mul_i32 s5, s0, 0xa000
	s_mul_hi_u32 s1, s38, 0x140000
	s_add_u32 s4, s4, s5
	s_addc_u32 s1, s1, 0
	s_add_u32 s4, s12, s4
	s_addc_u32 s5, s13, s1
	v_lshl_add_u64 v[6:7], v[224:225], 1, s[4:5]
	s_mov_b64 s[4:5], 0x3a402200
	v_lshl_add_u64 v[6:7], v[6:7], 0, s[4:5]
	v_mov_b32_e32 v10, 0
	s_mov_b32 s1, -4
	v_mov_b32_e32 v8, 0
	s_waitcnt vmcnt(0)
	v_pk_mov_b32 v[2:3], v[0:1], v[0:1] op_sel:[1,0]
	v_mov_b32_e32 v9, 0
	s_mov_b64 s[100:101], 0x1000
	v_mov_b64_e32 v[148:149], v[4:5]
	global_load_dword v101, v[148:149], off offset:-1024
	global_load_dword v100, v[148:149], off offset:-768
	global_load_dword v103, v[148:149], off offset:-512
	global_load_dword v102, v[148:149], off offset:-256
	global_load_dword v105, v[148:149], off
	global_load_dword v104, v[148:149], off offset:256
	global_load_dword v107, v[148:149], off offset:512
	global_load_dword v106, v[148:149], off offset:768
	global_load_dword v109, v[148:149], off offset:1024
	global_load_dword v108, v[148:149], off offset:1280
	global_load_dword v111, v[148:149], off offset:1536
	global_load_dword v110, v[148:149], off offset:1792
	global_load_dword v113, v[148:149], off offset:2048
	global_load_dword v112, v[148:149], off offset:2304
	global_load_dword v115, v[148:149], off offset:2560
	global_load_dword v114, v[148:149], off offset:2816
	v_lshl_add_u64 v[148:149], v[148:149], 0, s[100:101]
	global_load_dword v117, v[148:149], off offset:-1024
	global_load_dword v116, v[148:149], off offset:-768
	global_load_dword v119, v[148:149], off offset:-512
	global_load_dword v118, v[148:149], off offset:-256
	global_load_dword v121, v[148:149], off
	global_load_dword v120, v[148:149], off offset:256
	global_load_dword v123, v[148:149], off offset:512
	global_load_dword v122, v[148:149], off offset:768
	global_load_dword v125, v[148:149], off offset:1024
	global_load_dword v124, v[148:149], off offset:1280
	global_load_dword v127, v[148:149], off offset:1536
	global_load_dword v126, v[148:149], off offset:1792
	global_load_dword v129, v[148:149], off offset:2048
	global_load_dword v128, v[148:149], off offset:2304
	global_load_dword v131, v[148:149], off offset:2560
	global_load_dword v130, v[148:149], off offset:2816
	v_lshl_add_u64 v[148:149], v[148:149], 0, s[100:101]
	global_load_dword v133, v[148:149], off offset:-1024
	global_load_dword v132, v[148:149], off offset:-768
	global_load_dword v135, v[148:149], off offset:-512
	global_load_dword v134, v[148:149], off offset:-256
	global_load_dword v137, v[148:149], off
	global_load_dword v136, v[148:149], off offset:256
	global_load_dword v139, v[148:149], off offset:512
	global_load_dword v138, v[148:149], off offset:768
	global_load_dword v141, v[148:149], off offset:1024
	global_load_dword v140, v[148:149], off offset:1280
	global_load_dword v143, v[148:149], off offset:1536
	global_load_dword v142, v[148:149], off offset:1792
	global_load_dword v145, v[148:149], off offset:2048
	global_load_dword v144, v[148:149], off offset:2304
	global_load_dword v147, v[148:149], off offset:2560
	global_load_dword v146, v[148:149], off offset:2816
	v_lshl_add_u64 v[148:149], v[148:149], 0, s[100:101]
	s_waitcnt vmcnt(32)
	s_nop 0
	v_cvt_pk_bf16_f32 v10, v9, v9
	global_store_short_d16_hi v[6:7], v10, off offset:-512
	s_nop 0
	v_cvt_pk_bf16_f32 v11, v8, v8
	global_store_short_d16_hi v[6:7], v11, off offset:-384
	v_pk_mul_f32 v[16:17], v[0:1], v[8:9] op_sel_hi:[1,0]
	s_nop 0
	v_pk_fma_f32 v[18:19], v[2:3], v[8:9], v[16:17] op_sel:[0,1,0]
	v_pk_fma_f32 v[8:9], v[2:3], v[8:9], v[16:17] op_sel:[0,1,0] neg_lo:[0,0,1] neg_hi:[0,0,1]
	s_nop 0
	v_mov_b32_e32 v19, v9
	v_pk_add_f32 v[8:9], v[100:101], v[18:19]
	s_nop 0
	v_cvt_pk_bf16_f32 v10, v9, v9
	global_store_short_d16_hi v[6:7], v10, off offset:-256
	s_nop 0
	v_cvt_pk_bf16_f32 v11, v8, v8
	global_store_short_d16_hi v[6:7], v11, off offset:-128
	v_pk_mul_f32 v[16:17], v[0:1], v[8:9] op_sel_hi:[1,0]
	s_nop 0
	v_pk_fma_f32 v[18:19], v[2:3], v[8:9], v[16:17] op_sel:[0,1,0]
	v_pk_fma_f32 v[8:9], v[2:3], v[8:9], v[16:17] op_sel:[0,1,0] neg_lo:[0,0,1] neg_hi:[0,0,1]
	s_nop 0
	v_mov_b32_e32 v19, v9
	v_pk_add_f32 v[8:9], v[102:103], v[18:19]
	s_nop 0
	v_cvt_pk_bf16_f32 v10, v9, v9
	global_store_short_d16_hi v[6:7], v10, off
	s_nop 0
	v_cvt_pk_bf16_f32 v11, v8, v8
	global_store_short_d16_hi v[6:7], v11, off offset:128
	v_pk_mul_f32 v[16:17], v[0:1], v[8:9] op_sel_hi:[1,0]
	s_nop 0
	v_pk_fma_f32 v[18:19], v[2:3], v[8:9], v[16:17] op_sel:[0,1,0]
	v_pk_fma_f32 v[8:9], v[2:3], v[8:9], v[16:17] op_sel:[0,1,0] neg_lo:[0,0,1] neg_hi:[0,0,1]
	s_nop 0
	v_mov_b32_e32 v19, v9
	v_pk_add_f32 v[8:9], v[104:105], v[18:19]
	s_nop 0
	v_cvt_pk_bf16_f32 v10, v9, v9
	global_store_short_d16_hi v[6:7], v10, off offset:256
	s_nop 0
	v_cvt_pk_bf16_f32 v11, v8, v8
	global_store_short_d16_hi v[6:7], v11, off offset:384
	v_pk_mul_f32 v[16:17], v[0:1], v[8:9] op_sel_hi:[1,0]
	s_nop 0
	v_pk_fma_f32 v[18:19], v[2:3], v[8:9], v[16:17] op_sel:[0,1,0]
	v_pk_fma_f32 v[8:9], v[2:3], v[8:9], v[16:17] op_sel:[0,1,0] neg_lo:[0,0,1] neg_hi:[0,0,1]
	s_nop 0
	v_mov_b32_e32 v19, v9
	v_pk_add_f32 v[8:9], v[106:107], v[18:19]
	s_nop 0
	v_cvt_pk_bf16_f32 v10, v9, v9
	global_store_short_d16_hi v[6:7], v10, off offset:512
	s_nop 0
	v_cvt_pk_bf16_f32 v11, v8, v8
	global_store_short_d16_hi v[6:7], v11, off offset:640
	v_pk_mul_f32 v[16:17], v[0:1], v[8:9] op_sel_hi:[1,0]
	s_nop 0
	v_pk_fma_f32 v[18:19], v[2:3], v[8:9], v[16:17] op_sel:[0,1,0]
	v_pk_fma_f32 v[8:9], v[2:3], v[8:9], v[16:17] op_sel:[0,1,0] neg_lo:[0,0,1] neg_hi:[0,0,1]
	s_nop 0
	v_mov_b32_e32 v19, v9
	v_pk_add_f32 v[8:9], v[108:109], v[18:19]
	s_nop 0
	v_cvt_pk_bf16_f32 v10, v9, v9
	global_store_short_d16_hi v[6:7], v10, off offset:768
	s_nop 0
	v_cvt_pk_bf16_f32 v11, v8, v8
	global_store_short_d16_hi v[6:7], v11, off offset:896
	v_pk_mul_f32 v[16:17], v[0:1], v[8:9] op_sel_hi:[1,0]
	s_nop 0
	v_pk_fma_f32 v[18:19], v[2:3], v[8:9], v[16:17] op_sel:[0,1,0]
	v_pk_fma_f32 v[8:9], v[2:3], v[8:9], v[16:17] op_sel:[0,1,0] neg_lo:[0,0,1] neg_hi:[0,0,1]
	s_nop 0
	v_mov_b32_e32 v19, v9
	v_pk_add_f32 v[8:9], v[110:111], v[18:19]
	s_nop 0
	v_cvt_pk_bf16_f32 v10, v9, v9
	global_store_short_d16_hi v[6:7], v10, off offset:1024
	s_nop 0
	v_cvt_pk_bf16_f32 v11, v8, v8
	global_store_short_d16_hi v[6:7], v11, off offset:1152
	v_pk_mul_f32 v[16:17], v[0:1], v[8:9] op_sel_hi:[1,0]
	s_nop 0
	v_pk_fma_f32 v[18:19], v[2:3], v[8:9], v[16:17] op_sel:[0,1,0]
	v_pk_fma_f32 v[8:9], v[2:3], v[8:9], v[16:17] op_sel:[0,1,0] neg_lo:[0,0,1] neg_hi:[0,0,1]
	s_nop 0
	v_mov_b32_e32 v19, v9
	v_pk_add_f32 v[8:9], v[112:113], v[18:19]
	s_nop 0
	v_cvt_pk_bf16_f32 v10, v9, v9
	global_store_short_d16_hi v[6:7], v10, off offset:1280
	s_nop 0
	v_cvt_pk_bf16_f32 v11, v8, v8
	global_store_short_d16_hi v[6:7], v11, off offset:1408
	v_pk_mul_f32 v[16:17], v[0:1], v[8:9] op_sel_hi:[1,0]
	s_nop 0
	v_pk_fma_f32 v[18:19], v[2:3], v[8:9], v[16:17] op_sel:[0,1,0]
	v_pk_fma_f32 v[8:9], v[2:3], v[8:9], v[16:17] op_sel:[0,1,0] neg_lo:[0,0,1] neg_hi:[0,0,1]
	s_nop 0
	v_mov_b32_e32 v19, v9
	v_pk_add_f32 v[8:9], v[114:115], v[18:19]
	v_lshl_add_u64 v[6:7], v[6:7], 0, s[84:85]
	s_mov_b32 s1, 0
.Lmy_s5c_loop:
	global_load_dword v101, v[148:149], off offset:-1024
	global_load_dword v100, v[148:149], off offset:-768
	global_load_dword v103, v[148:149], off offset:-512
	global_load_dword v102, v[148:149], off offset:-256
	global_load_dword v105, v[148:149], off
	global_load_dword v104, v[148:149], off offset:256
	global_load_dword v107, v[148:149], off offset:512
	global_load_dword v106, v[148:149], off offset:768
	global_load_dword v109, v[148:149], off offset:1024
	global_load_dword v108, v[148:149], off offset:1280
	global_load_dword v111, v[148:149], off offset:1536
	global_load_dword v110, v[148:149], off offset:1792
	global_load_dword v113, v[148:149], off offset:2048
	global_load_dword v112, v[148:149], off offset:2304
	global_load_dword v115, v[148:149], off offset:2560
	global_load_dword v114, v[148:149], off offset:2816
	v_lshl_add_u64 v[148:149], v[148:149], 0, s[100:101]
	s_waitcnt vmcnt(48)
	s_nop 0
	v_cvt_pk_bf16_f32 v10, v9, v9
	global_store_short_d16_hi v[6:7], v10, off offset:-512
	s_nop 0
	v_cvt_pk_bf16_f32 v11, v8, v8
	global_store_short_d16_hi v[6:7], v11, off offset:-384
	v_pk_mul_f32 v[16:17], v[0:1], v[8:9] op_sel_hi:[1,0]
	s_nop 0
	v_pk_fma_f32 v[18:19], v[2:3], v[8:9], v[16:17] op_sel:[0,1,0]
	v_pk_fma_f32 v[8:9], v[2:3], v[8:9], v[16:17] op_sel:[0,1,0] neg_lo:[0,0,1] neg_hi:[0,0,1]
	s_nop 0
	v_mov_b32_e32 v19, v9
	v_pk_add_f32 v[8:9], v[116:117], v[18:19]
	s_nop 0
	v_cvt_pk_bf16_f32 v10, v9, v9
	global_store_short_d16_hi v[6:7], v10, off offset:-256
	s_nop 0
	v_cvt_pk_bf16_f32 v11, v8, v8
	global_store_short_d16_hi v[6:7], v11, off offset:-128
	v_pk_mul_f32 v[16:17], v[0:1], v[8:9] op_sel_hi:[1,0]
	s_nop 0
	v_pk_fma_f32 v[18:19], v[2:3], v[8:9], v[16:17] op_sel:[0,1,0]
	v_pk_fma_f32 v[8:9], v[2:3], v[8:9], v[16:17] op_sel:[0,1,0] neg_lo:[0,0,1] neg_hi:[0,0,1]
	s_nop 0
	v_mov_b32_e32 v19, v9
	v_pk_add_f32 v[8:9], v[118:119], v[18:19]
	s_nop 0
	v_cvt_pk_bf16_f32 v10, v9, v9
	global_store_short_d16_hi v[6:7], v10, off
	s_nop 0
	v_cvt_pk_bf16_f32 v11, v8, v8
	global_store_short_d16_hi v[6:7], v11, off offset:128
	v_pk_mul_f32 v[16:17], v[0:1], v[8:9] op_sel_hi:[1,0]
	s_nop 0
	v_pk_fma_f32 v[18:19], v[2:3], v[8:9], v[16:17] op_sel:[0,1,0]
	v_pk_fma_f32 v[8:9], v[2:3], v[8:9], v[16:17] op_sel:[0,1,0] neg_lo:[0,0,1] neg_hi:[0,0,1]
	s_nop 0
	v_mov_b32_e32 v19, v9
	v_pk_add_f32 v[8:9], v[120:121], v[18:19]
	s_nop 0
	v_cvt_pk_bf16_f32 v10, v9, v9
	global_store_short_d16_hi v[6:7], v10, off offset:256
	s_nop 0
	v_cvt_pk_bf16_f32 v11, v8, v8
	global_store_short_d16_hi v[6:7], v11, off offset:384
	v_pk_mul_f32 v[16:17], v[0:1], v[8:9] op_sel_hi:[1,0]
	s_nop 0
	v_pk_fma_f32 v[18:19], v[2:3], v[8:9], v[16:17] op_sel:[0,1,0]
	v_pk_fma_f32 v[8:9], v[2:3], v[8:9], v[16:17] op_sel:[0,1,0] neg_lo:[0,0,1] neg_hi:[0,0,1]
	s_nop 0
	v_mov_b32_e32 v19, v9
	v_pk_add_f32 v[8:9], v[122:123], v[18:19]
	s_nop 0
	v_cvt_pk_bf16_f32 v10, v9, v9
	global_store_short_d16_hi v[6:7], v10, off offset:512
	s_nop 0
	v_cvt_pk_bf16_f32 v11, v8, v8
	global_store_short_d16_hi v[6:7], v11, off offset:640
	v_pk_mul_f32 v[16:17], v[0:1], v[8:9] op_sel_hi:[1,0]
	s_nop 0
	v_pk_fma_f32 v[18:19], v[2:3], v[8:9], v[16:17] op_sel:[0,1,0]
	v_pk_fma_f32 v[8:9], v[2:3], v[8:9], v[16:17] op_sel:[0,1,0] neg_lo:[0,0,1] neg_hi:[0,0,1]
	s_nop 0
	v_mov_b32_e32 v19, v9
	v_pk_add_f32 v[8:9], v[124:125], v[18:19]
	s_nop 0
	v_cvt_pk_bf16_f32 v10, v9, v9
	global_store_short_d16_hi v[6:7], v10, off offset:768
	s_nop 0
	v_cvt_pk_bf16_f32 v11, v8, v8
	global_store_short_d16_hi v[6:7], v11, off offset:896
	v_pk_mul_f32 v[16:17], v[0:1], v[8:9] op_sel_hi:[1,0]
	s_nop 0
	v_pk_fma_f32 v[18:19], v[2:3], v[8:9], v[16:17] op_sel:[0,1,0]
	v_pk_fma_f32 v[8:9], v[2:3], v[8:9], v[16:17] op_sel:[0,1,0] neg_lo:[0,0,1] neg_hi:[0,0,1]
	s_nop 0
	v_mov_b32_e32 v19, v9
	v_pk_add_f32 v[8:9], v[126:127], v[18:19]
	s_nop 0
	v_cvt_pk_bf16_f32 v10, v9, v9
	global_store_short_d16_hi v[6:7], v10, off offset:1024
	s_nop 0
	v_cvt_pk_bf16_f32 v11, v8, v8
	global_store_short_d16_hi v[6:7], v11, off offset:1152
	v_pk_mul_f32 v[16:17], v[0:1], v[8:9] op_sel_hi:[1,0]
	s_nop 0
	v_pk_fma_f32 v[18:19], v[2:3], v[8:9], v[16:17] op_sel:[0,1,0]
	v_pk_fma_f32 v[8:9], v[2:3], v[8:9], v[16:17] op_sel:[0,1,0] neg_lo:[0,0,1] neg_hi:[0,0,1]
	s_nop 0
	v_mov_b32_e32 v19, v9
	v_pk_add_f32 v[8:9], v[128:129], v[18:19]
	s_nop 0
	v_cvt_pk_bf16_f32 v10, v9, v9
	global_store_short_d16_hi v[6:7], v10, off offset:1280
	s_nop 0
	v_cvt_pk_bf16_f32 v11, v8, v8
	global_store_short_d16_hi v[6:7], v11, off offset:1408
	v_pk_mul_f32 v[16:17], v[0:1], v[8:9] op_sel_hi:[1,0]
	s_nop 0
	v_pk_fma_f32 v[18:19], v[2:3], v[8:9], v[16:17] op_sel:[0,1,0]
	v_pk_fma_f32 v[8:9], v[2:3], v[8:9], v[16:17] op_sel:[0,1,0] neg_lo:[0,0,1] neg_hi:[0,0,1]
	s_nop 0
	v_mov_b32_e32 v19, v9
	v_pk_add_f32 v[8:9], v[130:131], v[18:19]
	v_lshl_add_u64 v[6:7], v[6:7], 0, s[84:85]
	global_load_dword v117, v[148:149], off offset:-1024
	global_load_dword v116, v[148:149], off offset:-768
	global_load_dword v119, v[148:149], off offset:-512
	global_load_dword v118, v[148:149], off offset:-256
	global_load_dword v121, v[148:149], off
	global_load_dword v120, v[148:149], off offset:256
	global_load_dword v123, v[148:149], off offset:512
	global_load_dword v122, v[148:149], off offset:768
	global_load_dword v125, v[148:149], off offset:1024
	global_load_dword v124, v[148:149], off offset:1280
	global_load_dword v127, v[148:149], off offset:1536
	global_load_dword v126, v[148:149], off offset:1792
	global_load_dword v129, v[148:149], off offset:2048
	global_load_dword v128, v[148:149], off offset:2304
	global_load_dword v131, v[148:149], off offset:2560
	global_load_dword v130, v[148:149], off offset:2816
	v_lshl_add_u64 v[148:149], v[148:149], 0, s[100:101]
	s_waitcnt vmcnt(48)
	s_nop 0
	v_cvt_pk_bf16_f32 v10, v9, v9
	global_store_short_d16_hi v[6:7], v10, off offset:-512
	s_nop 0
	v_cvt_pk_bf16_f32 v11, v8, v8
	global_store_short_d16_hi v[6:7], v11, off offset:-384
	v_pk_mul_f32 v[16:17], v[0:1], v[8:9] op_sel_hi:[1,0]
	s_nop 0
	v_pk_fma_f32 v[18:19], v[2:3], v[8:9], v[16:17] op_sel:[0,1,0]
	v_pk_fma_f32 v[8:9], v[2:3], v[8:9], v[16:17] op_sel:[0,1,0] neg_lo:[0,0,1] neg_hi:[0,0,1]
	s_nop 0
	v_mov_b32_e32 v19, v9
	v_pk_add_f32 v[8:9], v[132:133], v[18:19]
	s_nop 0
	v_cvt_pk_bf16_f32 v10, v9, v9
	global_store_short_d16_hi v[6:7], v10, off offset:-256
	s_nop 0
	v_cvt_pk_bf16_f32 v11, v8, v8
	global_store_short_d16_hi v[6:7], v11, off offset:-128
	v_pk_mul_f32 v[16:17], v[0:1], v[8:9] op_sel_hi:[1,0]
	s_nop 0
	v_pk_fma_f32 v[18:19], v[2:3], v[8:9], v[16:17] op_sel:[0,1,0]
	v_pk_fma_f32 v[8:9], v[2:3], v[8:9], v[16:17] op_sel:[0,1,0] neg_lo:[0,0,1] neg_hi:[0,0,1]
	s_nop 0
	v_mov_b32_e32 v19, v9
	v_pk_add_f32 v[8:9], v[134:135], v[18:19]
	s_nop 0
	v_cvt_pk_bf16_f32 v10, v9, v9
	global_store_short_d16_hi v[6:7], v10, off
	s_nop 0
	v_cvt_pk_bf16_f32 v11, v8, v8
	global_store_short_d16_hi v[6:7], v11, off offset:128
	v_pk_mul_f32 v[16:17], v[0:1], v[8:9] op_sel_hi:[1,0]
	s_nop 0
	v_pk_fma_f32 v[18:19], v[2:3], v[8:9], v[16:17] op_sel:[0,1,0]
	v_pk_fma_f32 v[8:9], v[2:3], v[8:9], v[16:17] op_sel:[0,1,0] neg_lo:[0,0,1] neg_hi:[0,0,1]
	s_nop 0
	v_mov_b32_e32 v19, v9
	v_pk_add_f32 v[8:9], v[136:137], v[18:19]
	s_nop 0
	v_cvt_pk_bf16_f32 v10, v9, v9
	global_store_short_d16_hi v[6:7], v10, off offset:256
	s_nop 0
	v_cvt_pk_bf16_f32 v11, v8, v8
	global_store_short_d16_hi v[6:7], v11, off offset:384
	v_pk_mul_f32 v[16:17], v[0:1], v[8:9] op_sel_hi:[1,0]
	s_nop 0
	v_pk_fma_f32 v[18:19], v[2:3], v[8:9], v[16:17] op_sel:[0,1,0]
	v_pk_fma_f32 v[8:9], v[2:3], v[8:9], v[16:17] op_sel:[0,1,0] neg_lo:[0,0,1] neg_hi:[0,0,1]
	s_nop 0
	v_mov_b32_e32 v19, v9
	v_pk_add_f32 v[8:9], v[138:139], v[18:19]
	s_nop 0
	v_cvt_pk_bf16_f32 v10, v9, v9
	global_store_short_d16_hi v[6:7], v10, off offset:512
	s_nop 0
	v_cvt_pk_bf16_f32 v11, v8, v8
	global_store_short_d16_hi v[6:7], v11, off offset:640
	v_pk_mul_f32 v[16:17], v[0:1], v[8:9] op_sel_hi:[1,0]
	s_nop 0
	v_pk_fma_f32 v[18:19], v[2:3], v[8:9], v[16:17] op_sel:[0,1,0]
	v_pk_fma_f32 v[8:9], v[2:3], v[8:9], v[16:17] op_sel:[0,1,0] neg_lo:[0,0,1] neg_hi:[0,0,1]
	s_nop 0
	v_mov_b32_e32 v19, v9
	v_pk_add_f32 v[8:9], v[140:141], v[18:19]
	s_nop 0
	v_cvt_pk_bf16_f32 v10, v9, v9
	global_store_short_d16_hi v[6:7], v10, off offset:768
	s_nop 0
	v_cvt_pk_bf16_f32 v11, v8, v8
	global_store_short_d16_hi v[6:7], v11, off offset:896
	v_pk_mul_f32 v[16:17], v[0:1], v[8:9] op_sel_hi:[1,0]
	s_nop 0
	v_pk_fma_f32 v[18:19], v[2:3], v[8:9], v[16:17] op_sel:[0,1,0]
	v_pk_fma_f32 v[8:9], v[2:3], v[8:9], v[16:17] op_sel:[0,1,0] neg_lo:[0,0,1] neg_hi:[0,0,1]
	s_nop 0
	v_mov_b32_e32 v19, v9
	v_pk_add_f32 v[8:9], v[142:143], v[18:19]
	s_nop 0
	v_cvt_pk_bf16_f32 v10, v9, v9
	global_store_short_d16_hi v[6:7], v10, off offset:1024
	s_nop 0
	v_cvt_pk_bf16_f32 v11, v8, v8
	global_store_short_d16_hi v[6:7], v11, off offset:1152
	v_pk_mul_f32 v[16:17], v[0:1], v[8:9] op_sel_hi:[1,0]
	s_nop 0
	v_pk_fma_f32 v[18:19], v[2:3], v[8:9], v[16:17] op_sel:[0,1,0]
	v_pk_fma_f32 v[8:9], v[2:3], v[8:9], v[16:17] op_sel:[0,1,0] neg_lo:[0,0,1] neg_hi:[0,0,1]
	s_nop 0
	v_mov_b32_e32 v19, v9
	v_pk_add_f32 v[8:9], v[144:145], v[18:19]
	s_nop 0
	v_cvt_pk_bf16_f32 v10, v9, v9
	global_store_short_d16_hi v[6:7], v10, off offset:1280
	s_nop 0
	v_cvt_pk_bf16_f32 v11, v8, v8
	global_store_short_d16_hi v[6:7], v11, off offset:1408
	v_pk_mul_f32 v[16:17], v[0:1], v[8:9] op_sel_hi:[1,0]
	s_nop 0
	v_pk_fma_f32 v[18:19], v[2:3], v[8:9], v[16:17] op_sel:[0,1,0]
	v_pk_fma_f32 v[8:9], v[2:3], v[8:9], v[16:17] op_sel:[0,1,0] neg_lo:[0,0,1] neg_hi:[0,0,1]
	s_nop 0
	v_mov_b32_e32 v19, v9
	v_pk_add_f32 v[8:9], v[146:147], v[18:19]
	v_lshl_add_u64 v[6:7], v[6:7], 0, s[84:85]
	global_load_dword v133, v[148:149], off offset:-1024
	global_load_dword v132, v[148:149], off offset:-768
	global_load_dword v135, v[148:149], off offset:-512
	global_load_dword v134, v[148:149], off offset:-256
	global_load_dword v137, v[148:149], off
	global_load_dword v136, v[148:149], off offset:256
	global_load_dword v139, v[148:149], off offset:512
	global_load_dword v138, v[148:149], off offset:768
	global_load_dword v141, v[148:149], off offset:1024
	global_load_dword v140, v[148:149], off offset:1280
	global_load_dword v143, v[148:149], off offset:1536
	global_load_dword v142, v[148:149], off offset:1792
	global_load_dword v145, v[148:149], off offset:2048
	global_load_dword v144, v[148:149], off offset:2304
	global_load_dword v147, v[148:149], off offset:2560
	global_load_dword v146, v[148:149], off offset:2816
	v_lshl_add_u64 v[148:149], v[148:149], 0, s[100:101]
	s_waitcnt vmcnt(48)
	s_nop 0
	v_cvt_pk_bf16_f32 v10, v9, v9
	global_store_short_d16_hi v[6:7], v10, off offset:-512
	s_nop 0
	v_cvt_pk_bf16_f32 v11, v8, v8
	global_store_short_d16_hi v[6:7], v11, off offset:-384
	v_pk_mul_f32 v[16:17], v[0:1], v[8:9] op_sel_hi:[1,0]
	s_nop 0
	v_pk_fma_f32 v[18:19], v[2:3], v[8:9], v[16:17] op_sel:[0,1,0]
	v_pk_fma_f32 v[8:9], v[2:3], v[8:9], v[16:17] op_sel:[0,1,0] neg_lo:[0,0,1] neg_hi:[0,0,1]
	s_nop 0
	v_mov_b32_e32 v19, v9
	v_pk_add_f32 v[8:9], v[100:101], v[18:19]
	s_nop 0
	v_cvt_pk_bf16_f32 v10, v9, v9
	global_store_short_d16_hi v[6:7], v10, off offset:-256
	s_nop 0
	v_cvt_pk_bf16_f32 v11, v8, v8
	global_store_short_d16_hi v[6:7], v11, off offset:-128
	v_pk_mul_f32 v[16:17], v[0:1], v[8:9] op_sel_hi:[1,0]
	s_nop 0
	v_pk_fma_f32 v[18:19], v[2:3], v[8:9], v[16:17] op_sel:[0,1,0]
	v_pk_fma_f32 v[8:9], v[2:3], v[8:9], v[16:17] op_sel:[0,1,0] neg_lo:[0,0,1] neg_hi:[0,0,1]
	s_nop 0
	v_mov_b32_e32 v19, v9
	v_pk_add_f32 v[8:9], v[102:103], v[18:19]
	s_nop 0
	v_cvt_pk_bf16_f32 v10, v9, v9
	global_store_short_d16_hi v[6:7], v10, off
	s_nop 0
	v_cvt_pk_bf16_f32 v11, v8, v8
	global_store_short_d16_hi v[6:7], v11, off offset:128
	v_pk_mul_f32 v[16:17], v[0:1], v[8:9] op_sel_hi:[1,0]
	s_nop 0
	v_pk_fma_f32 v[18:19], v[2:3], v[8:9], v[16:17] op_sel:[0,1,0]
	v_pk_fma_f32 v[8:9], v[2:3], v[8:9], v[16:17] op_sel:[0,1,0] neg_lo:[0,0,1] neg_hi:[0,0,1]
	s_nop 0
	v_mov_b32_e32 v19, v9
	v_pk_add_f32 v[8:9], v[104:105], v[18:19]
	s_nop 0
	v_cvt_pk_bf16_f32 v10, v9, v9
	global_store_short_d16_hi v[6:7], v10, off offset:256
	s_nop 0
	v_cvt_pk_bf16_f32 v11, v8, v8
	global_store_short_d16_hi v[6:7], v11, off offset:384
	v_pk_mul_f32 v[16:17], v[0:1], v[8:9] op_sel_hi:[1,0]
	s_nop 0
	v_pk_fma_f32 v[18:19], v[2:3], v[8:9], v[16:17] op_sel:[0,1,0]
	v_pk_fma_f32 v[8:9], v[2:3], v[8:9], v[16:17] op_sel:[0,1,0] neg_lo:[0,0,1] neg_hi:[0,0,1]
	s_nop 0
	v_mov_b32_e32 v19, v9
	v_pk_add_f32 v[8:9], v[106:107], v[18:19]
	s_nop 0
	v_cvt_pk_bf16_f32 v10, v9, v9
	global_store_short_d16_hi v[6:7], v10, off offset:512
	s_nop 0
	v_cvt_pk_bf16_f32 v11, v8, v8
	global_store_short_d16_hi v[6:7], v11, off offset:640
	v_pk_mul_f32 v[16:17], v[0:1], v[8:9] op_sel_hi:[1,0]
	s_nop 0
	v_pk_fma_f32 v[18:19], v[2:3], v[8:9], v[16:17] op_sel:[0,1,0]
	v_pk_fma_f32 v[8:9], v[2:3], v[8:9], v[16:17] op_sel:[0,1,0] neg_lo:[0,0,1] neg_hi:[0,0,1]
	s_nop 0
	v_mov_b32_e32 v19, v9
	v_pk_add_f32 v[8:9], v[108:109], v[18:19]
	s_nop 0
	v_cvt_pk_bf16_f32 v10, v9, v9
	global_store_short_d16_hi v[6:7], v10, off offset:768
	s_nop 0
	v_cvt_pk_bf16_f32 v11, v8, v8
	global_store_short_d16_hi v[6:7], v11, off offset:896
	v_pk_mul_f32 v[16:17], v[0:1], v[8:9] op_sel_hi:[1,0]
	s_nop 0
	v_pk_fma_f32 v[18:19], v[2:3], v[8:9], v[16:17] op_sel:[0,1,0]
	v_pk_fma_f32 v[8:9], v[2:3], v[8:9], v[16:17] op_sel:[0,1,0] neg_lo:[0,0,1] neg_hi:[0,0,1]
	s_nop 0
	v_mov_b32_e32 v19, v9
	v_pk_add_f32 v[8:9], v[110:111], v[18:19]
	s_nop 0
	v_cvt_pk_bf16_f32 v10, v9, v9
	global_store_short_d16_hi v[6:7], v10, off offset:1024
	s_nop 0
	v_cvt_pk_bf16_f32 v11, v8, v8
	global_store_short_d16_hi v[6:7], v11, off offset:1152
	v_pk_mul_f32 v[16:17], v[0:1], v[8:9] op_sel_hi:[1,0]
	s_nop 0
	v_pk_fma_f32 v[18:19], v[2:3], v[8:9], v[16:17] op_sel:[0,1,0]
	v_pk_fma_f32 v[8:9], v[2:3], v[8:9], v[16:17] op_sel:[0,1,0] neg_lo:[0,0,1] neg_hi:[0,0,1]
	s_nop 0
	v_mov_b32_e32 v19, v9
	v_pk_add_f32 v[8:9], v[112:113], v[18:19]
	s_nop 0
	v_cvt_pk_bf16_f32 v10, v9, v9
	global_store_short_d16_hi v[6:7], v10, off offset:1280
	s_nop 0
	v_cvt_pk_bf16_f32 v11, v8, v8
	global_store_short_d16_hi v[6:7], v11, off offset:1408
	v_pk_mul_f32 v[16:17], v[0:1], v[8:9] op_sel_hi:[1,0]
	s_nop 0
	v_pk_fma_f32 v[18:19], v[2:3], v[8:9], v[16:17] op_sel:[0,1,0]
	v_pk_fma_f32 v[8:9], v[2:3], v[8:9], v[16:17] op_sel:[0,1,0] neg_lo:[0,0,1] neg_hi:[0,0,1]
	s_nop 0
	v_mov_b32_e32 v19, v9
	v_pk_add_f32 v[8:9], v[114:115], v[18:19]
	v_lshl_add_u64 v[6:7], v[6:7], 0, s[84:85]
	s_add_i32 s1, s1, 1
	s_cmp_lt_u32 s1, 4
	s_cbranch_scc1 .Lmy_s5c_loop
	global_load_dword v101, v[148:149], off offset:-1024
	global_load_dword v100, v[148:149], off offset:-768
	global_load_dword v103, v[148:149], off offset:-512
	global_load_dword v102, v[148:149], off offset:-256
	global_load_dword v105, v[148:149], off
	global_load_dword v104, v[148:149], off offset:256
	global_load_dword v107, v[148:149], off offset:512
	global_load_dword v106, v[148:149], off offset:768
	global_load_dword v109, v[148:149], off offset:1024
	global_load_dword v108, v[148:149], off offset:1280
	global_load_dword v111, v[148:149], off offset:1536
	global_load_dword v110, v[148:149], off offset:1792
	global_load_dword v113, v[148:149], off offset:2048
	global_load_dword v112, v[148:149], off offset:2304
	global_load_dword v115, v[148:149], off offset:2560
	global_load_dword v114, v[148:149], off offset:2816
	v_lshl_add_u64 v[148:149], v[148:149], 0, s[100:101]
	s_waitcnt vmcnt(63)
	s_nop 0
	v_cvt_pk_bf16_f32 v10, v9, v9
	global_store_short_d16_hi v[6:7], v10, off offset:-512
	s_nop 0
	v_cvt_pk_bf16_f32 v11, v8, v8
	global_store_short_d16_hi v[6:7], v11, off offset:-384
	v_pk_mul_f32 v[16:17], v[0:1], v[8:9] op_sel_hi:[1,0]
	s_nop 0
	v_pk_fma_f32 v[18:19], v[2:3], v[8:9], v[16:17] op_sel:[0,1,0]
	v_pk_fma_f32 v[8:9], v[2:3], v[8:9], v[16:17] op_sel:[0,1,0] neg_lo:[0,0,1] neg_hi:[0,0,1]
	s_nop 0
	v_mov_b32_e32 v19, v9
	v_pk_add_f32 v[8:9], v[116:117], v[18:19]
	s_nop 0
	v_cvt_pk_bf16_f32 v10, v9, v9
	global_store_short_d16_hi v[6:7], v10, off offset:-256
	s_nop 0
	v_cvt_pk_bf16_f32 v11, v8, v8
	global_store_short_d16_hi v[6:7], v11, off offset:-128
	v_pk_mul_f32 v[16:17], v[0:1], v[8:9] op_sel_hi:[1,0]
	s_nop 0
	v_pk_fma_f32 v[18:19], v[2:3], v[8:9], v[16:17] op_sel:[0,1,0]
	v_pk_fma_f32 v[8:9], v[2:3], v[8:9], v[16:17] op_sel:[0,1,0] neg_lo:[0,0,1] neg_hi:[0,0,1]
	s_nop 0
	v_mov_b32_e32 v19, v9
	v_pk_add_f32 v[8:9], v[118:119], v[18:19]
	s_nop 0
	v_cvt_pk_bf16_f32 v10, v9, v9
	global_store_short_d16_hi v[6:7], v10, off
	s_nop 0
	v_cvt_pk_bf16_f32 v11, v8, v8
	global_store_short_d16_hi v[6:7], v11, off offset:128
	v_pk_mul_f32 v[16:17], v[0:1], v[8:9] op_sel_hi:[1,0]
	s_nop 0
	v_pk_fma_f32 v[18:19], v[2:3], v[8:9], v[16:17] op_sel:[0,1,0]
	v_pk_fma_f32 v[8:9], v[2:3], v[8:9], v[16:17] op_sel:[0,1,0] neg_lo:[0,0,1] neg_hi:[0,0,1]
	s_nop 0
	v_mov_b32_e32 v19, v9
	v_pk_add_f32 v[8:9], v[120:121], v[18:19]
	s_nop 0
	v_cvt_pk_bf16_f32 v10, v9, v9
	global_store_short_d16_hi v[6:7], v10, off offset:256
	s_nop 0
	v_cvt_pk_bf16_f32 v11, v8, v8
	global_store_short_d16_hi v[6:7], v11, off offset:384
	v_pk_mul_f32 v[16:17], v[0:1], v[8:9] op_sel_hi:[1,0]
	s_nop 0
	v_pk_fma_f32 v[18:19], v[2:3], v[8:9], v[16:17] op_sel:[0,1,0]
	v_pk_fma_f32 v[8:9], v[2:3], v[8:9], v[16:17] op_sel:[0,1,0] neg_lo:[0,0,1] neg_hi:[0,0,1]
	s_nop 0
	v_mov_b32_e32 v19, v9
	v_pk_add_f32 v[8:9], v[122:123], v[18:19]
	s_nop 0
	v_cvt_pk_bf16_f32 v10, v9, v9
	global_store_short_d16_hi v[6:7], v10, off offset:512
	s_nop 0
	v_cvt_pk_bf16_f32 v11, v8, v8
	global_store_short_d16_hi v[6:7], v11, off offset:640
	v_pk_mul_f32 v[16:17], v[0:1], v[8:9] op_sel_hi:[1,0]
	s_nop 0
	v_pk_fma_f32 v[18:19], v[2:3], v[8:9], v[16:17] op_sel:[0,1,0]
	v_pk_fma_f32 v[8:9], v[2:3], v[8:9], v[16:17] op_sel:[0,1,0] neg_lo:[0,0,1] neg_hi:[0,0,1]
	s_nop 0
	v_mov_b32_e32 v19, v9
	v_pk_add_f32 v[8:9], v[124:125], v[18:19]
	s_nop 0
	v_cvt_pk_bf16_f32 v10, v9, v9
	global_store_short_d16_hi v[6:7], v10, off offset:768
	s_nop 0
	v_cvt_pk_bf16_f32 v11, v8, v8
	global_store_short_d16_hi v[6:7], v11, off offset:896
	v_pk_mul_f32 v[16:17], v[0:1], v[8:9] op_sel_hi:[1,0]
	s_nop 0
	v_pk_fma_f32 v[18:19], v[2:3], v[8:9], v[16:17] op_sel:[0,1,0]
	v_pk_fma_f32 v[8:9], v[2:3], v[8:9], v[16:17] op_sel:[0,1,0] neg_lo:[0,0,1] neg_hi:[0,0,1]
	s_nop 0
	v_mov_b32_e32 v19, v9
	v_pk_add_f32 v[8:9], v[126:127], v[18:19]
	s_nop 0
	v_cvt_pk_bf16_f32 v10, v9, v9
	global_store_short_d16_hi v[6:7], v10, off offset:1024
	s_nop 0
	v_cvt_pk_bf16_f32 v11, v8, v8
	global_store_short_d16_hi v[6:7], v11, off offset:1152
	v_pk_mul_f32 v[16:17], v[0:1], v[8:9] op_sel_hi:[1,0]
	s_nop 0
	v_pk_fma_f32 v[18:19], v[2:3], v[8:9], v[16:17] op_sel:[0,1,0]
	v_pk_fma_f32 v[8:9], v[2:3], v[8:9], v[16:17] op_sel:[0,1,0] neg_lo:[0,0,1] neg_hi:[0,0,1]
	s_nop 0
	v_mov_b32_e32 v19, v9
	v_pk_add_f32 v[8:9], v[128:129], v[18:19]
	s_nop 0
	v_cvt_pk_bf16_f32 v10, v9, v9
	global_store_short_d16_hi v[6:7], v10, off offset:1280
	s_nop 0
	v_cvt_pk_bf16_f32 v11, v8, v8
	global_store_short_d16_hi v[6:7], v11, off offset:1408
	v_pk_mul_f32 v[16:17], v[0:1], v[8:9] op_sel_hi:[1,0]
	s_nop 0
	v_pk_fma_f32 v[18:19], v[2:3], v[8:9], v[16:17] op_sel:[0,1,0]
	v_pk_fma_f32 v[8:9], v[2:3], v[8:9], v[16:17] op_sel:[0,1,0] neg_lo:[0,0,1] neg_hi:[0,0,1]
	s_nop 0
	v_mov_b32_e32 v19, v9
	v_pk_add_f32 v[8:9], v[130:131], v[18:19]
	v_lshl_add_u64 v[6:7], v[6:7], 0, s[84:85]
	global_load_dword v117, v[148:149], off offset:-1024
	global_load_dword v116, v[148:149], off offset:-768
	v_lshl_add_u64 v[148:149], v[148:149], 0, s[100:101]
	s_waitcnt vmcnt(50)
	s_nop 0
	v_cvt_pk_bf16_f32 v10, v9, v9
	global_store_short_d16_hi v[6:7], v10, off offset:-512
	s_nop 0
	v_cvt_pk_bf16_f32 v11, v8, v8
	global_store_short_d16_hi v[6:7], v11, off offset:-384
	v_pk_mul_f32 v[16:17], v[0:1], v[8:9] op_sel_hi:[1,0]
	s_nop 0
	v_pk_fma_f32 v[18:19], v[2:3], v[8:9], v[16:17] op_sel:[0,1,0]
	v_pk_fma_f32 v[8:9], v[2:3], v[8:9], v[16:17] op_sel:[0,1,0] neg_lo:[0,0,1] neg_hi:[0,0,1]
	s_nop 0
	v_mov_b32_e32 v19, v9
	v_pk_add_f32 v[8:9], v[132:133], v[18:19]
	s_nop 0
	v_cvt_pk_bf16_f32 v10, v9, v9
	global_store_short_d16_hi v[6:7], v10, off offset:-256
	s_nop 0
	v_cvt_pk_bf16_f32 v11, v8, v8
	global_store_short_d16_hi v[6:7], v11, off offset:-128
	v_pk_mul_f32 v[16:17], v[0:1], v[8:9] op_sel_hi:[1,0]
	s_nop 0
	v_pk_fma_f32 v[18:19], v[2:3], v[8:9], v[16:17] op_sel:[0,1,0]
	v_pk_fma_f32 v[8:9], v[2:3], v[8:9], v[16:17] op_sel:[0,1,0] neg_lo:[0,0,1] neg_hi:[0,0,1]
	s_nop 0
	v_mov_b32_e32 v19, v9
	v_pk_add_f32 v[8:9], v[134:135], v[18:19]
	s_nop 0
	v_cvt_pk_bf16_f32 v10, v9, v9
	global_store_short_d16_hi v[6:7], v10, off
	s_nop 0
	v_cvt_pk_bf16_f32 v11, v8, v8
	global_store_short_d16_hi v[6:7], v11, off offset:128
	v_pk_mul_f32 v[16:17], v[0:1], v[8:9] op_sel_hi:[1,0]
	s_nop 0
	v_pk_fma_f32 v[18:19], v[2:3], v[8:9], v[16:17] op_sel:[0,1,0]
	v_pk_fma_f32 v[8:9], v[2:3], v[8:9], v[16:17] op_sel:[0,1,0] neg_lo:[0,0,1] neg_hi:[0,0,1]
	s_nop 0
	v_mov_b32_e32 v19, v9
	v_pk_add_f32 v[8:9], v[136:137], v[18:19]
	s_nop 0
	v_cvt_pk_bf16_f32 v10, v9, v9
	global_store_short_d16_hi v[6:7], v10, off offset:256
	s_nop 0
	v_cvt_pk_bf16_f32 v11, v8, v8
	global_store_short_d16_hi v[6:7], v11, off offset:384
	v_pk_mul_f32 v[16:17], v[0:1], v[8:9] op_sel_hi:[1,0]
	s_nop 0
	v_pk_fma_f32 v[18:19], v[2:3], v[8:9], v[16:17] op_sel:[0,1,0]
	v_pk_fma_f32 v[8:9], v[2:3], v[8:9], v[16:17] op_sel:[0,1,0] neg_lo:[0,0,1] neg_hi:[0,0,1]
	s_nop 0
	v_mov_b32_e32 v19, v9
	v_pk_add_f32 v[8:9], v[138:139], v[18:19]
	s_nop 0
	v_cvt_pk_bf16_f32 v10, v9, v9
	global_store_short_d16_hi v[6:7], v10, off offset:512
	s_nop 0
	v_cvt_pk_bf16_f32 v11, v8, v8
	global_store_short_d16_hi v[6:7], v11, off offset:640
	v_pk_mul_f32 v[16:17], v[0:1], v[8:9] op_sel_hi:[1,0]
	s_nop 0
	v_pk_fma_f32 v[18:19], v[2:3], v[8:9], v[16:17] op_sel:[0,1,0]
	v_pk_fma_f32 v[8:9], v[2:3], v[8:9], v[16:17] op_sel:[0,1,0] neg_lo:[0,0,1] neg_hi:[0,0,1]
	s_nop 0
	v_mov_b32_e32 v19, v9
	v_pk_add_f32 v[8:9], v[140:141], v[18:19]
	s_nop 0
	v_cvt_pk_bf16_f32 v10, v9, v9
	global_store_short_d16_hi v[6:7], v10, off offset:768
	s_nop 0
	v_cvt_pk_bf16_f32 v11, v8, v8
	global_store_short_d16_hi v[6:7], v11, off offset:896
	v_pk_mul_f32 v[16:17], v[0:1], v[8:9] op_sel_hi:[1,0]
	s_nop 0
	v_pk_fma_f32 v[18:19], v[2:3], v[8:9], v[16:17] op_sel:[0,1,0]
	v_pk_fma_f32 v[8:9], v[2:3], v[8:9], v[16:17] op_sel:[0,1,0] neg_lo:[0,0,1] neg_hi:[0,0,1]
	s_nop 0
	v_mov_b32_e32 v19, v9
	v_pk_add_f32 v[8:9], v[142:143], v[18:19]
	s_nop 0
	v_cvt_pk_bf16_f32 v10, v9, v9
	global_store_short_d16_hi v[6:7], v10, off offset:1024
	s_nop 0
	v_cvt_pk_bf16_f32 v11, v8, v8
	global_store_short_d16_hi v[6:7], v11, off offset:1152
	v_pk_mul_f32 v[16:17], v[0:1], v[8:9] op_sel_hi:[1,0]
	s_nop 0
	v_pk_fma_f32 v[18:19], v[2:3], v[8:9], v[16:17] op_sel:[0,1,0]
	v_pk_fma_f32 v[8:9], v[2:3], v[8:9], v[16:17] op_sel:[0,1,0] neg_lo:[0,0,1] neg_hi:[0,0,1]
	s_nop 0
	v_mov_b32_e32 v19, v9
	v_pk_add_f32 v[8:9], v[144:145], v[18:19]
	s_nop 0
	v_cvt_pk_bf16_f32 v10, v9, v9
	global_store_short_d16_hi v[6:7], v10, off offset:1280
	s_nop 0
	v_cvt_pk_bf16_f32 v11, v8, v8
	global_store_short_d16_hi v[6:7], v11, off offset:1408
	v_pk_mul_f32 v[16:17], v[0:1], v[8:9] op_sel_hi:[1,0]
	s_nop 0
	v_pk_fma_f32 v[18:19], v[2:3], v[8:9], v[16:17] op_sel:[0,1,0]
	v_pk_fma_f32 v[8:9], v[2:3], v[8:9], v[16:17] op_sel:[0,1,0] neg_lo:[0,0,1] neg_hi:[0,0,1]
	s_nop 0
	v_mov_b32_e32 v19, v9
	v_pk_add_f32 v[8:9], v[146:147], v[18:19]
	v_lshl_add_u64 v[6:7], v[6:7], 0, s[84:85]
	s_waitcnt vmcnt(34)
	s_nop 0
	v_cvt_pk_bf16_f32 v10, v9, v9
	global_store_short_d16_hi v[6:7], v10, off offset:-512
	s_nop 0
	v_cvt_pk_bf16_f32 v11, v8, v8
	global_store_short_d16_hi v[6:7], v11, off offset:-384
	v_pk_mul_f32 v[16:17], v[0:1], v[8:9] op_sel_hi:[1,0]
	s_nop 0
	v_pk_fma_f32 v[18:19], v[2:3], v[8:9], v[16:17] op_sel:[0,1,0]
	v_pk_fma_f32 v[8:9], v[2:3], v[8:9], v[16:17] op_sel:[0,1,0] neg_lo:[0,0,1] neg_hi:[0,0,1]
	s_nop 0
	v_mov_b32_e32 v19, v9
	v_pk_add_f32 v[8:9], v[100:101], v[18:19]
	s_nop 0
	v_cvt_pk_bf16_f32 v10, v9, v9
	global_store_short_d16_hi v[6:7], v10, off offset:-256
	s_nop 0
	v_cvt_pk_bf16_f32 v11, v8, v8
	global_store_short_d16_hi v[6:7], v11, off offset:-128
	v_pk_mul_f32 v[16:17], v[0:1], v[8:9] op_sel_hi:[1,0]
	s_nop 0
	v_pk_fma_f32 v[18:19], v[2:3], v[8:9], v[16:17] op_sel:[0,1,0]
	v_pk_fma_f32 v[8:9], v[2:3], v[8:9], v[16:17] op_sel:[0,1,0] neg_lo:[0,0,1] neg_hi:[0,0,1]
	s_nop 0
	v_mov_b32_e32 v19, v9
	v_pk_add_f32 v[8:9], v[102:103], v[18:19]
	s_nop 0
	v_cvt_pk_bf16_f32 v10, v9, v9
	global_store_short_d16_hi v[6:7], v10, off
	s_nop 0
	v_cvt_pk_bf16_f32 v11, v8, v8
	global_store_short_d16_hi v[6:7], v11, off offset:128
	v_pk_mul_f32 v[16:17], v[0:1], v[8:9] op_sel_hi:[1,0]
	s_nop 0
	v_pk_fma_f32 v[18:19], v[2:3], v[8:9], v[16:17] op_sel:[0,1,0]
	v_pk_fma_f32 v[8:9], v[2:3], v[8:9], v[16:17] op_sel:[0,1,0] neg_lo:[0,0,1] neg_hi:[0,0,1]
	s_nop 0
	v_mov_b32_e32 v19, v9
	v_pk_add_f32 v[8:9], v[104:105], v[18:19]
	s_nop 0
	v_cvt_pk_bf16_f32 v10, v9, v9
	global_store_short_d16_hi v[6:7], v10, off offset:256
	s_nop 0
	v_cvt_pk_bf16_f32 v11, v8, v8
	global_store_short_d16_hi v[6:7], v11, off offset:384
	v_pk_mul_f32 v[16:17], v[0:1], v[8:9] op_sel_hi:[1,0]
	s_nop 0
	v_pk_fma_f32 v[18:19], v[2:3], v[8:9], v[16:17] op_sel:[0,1,0]
	v_pk_fma_f32 v[8:9], v[2:3], v[8:9], v[16:17] op_sel:[0,1,0] neg_lo:[0,0,1] neg_hi:[0,0,1]
	s_nop 0
	v_mov_b32_e32 v19, v9
	v_pk_add_f32 v[8:9], v[106:107], v[18:19]
	s_nop 0
	v_cvt_pk_bf16_f32 v10, v9, v9
	global_store_short_d16_hi v[6:7], v10, off offset:512
	s_nop 0
	v_cvt_pk_bf16_f32 v11, v8, v8
	global_store_short_d16_hi v[6:7], v11, off offset:640
	v_pk_mul_f32 v[16:17], v[0:1], v[8:9] op_sel_hi:[1,0]
	s_nop 0
	v_pk_fma_f32 v[18:19], v[2:3], v[8:9], v[16:17] op_sel:[0,1,0]
	v_pk_fma_f32 v[8:9], v[2:3], v[8:9], v[16:17] op_sel:[0,1,0] neg_lo:[0,0,1] neg_hi:[0,0,1]
	s_nop 0
	v_mov_b32_e32 v19, v9
	v_pk_add_f32 v[8:9], v[108:109], v[18:19]
	s_nop 0
	v_cvt_pk_bf16_f32 v10, v9, v9
	global_store_short_d16_hi v[6:7], v10, off offset:768
	s_nop 0
	v_cvt_pk_bf16_f32 v11, v8, v8
	global_store_short_d16_hi v[6:7], v11, off offset:896
	v_pk_mul_f32 v[16:17], v[0:1], v[8:9] op_sel_hi:[1,0]
	s_nop 0
	v_pk_fma_f32 v[18:19], v[2:3], v[8:9], v[16:17] op_sel:[0,1,0]
	v_pk_fma_f32 v[8:9], v[2:3], v[8:9], v[16:17] op_sel:[0,1,0] neg_lo:[0,0,1] neg_hi:[0,0,1]
	s_nop 0
	v_mov_b32_e32 v19, v9
	v_pk_add_f32 v[8:9], v[110:111], v[18:19]
	s_nop 0
	v_cvt_pk_bf16_f32 v10, v9, v9
	global_store_short_d16_hi v[6:7], v10, off offset:1024
	s_nop 0
	v_cvt_pk_bf16_f32 v11, v8, v8
	global_store_short_d16_hi v[6:7], v11, off offset:1152
	v_pk_mul_f32 v[16:17], v[0:1], v[8:9] op_sel_hi:[1,0]
	s_nop 0
	v_pk_fma_f32 v[18:19], v[2:3], v[8:9], v[16:17] op_sel:[0,1,0]
	v_pk_fma_f32 v[8:9], v[2:3], v[8:9], v[16:17] op_sel:[0,1,0] neg_lo:[0,0,1] neg_hi:[0,0,1]
	s_nop 0
	v_mov_b32_e32 v19, v9
	v_pk_add_f32 v[8:9], v[112:113], v[18:19]
	s_nop 0
	v_cvt_pk_bf16_f32 v10, v9, v9
	global_store_short_d16_hi v[6:7], v10, off offset:1280
	s_nop 0
	v_cvt_pk_bf16_f32 v11, v8, v8
	global_store_short_d16_hi v[6:7], v11, off offset:1408
	v_pk_mul_f32 v[16:17], v[0:1], v[8:9] op_sel_hi:[1,0]
	s_nop 0
	v_pk_fma_f32 v[18:19], v[2:3], v[8:9], v[16:17] op_sel:[0,1,0]
	v_pk_fma_f32 v[8:9], v[2:3], v[8:9], v[16:17] op_sel:[0,1,0] neg_lo:[0,0,1] neg_hi:[0,0,1]
	s_nop 0
	v_mov_b32_e32 v19, v9
	v_pk_add_f32 v[8:9], v[114:115], v[18:19]
	v_lshl_add_u64 v[6:7], v[6:7], 0, s[84:85]
	s_waitcnt vmcnt(32)
	v_bfe_u32 v10, v9, 16, 1
	v_add3_u32 v10, v9, v10, s48
	global_store_short_d16_hi v[6:7], v10, off offset:-512
	v_bfe_u32 v11, v8, 16, 1
	v_add3_u32 v11, v8, v11, s48
	global_store_short_d16_hi v[6:7], v11, off offset:-384
	v_pk_mul_f32 v[16:17], v[0:1], v[8:9] op_sel_hi:[1,0]
	s_nop 0
	v_pk_fma_f32 v[18:19], v[2:3], v[8:9], v[16:17] op_sel:[0,1,0]
	v_pk_fma_f32 v[8:9], v[2:3], v[8:9], v[16:17] op_sel:[0,1,0] neg_lo:[0,0,1] neg_hi:[0,0,1]
	s_nop 0
	v_mov_b32_e32 v19, v9
	v_pk_add_f32 v[8:9], v[116:117], v[18:19]

.LBB0_1157:
	s_or_b64 exec, exec, s[8:9]
	v_lshl_add_u64 v[0:1], s[20:21], 0, v[0:1]
	s_mov_b32 s5, s39
	v_lshl_add_u64 v[0:1], v[0:1], 0, s[4:5]
	v_lshl_add_u64 v[0:1], v[12:13], 1, v[0:1]
	v_add_co_u32_e32 v0, vcc, s74, v0
	v_mov_b32_e32 v65, s86
	s_nop 0
	v_addc_co_u32_e32 v1, vcc, 0, v1, vcc
	global_load_ushort v0, v[0:1], off offset:1536
	s_waitcnt lgkmcnt(0)
	s_lshl_b64 s[6:7], s[38:39], 10
	s_add_i32 s33, s33, 1
	v_lshl_add_u64 v[82:83], v[82:83], 0, s[54:55]
	v_lshl_add_u64 v[84:85], v[84:85], 0, s[96:97]
	s_cmp_eq_u32 s33, 4
	s_waitcnt vmcnt(0)
	v_lshlrev_b32_e32 v86, 16, v0
	ds_read_b128 v[0:3], v65 offset:12288
	ds_read_b128 v[4:7], v65 offset:12304
	ds_read_b128 v[8:11], v65 offset:12320
	ds_read_b128 v[90:93], v65 offset:12336
	ds_read_b128 v[98:101], v65 offset:12544
	ds_read_b128 v[102:105], v65 offset:12800
	s_waitcnt lgkmcnt(0)
	v_pk_mul_f32 v[94:95], v[102:103], v[86:87] op_sel_hi:[1,0]
	s_nop 0
	v_pk_fma_f32 v[20:21], v[20:21], v[98:99], v[94:95]
	s_nop 0
	v_fma_f32 v89, v0, v20, 0
	v_fmac_f32_e32 v89, v1, v21
	v_pk_mul_f32 v[0:1], v[104:105], v[86:87] op_sel_hi:[1,0]
	s_nop 0
	v_pk_fma_f32 v[18:19], v[18:19], v[100:101], v[0:1]
	s_nop 0
	v_fmac_f32_e32 v89, v2, v18
	v_fmac_f32_e32 v89, v3, v19
	ds_read_b128 v[0:3], v65 offset:12560
	ds_read_b128 v[98:101], v65 offset:12816
	s_waitcnt lgkmcnt(0)
	v_pk_mul_f32 v[94:95], v[98:99], v[86:87] op_sel_hi:[1,0]
	s_nop 0
	v_pk_fma_f32 v[16:17], v[16:17], v[0:1], v[94:95]
	v_pk_mul_f32 v[0:1], v[100:101], v[86:87] op_sel_hi:[1,0]
	v_fmac_f32_e32 v89, v4, v16
	v_fmac_f32_e32 v89, v5, v17
	v_pk_fma_f32 v[14:15], v[14:15], v[2:3], v[0:1]
	s_nop 0
	v_fmac_f32_e32 v89, v6, v14
	v_fmac_f32_e32 v89, v7, v15
	ds_read_b128 v[0:3], v65 offset:12576
	ds_read_b128 v[4:7], v65 offset:12832
	s_waitcnt lgkmcnt(0)
	v_pk_mul_f32 v[4:5], v[4:5], v[86:87] op_sel_hi:[1,0]
	s_nop 0
	v_pk_fma_f32 v[34:35], v[34:35], v[0:1], v[4:5]
	v_pk_mul_f32 v[0:1], v[6:7], v[86:87] op_sel_hi:[1,0]
	v_fmac_f32_e32 v89, v8, v34
	v_pk_fma_f32 v[32:33], v[32:33], v[2:3], v[0:1]
	ds_read_b128 v[0:3], v65 offset:12592
	ds_read_b128 v[4:7], v65 offset:12848
	v_fmac_f32_e32 v89, v9, v35
	v_fmac_f32_e32 v89, v10, v32
	v_fmac_f32_e32 v89, v11, v33
	s_waitcnt lgkmcnt(0)
	v_pk_mul_f32 v[4:5], v[4:5], v[86:87] op_sel_hi:[1,0]
	s_nop 0
	v_pk_fma_f32 v[30:31], v[30:31], v[0:1], v[4:5]
	v_pk_mul_f32 v[0:1], v[6:7], v[86:87] op_sel_hi:[1,0]
	v_fmac_f32_e32 v89, v90, v30
	v_pk_fma_f32 v[28:29], v[28:29], v[2:3], v[0:1]
	ds_read_b128 v[0:3], v65 offset:12352
	ds_read_b128 v[4:7], v65 offset:12608
	ds_read_b128 v[8:11], v65 offset:12864
	v_fmac_f32_e32 v89, v91, v31
	v_fmac_f32_e32 v89, v92, v28
	v_fmac_f32_e32 v89, v93, v29
	s_waitcnt lgkmcnt(0)
	v_pk_mul_f32 v[8:9], v[8:9], v[86:87] op_sel_hi:[1,0]
	s_nop 0
	v_pk_fma_f32 v[78:79], v[78:79], v[4:5], v[8:9]
	s_nop 0
	v_fmac_f32_e32 v89, v0, v78
	v_fmac_f32_e32 v89, v1, v79
	v_pk_mul_f32 v[0:1], v[10:11], v[86:87] op_sel_hi:[1,0]
	s_nop 0
	v_pk_fma_f32 v[40:41], v[40:41], v[6:7], v[0:1]
	s_nop 0
	v_fmac_f32_e32 v89, v2, v40
	v_fmac_f32_e32 v89, v3, v41
	ds_read_b128 v[0:3], v65 offset:12368
	ds_read_b128 v[4:7], v65 offset:12624
	ds_read_b128 v[8:11], v65 offset:12880
	s_waitcnt lgkmcnt(0)
	v_pk_mul_f32 v[8:9], v[8:9], v[86:87] op_sel_hi:[1,0]
	s_nop 0
	v_pk_fma_f32 v[38:39], v[38:39], v[4:5], v[8:9]
	s_nop 0
	v_fmac_f32_e32 v89, v0, v38
	v_fmac_f32_e32 v89, v1, v39
	v_pk_mul_f32 v[0:1], v[10:11], v[86:87] op_sel_hi:[1,0]
	s_nop 0
	v_pk_fma_f32 v[36:37], v[36:37], v[6:7], v[0:1]
	s_nop 0
	v_fmac_f32_e32 v89, v2, v36
	v_fmac_f32_e32 v89, v3, v37
	ds_read_b128 v[0:3], v65 offset:12384
	ds_read_b128 v[4:7], v65 offset:12640
	ds_read_b128 v[8:11], v65 offset:12896
	s_waitcnt lgkmcnt(0)
	v_pk_mul_f32 v[8:9], v[8:9], v[86:87] op_sel_hi:[1,0]
	s_nop 0
	v_pk_fma_f32 v[22:23], v[22:23], v[4:5], v[8:9]
	s_nop 0
	v_fmac_f32_e32 v89, v0, v22
	v_fmac_f32_e32 v89, v1, v23
	v_pk_mul_f32 v[0:1], v[10:11], v[86:87] op_sel_hi:[1,0]
	s_nop 0
	v_pk_fma_f32 v[76:77], v[76:77], v[6:7], v[0:1]
	s_nop 0
	v_fmac_f32_e32 v89, v2, v76
	v_fmac_f32_e32 v89, v3, v77
	ds_read_b128 v[0:3], v65 offset:12400
	ds_read_b128 v[4:7], v65 offset:12656
	ds_read_b128 v[8:11], v65 offset:12912
	s_waitcnt lgkmcnt(0)
	v_pk_mul_f32 v[8:9], v[8:9], v[86:87] op_sel_hi:[1,0]
	s_nop 0
	v_pk_fma_f32 v[74:75], v[74:75], v[4:5], v[8:9]
	s_nop 0
	v_fmac_f32_e32 v89, v0, v74
	v_fmac_f32_e32 v89, v1, v75
	v_pk_mul_f32 v[0:1], v[10:11], v[86:87] op_sel_hi:[1,0]
	s_nop 0
	v_pk_fma_f32 v[72:73], v[72:73], v[6:7], v[0:1]
	s_nop 0
	v_fmac_f32_e32 v89, v2, v72
	v_fmac_f32_e32 v89, v3, v73
	ds_read_b128 v[0:3], v65 offset:12416
	ds_read_b128 v[4:7], v65 offset:12672
	ds_read_b128 v[8:11], v65 offset:12928
	s_waitcnt lgkmcnt(0)
	v_pk_mul_f32 v[8:9], v[8:9], v[86:87] op_sel_hi:[1,0]
	s_nop 0
	v_pk_fma_f32 v[24:25], v[24:25], v[4:5], v[8:9]
	s_nop 0
	v_fmac_f32_e32 v89, v0, v24
	v_fmac_f32_e32 v89, v1, v25
	v_pk_mul_f32 v[0:1], v[10:11], v[86:87] op_sel_hi:[1,0]
	s_nop 0
	v_pk_fma_f32 v[56:57], v[56:57], v[6:7], v[0:1]
	s_nop 0
	v_fmac_f32_e32 v89, v2, v56
	v_fmac_f32_e32 v89, v3, v57
	ds_read_b128 v[0:3], v65 offset:12432
	ds_read_b128 v[4:7], v65 offset:12688
	ds_read_b128 v[8:11], v65 offset:12944
	s_waitcnt lgkmcnt(0)
	v_pk_mul_f32 v[8:9], v[8:9], v[86:87] op_sel_hi:[1,0]
	s_nop 0
	v_pk_fma_f32 v[54:55], v[54:55], v[4:5], v[8:9]
	s_nop 0
	v_fmac_f32_e32 v89, v0, v54
	v_fmac_f32_e32 v89, v1, v55
	v_pk_mul_f32 v[0:1], v[10:11], v[86:87] op_sel_hi:[1,0]
	s_nop 0
	v_pk_fma_f32 v[52:53], v[52:53], v[6:7], v[0:1]
	s_nop 0
	v_fmac_f32_e32 v89, v2, v52
	v_fmac_f32_e32 v89, v3, v53
	ds_read_b128 v[0:3], v65 offset:12448
	ds_read_b128 v[4:7], v65 offset:12704
	ds_read_b128 v[8:11], v65 offset:12960
	s_waitcnt lgkmcnt(0)
	v_pk_mul_f32 v[8:9], v[8:9], v[86:87] op_sel_hi:[1,0]
	s_nop 0
	v_pk_fma_f32 v[26:27], v[26:27], v[4:5], v[8:9]
	s_nop 0
	v_fmac_f32_e32 v89, v0, v26
	v_fmac_f32_e32 v89, v1, v27
	v_pk_mul_f32 v[0:1], v[10:11], v[86:87] op_sel_hi:[1,0]
	s_nop 0
	v_pk_fma_f32 v[50:51], v[50:51], v[6:7], v[0:1]
	s_nop 0
	v_fmac_f32_e32 v89, v2, v50
	v_fmac_f32_e32 v89, v3, v51
	ds_read_b128 v[0:3], v65 offset:12464
	ds_read_b128 v[4:7], v65 offset:12720
	ds_read_b128 v[8:11], v65 offset:12976
	s_waitcnt lgkmcnt(0)
	v_pk_mul_f32 v[8:9], v[8:9], v[86:87] op_sel_hi:[1,0]
	s_nop 0
	v_pk_fma_f32 v[70:71], v[70:71], v[4:5], v[8:9]
	s_nop 0
	v_fmac_f32_e32 v89, v0, v70
	v_fmac_f32_e32 v89, v1, v71
	v_pk_mul_f32 v[0:1], v[10:11], v[86:87] op_sel_hi:[1,0]
	s_nop 0
	v_pk_fma_f32 v[68:69], v[68:69], v[6:7], v[0:1]
	s_nop 0
	v_fmac_f32_e32 v89, v2, v68
	v_fmac_f32_e32 v89, v3, v69
	ds_read_b128 v[0:3], v65 offset:12480
	ds_read_b128 v[4:7], v65 offset:12736
	ds_read_b128 v[8:11], v65 offset:12992
	s_waitcnt lgkmcnt(0)
	v_pk_mul_f32 v[8:9], v[8:9], v[86:87] op_sel_hi:[1,0]
	s_nop 0
	v_pk_fma_f32 v[48:49], v[48:49], v[4:5], v[8:9]
	s_nop 0
	v_fmac_f32_e32 v89, v0, v48
	v_fmac_f32_e32 v89, v1, v49
	v_pk_mul_f32 v[0:1], v[10:11], v[86:87] op_sel_hi:[1,0]
	s_nop 0
	v_pk_fma_f32 v[46:47], v[46:47], v[6:7], v[0:1]
	s_nop 0
	v_fmac_f32_e32 v89, v2, v46
	v_fmac_f32_e32 v89, v3, v47
	ds_read_b128 v[0:3], v65 offset:12496
	ds_read_b128 v[4:7], v65 offset:12752
	ds_read_b128 v[8:11], v65 offset:13008
	s_waitcnt lgkmcnt(0)
	v_pk_mul_f32 v[8:9], v[8:9], v[86:87] op_sel_hi:[1,0]
	s_nop 0
	v_pk_fma_f32 v[44:45], v[44:45], v[4:5], v[8:9]
	s_nop 0
	v_fmac_f32_e32 v89, v0, v44
	v_fmac_f32_e32 v89, v1, v45
	v_pk_mul_f32 v[0:1], v[10:11], v[86:87] op_sel_hi:[1,0]
	s_nop 0
	v_pk_fma_f32 v[42:43], v[42:43], v[6:7], v[0:1]
	s_nop 0
	v_fmac_f32_e32 v89, v2, v42
	v_fmac_f32_e32 v89, v3, v43
	ds_read_b128 v[0:3], v65 offset:12768
	ds_read_b128 v[4:7], v65 offset:13024
	ds_read_b128 v[8:11], v65 offset:12512
	s_waitcnt lgkmcnt(1)
	v_pk_mul_f32 v[4:5], v[4:5], v[86:87] op_sel_hi:[1,0]
	s_nop 0
	v_pk_fma_f32 v[60:61], v[60:61], v[0:1], v[4:5]
	s_waitcnt lgkmcnt(0)
	v_pk_mul_f32 v[0:1], v[8:9], v[60:61]
	s_nop 0
	v_add_f32_e32 v0, v89, v0
	v_add_f32_e32 v4, v0, v1
	v_pk_mul_f32 v[0:1], v[6:7], v[86:87] op_sel_hi:[1,0]
	s_nop 0
	v_pk_fma_f32 v[58:59], v[58:59], v[2:3], v[0:1]
	s_nop 0
	v_pk_mul_f32 v[0:1], v[10:11], v[58:59]
	s_nop 0
	v_add_f32_e32 v0, v4, v0
	v_add_f32_e32 v89, v0, v1
	ds_read_b128 v[0:3], v65 offset:12784
	ds_read_b128 v[4:7], v65 offset:13040
	ds_read_b128 v[8:11], v65 offset:12528
	s_waitcnt lgkmcnt(1)
	v_pk_mul_f32 v[4:5], v[4:5], v[86:87] op_sel_hi:[1,0]
	s_nop 0
	v_pk_fma_f32 v[66:67], v[66:67], v[0:1], v[4:5]
	s_waitcnt lgkmcnt(0)
	v_pk_mul_f32 v[0:1], v[8:9], v[66:67]
	s_nop 0
	v_add_f32_e32 v0, v89, v0
	v_add_f32_e32 v4, v0, v1
	v_pk_mul_f32 v[0:1], v[6:7], v[86:87] op_sel_hi:[1,0]
	s_nop 0
	v_pk_fma_f32 v[62:63], v[62:63], v[2:3], v[0:1]
	s_nop 0
	v_pk_mul_f32 v[0:1], v[10:11], v[62:63]
	s_nop 0
	v_add_f32_e32 v0, v4, v0
	v_add_f32_e32 v0, v0, v1
	s_nop 0
	v_cvt_pk_bf16_f32 v2, v0, v0
	v_lshl_add_u64 v[0:1], v[80:81], 0, s[6:7]
	global_store_short_d16_hi v[0:1], v2, off
	s_cbranch_scc1 .LBB0_1161

.LBB0_1165:
	s_or_b64 exec, exec, s[64:65]
	v_mad_u64_u32 v[0:1], s[64:65], s62, v232, v[142:143]
	global_load_ushort v0, v[0:1], off
	s_waitcnt lgkmcnt(0)
	v_mov_b32_e32 v151, s86
	s_mov_b32 s63, s39
	s_lshl_b64 s[62:63], s[62:63], 10
	s_add_i32 s28, s28, 1
	s_addk_i32 s58, 0x200
	s_cmp_eq_u32 s28, 4
	s_waitcnt vmcnt(0)
	v_lshlrev_b32_e32 v96, 16, v0
	ds_read_b128 v[0:3], v151 offset:12288
	ds_read_b128 v[4:7], v151 offset:12304
	ds_read_b128 v[154:157], v151 offset:12320
	ds_read_b128 v[158:161], v151 offset:12336
	ds_read_b128 v[162:165], v151 offset:12800
	ds_read_b128 v[166:169], v151 offset:13312
	s_waitcnt lgkmcnt(0)
	v_pk_mul_f32 v[152:153], v[166:167], v[96:97] op_sel_hi:[1,0]
	s_nop 0
	v_pk_fma_f32 v[16:17], v[16:17], v[162:163], v[152:153]
	s_nop 0
	v_fma_f32 v152, v0, v16, 0
	v_fmac_f32_e32 v152, v1, v17
	v_pk_mul_f32 v[0:1], v[168:169], v[96:97] op_sel_hi:[1,0]
	s_nop 0
	v_pk_fma_f32 v[14:15], v[14:15], v[164:165], v[0:1]
	s_nop 0
	v_fmac_f32_e32 v152, v2, v14
	v_fmac_f32_e32 v152, v3, v15
	ds_read_b128 v[0:3], v151 offset:12816
	ds_read_b128 v[162:165], v151 offset:13328
	s_waitcnt lgkmcnt(0)
	v_pk_mul_f32 v[162:163], v[162:163], v[96:97] op_sel_hi:[1,0]
	s_nop 0
	v_pk_fma_f32 v[12:13], v[12:13], v[0:1], v[162:163]
	v_pk_mul_f32 v[0:1], v[164:165], v[96:97] op_sel_hi:[1,0]
	v_fmac_f32_e32 v152, v4, v12
	v_fmac_f32_e32 v152, v5, v13
	v_pk_fma_f32 v[10:11], v[10:11], v[2:3], v[0:1]
	s_nop 0
	v_fmac_f32_e32 v152, v6, v10
	v_fmac_f32_e32 v152, v7, v11
	ds_read_b128 v[0:3], v151 offset:12832
	ds_read_b128 v[4:7], v151 offset:13344
	s_waitcnt lgkmcnt(0)
	v_pk_mul_f32 v[4:5], v[4:5], v[96:97] op_sel_hi:[1,0]
	s_nop 0
	v_pk_fma_f32 v[42:43], v[42:43], v[0:1], v[4:5]
	v_pk_mul_f32 v[0:1], v[6:7], v[96:97] op_sel_hi:[1,0]
	v_fmac_f32_e32 v152, v154, v42
	v_pk_fma_f32 v[40:41], v[40:41], v[2:3], v[0:1]
	ds_read_b128 v[0:3], v151 offset:12848
	ds_read_b128 v[4:7], v151 offset:13360
	v_fmac_f32_e32 v152, v155, v43
	v_fmac_f32_e32 v152, v156, v40
	v_fmac_f32_e32 v152, v157, v41
	s_waitcnt lgkmcnt(0)
	v_pk_mul_f32 v[4:5], v[4:5], v[96:97] op_sel_hi:[1,0]
	s_nop 0
	v_pk_fma_f32 v[38:39], v[38:39], v[0:1], v[4:5]
	v_pk_mul_f32 v[0:1], v[6:7], v[96:97] op_sel_hi:[1,0]
	v_fmac_f32_e32 v152, v158, v38
	v_pk_fma_f32 v[36:37], v[36:37], v[2:3], v[0:1]
	ds_read_b128 v[0:3], v151 offset:12352
	ds_read_b128 v[4:7], v151 offset:12864
	ds_read_b128 v[154:157], v151 offset:13376
	v_fmac_f32_e32 v152, v159, v39
	v_fmac_f32_e32 v152, v160, v36
	v_fmac_f32_e32 v152, v161, v37
	s_waitcnt lgkmcnt(0)
	v_pk_mul_f32 v[154:155], v[154:155], v[96:97] op_sel_hi:[1,0]
	s_nop 0
	v_pk_fma_f32 v[140:141], v[140:141], v[4:5], v[154:155]
	s_nop 0
	v_fmac_f32_e32 v152, v0, v140
	v_fmac_f32_e32 v152, v1, v141
	v_pk_mul_f32 v[0:1], v[156:157], v[96:97] op_sel_hi:[1,0]
	s_nop 0
	v_pk_fma_f32 v[138:139], v[138:139], v[6:7], v[0:1]
	s_nop 0
	v_fmac_f32_e32 v152, v2, v138
	v_fmac_f32_e32 v152, v3, v139
	ds_read_b128 v[0:3], v151 offset:12368
	ds_read_b128 v[4:7], v151 offset:12880
	ds_read_b128 v[154:157], v151 offset:13392
	s_waitcnt lgkmcnt(0)
	v_pk_mul_f32 v[154:155], v[154:155], v[96:97] op_sel_hi:[1,0]
	s_nop 0
	v_pk_fma_f32 v[136:137], v[136:137], v[4:5], v[154:155]
	s_nop 0
	v_fmac_f32_e32 v152, v0, v136
	v_fmac_f32_e32 v152, v1, v137
	v_pk_mul_f32 v[0:1], v[156:157], v[96:97] op_sel_hi:[1,0]
	s_nop 0
	v_pk_fma_f32 v[34:35], v[34:35], v[6:7], v[0:1]
	s_nop 0
	v_fmac_f32_e32 v152, v2, v34
	v_fmac_f32_e32 v152, v3, v35
	ds_read_b128 v[0:3], v151 offset:12384
	ds_read_b128 v[4:7], v151 offset:12896
	ds_read_b128 v[154:157], v151 offset:13408
	s_waitcnt lgkmcnt(0)
	v_pk_mul_f32 v[154:155], v[154:155], v[96:97] op_sel_hi:[1,0]
	s_nop 0
	v_pk_fma_f32 v[18:19], v[18:19], v[4:5], v[154:155]
	s_nop 0
	v_fmac_f32_e32 v152, v0, v18
	v_fmac_f32_e32 v152, v1, v19
	v_pk_mul_f32 v[0:1], v[156:157], v[96:97] op_sel_hi:[1,0]
	s_nop 0
	v_pk_fma_f32 v[58:59], v[58:59], v[6:7], v[0:1]
	s_nop 0
	v_fmac_f32_e32 v152, v2, v58
	v_fmac_f32_e32 v152, v3, v59
	ds_read_b128 v[0:3], v151 offset:12400
	ds_read_b128 v[4:7], v151 offset:12912
	ds_read_b128 v[154:157], v151 offset:13424
	s_waitcnt lgkmcnt(0)
	v_pk_mul_f32 v[154:155], v[154:155], v[96:97] op_sel_hi:[1,0]
	s_nop 0
	v_pk_fma_f32 v[56:57], v[56:57], v[4:5], v[154:155]
	s_nop 0
	v_fmac_f32_e32 v152, v0, v56
	v_fmac_f32_e32 v152, v1, v57
	v_pk_mul_f32 v[0:1], v[156:157], v[96:97] op_sel_hi:[1,0]
	s_nop 0
	v_pk_fma_f32 v[54:55], v[54:55], v[6:7], v[0:1]
	s_nop 0
	v_fmac_f32_e32 v152, v2, v54
	v_fmac_f32_e32 v152, v3, v55
	ds_read_b128 v[0:3], v151 offset:12416
	ds_read_b128 v[4:7], v151 offset:12928
	ds_read_b128 v[154:157], v151 offset:13440
	s_waitcnt lgkmcnt(0)
	v_pk_mul_f32 v[154:155], v[154:155], v[96:97] op_sel_hi:[1,0]
	s_nop 0
	v_pk_fma_f32 v[24:25], v[24:25], v[4:5], v[154:155]
	s_nop 0
	v_fmac_f32_e32 v152, v0, v24
	v_fmac_f32_e32 v152, v1, v25
	v_pk_mul_f32 v[0:1], v[156:157], v[96:97] op_sel_hi:[1,0]
	s_nop 0
	v_pk_fma_f32 v[22:23], v[22:23], v[6:7], v[0:1]
	s_nop 0
	v_fmac_f32_e32 v152, v2, v22
	v_fmac_f32_e32 v152, v3, v23
	ds_read_b128 v[0:3], v151 offset:12432
	ds_read_b128 v[4:7], v151 offset:12944
	ds_read_b128 v[154:157], v151 offset:13456
	s_waitcnt lgkmcnt(0)
	v_pk_mul_f32 v[154:155], v[154:155], v[96:97] op_sel_hi:[1,0]
	s_nop 0
	v_pk_fma_f32 v[20:21], v[20:21], v[4:5], v[154:155]
	s_nop 0
	v_fmac_f32_e32 v152, v0, v20
	v_fmac_f32_e32 v152, v1, v21
	v_pk_mul_f32 v[0:1], v[156:157], v[96:97] op_sel_hi:[1,0]
	s_nop 0
	v_pk_fma_f32 v[52:53], v[52:53], v[6:7], v[0:1]
	s_nop 0
	v_fmac_f32_e32 v152, v2, v52
	v_fmac_f32_e32 v152, v3, v53
	ds_read_b128 v[0:3], v151 offset:12448
	ds_read_b128 v[4:7], v151 offset:12960
	ds_read_b128 v[154:157], v151 offset:13472
	s_waitcnt lgkmcnt(0)
	v_pk_mul_f32 v[154:155], v[154:155], v[96:97] op_sel_hi:[1,0]
	s_nop 0
	v_pk_fma_f32 v[28:29], v[28:29], v[4:5], v[154:155]
	s_nop 0
	v_fmac_f32_e32 v152, v0, v28
	v_fmac_f32_e32 v152, v1, v29
	v_pk_mul_f32 v[0:1], v[156:157], v[96:97] op_sel_hi:[1,0]
	s_nop 0
	v_pk_fma_f32 v[26:27], v[26:27], v[6:7], v[0:1]
	s_nop 0
	v_fmac_f32_e32 v152, v2, v26
	v_fmac_f32_e32 v152, v3, v27
	ds_read_b128 v[0:3], v151 offset:12464
	ds_read_b128 v[4:7], v151 offset:12976
	ds_read_b128 v[154:157], v151 offset:13488
	s_waitcnt lgkmcnt(0)
	v_pk_mul_f32 v[154:155], v[154:155], v[96:97] op_sel_hi:[1,0]
	s_nop 0
	v_pk_fma_f32 v[72:73], v[72:73], v[4:5], v[154:155]
	s_nop 0
	v_fmac_f32_e32 v152, v0, v72
	v_fmac_f32_e32 v152, v1, v73
	v_pk_mul_f32 v[0:1], v[156:157], v[96:97] op_sel_hi:[1,0]
	s_nop 0
	v_pk_fma_f32 v[70:71], v[70:71], v[6:7], v[0:1]
	s_nop 0
	v_fmac_f32_e32 v152, v2, v70
	v_fmac_f32_e32 v152, v3, v71
	ds_read_b128 v[0:3], v151 offset:12480
	ds_read_b128 v[4:7], v151 offset:12992
	ds_read_b128 v[154:157], v151 offset:13504
	s_waitcnt lgkmcnt(0)
	v_pk_mul_f32 v[154:155], v[154:155], v[96:97] op_sel_hi:[1,0]
	s_nop 0
	v_pk_fma_f32 v[32:33], v[32:33], v[4:5], v[154:155]
	s_nop 0
	v_fmac_f32_e32 v152, v0, v32
	v_fmac_f32_e32 v152, v1, v33
	v_pk_mul_f32 v[0:1], v[156:157], v[96:97] op_sel_hi:[1,0]
	s_nop 0
	v_pk_fma_f32 v[30:31], v[30:31], v[6:7], v[0:1]
	s_nop 0
	v_fmac_f32_e32 v152, v2, v30
	v_fmac_f32_e32 v152, v3, v31
	ds_read_b128 v[0:3], v151 offset:12496
	ds_read_b128 v[4:7], v151 offset:13008
	ds_read_b128 v[154:157], v151 offset:13520
	s_waitcnt lgkmcnt(0)
	v_pk_mul_f32 v[154:155], v[154:155], v[96:97] op_sel_hi:[1,0]
	s_nop 0
	v_pk_fma_f32 v[80:81], v[80:81], v[4:5], v[154:155]
	s_nop 0
	v_fmac_f32_e32 v152, v0, v80
	v_fmac_f32_e32 v152, v1, v81
	v_pk_mul_f32 v[0:1], v[156:157], v[96:97] op_sel_hi:[1,0]
	s_nop 0
	v_pk_fma_f32 v[78:79], v[78:79], v[6:7], v[0:1]
	s_nop 0
	v_fmac_f32_e32 v152, v2, v78
	v_fmac_f32_e32 v152, v3, v79
	ds_read_b128 v[0:3], v151 offset:12512
	ds_read_b128 v[4:7], v151 offset:13024
	ds_read_b128 v[154:157], v151 offset:13536
	s_waitcnt lgkmcnt(0)
	v_pk_mul_f32 v[154:155], v[154:155], v[96:97] op_sel_hi:[1,0]
	s_nop 0
	v_pk_fma_f32 v[46:47], v[46:47], v[4:5], v[154:155]
	s_nop 0
	v_fmac_f32_e32 v152, v0, v46
	v_fmac_f32_e32 v152, v1, v47
	v_pk_mul_f32 v[0:1], v[156:157], v[96:97] op_sel_hi:[1,0]
	s_nop 0
	v_pk_fma_f32 v[44:45], v[44:45], v[6:7], v[0:1]
	s_nop 0
	v_fmac_f32_e32 v152, v2, v44
	v_fmac_f32_e32 v152, v3, v45
	ds_read_b128 v[0:3], v151 offset:12528
	ds_read_b128 v[4:7], v151 offset:13040
	ds_read_b128 v[154:157], v151 offset:13552
	s_waitcnt lgkmcnt(0)
	v_pk_mul_f32 v[154:155], v[154:155], v[96:97] op_sel_hi:[1,0]
	s_nop 0
	v_pk_fma_f32 v[88:89], v[88:89], v[4:5], v[154:155]
	s_nop 0
	v_fmac_f32_e32 v152, v0, v88
	v_fmac_f32_e32 v152, v1, v89
	v_pk_mul_f32 v[0:1], v[156:157], v[96:97] op_sel_hi:[1,0]
	s_nop 0
	v_pk_fma_f32 v[86:87], v[86:87], v[6:7], v[0:1]
	s_nop 0
	v_fmac_f32_e32 v152, v2, v86
	v_fmac_f32_e32 v152, v3, v87
	ds_read_b128 v[0:3], v151 offset:12544
	ds_read_b128 v[4:7], v151 offset:13056
	ds_read_b128 v[154:157], v151 offset:13568
	s_waitcnt lgkmcnt(0)
	v_pk_mul_f32 v[154:155], v[154:155], v[96:97] op_sel_hi:[1,0]
	s_nop 0
	v_pk_fma_f32 v[50:51], v[50:51], v[4:5], v[154:155]
	s_nop 0
	v_fmac_f32_e32 v152, v0, v50
	v_fmac_f32_e32 v152, v1, v51
	v_pk_mul_f32 v[0:1], v[156:157], v[96:97] op_sel_hi:[1,0]
	s_nop 0
	v_pk_fma_f32 v[48:49], v[48:49], v[6:7], v[0:1]
	s_nop 0
	v_fmac_f32_e32 v152, v2, v48
	v_fmac_f32_e32 v152, v3, v49
	ds_read_b128 v[0:3], v151 offset:12560
	ds_read_b128 v[4:7], v151 offset:13072
	ds_read_b128 v[154:157], v151 offset:13584
	s_waitcnt lgkmcnt(0)
	v_pk_mul_f32 v[154:155], v[154:155], v[96:97] op_sel_hi:[1,0]
	s_nop 0
	v_pk_fma_f32 v[92:93], v[92:93], v[4:5], v[154:155]
	s_nop 0
	v_fmac_f32_e32 v152, v0, v92
	v_fmac_f32_e32 v152, v1, v93
	v_pk_mul_f32 v[0:1], v[156:157], v[96:97] op_sel_hi:[1,0]
	s_nop 0
	v_pk_fma_f32 v[90:91], v[90:91], v[6:7], v[0:1]
	s_nop 0
	v_fmac_f32_e32 v152, v2, v90
	v_fmac_f32_e32 v152, v3, v91
	ds_read_b128 v[0:3], v151 offset:12576
	ds_read_b128 v[4:7], v151 offset:13088
	ds_read_b128 v[154:157], v151 offset:13600
	s_waitcnt lgkmcnt(0)
	v_pk_mul_f32 v[154:155], v[154:155], v[96:97] op_sel_hi:[1,0]
	s_nop 0
	v_pk_fma_f32 v[66:67], v[66:67], v[4:5], v[154:155]
	s_nop 0
	v_fmac_f32_e32 v152, v0, v66
	v_fmac_f32_e32 v152, v1, v67
	v_pk_mul_f32 v[0:1], v[156:157], v[96:97] op_sel_hi:[1,0]
	s_nop 0
	v_pk_fma_f32 v[62:63], v[62:63], v[6:7], v[0:1]
	s_nop 0
	v_fmac_f32_e32 v152, v2, v62
	v_fmac_f32_e32 v152, v3, v63
	ds_read_b128 v[0:3], v151 offset:12592
	ds_read_b128 v[4:7], v151 offset:13104
	ds_read_b128 v[154:157], v151 offset:13616
	s_waitcnt lgkmcnt(0)
	v_pk_mul_f32 v[154:155], v[154:155], v[96:97] op_sel_hi:[1,0]
	s_nop 0
	v_pk_fma_f32 v[60:61], v[60:61], v[4:5], v[154:155]
	s_nop 0
	v_fmac_f32_e32 v152, v0, v60
	v_fmac_f32_e32 v152, v1, v61
	v_pk_mul_f32 v[0:1], v[156:157], v[96:97] op_sel_hi:[1,0]
	s_nop 0
	v_pk_fma_f32 v[120:121], v[120:121], v[6:7], v[0:1]
	s_nop 0
	v_fmac_f32_e32 v152, v2, v120
	v_fmac_f32_e32 v152, v3, v121
	ds_read_b128 v[0:3], v151 offset:12608
	ds_read_b128 v[4:7], v151 offset:13120
	ds_read_b128 v[154:157], v151 offset:13632
	s_waitcnt lgkmcnt(0)
	v_pk_mul_f32 v[154:155], v[154:155], v[96:97] op_sel_hi:[1,0]
	s_nop 0
	v_pk_fma_f32 v[68:69], v[68:69], v[4:5], v[154:155]
	s_nop 0
	v_fmac_f32_e32 v152, v0, v68
	v_fmac_f32_e32 v152, v1, v69
	v_pk_mul_f32 v[0:1], v[156:157], v[96:97] op_sel_hi:[1,0]
	s_nop 0
	v_pk_fma_f32 v[132:133], v[132:133], v[6:7], v[0:1]
	s_nop 0
	v_fmac_f32_e32 v152, v2, v132
	v_fmac_f32_e32 v152, v3, v133
	ds_read_b128 v[0:3], v151 offset:12624
	ds_read_b128 v[4:7], v151 offset:13136
	ds_read_b128 v[154:157], v151 offset:13648
	s_waitcnt lgkmcnt(0)
	v_pk_mul_f32 v[154:155], v[154:155], v[96:97] op_sel_hi:[1,0]
	s_nop 0
	v_pk_fma_f32 v[130:131], v[130:131], v[4:5], v[154:155]
	s_nop 0
	v_fmac_f32_e32 v152, v0, v130
	v_fmac_f32_e32 v152, v1, v131
	v_pk_mul_f32 v[0:1], v[156:157], v[96:97] op_sel_hi:[1,0]
	s_nop 0
	v_pk_fma_f32 v[128:129], v[128:129], v[6:7], v[0:1]
	s_nop 0
	v_fmac_f32_e32 v152, v2, v128
	v_fmac_f32_e32 v152, v3, v129
	ds_read_b128 v[0:3], v151 offset:12640
	ds_read_b128 v[4:7], v151 offset:13152
	ds_read_b128 v[154:157], v151 offset:13664
	s_waitcnt lgkmcnt(0)
	v_pk_mul_f32 v[154:155], v[154:155], v[96:97] op_sel_hi:[1,0]
	s_nop 0
	v_pk_fma_f32 v[82:83], v[82:83], v[4:5], v[154:155]
	s_nop 0
	v_fmac_f32_e32 v152, v0, v82
	v_fmac_f32_e32 v152, v1, v83
	v_pk_mul_f32 v[0:1], v[156:157], v[96:97] op_sel_hi:[1,0]
	s_nop 0
	v_pk_fma_f32 v[76:77], v[76:77], v[6:7], v[0:1]
	s_nop 0
	v_fmac_f32_e32 v152, v2, v76
	v_fmac_f32_e32 v152, v3, v77
	ds_read_b128 v[0:3], v151 offset:12656
	ds_read_b128 v[4:7], v151 offset:13168
	ds_read_b128 v[154:157], v151 offset:13680
	s_waitcnt lgkmcnt(0)
	v_pk_mul_f32 v[154:155], v[154:155], v[96:97] op_sel_hi:[1,0]
	s_nop 0
	v_pk_fma_f32 v[74:75], v[74:75], v[4:5], v[154:155]
	s_nop 0
	v_fmac_f32_e32 v152, v0, v74
	v_fmac_f32_e32 v152, v1, v75
	v_pk_mul_f32 v[0:1], v[156:157], v[96:97] op_sel_hi:[1,0]
	s_nop 0
	v_pk_fma_f32 v[134:135], v[134:135], v[6:7], v[0:1]
	s_nop 0
	v_fmac_f32_e32 v152, v2, v134
	v_fmac_f32_e32 v152, v3, v135
	ds_read_b128 v[0:3], v151 offset:12672
	ds_read_b128 v[4:7], v151 offset:13184
	ds_read_b128 v[154:157], v151 offset:13696
	s_waitcnt lgkmcnt(0)
	v_pk_mul_f32 v[154:155], v[154:155], v[96:97] op_sel_hi:[1,0]
	s_nop 0
	v_pk_fma_f32 v[84:85], v[84:85], v[4:5], v[154:155]
	s_nop 0
	v_fmac_f32_e32 v152, v0, v84
	v_fmac_f32_e32 v152, v1, v85
	v_pk_mul_f32 v[0:1], v[156:157], v[96:97] op_sel_hi:[1,0]
	s_nop 0
	v_pk_fma_f32 v[126:127], v[126:127], v[6:7], v[0:1]
	s_nop 0
	v_fmac_f32_e32 v152, v2, v126
	v_fmac_f32_e32 v152, v3, v127
	ds_read_b128 v[0:3], v151 offset:12688
	ds_read_b128 v[4:7], v151 offset:13200
	ds_read_b128 v[154:157], v151 offset:13712
	s_waitcnt lgkmcnt(0)
	v_pk_mul_f32 v[154:155], v[154:155], v[96:97] op_sel_hi:[1,0]
	s_nop 0
	v_pk_fma_f32 v[124:125], v[124:125], v[4:5], v[154:155]
	s_nop 0
	v_fmac_f32_e32 v152, v0, v124
	v_fmac_f32_e32 v152, v1, v125
	v_pk_mul_f32 v[0:1], v[156:157], v[96:97] op_sel_hi:[1,0]
	s_nop 0
	v_pk_fma_f32 v[122:123], v[122:123], v[6:7], v[0:1]
	s_nop 0
	v_fmac_f32_e32 v152, v2, v122
	v_fmac_f32_e32 v152, v3, v123
	ds_read_b128 v[0:3], v151 offset:12704
	ds_read_b128 v[4:7], v151 offset:13216
	ds_read_b128 v[154:157], v151 offset:13728
	s_waitcnt lgkmcnt(0)
	v_pk_mul_f32 v[154:155], v[154:155], v[96:97] op_sel_hi:[1,0]
	s_nop 0
	v_pk_fma_f32 v[94:95], v[94:95], v[4:5], v[154:155]
	s_nop 0
	v_fmac_f32_e32 v152, v0, v94
	v_fmac_f32_e32 v152, v1, v95
	v_pk_mul_f32 v[0:1], v[156:157], v[96:97] op_sel_hi:[1,0]
	s_nop 0
	v_pk_fma_f32 v[118:119], v[118:119], v[6:7], v[0:1]
	s_nop 0
	v_fmac_f32_e32 v152, v2, v118
	v_fmac_f32_e32 v152, v3, v119
	ds_read_b128 v[0:3], v151 offset:12720
	ds_read_b128 v[4:7], v151 offset:13232
	ds_read_b128 v[154:157], v151 offset:13744
	s_waitcnt lgkmcnt(0)
	v_pk_mul_f32 v[154:155], v[154:155], v[96:97] op_sel_hi:[1,0]
	s_nop 0
	v_pk_fma_f32 v[116:117], v[116:117], v[4:5], v[154:155]
	s_nop 0
	v_fmac_f32_e32 v152, v0, v116
	v_fmac_f32_e32 v152, v1, v117
	v_pk_mul_f32 v[0:1], v[156:157], v[96:97] op_sel_hi:[1,0]
	s_nop 0
	v_pk_fma_f32 v[114:115], v[114:115], v[6:7], v[0:1]
	s_nop 0
	v_fmac_f32_e32 v152, v2, v114
	v_fmac_f32_e32 v152, v3, v115
	ds_read_b128 v[0:3], v151 offset:12736
	ds_read_b128 v[4:7], v151 offset:13248
	ds_read_b128 v[154:157], v151 offset:13760
	s_waitcnt lgkmcnt(0)
	v_pk_mul_f32 v[154:155], v[154:155], v[96:97] op_sel_hi:[1,0]
	s_nop 0
	v_pk_fma_f32 v[112:113], v[112:113], v[4:5], v[154:155]
	s_nop 0
	v_fmac_f32_e32 v152, v0, v112
	v_fmac_f32_e32 v152, v1, v113
	v_pk_mul_f32 v[0:1], v[156:157], v[96:97] op_sel_hi:[1,0]
	s_nop 0
	v_pk_fma_f32 v[110:111], v[110:111], v[6:7], v[0:1]
	s_nop 0
	v_fmac_f32_e32 v152, v2, v110
	v_fmac_f32_e32 v152, v3, v111
	ds_read_b128 v[0:3], v151 offset:12752
	ds_read_b128 v[4:7], v151 offset:13264
	ds_read_b128 v[154:157], v151 offset:13776
	s_waitcnt lgkmcnt(0)
	v_pk_mul_f32 v[154:155], v[154:155], v[96:97] op_sel_hi:[1,0]
	s_nop 0
	v_pk_fma_f32 v[108:109], v[108:109], v[4:5], v[154:155]
	s_nop 0
	v_fmac_f32_e32 v152, v0, v108
	v_fmac_f32_e32 v152, v1, v109
	v_pk_mul_f32 v[0:1], v[156:157], v[96:97] op_sel_hi:[1,0]
	s_nop 0
	v_pk_fma_f32 v[106:107], v[106:107], v[6:7], v[0:1]
	s_nop 0
	v_fmac_f32_e32 v152, v2, v106
	v_fmac_f32_e32 v152, v3, v107
	ds_read_b128 v[0:3], v151 offset:13280
	ds_read_b128 v[4:7], v151 offset:13792
	ds_read_b128 v[154:157], v151 offset:12768
	s_waitcnt lgkmcnt(1)
	v_pk_mul_f32 v[4:5], v[4:5], v[96:97] op_sel_hi:[1,0]
	s_nop 0
	v_pk_fma_f32 v[104:105], v[104:105], v[0:1], v[4:5]
	s_waitcnt lgkmcnt(0)
	v_pk_mul_f32 v[0:1], v[154:155], v[104:105]
	s_nop 0
	v_add_f32_e32 v0, v152, v0
	v_add_f32_e32 v4, v0, v1
	v_pk_mul_f32 v[0:1], v[6:7], v[96:97] op_sel_hi:[1,0]
	s_nop 0
	v_pk_fma_f32 v[102:103], v[102:103], v[2:3], v[0:1]
	s_nop 0
	v_pk_mul_f32 v[0:1], v[156:157], v[102:103]
	s_nop 0
	v_add_f32_e32 v0, v4, v0
	v_add_f32_e32 v156, v0, v1
	ds_read_b128 v[0:3], v151 offset:13296
	ds_read_b128 v[4:7], v151 offset:13808
	ds_read_b128 v[152:155], v151 offset:12784
	s_waitcnt lgkmcnt(1)
	v_pk_mul_f32 v[4:5], v[4:5], v[96:97] op_sel_hi:[1,0]
	s_nop 0
	v_pk_fma_f32 v[100:101], v[100:101], v[0:1], v[4:5]
	s_waitcnt lgkmcnt(0)
	v_pk_mul_f32 v[0:1], v[152:153], v[100:101]
	s_nop 0
	v_add_f32_e32 v0, v156, v0
	v_add_f32_e32 v4, v0, v1
	v_pk_mul_f32 v[0:1], v[6:7], v[96:97] op_sel_hi:[1,0]
	s_nop 0
	v_pk_fma_f32 v[98:99], v[98:99], v[2:3], v[0:1]
	s_nop 0
	v_pk_mul_f32 v[0:1], v[154:155], v[98:99]
	s_nop 0
	v_add_f32_e32 v0, v4, v0
	v_add_f32_e32 v0, v0, v1
	s_nop 0
	v_cvt_pk_bf16_f32 v2, v0, v0
	v_lshl_add_u64 v[0:1], v[144:145], 0, s[62:63]
	global_store_short_d16_hi v[0:1], v2, off
	s_cbranch_scc1 .LBB0_1181

.LBB0_1193:
	s_ashr_i32 s3, s2, 31
	s_lshl_b64 s[4:5], s[2:3], 11
	v_lshl_add_u64 v[78:79], v[68:69], 0, s[4:5]
	v_add_co_u32_e32 v76, vcc, s91, v78
	global_load_dword v74, v[78:79], off
	s_nop 0
	v_addc_co_u32_e32 v77, vcc, 0, v79, vcc
	global_load_dword v82, v[76:77], off
	v_add_co_u32_e32 v76, vcc, s6, v78
	s_lshl_b64 s[4:5], s[2:3], 12
	s_nop 0
	v_addc_co_u32_e32 v77, vcc, 0, v79, vcc
	v_add_co_u32_e32 v80, vcc, s7, v78
	global_load_dword v76, v[76:77], off
	s_nop 0
	v_addc_co_u32_e32 v81, vcc, 0, v79, vcc
	global_load_dword v66, v[80:81], off
	v_add_co_u32_e32 v80, vcc, s33, v78
	s_add_i32 s9, s9, -1
	s_nop 0
	v_addc_co_u32_e32 v81, vcc, 0, v79, vcc
	global_load_dword v77, v[80:81], off
	v_add_co_u32_e32 v80, vcc, s49, v78
	s_add_i32 s2, s2, 1
	s_nop 0
	v_addc_co_u32_e32 v81, vcc, 0, v79, vcc
	global_load_dword v80, v[80:81], off
	v_add_co_u32_e32 v78, vcc, s28, v78
	s_cmp_lg_u32 s9, 0
	s_nop 0
	v_addc_co_u32_e32 v79, vcc, 0, v79, vcc
	global_load_dword v75, v[78:79], off
	v_cmp_lt_i32_e32 vcc, v246, v252
	s_waitcnt vmcnt(0)
	ds_write2st64_b32 v73, v74, v82 offset0:48 offset1:49
	ds_write2st64_b32 v73, v76, v77 offset0:50 offset1:51
	ds_write_b32 v73, v80 offset:13312
	s_waitcnt lgkmcnt(0)
	v_mov_b32_e32 v77, s86
	ds_read_b128 v[78:81], v77 offset:13056
	v_mul_f32_e32 v74, v74, v76
	v_mul_f32_e32 v76, v72, v74
	s_waitcnt lgkmcnt(0)
	v_fma_f32 v82, v60, v78, 0
	v_fmac_f32_e32 v82, v61, v79
	v_fmac_f32_e32 v82, v62, v80
	v_fmac_f32_e32 v82, v63, v81
	ds_read_b128 v[78:81], v77 offset:13072
	s_waitcnt lgkmcnt(0)
	v_fmac_f32_e32 v82, v56, v78
	v_fmac_f32_e32 v82, v57, v79
	v_fmac_f32_e32 v82, v58, v80
	v_fmac_f32_e32 v82, v59, v81
	ds_read_b128 v[78:81], v77 offset:13088
	s_waitcnt lgkmcnt(0)
	v_fmac_f32_e32 v82, v52, v78
	v_fmac_f32_e32 v82, v53, v79
	v_fmac_f32_e32 v82, v54, v80
	v_fmac_f32_e32 v82, v55, v81
	ds_read_b128 v[78:81], v77 offset:13104
	s_waitcnt lgkmcnt(0)
	v_fmac_f32_e32 v82, v44, v78
	v_fmac_f32_e32 v82, v45, v79
	v_fmac_f32_e32 v82, v46, v80
	v_fmac_f32_e32 v82, v47, v81
	ds_read_b128 v[78:81], v77 offset:13120
	s_waitcnt lgkmcnt(0)
	v_fmac_f32_e32 v82, v48, v78
	v_fmac_f32_e32 v82, v49, v79
	v_fmac_f32_e32 v82, v50, v80
	v_fmac_f32_e32 v82, v51, v81
	ds_read_b128 v[78:81], v77 offset:13136
	s_waitcnt lgkmcnt(0)
	v_fmac_f32_e32 v82, v40, v78
	v_fmac_f32_e32 v82, v41, v79
	v_fmac_f32_e32 v82, v42, v80
	v_fmac_f32_e32 v82, v43, v81
	ds_read_b128 v[78:81], v77 offset:13152
	s_waitcnt lgkmcnt(0)
	v_fmac_f32_e32 v82, v36, v78
	v_fmac_f32_e32 v82, v37, v79
	v_fmac_f32_e32 v82, v38, v80
	v_fmac_f32_e32 v82, v39, v81
	ds_read_b128 v[78:81], v77 offset:13168
	s_waitcnt lgkmcnt(0)
	v_fmac_f32_e32 v82, v28, v78
	v_fmac_f32_e32 v82, v29, v79
	v_fmac_f32_e32 v82, v30, v80
	v_fmac_f32_e32 v82, v31, v81
	ds_read_b128 v[78:81], v77 offset:13184
	s_waitcnt lgkmcnt(0)
	v_fmac_f32_e32 v82, v32, v78
	v_fmac_f32_e32 v82, v33, v79
	v_fmac_f32_e32 v82, v34, v80
	v_fmac_f32_e32 v82, v35, v81
	ds_read_b128 v[78:81], v77 offset:13200
	s_waitcnt lgkmcnt(0)
	v_fmac_f32_e32 v82, v24, v78
	v_fmac_f32_e32 v82, v25, v79
	v_fmac_f32_e32 v82, v26, v80
	v_fmac_f32_e32 v82, v27, v81
	ds_read_b128 v[78:81], v77 offset:13216
	s_waitcnt lgkmcnt(0)
	v_fmac_f32_e32 v82, v20, v78
	v_fmac_f32_e32 v82, v21, v79
	v_fmac_f32_e32 v82, v22, v80
	v_fmac_f32_e32 v82, v23, v81
	ds_read_b128 v[78:81], v77 offset:13232
	s_waitcnt lgkmcnt(0)
	v_fmac_f32_e32 v82, v12, v78
	v_fmac_f32_e32 v82, v13, v79
	v_fmac_f32_e32 v82, v14, v80
	v_fmac_f32_e32 v82, v15, v81
	ds_read_b128 v[78:81], v77 offset:13248
	s_waitcnt lgkmcnt(0)
	v_fmac_f32_e32 v82, v16, v78
	v_fmac_f32_e32 v82, v17, v79
	v_fmac_f32_e32 v82, v18, v80
	v_fmac_f32_e32 v82, v19, v81
	ds_read_b128 v[78:81], v77 offset:13264
	s_waitcnt lgkmcnt(0)
	v_pk_mul_f32 v[78:79], v[8:9], v[78:79]
	s_nop 0
	v_add_f32_e32 v78, v82, v78
	v_add_f32_e32 v82, v78, v79
	v_pk_mul_f32 v[78:79], v[10:11], v[80:81]
	s_nop 0
	v_add_f32_e32 v78, v82, v78
	v_add_f32_e32 v82, v78, v79
	ds_read_b128 v[78:81], v77 offset:13280
	s_waitcnt lgkmcnt(0)
	v_pk_mul_f32 v[78:79], v[4:5], v[78:79]
	s_nop 0
	v_add_f32_e32 v78, v82, v78
	v_add_f32_e32 v82, v78, v79
	v_pk_mul_f32 v[78:79], v[6:7], v[80:81]
	s_nop 0
	v_add_f32_e32 v78, v82, v78
	v_add_f32_e32 v82, v78, v79
	ds_read_b128 v[78:81], v77 offset:13296
	s_waitcnt lgkmcnt(0)
	v_pk_mul_f32 v[78:79], v[0:1], v[78:79]
	s_nop 0
	v_add_f32_e32 v78, v82, v78
	v_add_f32_e32 v82, v78, v79
	v_pk_mul_f32 v[78:79], v[2:3], v[80:81]
	s_nop 0
	v_add_f32_e32 v78, v82, v78
	v_add_f32_e32 v94, v78, v79
	ds_read_b128 v[78:81], v77 offset:12288
	ds_read_b128 v[82:85], v77 offset:12304
	ds_read_b128 v[86:89], v77 offset:12320
	ds_read_b128 v[90:93], v77 offset:12336
	ds_read_b128 v[98:101], v77 offset:12544
	ds_read_b128 v[102:105], v77 offset:13312
	ds_read_b128 v[106:109], v77 offset:12800
	s_waitcnt lgkmcnt(1)
	v_pk_mul_f32 v[102:103], v[94:95], v[102:103] op_sel_hi:[0,1]
	v_pk_fma_f32 v[60:61], v[60:61], v[98:99], v[102:103] neg_lo:[0,0,1] neg_hi:[0,0,1]
	s_waitcnt lgkmcnt(0)
	v_pk_fma_f32 v[60:61], v[66:67], v[106:107], v[60:61] op_sel_hi:[0,1,1]
	v_fma_f32 v95, v78, v60, 0
	v_fmac_f32_e32 v95, v79, v61
	v_pk_mul_f32 v[78:79], v[94:95], v[104:105] op_sel_hi:[0,1]
	v_pk_fma_f32 v[62:63], v[62:63], v[100:101], v[78:79] neg_lo:[0,0,1] neg_hi:[0,0,1]
	s_nop 0
	v_pk_fma_f32 v[62:63], v[66:67], v[108:109], v[62:63] op_sel_hi:[0,1,1]
	v_fmac_f32_e32 v95, v80, v62
	v_fmac_f32_e32 v95, v81, v63
	ds_read_b128 v[78:81], v77 offset:12560
	ds_read_b128 v[98:101], v77 offset:13328
	ds_read_b128 v[102:105], v77 offset:12816
	s_waitcnt lgkmcnt(1)
	v_pk_mul_f32 v[98:99], v[94:95], v[98:99] op_sel_hi:[0,1]
	v_pk_fma_f32 v[56:57], v[56:57], v[78:79], v[98:99] neg_lo:[0,0,1] neg_hi:[0,0,1]
	s_waitcnt lgkmcnt(0)
	v_pk_fma_f32 v[56:57], v[66:67], v[102:103], v[56:57] op_sel_hi:[0,1,1]
	v_fmac_f32_e32 v95, v82, v56
	v_fmac_f32_e32 v95, v83, v57
	v_pk_mul_f32 v[78:79], v[94:95], v[100:101] op_sel_hi:[0,1]
	v_pk_fma_f32 v[58:59], v[58:59], v[80:81], v[78:79] neg_lo:[0,0,1] neg_hi:[0,0,1]
	s_nop 0
	v_pk_fma_f32 v[58:59], v[66:67], v[104:105], v[58:59] op_sel_hi:[0,1,1]
	v_fmac_f32_e32 v95, v84, v58
	v_fmac_f32_e32 v95, v85, v59
	ds_read_b128 v[78:81], v77 offset:12576
	ds_read_b128 v[82:85], v77 offset:13344
	ds_read_b128 v[98:101], v77 offset:12832
	s_waitcnt lgkmcnt(1)
	v_pk_mul_f32 v[82:83], v[94:95], v[82:83] op_sel_hi:[0,1]
	v_pk_fma_f32 v[52:53], v[52:53], v[78:79], v[82:83] neg_lo:[0,0,1] neg_hi:[0,0,1]
	s_waitcnt lgkmcnt(0)
	v_pk_fma_f32 v[52:53], v[66:67], v[98:99], v[52:53] op_sel_hi:[0,1,1]
	v_fmac_f32_e32 v95, v86, v52
	v_fmac_f32_e32 v95, v87, v53
	v_pk_mul_f32 v[78:79], v[94:95], v[84:85] op_sel_hi:[0,1]
	v_pk_fma_f32 v[54:55], v[54:55], v[80:81], v[78:79] neg_lo:[0,0,1] neg_hi:[0,0,1]
	ds_read_b128 v[78:81], v77 offset:12592
	ds_read_b128 v[82:85], v77 offset:13360
	v_pk_fma_f32 v[54:55], v[66:67], v[100:101], v[54:55] op_sel_hi:[0,1,1]
	v_fmac_f32_e32 v95, v88, v54
	v_fmac_f32_e32 v95, v89, v55
	ds_read_b128 v[86:89], v77 offset:12848
	s_waitcnt lgkmcnt(1)
	v_pk_mul_f32 v[82:83], v[94:95], v[82:83] op_sel_hi:[0,1]
	v_pk_fma_f32 v[44:45], v[44:45], v[78:79], v[82:83] neg_lo:[0,0,1] neg_hi:[0,0,1]
	s_waitcnt lgkmcnt(0)
	v_pk_fma_f32 v[44:45], v[66:67], v[86:87], v[44:45] op_sel_hi:[0,1,1]
	v_fmac_f32_e32 v95, v90, v44
	v_fmac_f32_e32 v95, v91, v45
	v_pk_mul_f32 v[78:79], v[94:95], v[84:85] op_sel_hi:[0,1]
	v_pk_fma_f32 v[46:47], v[46:47], v[80:81], v[78:79] neg_lo:[0,0,1] neg_hi:[0,0,1]
	s_nop 0
	v_pk_fma_f32 v[46:47], v[66:67], v[88:89], v[46:47] op_sel_hi:[0,1,1]
	ds_read_b128 v[78:81], v77 offset:12352
	ds_read_b128 v[82:85], v77 offset:12608
	ds_read_b128 v[86:89], v77 offset:13376
	v_fmac_f32_e32 v95, v92, v46
	v_fmac_f32_e32 v95, v93, v47
	ds_read_b128 v[90:93], v77 offset:12864
	s_waitcnt lgkmcnt(1)
	v_pk_mul_f32 v[86:87], v[94:95], v[86:87] op_sel_hi:[0,1]
	v_pk_fma_f32 v[48:49], v[48:49], v[82:83], v[86:87] neg_lo:[0,0,1] neg_hi:[0,0,1]
	s_waitcnt lgkmcnt(0)
	v_pk_fma_f32 v[48:49], v[66:67], v[90:91], v[48:49] op_sel_hi:[0,1,1]
	v_fmac_f32_e32 v95, v78, v48
	v_fmac_f32_e32 v95, v79, v49
	v_pk_mul_f32 v[78:79], v[94:95], v[88:89] op_sel_hi:[0,1]
	v_pk_fma_f32 v[50:51], v[50:51], v[84:85], v[78:79] neg_lo:[0,0,1] neg_hi:[0,0,1]
	s_nop 0
	v_pk_fma_f32 v[50:51], v[66:67], v[92:93], v[50:51] op_sel_hi:[0,1,1]
	v_fmac_f32_e32 v95, v80, v50
	v_fmac_f32_e32 v95, v81, v51
	ds_read_b128 v[78:81], v77 offset:12368
	ds_read_b128 v[82:85], v77 offset:12624
	ds_read_b128 v[86:89], v77 offset:13392
	ds_read_b128 v[90:93], v77 offset:12880
	s_waitcnt lgkmcnt(1)
	v_pk_mul_f32 v[86:87], v[94:95], v[86:87] op_sel_hi:[0,1]
	v_pk_fma_f32 v[40:41], v[40:41], v[82:83], v[86:87] neg_lo:[0,0,1] neg_hi:[0,0,1]
	s_waitcnt lgkmcnt(0)
	v_pk_fma_f32 v[40:41], v[66:67], v[90:91], v[40:41] op_sel_hi:[0,1,1]
	v_fmac_f32_e32 v95, v78, v40
	v_fmac_f32_e32 v95, v79, v41
	v_pk_mul_f32 v[78:79], v[94:95], v[88:89] op_sel_hi:[0,1]
	v_pk_fma_f32 v[42:43], v[42:43], v[84:85], v[78:79] neg_lo:[0,0,1] neg_hi:[0,0,1]
	s_nop 0
	v_pk_fma_f32 v[42:43], v[66:67], v[92:93], v[42:43] op_sel_hi:[0,1,1]
	v_fmac_f32_e32 v95, v80, v42
	v_fmac_f32_e32 v95, v81, v43
	ds_read_b128 v[78:81], v77 offset:12384
	ds_read_b128 v[82:85], v77 offset:12640
	ds_read_b128 v[86:89], v77 offset:13408
	ds_read_b128 v[90:93], v77 offset:12896
	s_waitcnt lgkmcnt(1)
	v_pk_mul_f32 v[86:87], v[94:95], v[86:87] op_sel_hi:[0,1]
	v_pk_fma_f32 v[36:37], v[36:37], v[82:83], v[86:87] neg_lo:[0,0,1] neg_hi:[0,0,1]
	s_waitcnt lgkmcnt(0)
	v_pk_fma_f32 v[36:37], v[66:67], v[90:91], v[36:37] op_sel_hi:[0,1,1]
	v_fmac_f32_e32 v95, v78, v36
	v_fmac_f32_e32 v95, v79, v37
	v_pk_mul_f32 v[78:79], v[94:95], v[88:89] op_sel_hi:[0,1]
	v_pk_fma_f32 v[38:39], v[38:39], v[84:85], v[78:79] neg_lo:[0,0,1] neg_hi:[0,0,1]
	s_nop 0
	v_pk_fma_f32 v[38:39], v[66:67], v[92:93], v[38:39] op_sel_hi:[0,1,1]
	v_fmac_f32_e32 v95, v80, v38
	v_fmac_f32_e32 v95, v81, v39
	ds_read_b128 v[78:81], v77 offset:12400
	ds_read_b128 v[82:85], v77 offset:12656
	ds_read_b128 v[86:89], v77 offset:13424
	ds_read_b128 v[90:93], v77 offset:12912
	s_waitcnt lgkmcnt(1)
	v_pk_mul_f32 v[86:87], v[94:95], v[86:87] op_sel_hi:[0,1]
	v_pk_fma_f32 v[28:29], v[28:29], v[82:83], v[86:87] neg_lo:[0,0,1] neg_hi:[0,0,1]
	s_waitcnt lgkmcnt(0)
	v_pk_fma_f32 v[28:29], v[66:67], v[90:91], v[28:29] op_sel_hi:[0,1,1]
	v_fmac_f32_e32 v95, v78, v28
	v_fmac_f32_e32 v95, v79, v29
	v_pk_mul_f32 v[78:79], v[94:95], v[88:89] op_sel_hi:[0,1]
	v_pk_fma_f32 v[30:31], v[30:31], v[84:85], v[78:79] neg_lo:[0,0,1] neg_hi:[0,0,1]
	s_nop 0
	v_pk_fma_f32 v[30:31], v[66:67], v[92:93], v[30:31] op_sel_hi:[0,1,1]
	v_fmac_f32_e32 v95, v80, v30
	v_fmac_f32_e32 v95, v81, v31
	ds_read_b128 v[78:81], v77 offset:12416
	ds_read_b128 v[82:85], v77 offset:12672
	ds_read_b128 v[86:89], v77 offset:13440
	ds_read_b128 v[90:93], v77 offset:12928
	s_waitcnt lgkmcnt(1)
	v_pk_mul_f32 v[86:87], v[94:95], v[86:87] op_sel_hi:[0,1]
	v_pk_fma_f32 v[32:33], v[32:33], v[82:83], v[86:87] neg_lo:[0,0,1] neg_hi:[0,0,1]
	s_waitcnt lgkmcnt(0)
	v_pk_fma_f32 v[32:33], v[66:67], v[90:91], v[32:33] op_sel_hi:[0,1,1]
	v_fmac_f32_e32 v95, v78, v32
	v_fmac_f32_e32 v95, v79, v33
	v_pk_mul_f32 v[78:79], v[94:95], v[88:89] op_sel_hi:[0,1]
	v_pk_fma_f32 v[34:35], v[34:35], v[84:85], v[78:79] neg_lo:[0,0,1] neg_hi:[0,0,1]
	s_nop 0
	v_pk_fma_f32 v[34:35], v[66:67], v[92:93], v[34:35] op_sel_hi:[0,1,1]
	v_fmac_f32_e32 v95, v80, v34
	v_fmac_f32_e32 v95, v81, v35
	ds_read_b128 v[78:81], v77 offset:12432
	ds_read_b128 v[82:85], v77 offset:12688
	ds_read_b128 v[86:89], v77 offset:13456
	ds_read_b128 v[90:93], v77 offset:12944
	s_waitcnt lgkmcnt(1)
	v_pk_mul_f32 v[86:87], v[94:95], v[86:87] op_sel_hi:[0,1]
	v_pk_fma_f32 v[24:25], v[24:25], v[82:83], v[86:87] neg_lo:[0,0,1] neg_hi:[0,0,1]
	s_waitcnt lgkmcnt(0)
	v_pk_fma_f32 v[24:25], v[66:67], v[90:91], v[24:25] op_sel_hi:[0,1,1]
	v_fmac_f32_e32 v95, v78, v24
	v_fmac_f32_e32 v95, v79, v25
	v_pk_mul_f32 v[78:79], v[94:95], v[88:89] op_sel_hi:[0,1]
	v_pk_fma_f32 v[26:27], v[26:27], v[84:85], v[78:79] neg_lo:[0,0,1] neg_hi:[0,0,1]
	s_nop 0
	v_pk_fma_f32 v[26:27], v[66:67], v[92:93], v[26:27] op_sel_hi:[0,1,1]
	v_fmac_f32_e32 v95, v80, v26
	v_fmac_f32_e32 v95, v81, v27
	ds_read_b128 v[78:81], v77 offset:12448
	ds_read_b128 v[82:85], v77 offset:12704
	ds_read_b128 v[86:89], v77 offset:13472
	ds_read_b128 v[90:93], v77 offset:12960
	s_waitcnt lgkmcnt(1)
	v_pk_mul_f32 v[86:87], v[94:95], v[86:87] op_sel_hi:[0,1]
	v_pk_fma_f32 v[20:21], v[20:21], v[82:83], v[86:87] neg_lo:[0,0,1] neg_hi:[0,0,1]
	s_waitcnt lgkmcnt(0)
	v_pk_fma_f32 v[20:21], v[66:67], v[90:91], v[20:21] op_sel_hi:[0,1,1]
	v_fmac_f32_e32 v95, v78, v20
	v_fmac_f32_e32 v95, v79, v21
	v_pk_mul_f32 v[78:79], v[94:95], v[88:89] op_sel_hi:[0,1]
	v_pk_fma_f32 v[22:23], v[22:23], v[84:85], v[78:79] neg_lo:[0,0,1] neg_hi:[0,0,1]
	s_nop 0
	v_pk_fma_f32 v[22:23], v[66:67], v[92:93], v[22:23] op_sel_hi:[0,1,1]
	v_fmac_f32_e32 v95, v80, v22
	v_fmac_f32_e32 v95, v81, v23
	ds_read_b128 v[78:81], v77 offset:12464
	ds_read_b128 v[82:85], v77 offset:12720
	ds_read_b128 v[86:89], v77 offset:13488
	ds_read_b128 v[90:93], v77 offset:12976
	s_waitcnt lgkmcnt(1)
	v_pk_mul_f32 v[86:87], v[94:95], v[86:87] op_sel_hi:[0,1]
	v_pk_fma_f32 v[12:13], v[12:13], v[82:83], v[86:87] neg_lo:[0,0,1] neg_hi:[0,0,1]
	s_waitcnt lgkmcnt(0)
	v_pk_fma_f32 v[12:13], v[66:67], v[90:91], v[12:13] op_sel_hi:[0,1,1]
	v_fmac_f32_e32 v95, v78, v12
	v_fmac_f32_e32 v95, v79, v13
	v_pk_mul_f32 v[78:79], v[94:95], v[88:89] op_sel_hi:[0,1]
	v_pk_fma_f32 v[14:15], v[14:15], v[84:85], v[78:79] neg_lo:[0,0,1] neg_hi:[0,0,1]
	s_nop 0
	v_pk_fma_f32 v[14:15], v[66:67], v[92:93], v[14:15] op_sel_hi:[0,1,1]
	v_fmac_f32_e32 v95, v80, v14
	v_fmac_f32_e32 v95, v81, v15
	ds_read_b128 v[78:81], v77 offset:12480
	ds_read_b128 v[82:85], v77 offset:12736
	ds_read_b128 v[86:89], v77 offset:13504
	ds_read_b128 v[90:93], v77 offset:12992
	s_waitcnt lgkmcnt(1)
	v_pk_mul_f32 v[86:87], v[94:95], v[86:87] op_sel_hi:[0,1]
	v_pk_fma_f32 v[16:17], v[16:17], v[82:83], v[86:87] neg_lo:[0,0,1] neg_hi:[0,0,1]
	s_waitcnt lgkmcnt(0)
	v_pk_fma_f32 v[16:17], v[66:67], v[90:91], v[16:17] op_sel_hi:[0,1,1]
	v_fmac_f32_e32 v95, v78, v16
	v_fmac_f32_e32 v95, v79, v17
	v_pk_mul_f32 v[78:79], v[94:95], v[88:89] op_sel_hi:[0,1]
	v_pk_fma_f32 v[18:19], v[18:19], v[84:85], v[78:79] neg_lo:[0,0,1] neg_hi:[0,0,1]
	s_nop 0
	v_pk_fma_f32 v[18:19], v[66:67], v[92:93], v[18:19] op_sel_hi:[0,1,1]
	v_fmac_f32_e32 v95, v80, v18
	v_fmac_f32_e32 v95, v81, v19
	ds_read_b128 v[78:81], v77 offset:12496
	ds_read_b128 v[82:85], v77 offset:12752
	ds_read_b128 v[86:89], v77 offset:13520
	ds_read_b128 v[90:93], v77 offset:13008
	s_waitcnt lgkmcnt(1)
	v_pk_mul_f32 v[86:87], v[94:95], v[86:87] op_sel_hi:[0,1]
	v_pk_fma_f32 v[8:9], v[8:9], v[82:83], v[86:87] neg_lo:[0,0,1] neg_hi:[0,0,1]
	s_waitcnt lgkmcnt(0)
	v_pk_fma_f32 v[8:9], v[66:67], v[90:91], v[8:9] op_sel_hi:[0,1,1]
	v_fmac_f32_e32 v95, v78, v8
	v_fmac_f32_e32 v95, v79, v9
	v_pk_mul_f32 v[78:79], v[94:95], v[88:89] op_sel_hi:[0,1]
	v_pk_fma_f32 v[10:11], v[10:11], v[84:85], v[78:79] neg_lo:[0,0,1] neg_hi:[0,0,1]
	s_nop 0
	v_pk_fma_f32 v[10:11], v[66:67], v[92:93], v[10:11] op_sel_hi:[0,1,1]
	v_pk_mul_f32 v[78:79], v[80:81], v[10:11]
	s_nop 0
	v_add_f32_e32 v78, v95, v78
	v_add_f32_e32 v95, v78, v79
	ds_read_b128 v[78:81], v77 offset:12768
	ds_read_b128 v[82:85], v77 offset:13536
	ds_read_b128 v[86:89], v77 offset:13024
	ds_read_b128 v[90:93], v77 offset:12512
	s_waitcnt lgkmcnt(2)
	v_pk_mul_f32 v[82:83], v[94:95], v[82:83] op_sel_hi:[0,1]
	v_pk_fma_f32 v[4:5], v[4:5], v[78:79], v[82:83] neg_lo:[0,0,1] neg_hi:[0,0,1]
	s_waitcnt lgkmcnt(1)
	v_pk_fma_f32 v[4:5], v[66:67], v[86:87], v[4:5] op_sel_hi:[0,1,1]
	s_waitcnt lgkmcnt(0)
	v_pk_mul_f32 v[78:79], v[90:91], v[4:5]
	s_nop 0
	v_add_f32_e32 v78, v95, v78
	v_add_f32_e32 v82, v78, v79
	v_pk_mul_f32 v[78:79], v[94:95], v[84:85] op_sel_hi:[0,1]
	v_pk_fma_f32 v[6:7], v[6:7], v[80:81], v[78:79] neg_lo:[0,0,1] neg_hi:[0,0,1]
	s_nop 0
	v_pk_fma_f32 v[6:7], v[66:67], v[88:89], v[6:7] op_sel_hi:[0,1,1]
	v_pk_mul_f32 v[78:79], v[92:93], v[6:7]
	s_nop 0
	v_add_f32_e32 v78, v82, v78
	v_add_f32_e32 v95, v78, v79
	ds_read_b128 v[78:81], v77 offset:12784
	ds_read_b128 v[82:85], v77 offset:13552
	ds_read_b128 v[86:89], v77 offset:13040
	ds_read_b128 v[90:93], v77 offset:12528
	s_waitcnt lgkmcnt(2)
	v_pk_mul_f32 v[82:83], v[94:95], v[82:83] op_sel_hi:[0,1]
	v_pk_fma_f32 v[0:1], v[0:1], v[78:79], v[82:83] neg_lo:[0,0,1] neg_hi:[0,0,1]
	s_waitcnt lgkmcnt(1)
	v_pk_fma_f32 v[0:1], v[66:67], v[86:87], v[0:1] op_sel_hi:[0,1,1]
	s_waitcnt lgkmcnt(0)
	v_pk_mul_f32 v[78:79], v[90:91], v[0:1]
	s_nop 0
	v_add_f32_e32 v77, v95, v78
	v_add_f32_e32 v77, v77, v79
	v_pk_mul_f32 v[78:79], v[94:95], v[84:85] op_sel_hi:[0,1]
	v_pk_fma_f32 v[2:3], v[2:3], v[80:81], v[78:79] neg_lo:[0,0,1] neg_hi:[0,0,1]
	s_nop 0
	v_pk_fma_f32 v[2:3], v[66:67], v[88:89], v[2:3] op_sel_hi:[0,1,1]
	v_pk_mul_f32 v[78:79], v[92:93], v[2:3]
	s_nop 0
	v_add_f32_e32 v77, v77, v78
	v_cndmask_b32_e32 v78, v217, v246, vcc
	v_add_f32_e32 v77, v77, v79
	v_lshlrev_b32_e32 v78, 2, v78
	ds_bpermute_b32 v79, v78, v77
	v_cmp_lt_i32_e32 vcc, v247, v252
	ds_bpermute_b32 v76, v78, v76
	s_waitcnt lgkmcnt(1)
	v_add_f32_e32 v79, v77, v79
	v_cndmask_b32_e32 v80, v217, v247, vcc
	v_lshlrev_b32_e32 v80, 2, v80
	ds_bpermute_b32 v81, v80, v79
	v_cmp_lt_i32_e32 vcc, v248, v252
	s_waitcnt lgkmcnt(1)
	v_fmac_f32_e32 v76, v72, v74
	ds_bpermute_b32 v74, v80, v76
	s_waitcnt lgkmcnt(1)
	v_add_f32_e32 v79, v79, v81
	v_cndmask_b32_e32 v81, v217, v248, vcc
	v_lshlrev_b32_e32 v81, 2, v81
	ds_bpermute_b32 v82, v81, v79
	v_cmp_lt_i32_e32 vcc, v221, v252
	s_waitcnt lgkmcnt(1)
	v_add_f32_e32 v74, v76, v74
	ds_bpermute_b32 v76, v81, v74
	s_waitcnt lgkmcnt(1)
	v_add_f32_e32 v79, v79, v82
	v_cndmask_b32_e32 v82, v217, v221, vcc
	v_lshlrev_b32_e32 v82, 2, v82
	ds_bpermute_b32 v83, v82, v79
	v_cmp_lt_i32_e32 vcc, v216, v252
	s_waitcnt lgkmcnt(1)
	v_add_f32_e32 v74, v74, v76
	ds_bpermute_b32 v76, v82, v74
	s_waitcnt lgkmcnt(1)
	v_add_f32_e32 v79, v79, v83
	v_cndmask_b32_e32 v83, v217, v216, vcc
	v_lshlrev_b32_e32 v83, 2, v83
	ds_bpermute_b32 v84, v83, v79
	v_cmp_lt_i32_e32 vcc, v218, v252
	s_waitcnt lgkmcnt(1)
	v_add_f32_e32 v74, v74, v76
	ds_bpermute_b32 v76, v83, v74
	s_waitcnt lgkmcnt(1)
	v_add_f32_e32 v79, v79, v84
	v_cndmask_b32_e32 v84, v217, v218, vcc
	v_lshlrev_b32_e32 v84, 2, v84
	ds_bpermute_b32 v85, v84, v79
	s_waitcnt lgkmcnt(1)
	v_add_f32_e32 v74, v74, v76
	ds_bpermute_b32 v76, v84, v74
	s_waitcnt lgkmcnt(1)
	v_add_f32_e32 v79, v79, v85
	v_fmac_f32_e32 v77, 0xbc800000, v79
	v_mul_f32_e32 v79, v77, v77
	ds_bpermute_b32 v79, v78, v79
	s_waitcnt lgkmcnt(1)
	v_add_f32_e32 v76, v74, v76
	s_waitcnt lgkmcnt(0)
	v_fmac_f32_e32 v79, v77, v77
	ds_bpermute_b32 v85, v80, v79
	s_waitcnt lgkmcnt(0)
	v_add_f32_e32 v79, v79, v85
	ds_bpermute_b32 v85, v81, v79
	s_waitcnt lgkmcnt(0)
	v_add_f32_e32 v79, v79, v85
	ds_bpermute_b32 v85, v82, v79
	s_waitcnt lgkmcnt(0)
	v_add_f32_e32 v79, v79, v85
	ds_bpermute_b32 v85, v83, v79
	s_waitcnt lgkmcnt(0)
	v_add_f32_e32 v79, v79, v85
	ds_bpermute_b32 v85, v84, v79
	s_waitcnt lgkmcnt(0)
	v_add_f32_e32 v79, v79, v85
	v_fmamk_f32 v79, v79, 0x3c800000, v231
	v_cmp_gt_f32_e32 vcc, s45, v79
	v_mul_f32_e32 v85, 0x4b800000, v79
	s_nop 0
	v_cndmask_b32_e32 v79, v79, v85, vcc
	v_rsq_f32_e32 v79, v79
	s_nop 0
	v_mul_f32_e32 v85, 0x45800000, v79
	v_cndmask_b32_e32 v79, v79, v85, vcc
	v_mul_f32_e32 v77, v77, v79
	v_pk_mul_f32 v[76:77], v[66:67], v[76:77]
	s_nop 0
	v_add_f32_e32 v66, v76, v77
	v_mul_f32_e32 v66, v75, v66
	s_nop 0
	v_cvt_pk_bf16_f32 v66, v66, v66
	v_lshl_add_u64 v[74:75], v[70:71], 0, s[4:5]
	global_store_short_d16_hi v[74:75], v66, off
	s_cbranch_scc1 .LBB0_1193
	s_ashr_i32 s4, s8, 31
	s_and_b64 s[2:3], s[0:1], exec
	s_cselect_b32 s3, s4, 0
	s_mov_b32 s4, 0x4400000
	s_cselect_b32 s4, s4, 0x4600000
	s_cselect_b32 s2, s8, s38
	s_add_u32 s4, s10, s4
	s_addc_u32 s5, s11, 0
	s_and_b64 s[0:1], s[0:1], exec
	v_readlane_b32 s6, v255, 40
	s_cselect_b32 s0, 5, 10
	v_readlane_b32 s7, v255, 41
	s_lshl_b64 s[0:1], s[6:7], s0
	s_add_u32 s0, s0, s26
	s_addc_u32 s1, s1, 0
	s_lshl_b64 s[2:3], s[2:3], 17
	s_lshl_b64 s[0:1], s[0:1], 14
	s_add_u32 s2, s4, s2
	s_addc_u32 s3, s5, s3
	s_add_u32 s0, s2, s0
	s_addc_u32 s1, s3, s1
	v_lshlrev_b64 v[66:67], 8, v[64:65]
	v_lshl_add_u64 v[66:67], s[0:1], 0, v[66:67]
	s_movk_i32 s52, 0x4000
	s_movk_i32 s53, 0x6000
	global_store_dwordx4 v[66:67], v[60:63], off
	global_store_dwordx4 v[66:67], v[56:59], off offset:16
	global_store_dwordx4 v[66:67], v[52:55], off offset:32
	global_store_dwordx4 v[66:67], v[44:47], off offset:48
	global_store_dwordx4 v[66:67], v[48:51], off offset:64
	global_store_dwordx4 v[66:67], v[40:43], off offset:80
	global_store_dwordx4 v[66:67], v[36:39], off offset:96
	global_store_dwordx4 v[66:67], v[28:31], off offset:112
	global_store_dwordx4 v[66:67], v[32:35], off offset:128
	global_store_dwordx4 v[66:67], v[24:27], off offset:144
	global_store_dwordx4 v[66:67], v[20:23], off offset:160
	global_store_dwordx4 v[66:67], v[12:15], off offset:176
	global_store_dwordx4 v[66:67], v[16:19], off offset:192
	global_store_dwordx4 v[66:67], v[8:11], off offset:208
	global_store_dwordx4 v[66:67], v[4:7], off offset:224
	global_store_dwordx4 v[66:67], v[0:3], off offset:240
	s_branch .LBB0_1149

.LBB0_1200:
	s_nop 0
	v_cvt_pk_bf16_f32 v0, v4, v4
	s_nop 0
	v_lshrrev_b32_e32 v0, 16, v0
	v_cvt_pk_bf16_f32 v1, v5, v5
	v_and_or_b32 v0, v1, s36, v0
	s_nop 0
	v_cvt_pk_bf16_f32 v1, v6, v6
	s_nop 0
	v_lshrrev_b32_e32 v1, 16, v1
	v_cvt_pk_bf16_f32 v2, v7, v7
	v_and_or_b32 v1, v2, s36, v1
	ds_write_b64 v56, v[0:1] offset:7392
	s_waitcnt lgkmcnt(0)
	ds_read_u16 v0, v84 offset:132
	ds_read_u16 v1, v84
	ds_read_u16 v10, v84 offset:16
	v_lshl_add_u64 v[4:5], s[20:21], 1, v[74:75]
	s_waitcnt lgkmcnt(1)
	v_lshl_or_b32 v0, v0, 16, v1
	ds_read_u16 v1, v84 offset:264
	ds_read_u16 v2, v84 offset:396
	s_waitcnt lgkmcnt(0)
	v_lshl_or_b32 v1, v2, 16, v1
	ds_read_u16 v2, v84 offset:528
	ds_read_u16 v3, v84 offset:660
	s_waitcnt lgkmcnt(0)
	v_lshl_or_b32 v2, v3, 16, v2
	ds_read_u16 v3, v84 offset:792
	ds_read_u16 v6, v84 offset:924
	s_waitcnt lgkmcnt(0)
	v_lshl_or_b32 v3, v6, 16, v3
	v_add_u32_e32 v6, s28, v83
	v_ashrrev_i32_e32 v7, 31, v6
	v_lshlrev_b64 v[8:9], 12, v[6:7]
	v_lshl_add_u64 v[8:9], v[4:5], 0, v[8:9]
	global_store_dwordx4 v[8:9], v[0:3], off
	ds_read_u16 v0, v84 offset:148
	ds_read_u16 v1, v84 offset:280
	ds_read_u16 v2, v84 offset:412
	v_add_u32_e32 v8, 8, v6
	v_ashrrev_i32_e32 v9, 31, v8
	v_lshlrev_b64 v[8:9], 12, v[8:9]
	s_waitcnt lgkmcnt(2)
	v_lshl_or_b32 v0, v0, 16, v10
	s_waitcnt lgkmcnt(0)
	v_lshl_or_b32 v1, v2, 16, v1
	ds_read_u16 v2, v84 offset:544
	ds_read_u16 v3, v84 offset:676
	v_lshl_add_u64 v[8:9], v[4:5], 0, v[8:9]
	s_waitcnt lgkmcnt(0)
	v_lshl_or_b32 v2, v3, 16, v2
	ds_read_u16 v3, v84 offset:808
	ds_read_u16 v7, v84 offset:940
	s_waitcnt lgkmcnt(0)
	v_lshl_or_b32 v3, v7, 16, v3
	global_store_dwordx4 v[8:9], v[0:3], off
	ds_read_u16 v0, v84 offset:164
	ds_read_u16 v1, v84 offset:32
	ds_read_u16 v7, v84 offset:48
	s_waitcnt lgkmcnt(1)
	v_lshl_or_b32 v0, v0, 16, v1
	ds_read_u16 v1, v84 offset:296
	ds_read_u16 v2, v84 offset:428
	s_waitcnt lgkmcnt(0)
	v_lshl_or_b32 v1, v2, 16, v1
	ds_read_u16 v2, v84 offset:560
	ds_read_u16 v3, v84 offset:692
	s_waitcnt lgkmcnt(0)
	v_lshl_or_b32 v2, v3, 16, v2
	ds_read_u16 v3, v84 offset:824
	ds_read_u16 v8, v84 offset:956
	s_waitcnt lgkmcnt(0)
	v_lshl_or_b32 v3, v8, 16, v3
	v_add_u32_e32 v8, 16, v6
	v_ashrrev_i32_e32 v9, 31, v8
	v_lshlrev_b64 v[8:9], 12, v[8:9]
	v_lshl_add_u64 v[8:9], v[4:5], 0, v[8:9]
	global_store_dwordx4 v[8:9], v[0:3], off
	ds_read_u16 v0, v84 offset:180
	ds_read_u16 v1, v84 offset:312
	ds_read_u16 v2, v84 offset:444
	v_add_u32_e32 v8, 24, v6
	v_ashrrev_i32_e32 v9, 31, v8
	v_lshlrev_b64 v[8:9], 12, v[8:9]
	s_waitcnt lgkmcnt(2)
	v_lshl_or_b32 v0, v0, 16, v7
	s_waitcnt lgkmcnt(0)
	v_lshl_or_b32 v1, v2, 16, v1
	ds_read_u16 v2, v84 offset:576
	ds_read_u16 v3, v84 offset:708
	v_lshl_add_u64 v[8:9], v[4:5], 0, v[8:9]
	s_waitcnt lgkmcnt(0)
	v_lshl_or_b32 v2, v3, 16, v2
	ds_read_u16 v3, v84 offset:840
	ds_read_u16 v7, v84 offset:972
	s_waitcnt lgkmcnt(0)
	v_lshl_or_b32 v3, v7, 16, v3
	global_store_dwordx4 v[8:9], v[0:3], off
	ds_read_u16 v0, v84 offset:64
	ds_read_u16 v1, v84 offset:196
	v_add_u32_e32 v8, 32, v6
	v_ashrrev_i32_e32 v9, 31, v8
	v_lshlrev_b64 v[8:9], 12, v[8:9]
	v_lshl_add_u64 v[8:9], v[4:5], 0, v[8:9]
	s_waitcnt lgkmcnt(0)
	v_lshl_or_b32 v0, v1, 16, v0
	ds_read_u16 v1, v84 offset:328
	ds_read_u16 v2, v84 offset:460
	s_waitcnt lgkmcnt(0)
	v_lshl_or_b32 v1, v2, 16, v1
	ds_read_u16 v2, v84 offset:592
	ds_read_u16 v3, v84 offset:724
	s_waitcnt lgkmcnt(0)
	v_lshl_or_b32 v2, v3, 16, v2
	ds_read_u16 v3, v84 offset:856
	ds_read_u16 v7, v84 offset:988
	s_waitcnt lgkmcnt(0)
	v_lshl_or_b32 v3, v7, 16, v3
	global_store_dwordx4 v[8:9], v[0:3], off
	ds_read_u16 v0, v84 offset:80
	ds_read_u16 v1, v84 offset:212
	v_add_u32_e32 v8, 40, v6
	v_ashrrev_i32_e32 v9, 31, v8
	v_lshlrev_b64 v[8:9], 12, v[8:9]
	v_lshl_add_u64 v[8:9], v[4:5], 0, v[8:9]
	s_waitcnt lgkmcnt(0)
	v_lshl_or_b32 v0, v1, 16, v0
	ds_read_u16 v1, v84 offset:344
	ds_read_u16 v2, v84 offset:476
	s_waitcnt lgkmcnt(0)
	v_lshl_or_b32 v1, v2, 16, v1
	ds_read_u16 v2, v84 offset:608
	ds_read_u16 v3, v84 offset:740
	s_waitcnt lgkmcnt(0)
	v_lshl_or_b32 v2, v3, 16, v2
	ds_read_u16 v3, v84 offset:872
	ds_read_u16 v7, v84 offset:1004
	s_waitcnt lgkmcnt(0)
	v_lshl_or_b32 v3, v7, 16, v3
	global_store_dwordx4 v[8:9], v[0:3], off
	ds_read_u16 v0, v84 offset:96
	ds_read_u16 v1, v84 offset:228
	v_add_u32_e32 v8, 48, v6
	v_ashrrev_i32_e32 v9, 31, v8
	v_lshlrev_b64 v[8:9], 12, v[8:9]
	v_lshl_add_u64 v[8:9], v[4:5], 0, v[8:9]
	s_waitcnt lgkmcnt(0)
	v_lshl_or_b32 v0, v1, 16, v0
	ds_read_u16 v1, v84 offset:360
	ds_read_u16 v2, v84 offset:492
	v_add_u32_e32 v6, 56, v6
	s_waitcnt lgkmcnt(0)
	v_lshl_or_b32 v1, v2, 16, v1
	ds_read_u16 v2, v84 offset:624
	ds_read_u16 v3, v84 offset:756
	s_waitcnt lgkmcnt(0)
	v_lshl_or_b32 v2, v3, 16, v2
	ds_read_u16 v3, v84 offset:888
	ds_read_u16 v7, v84 offset:1020
	s_waitcnt lgkmcnt(0)
	v_lshl_or_b32 v3, v7, 16, v3
	global_store_dwordx4 v[8:9], v[0:3], off
	ds_read_u16 v0, v84 offset:112
	ds_read_u16 v1, v84 offset:244
	s_waitcnt lgkmcnt(0)
	v_lshl_or_b32 v0, v1, 16, v0
	ds_read_u16 v1, v84 offset:376
	ds_read_u16 v2, v84 offset:508
	s_waitcnt lgkmcnt(0)
	v_lshl_or_b32 v1, v2, 16, v1
	ds_read_u16 v2, v84 offset:640
	ds_read_u16 v3, v84 offset:772
	s_waitcnt lgkmcnt(0)
	v_lshl_or_b32 v2, v3, 16, v2
	ds_read_u16 v3, v84 offset:904
	ds_read_u16 v7, v84 offset:1036
	s_waitcnt lgkmcnt(0)
	v_lshl_or_b32 v3, v7, 16, v3
	v_ashrrev_i32_e32 v7, 31, v6
	v_lshlrev_b64 v[6:7], 12, v[6:7]
	v_lshl_add_u64 v[4:5], v[4:5], 0, v[6:7]
	global_store_dwordx4 v[4:5], v[0:3], off
	s_waitcnt lgkmcnt(0)

.LBB0_1202:
	s_cmpk_gt_i32 s95, 0xbff
	s_mov_b64 s[0:1], -1
	s_cbranch_scc0 .LBB0_1248
	s_cmpk_gt_u32 s95, 0xfff
	s_cbranch_scc0 .LBB0_1245
	s_cmpk_gt_u32 s95, 0x257f
	s_cbranch_scc0 .LBB0_1210
	s_cmpk_gt_u32 s95, 0x303f
	s_cbranch_scc0 .LBB0_1207
	s_and_b32 s0, s24, 0x7fffffc0
	s_add_i32 s38, s0, 0xfffe7e00
	s_and_b32 s0, s22, 0x1c0
	v_or_b32_e32 v1, s0, v80
	v_add_u32_e32 v0, s38, v66
	v_lshlrev_b32_e32 v96, 2, v1
	v_ashrrev_i32_e32 v1, 31, v0
	v_lshl_add_u64 v[2:3], s[2:3], 0, v[96:97]
	v_lshlrev_b64 v[0:1], 11, v[0:1]
	v_lshl_add_u64 v[56:57], v[2:3], 0, v[0:1]
	v_add_co_u32_e32 v4, vcc, 0x2000, v56
	s_mov_b32 s1, 0x12000
	s_nop 0
	v_addc_co_u32_e32 v5, vcc, 0, v57, vcc
	global_load_dwordx4 v[0:3], v[56:57], off
	s_nop 0
	global_load_dwordx4 v[4:7], v[4:5], off
	v_add_co_u32_e32 v8, vcc, 0x4000, v56
	s_waitcnt vmcnt(0)
	s_nop 0
	v_addc_co_u32_e32 v9, vcc, 0, v57, vcc
	v_add_co_u32_e32 v12, vcc, 0x6000, v56
	v_cvt_pk_bf16_f32 v0, v0, v0
	s_nop 0
	v_addc_co_u32_e32 v13, vcc, 0, v57, vcc
	global_load_dwordx4 v[8:11], v[8:9], off
	s_nop 0
	global_load_dwordx4 v[12:15], v[12:13], off
	v_add_co_u32_e32 v16, vcc, 0x8000, v56
	s_nop 0
	s_nop 0
	v_addc_co_u32_e32 v17, vcc, 0, v57, vcc
	v_add_co_u32_e32 v20, vcc, 0xa000, v56
	v_lshrrev_b32_e32 v0, 16, v0
	s_nop 0
	v_addc_co_u32_e32 v21, vcc, 0, v57, vcc
	global_load_dwordx4 v[16:19], v[16:17], off
	s_nop 0
	global_load_dwordx4 v[20:23], v[20:21], off
	v_add_co_u32_e32 v24, vcc, 0xc000, v56
	v_cvt_pk_bf16_f32 v1, v1, v1
	s_nop 0
	v_addc_co_u32_e32 v25, vcc, 0, v57, vcc
	v_add_co_u32_e32 v28, vcc, 0xe000, v56
	v_and_or_b32 v0, v1, s36, v0
	s_nop 0
	v_addc_co_u32_e32 v29, vcc, 0, v57, vcc
	global_load_dwordx4 v[24:27], v[24:25], off
	s_nop 0
	global_load_dwordx4 v[28:31], v[28:29], off
	v_add_co_u32_e32 v32, vcc, s75, v56
	v_bfe_u32 v1, v2, 16, 1
	s_nop 0
	v_addc_co_u32_e32 v33, vcc, 0, v57, vcc
	v_add_co_u32_e32 v36, vcc, s1, v56
	s_mov_b32 s1, 0x14000
	s_nop 0
	v_addc_co_u32_e32 v37, vcc, 0, v57, vcc
	global_load_dwordx4 v[32:35], v[32:33], off
	s_nop 0
	global_load_dwordx4 v[36:39], v[36:37], off
	v_add_co_u32_e32 v40, vcc, s1, v56
	s_mov_b32 s1, 0x16000
	s_nop 0
	v_addc_co_u32_e32 v41, vcc, 0, v57, vcc
	v_add_co_u32_e32 v44, vcc, s1, v56
	s_mov_b32 s1, 0x18000
	s_nop 0
	v_addc_co_u32_e32 v45, vcc, 0, v57, vcc
	global_load_dwordx4 v[40:43], v[40:41], off
	s_nop 0
	global_load_dwordx4 v[44:47], v[44:45], off
	v_add_co_u32_e32 v48, vcc, s1, v56
	s_mov_b32 s1, 0x1a000
	s_nop 0
	v_addc_co_u32_e32 v49, vcc, 0, v57, vcc
	v_add_co_u32_e32 v52, vcc, s1, v56
	v_add3_u32 v1, v2, v1, s48
	s_nop 0
	v_addc_co_u32_e32 v53, vcc, 0, v57, vcc
	global_load_dwordx4 v[48:51], v[48:49], off
	s_nop 0
	global_load_dwordx4 v[52:55], v[52:53], off
	s_nop 0
	v_lshrrev_b32_e32 v1, 16, v1
	v_cvt_pk_bf16_f32 v2, v3, v3
	v_and_or_b32 v1, v2, s36, v1
	s_nop 0
	s_mov_b32 s1, 0x1c000
	v_cvt_pk_bf16_f32 v2, v4, v4
	s_nop 0
	v_add_co_u32_e32 v58, vcc, s1, v56
	v_lshrrev_b32_e32 v2, 16, v2
	v_cvt_pk_bf16_f32 v3, v5, v5
	v_addc_co_u32_e32 v59, vcc, 0, v57, vcc
	s_mov_b32 s1, 0x1e000
	v_and_or_b32 v2, v3, s36, v2
	s_nop 0
	v_add_co_u32_e32 v60, vcc, s1, v56
	v_cvt_pk_bf16_f32 v3, v6, v6
	s_nop 0
	v_addc_co_u32_e32 v61, vcc, 0, v57, vcc
	v_lshrrev_b32_e32 v3, 16, v3
	v_cvt_pk_bf16_f32 v4, v7, v7
	global_load_dwordx4 v[56:59], v[58:59], off
	s_nop 0
	global_load_dwordx4 v[60:63], v[60:61], off
	v_add_u32_e32 v76, v81, v82
	v_and_or_b32 v3, v4, s36, v3
	ds_write2_b64 v76, v[0:1], v[2:3] offset1:66
	s_waitcnt vmcnt(13)
	s_nop 0
	v_cvt_pk_bf16_f32 v0, v8, v8
	s_nop 0
	v_lshrrev_b32_e32 v0, 16, v0
	v_cvt_pk_bf16_f32 v1, v9, v9
	v_and_or_b32 v0, v1, s36, v0
	s_nop 0
	v_cvt_pk_bf16_f32 v1, v10, v10
	s_nop 0
	v_lshrrev_b32_e32 v1, 16, v1
	v_cvt_pk_bf16_f32 v2, v11, v11
	v_and_or_b32 v1, v2, s36, v1
	s_waitcnt vmcnt(12)
	s_nop 0
	v_cvt_pk_bf16_f32 v2, v12, v12
	s_nop 0
	v_lshrrev_b32_e32 v2, 16, v2
	v_cvt_pk_bf16_f32 v3, v13, v13
	v_and_or_b32 v2, v3, s36, v2
	s_nop 0
	v_cvt_pk_bf16_f32 v3, v14, v14
	s_nop 0
	v_lshrrev_b32_e32 v3, 16, v3
	v_cvt_pk_bf16_f32 v4, v15, v15
	v_and_or_b32 v3, v4, s36, v3
	ds_write2_b64 v76, v[0:1], v[2:3] offset0:132 offset1:198
	s_waitcnt vmcnt(11)
	s_nop 0
	v_cvt_pk_bf16_f32 v0, v16, v16
	s_nop 0
	v_lshrrev_b32_e32 v0, 16, v0
	v_cvt_pk_bf16_f32 v1, v17, v17
	v_and_or_b32 v0, v1, s36, v0
	s_nop 0
	v_cvt_pk_bf16_f32 v1, v18, v18
	s_nop 0
	v_lshrrev_b32_e32 v1, 16, v1
	v_cvt_pk_bf16_f32 v2, v19, v19
	v_and_or_b32 v1, v2, s36, v1
	s_waitcnt vmcnt(10)
	s_nop 0
	v_cvt_pk_bf16_f32 v2, v20, v20
	s_nop 0
	v_lshrrev_b32_e32 v2, 16, v2
	v_cvt_pk_bf16_f32 v3, v21, v21
	v_and_or_b32 v2, v3, s36, v2
	s_nop 0
	v_cvt_pk_bf16_f32 v3, v22, v22
	s_nop 0
	v_lshrrev_b32_e32 v3, 16, v3
	v_cvt_pk_bf16_f32 v4, v23, v23
	v_and_or_b32 v3, v4, s36, v3
	v_add_u32_e32 v4, 0x800, v76
	ds_write2_b64 v4, v[0:1], v[2:3] offset0:8 offset1:74
	s_waitcnt vmcnt(9)
	s_nop 0
	v_cvt_pk_bf16_f32 v0, v24, v24
	s_nop 0
	v_lshrrev_b32_e32 v0, 16, v0
	v_cvt_pk_bf16_f32 v1, v25, v25
	v_and_or_b32 v0, v1, s36, v0
	s_nop 0
	v_cvt_pk_bf16_f32 v1, v26, v26
	s_nop 0
	v_lshrrev_b32_e32 v1, 16, v1
	v_cvt_pk_bf16_f32 v2, v27, v27
	v_and_or_b32 v1, v2, s36, v1
	s_waitcnt vmcnt(8)
	s_nop 0
	v_cvt_pk_bf16_f32 v2, v28, v28
	s_nop 0
	v_lshrrev_b32_e32 v2, 16, v2
	v_cvt_pk_bf16_f32 v3, v29, v29
	v_and_or_b32 v2, v3, s36, v2
	s_nop 0
	v_cvt_pk_bf16_f32 v3, v30, v30
	s_nop 0
	v_lshrrev_b32_e32 v3, 16, v3
	v_cvt_pk_bf16_f32 v5, v31, v31
	v_and_or_b32 v3, v5, s36, v3
	ds_write2_b64 v4, v[0:1], v[2:3] offset0:140 offset1:206
	s_waitcnt vmcnt(7)
	s_nop 0
	v_cvt_pk_bf16_f32 v0, v32, v32
	s_nop 0
	v_lshrrev_b32_e32 v0, 16, v0
	v_cvt_pk_bf16_f32 v1, v33, v33
	v_and_or_b32 v0, v1, s36, v0
	s_nop 0
	v_cvt_pk_bf16_f32 v1, v34, v34
	s_nop 0
	v_lshrrev_b32_e32 v1, 16, v1
	v_cvt_pk_bf16_f32 v2, v35, v35
	v_and_or_b32 v1, v2, s36, v1
	s_waitcnt vmcnt(6)
	s_nop 0
	v_cvt_pk_bf16_f32 v2, v36, v36
	s_nop 0
	v_lshrrev_b32_e32 v2, 16, v2
	v_cvt_pk_bf16_f32 v3, v37, v37
	v_and_or_b32 v2, v3, s36, v2
	s_nop 0
	v_cvt_pk_bf16_f32 v3, v38, v38
	s_nop 0
	v_lshrrev_b32_e32 v3, 16, v3
	v_cvt_pk_bf16_f32 v4, v39, v39
	v_and_or_b32 v3, v4, s36, v3
	v_add_u32_e32 v4, 0x1000, v76
	ds_write2_b64 v4, v[0:1], v[2:3] offset0:16 offset1:82
	s_waitcnt vmcnt(5)
	s_nop 0
	v_cvt_pk_bf16_f32 v0, v40, v40
	s_nop 0
	v_lshrrev_b32_e32 v0, 16, v0
	v_cvt_pk_bf16_f32 v1, v41, v41
	v_and_or_b32 v0, v1, s36, v0
	s_nop 0
	v_cvt_pk_bf16_f32 v1, v42, v42
	s_nop 0
	v_lshrrev_b32_e32 v1, 16, v1
	v_cvt_pk_bf16_f32 v2, v43, v43
	v_and_or_b32 v1, v2, s36, v1
	s_waitcnt vmcnt(4)
	s_nop 0
	v_cvt_pk_bf16_f32 v2, v44, v44
	s_nop 0
	v_lshrrev_b32_e32 v2, 16, v2
	v_cvt_pk_bf16_f32 v3, v45, v45
	v_and_or_b32 v2, v3, s36, v2
	s_nop 0
	v_cvt_pk_bf16_f32 v3, v46, v46
	s_nop 0
	v_lshrrev_b32_e32 v3, 16, v3
	v_cvt_pk_bf16_f32 v5, v47, v47
	v_and_or_b32 v3, v5, s36, v3
	ds_write2_b64 v4, v[0:1], v[2:3] offset0:148 offset1:214
	s_waitcnt vmcnt(3)
	s_nop 0
	v_cvt_pk_bf16_f32 v0, v48, v48
	s_nop 0
	v_lshrrev_b32_e32 v0, 16, v0
	v_cvt_pk_bf16_f32 v1, v49, v49
	v_and_or_b32 v0, v1, s36, v0
	s_nop 0
	v_cvt_pk_bf16_f32 v1, v50, v50
	s_nop 0
	v_lshrrev_b32_e32 v1, 16, v1
	v_cvt_pk_bf16_f32 v2, v51, v51
	v_and_or_b32 v1, v2, s36, v1
	s_waitcnt vmcnt(2)
	s_nop 0
	v_cvt_pk_bf16_f32 v2, v52, v52
	s_nop 0
	v_lshrrev_b32_e32 v2, 16, v2
	v_cvt_pk_bf16_f32 v3, v53, v53
	v_and_or_b32 v2, v3, s36, v2
	s_nop 0
	v_cvt_pk_bf16_f32 v3, v54, v54
	s_nop 0
	v_lshrrev_b32_e32 v3, 16, v3
	v_cvt_pk_bf16_f32 v4, v55, v55
	v_and_or_b32 v3, v4, s36, v3
	v_add_u32_e32 v4, 0x1800, v76
	ds_write2_b64 v4, v[0:1], v[2:3] offset0:24 offset1:90
	s_waitcnt vmcnt(1)
	s_nop 0
	v_cvt_pk_bf16_f32 v0, v56, v56
	s_nop 0
	v_lshrrev_b32_e32 v0, 16, v0
	v_cvt_pk_bf16_f32 v1, v57, v57
	v_and_or_b32 v0, v1, s36, v0
	s_nop 0
	v_cvt_pk_bf16_f32 v1, v58, v58
	s_nop 0
	v_lshrrev_b32_e32 v1, 16, v1
	v_cvt_pk_bf16_f32 v2, v59, v59
	v_and_or_b32 v1, v2, s36, v1
	s_waitcnt vmcnt(0)
	s_nop 0
	v_cvt_pk_bf16_f32 v2, v60, v60
	s_nop 0
	v_lshrrev_b32_e32 v2, 16, v2
	v_cvt_pk_bf16_f32 v3, v61, v61
	v_and_or_b32 v2, v3, s36, v2
	s_nop 0
	v_cvt_pk_bf16_f32 v3, v62, v62
	s_nop 0
	v_lshrrev_b32_e32 v3, 16, v3
	v_cvt_pk_bf16_f32 v5, v63, v63
	v_and_or_b32 v3, v5, s36, v3
	ds_write2_b64 v4, v[0:1], v[2:3] offset0:156 offset1:222
	s_waitcnt lgkmcnt(0)
	ds_read_u16 v2, v84
	ds_read_u16 v8, v84 offset:16
	ds_read_u16 v9, v84 offset:32
	ds_read_u16 v10, v84 offset:48
	ds_read_u16 v11, v84 offset:64
	ds_read_u16 v12, v84 offset:80
	ds_read_u16 v13, v84 offset:96
	ds_read_u16 v14, v84 offset:112
	ds_read_u16 v3, v84 offset:132
	ds_read_u16 v15, v84 offset:148
	ds_read_u16 v16, v84 offset:164
	ds_read_u16 v17, v84 offset:180
	ds_read_u16 v18, v84 offset:196
	ds_read_u16 v19, v84 offset:212
	ds_read_u16 v20, v84 offset:228
	ds_read_u16 v21, v84 offset:244
	s_waitcnt lgkmcnt(7)
	v_lshl_or_b32 v2, v3, 16, v2
	ds_read_u16 v3, v84 offset:264
	ds_read_u16 v22, v84 offset:280
	ds_read_u16 v23, v84 offset:296
	ds_read_u16 v24, v84 offset:312
	ds_read_u16 v25, v84 offset:328
	ds_read_u16 v26, v84 offset:344
	ds_read_u16 v27, v84 offset:360
	ds_read_u16 v28, v84 offset:376
	ds_read_u16 v4, v84 offset:396
	ds_read_u16 v29, v84 offset:412
	ds_read_u16 v30, v84 offset:428
	ds_read_u16 v31, v84 offset:444
	ds_read_u16 v32, v84 offset:460
	ds_read_u16 v33, v84 offset:476
	ds_read_u16 v34, v84 offset:492
	ds_read_u16 v35, v84 offset:508
	s_waitcnt lgkmcnt(7)
	v_lshl_or_b32 v3, v4, 16, v3
	ds_read_u16 v4, v84 offset:528
	ds_read_u16 v36, v84 offset:544
	ds_read_u16 v37, v84 offset:560
	ds_read_u16 v38, v84 offset:576
	ds_read_u16 v39, v84 offset:592
	ds_read_u16 v40, v84 offset:608
	ds_read_u16 v41, v84 offset:624
	ds_read_u16 v42, v84 offset:640
	ds_read_u16 v5, v84 offset:660
	ds_read_u16 v43, v84 offset:676
	ds_read_u16 v44, v84 offset:692
	ds_read_u16 v45, v84 offset:708
	ds_read_u16 v46, v84 offset:724
	ds_read_u16 v47, v84 offset:740
	ds_read_u16 v48, v84 offset:756
	ds_read_u16 v49, v84 offset:772
	s_waitcnt lgkmcnt(7)
	v_lshl_or_b32 v4, v5, 16, v4
	ds_read_u16 v5, v84 offset:792
	ds_read_u16 v50, v84 offset:808
	ds_read_u16 v51, v84 offset:824
	ds_read_u16 v52, v84 offset:840
	ds_read_u16 v53, v84 offset:856
	ds_read_u16 v54, v84 offset:872
	ds_read_u16 v55, v84 offset:888
	ds_read_u16 v56, v84 offset:904
	ds_read_u16 v6, v84 offset:924
	ds_read_u16 v57, v84 offset:940
	ds_read_u16 v58, v84 offset:956
	ds_read_u16 v59, v84 offset:972
	ds_read_u16 v60, v84 offset:988
	ds_read_u16 v61, v84 offset:1004
	ds_read_u16 v62, v84 offset:1020
	ds_read_u16 v63, v84 offset:1036
	s_waitcnt lgkmcnt(7)
	v_lshl_or_b32 v5, v6, 16, v5
	v_add_u32_e32 v6, s0, v83
	v_ashrrev_i32_e32 v7, 31, v6
	v_lshl_add_u64 v[0:1], s[38:39], 1, v[64:65]
	v_lshlrev_b64 v[6:7], 10, v[6:7]
	v_lshl_add_u64 v[6:7], v[0:1], 0, v[6:7]
	global_store_dwordx4 v[6:7], v[2:5], off
	v_add_u32_e32 v6, s0, v85
	v_ashrrev_i32_e32 v7, 31, v6
	v_lshlrev_b64 v[6:7], 10, v[6:7]
	v_lshl_or_b32 v2, v15, 16, v8
	v_lshl_or_b32 v3, v29, 16, v22
	v_lshl_or_b32 v4, v43, 16, v36
	s_waitcnt lgkmcnt(6)
	v_lshl_or_b32 v5, v57, 16, v50
	v_lshl_add_u64 v[6:7], v[0:1], 0, v[6:7]
	global_store_dwordx4 v[6:7], v[2:5], off
	v_add_u32_e32 v6, s0, v86
	v_ashrrev_i32_e32 v7, 31, v6
	v_lshlrev_b64 v[6:7], 10, v[6:7]
	v_lshl_or_b32 v2, v16, 16, v9
	v_lshl_or_b32 v3, v30, 16, v23
	v_lshl_or_b32 v4, v44, 16, v37
	s_waitcnt lgkmcnt(5)
	v_lshl_or_b32 v5, v58, 16, v51
	v_lshl_add_u64 v[6:7], v[0:1], 0, v[6:7]
	global_store_dwordx4 v[6:7], v[2:5], off
	v_add_u32_e32 v6, s0, v87
	v_ashrrev_i32_e32 v7, 31, v6
	v_lshlrev_b64 v[6:7], 10, v[6:7]
	v_lshl_or_b32 v2, v17, 16, v10
	v_lshl_or_b32 v3, v31, 16, v24
	v_lshl_or_b32 v4, v45, 16, v38
	s_waitcnt lgkmcnt(4)
	v_lshl_or_b32 v5, v59, 16, v52
	v_lshl_add_u64 v[6:7], v[0:1], 0, v[6:7]
	global_store_dwordx4 v[6:7], v[2:5], off
	v_add_u32_e32 v6, s0, v88
	v_ashrrev_i32_e32 v7, 31, v6
	v_lshlrev_b64 v[6:7], 10, v[6:7]
	v_lshl_or_b32 v2, v18, 16, v11
	v_lshl_or_b32 v3, v32, 16, v25
	v_lshl_or_b32 v4, v46, 16, v39
	s_waitcnt lgkmcnt(3)
	v_lshl_or_b32 v5, v60, 16, v53
	v_lshl_add_u64 v[6:7], v[0:1], 0, v[6:7]
	global_store_dwordx4 v[6:7], v[2:5], off
	v_add_u32_e32 v6, s0, v89
	v_ashrrev_i32_e32 v7, 31, v6
	v_lshlrev_b64 v[6:7], 10, v[6:7]
	v_lshl_or_b32 v2, v19, 16, v12
	v_lshl_or_b32 v3, v33, 16, v26
	v_lshl_or_b32 v4, v47, 16, v40
	s_waitcnt lgkmcnt(2)
	v_lshl_or_b32 v5, v61, 16, v54
	v_lshl_add_u64 v[6:7], v[0:1], 0, v[6:7]
	global_store_dwordx4 v[6:7], v[2:5], off
	v_add_u32_e32 v6, s0, v90
	v_ashrrev_i32_e32 v7, 31, v6
	v_lshlrev_b64 v[6:7], 10, v[6:7]
	v_lshl_or_b32 v2, v20, 16, v13
	v_lshl_or_b32 v3, v34, 16, v27
	v_lshl_or_b32 v4, v48, 16, v41
	s_waitcnt lgkmcnt(1)
	v_lshl_or_b32 v5, v62, 16, v55
	v_lshl_add_u64 v[6:7], v[0:1], 0, v[6:7]
	global_store_dwordx4 v[6:7], v[2:5], off
	v_add_u32_e32 v6, s0, v91
	v_ashrrev_i32_e32 v7, 31, v6
	v_lshlrev_b64 v[6:7], 10, v[6:7]
	v_lshl_or_b32 v2, v21, 16, v14
	v_lshl_or_b32 v3, v35, 16, v28
	v_lshl_or_b32 v4, v49, 16, v42
	s_waitcnt lgkmcnt(0)
	v_lshl_or_b32 v5, v63, 16, v56
	v_lshl_add_u64 v[0:1], v[0:1], 0, v[6:7]
	global_store_dwordx4 v[0:1], v[2:5], off
	s_waitcnt lgkmcnt(0)
	s_mov_b64 s[0:1], 0
.LBB0_1207:
	s_andn2_b64 vcc, exec, s[0:1]
	s_cbranch_vccnz .LBB0_1209
	s_and_b32 s0, s26, 0x7fc0
	s_add_i32 s38, s0, 0xffffb500
	s_and_b32 s0, s22, 0x7c0
	v_or_b32_e32 v1, s0, v80
	v_add_u32_e32 v0, s38, v66
	v_lshlrev_b32_e32 v96, 2, v1
	v_ashrrev_i32_e32 v1, 31, v0
	v_lshl_add_u64 v[2:3], s[4:5], 0, v[96:97]
	v_lshlrev_b64 v[0:1], 13, v[0:1]
	v_lshl_add_u64 v[56:57], v[2:3], 0, v[0:1]
	v_add_co_u32_e32 v4, vcc, 0x8000, v56
	s_mov_b32 s1, 0x18000
	s_nop 0
	v_addc_co_u32_e32 v5, vcc, 0, v57, vcc
	global_load_dwordx4 v[0:3], v[56:57], off
	s_nop 0
	global_load_dwordx4 v[4:7], v[4:5], off
	v_add_co_u32_e32 v8, vcc, s75, v56
	s_movk_i32 s43, 0x2b00
	s_nop 0
	v_addc_co_u32_e32 v9, vcc, 0, v57, vcc
	v_add_co_u32_e32 v12, vcc, s1, v56
	s_mov_b32 s1, 0x40000
	s_nop 0
	v_addc_co_u32_e32 v13, vcc, 0, v57, vcc
	global_load_dwordx4 v[8:11], v[8:9], off
	s_nop 0
	global_load_dwordx4 v[12:15], v[12:13], off
	v_add_co_u32_e32 v16, vcc, 0x20000, v56
	s_waitcnt vmcnt(0)
	s_nop 0
	v_addc_co_u32_e32 v17, vcc, 0, v57, vcc
	v_add_co_u32_e32 v20, vcc, 0x28000, v56
	v_cvt_pk_bf16_f32 v0, v0, v0
	s_nop 0
	v_addc_co_u32_e32 v21, vcc, 0, v57, vcc
	global_load_dwordx4 v[16:19], v[16:17], off
	s_nop 0
	global_load_dwordx4 v[20:23], v[20:21], off
	v_add_co_u32_e32 v24, vcc, 0x30000, v56
	s_nop 0
	s_nop 0
	v_addc_co_u32_e32 v25, vcc, 0, v57, vcc
	v_add_co_u32_e32 v28, vcc, 0x38000, v56
	v_lshrrev_b32_e32 v0, 16, v0
	s_nop 0
	v_addc_co_u32_e32 v29, vcc, 0, v57, vcc
	global_load_dwordx4 v[24:27], v[24:25], off
	s_nop 0
	global_load_dwordx4 v[28:31], v[28:29], off
	v_add_co_u32_e32 v32, vcc, s1, v56
	v_cvt_pk_bf16_f32 v1, v1, v1
	s_nop 0
	v_addc_co_u32_e32 v33, vcc, 0, v57, vcc
	v_add_co_u32_e32 v36, vcc, 0x48000, v56
	v_and_or_b32 v0, v1, s36, v0
	s_nop 0
	v_addc_co_u32_e32 v37, vcc, 0, v57, vcc
	global_load_dwordx4 v[32:35], v[32:33], off
	s_nop 0
	global_load_dwordx4 v[36:39], v[36:37], off
	v_add_co_u32_e32 v40, vcc, 0x50000, v56
	s_nop 0
	s_nop 0
	v_addc_co_u32_e32 v41, vcc, 0, v57, vcc
	v_add_co_u32_e32 v44, vcc, 0x58000, v56
	v_cvt_pk_bf16_f32 v1, v2, v2
	s_nop 0
	v_addc_co_u32_e32 v45, vcc, 0, v57, vcc
	global_load_dwordx4 v[40:43], v[40:41], off
	s_nop 0
	global_load_dwordx4 v[44:47], v[44:45], off
	v_add_co_u32_e32 v48, vcc, 0x60000, v56
	s_nop 0
	s_nop 0
	v_addc_co_u32_e32 v49, vcc, 0, v57, vcc
	v_add_co_u32_e32 v52, vcc, 0x68000, v56
	v_lshrrev_b32_e32 v1, 16, v1
	s_nop 0
	v_addc_co_u32_e32 v53, vcc, 0, v57, vcc
	global_load_dwordx4 v[48:51], v[48:49], off
	s_nop 0
	global_load_dwordx4 v[52:55], v[52:53], off
	v_cvt_pk_bf16_f32 v2, v3, v3
	v_and_or_b32 v1, v2, s36, v1
	s_nop 0
	v_cvt_pk_bf16_f32 v2, v4, v4
	s_nop 0
	v_add_co_u32_e32 v58, vcc, 0x70000, v56
	v_lshrrev_b32_e32 v2, 16, v2
	v_cvt_pk_bf16_f32 v3, v5, v5
	v_addc_co_u32_e32 v59, vcc, 0, v57, vcc
	v_and_or_b32 v2, v3, s36, v2
	s_nop 0
	v_add_co_u32_e32 v60, vcc, 0x78000, v56
	v_cvt_pk_bf16_f32 v3, v6, v6
	s_nop 0
	v_addc_co_u32_e32 v61, vcc, 0, v57, vcc
	v_lshrrev_b32_e32 v3, 16, v3
	v_cvt_pk_bf16_f32 v4, v7, v7
	global_load_dwordx4 v[56:59], v[58:59], off
	s_nop 0
	global_load_dwordx4 v[60:63], v[60:61], off
	v_add_u32_e32 v76, v81, v82
	v_and_or_b32 v3, v4, s36, v3
	ds_write2_b64 v76, v[0:1], v[2:3] offset1:66
	s_nop 0
	v_cvt_pk_bf16_f32 v0, v8, v8
	s_nop 0
	v_lshrrev_b32_e32 v0, 16, v0
	v_cvt_pk_bf16_f32 v1, v9, v9
	v_and_or_b32 v0, v1, s36, v0
	s_nop 0
	v_cvt_pk_bf16_f32 v1, v10, v10
	s_nop 0
	v_lshrrev_b32_e32 v1, 16, v1
	v_cvt_pk_bf16_f32 v2, v11, v11
	v_and_or_b32 v1, v2, s36, v1
	s_nop 0
	v_cvt_pk_bf16_f32 v2, v12, v12
	s_nop 0
	v_lshrrev_b32_e32 v2, 16, v2
	v_cvt_pk_bf16_f32 v3, v13, v13
	v_and_or_b32 v2, v3, s36, v2
	s_nop 0
	v_cvt_pk_bf16_f32 v3, v14, v14
	s_nop 0
	v_lshrrev_b32_e32 v3, 16, v3
	v_cvt_pk_bf16_f32 v4, v15, v15
	v_and_or_b32 v3, v4, s36, v3
	ds_write2_b64 v76, v[0:1], v[2:3] offset0:132 offset1:198
	s_waitcnt vmcnt(11)
	s_nop 0
	v_cvt_pk_bf16_f32 v0, v16, v16
	s_nop 0
	v_lshrrev_b32_e32 v0, 16, v0
	v_cvt_pk_bf16_f32 v1, v17, v17
	v_and_or_b32 v0, v1, s36, v0
	s_nop 0
	v_cvt_pk_bf16_f32 v1, v18, v18
	s_nop 0
	v_lshrrev_b32_e32 v1, 16, v1
	v_cvt_pk_bf16_f32 v2, v19, v19
	v_and_or_b32 v1, v2, s36, v1
	s_waitcnt vmcnt(10)
	s_nop 0
	v_cvt_pk_bf16_f32 v2, v20, v20
	s_nop 0
	v_lshrrev_b32_e32 v2, 16, v2
	v_cvt_pk_bf16_f32 v3, v21, v21
	v_and_or_b32 v2, v3, s36, v2
	s_nop 0
	v_cvt_pk_bf16_f32 v3, v22, v22
	s_nop 0
	v_lshrrev_b32_e32 v3, 16, v3
	v_cvt_pk_bf16_f32 v4, v23, v23
	v_and_or_b32 v3, v4, s36, v3
	v_add_u32_e32 v4, 0x800, v76
	ds_write2_b64 v4, v[0:1], v[2:3] offset0:8 offset1:74
	s_waitcnt vmcnt(9)
	s_nop 0
	v_cvt_pk_bf16_f32 v0, v24, v24
	s_nop 0
	v_lshrrev_b32_e32 v0, 16, v0
	v_cvt_pk_bf16_f32 v1, v25, v25
	v_and_or_b32 v0, v1, s36, v0
	s_nop 0
	v_cvt_pk_bf16_f32 v1, v26, v26
	s_nop 0
	v_lshrrev_b32_e32 v1, 16, v1
	v_cvt_pk_bf16_f32 v2, v27, v27
	v_and_or_b32 v1, v2, s36, v1
	s_waitcnt vmcnt(8)
	s_nop 0
	v_cvt_pk_bf16_f32 v2, v28, v28
	s_nop 0
	v_lshrrev_b32_e32 v2, 16, v2
	v_cvt_pk_bf16_f32 v3, v29, v29
	v_and_or_b32 v2, v3, s36, v2
	s_nop 0
	v_cvt_pk_bf16_f32 v3, v30, v30
	s_nop 0
	v_lshrrev_b32_e32 v3, 16, v3
	v_cvt_pk_bf16_f32 v5, v31, v31
	v_and_or_b32 v3, v5, s36, v3
	ds_write2_b64 v4, v[0:1], v[2:3] offset0:140 offset1:206
	s_waitcnt vmcnt(7)
	s_nop 0
	v_cvt_pk_bf16_f32 v0, v32, v32
	s_nop 0
	v_lshrrev_b32_e32 v0, 16, v0
	v_cvt_pk_bf16_f32 v1, v33, v33
	v_and_or_b32 v0, v1, s36, v0
	s_nop 0
	v_cvt_pk_bf16_f32 v1, v34, v34
	s_nop 0
	v_lshrrev_b32_e32 v1, 16, v1
	v_cvt_pk_bf16_f32 v2, v35, v35
	v_and_or_b32 v1, v2, s36, v1
	s_waitcnt vmcnt(6)
	s_nop 0
	v_cvt_pk_bf16_f32 v2, v36, v36
	s_nop 0
	v_lshrrev_b32_e32 v2, 16, v2
	v_cvt_pk_bf16_f32 v3, v37, v37
	v_and_or_b32 v2, v3, s36, v2
	s_nop 0
	v_cvt_pk_bf16_f32 v3, v38, v38
	s_nop 0
	v_lshrrev_b32_e32 v3, 16, v3
	v_cvt_pk_bf16_f32 v4, v39, v39
	v_and_or_b32 v3, v4, s36, v3
	v_add_u32_e32 v4, 0x1000, v76
	ds_write2_b64 v4, v[0:1], v[2:3] offset0:16 offset1:82
	s_waitcnt vmcnt(5)
	s_nop 0
	v_cvt_pk_bf16_f32 v0, v40, v40
	s_nop 0
	v_lshrrev_b32_e32 v0, 16, v0
	v_cvt_pk_bf16_f32 v1, v41, v41
	v_and_or_b32 v0, v1, s36, v0
	s_nop 0
	v_cvt_pk_bf16_f32 v1, v42, v42
	s_nop 0
	v_lshrrev_b32_e32 v1, 16, v1
	v_cvt_pk_bf16_f32 v2, v43, v43
	v_and_or_b32 v1, v2, s36, v1
	s_waitcnt vmcnt(4)
	s_nop 0
	v_cvt_pk_bf16_f32 v2, v44, v44
	s_nop 0
	v_lshrrev_b32_e32 v2, 16, v2
	v_cvt_pk_bf16_f32 v3, v45, v45
	v_and_or_b32 v2, v3, s36, v2
	s_nop 0
	v_cvt_pk_bf16_f32 v3, v46, v46
	s_nop 0
	v_lshrrev_b32_e32 v3, 16, v3
	v_cvt_pk_bf16_f32 v5, v47, v47
	v_and_or_b32 v3, v5, s36, v3
	ds_write2_b64 v4, v[0:1], v[2:3] offset0:148 offset1:214
	s_waitcnt vmcnt(3)
	s_nop 0
	v_cvt_pk_bf16_f32 v0, v48, v48
	s_nop 0
	v_lshrrev_b32_e32 v0, 16, v0
	v_cvt_pk_bf16_f32 v1, v49, v49
	v_and_or_b32 v0, v1, s36, v0
	s_nop 0
	v_cvt_pk_bf16_f32 v1, v50, v50
	s_nop 0
	v_lshrrev_b32_e32 v1, 16, v1
	v_cvt_pk_bf16_f32 v2, v51, v51
	v_and_or_b32 v1, v2, s36, v1
	s_waitcnt vmcnt(2)
	s_nop 0
	v_cvt_pk_bf16_f32 v2, v52, v52
	s_nop 0
	v_lshrrev_b32_e32 v2, 16, v2
	v_cvt_pk_bf16_f32 v3, v53, v53
	v_and_or_b32 v2, v3, s36, v2
	s_nop 0
	v_cvt_pk_bf16_f32 v3, v54, v54
	s_nop 0
	v_lshrrev_b32_e32 v3, 16, v3
	v_cvt_pk_bf16_f32 v4, v55, v55
	v_and_or_b32 v3, v4, s36, v3
	v_add_u32_e32 v4, 0x1800, v76
	ds_write2_b64 v4, v[0:1], v[2:3] offset0:24 offset1:90
	s_waitcnt vmcnt(1)
	s_nop 0
	v_cvt_pk_bf16_f32 v0, v56, v56
	s_nop 0
	v_lshrrev_b32_e32 v0, 16, v0
	v_cvt_pk_bf16_f32 v1, v57, v57
	v_and_or_b32 v0, v1, s36, v0
	s_nop 0
	v_cvt_pk_bf16_f32 v1, v58, v58
	s_nop 0
	v_lshrrev_b32_e32 v1, 16, v1
	v_cvt_pk_bf16_f32 v2, v59, v59
	v_and_or_b32 v1, v2, s36, v1
	s_waitcnt vmcnt(0)
	s_nop 0
	v_cvt_pk_bf16_f32 v2, v60, v60
	s_nop 0
	v_lshrrev_b32_e32 v2, 16, v2
	v_cvt_pk_bf16_f32 v3, v61, v61
	v_and_or_b32 v2, v3, s36, v2
	s_nop 0
	v_cvt_pk_bf16_f32 v3, v62, v62
	s_nop 0
	v_lshrrev_b32_e32 v3, 16, v3
	v_cvt_pk_bf16_f32 v5, v63, v63
	v_and_or_b32 v3, v5, s36, v3
	ds_write2_b64 v4, v[0:1], v[2:3] offset0:156 offset1:222
	s_waitcnt lgkmcnt(0)
	ds_read_u16 v2, v84
	ds_read_u16 v8, v84 offset:16
	ds_read_u16 v9, v84 offset:32
	ds_read_u16 v10, v84 offset:48
	ds_read_u16 v11, v84 offset:64
	ds_read_u16 v12, v84 offset:80
	ds_read_u16 v13, v84 offset:96
	ds_read_u16 v14, v84 offset:112
	ds_read_u16 v3, v84 offset:132
	ds_read_u16 v15, v84 offset:148
	ds_read_u16 v16, v84 offset:164
	ds_read_u16 v17, v84 offset:180
	ds_read_u16 v18, v84 offset:196
	ds_read_u16 v19, v84 offset:212
	ds_read_u16 v20, v84 offset:228
	ds_read_u16 v21, v84 offset:244
	s_waitcnt lgkmcnt(7)
	v_lshl_or_b32 v2, v3, 16, v2
	ds_read_u16 v3, v84 offset:264
	ds_read_u16 v22, v84 offset:280
	ds_read_u16 v23, v84 offset:296
	ds_read_u16 v24, v84 offset:312
	ds_read_u16 v25, v84 offset:328
	ds_read_u16 v26, v84 offset:344
	ds_read_u16 v27, v84 offset:360
	ds_read_u16 v28, v84 offset:376
	ds_read_u16 v4, v84 offset:396
	ds_read_u16 v29, v84 offset:412
	ds_read_u16 v30, v84 offset:428
	ds_read_u16 v31, v84 offset:444
	ds_read_u16 v32, v84 offset:460
	ds_read_u16 v33, v84 offset:476
	ds_read_u16 v34, v84 offset:492
	ds_read_u16 v35, v84 offset:508
	s_waitcnt lgkmcnt(7)
	v_lshl_or_b32 v3, v4, 16, v3
	ds_read_u16 v4, v84 offset:528
	ds_read_u16 v36, v84 offset:544
	ds_read_u16 v37, v84 offset:560
	ds_read_u16 v38, v84 offset:576
	ds_read_u16 v39, v84 offset:592
	ds_read_u16 v40, v84 offset:608
	ds_read_u16 v41, v84 offset:624
	ds_read_u16 v42, v84 offset:640
	ds_read_u16 v5, v84 offset:660
	ds_read_u16 v43, v84 offset:676
	ds_read_u16 v44, v84 offset:692
	ds_read_u16 v45, v84 offset:708
	ds_read_u16 v46, v84 offset:724
	ds_read_u16 v47, v84 offset:740
	ds_read_u16 v48, v84 offset:756
	ds_read_u16 v49, v84 offset:772
	s_waitcnt lgkmcnt(7)
	v_lshl_or_b32 v4, v5, 16, v4
	ds_read_u16 v5, v84 offset:792
	ds_read_u16 v50, v84 offset:808
	ds_read_u16 v51, v84 offset:824
	ds_read_u16 v52, v84 offset:840
	ds_read_u16 v53, v84 offset:856
	ds_read_u16 v54, v84 offset:872
	ds_read_u16 v55, v84 offset:888
	ds_read_u16 v56, v84 offset:904
	ds_read_u16 v6, v84 offset:924
	ds_read_u16 v57, v84 offset:940
	ds_read_u16 v58, v84 offset:956
	ds_read_u16 v59, v84 offset:972
	ds_read_u16 v60, v84 offset:988
	ds_read_u16 v61, v84 offset:1004
	ds_read_u16 v62, v84 offset:1020
	ds_read_u16 v63, v84 offset:1036
	v_lshl_add_u64 v[0:1], s[38:39], 1, v[68:69]
	s_waitcnt lgkmcnt(7)
	v_lshl_or_b32 v5, v6, 16, v5
	v_add_u32_e32 v6, s0, v83
	s_movk_i32 s1, 0x2b00
	v_mad_i64_i32 v[6:7], s[20:21], v6, s1, v[0:1]
	global_store_dwordx4 v[6:7], v[2:5], off
	v_add_u32_e32 v6, s0, v85
	v_mad_i64_i32 v[6:7], s[20:21], v6, s1, v[0:1]
	v_lshl_or_b32 v2, v15, 16, v8
	v_lshl_or_b32 v3, v29, 16, v22
	v_lshl_or_b32 v4, v43, 16, v36
	s_waitcnt lgkmcnt(6)
	v_lshl_or_b32 v5, v57, 16, v50
	global_store_dwordx4 v[6:7], v[2:5], off
	v_add_u32_e32 v6, s0, v86
	v_mad_i64_i32 v[6:7], s[20:21], v6, s1, v[0:1]
	v_lshl_or_b32 v2, v16, 16, v9
	v_lshl_or_b32 v3, v30, 16, v23
	v_lshl_or_b32 v4, v44, 16, v37
	s_waitcnt lgkmcnt(5)
	v_lshl_or_b32 v5, v58, 16, v51
	global_store_dwordx4 v[6:7], v[2:5], off
	v_add_u32_e32 v6, s0, v87
	v_mad_i64_i32 v[6:7], s[20:21], v6, s1, v[0:1]
	v_lshl_or_b32 v2, v17, 16, v10
	v_lshl_or_b32 v3, v31, 16, v24
	v_lshl_or_b32 v4, v45, 16, v38
	s_waitcnt lgkmcnt(4)
	v_lshl_or_b32 v5, v59, 16, v52
	global_store_dwordx4 v[6:7], v[2:5], off
	v_add_u32_e32 v6, s0, v88
	v_mad_i64_i32 v[6:7], s[20:21], v6, s1, v[0:1]
	v_lshl_or_b32 v2, v18, 16, v11
	v_lshl_or_b32 v3, v32, 16, v25
	v_lshl_or_b32 v4, v46, 16, v39
	s_waitcnt lgkmcnt(3)
	v_lshl_or_b32 v5, v60, 16, v53
	global_store_dwordx4 v[6:7], v[2:5], off
	v_add_u32_e32 v6, s0, v89
	v_mad_i64_i32 v[6:7], s[20:21], v6, s1, v[0:1]
	v_lshl_or_b32 v2, v19, 16, v12
	v_lshl_or_b32 v3, v33, 16, v26
	v_lshl_or_b32 v4, v47, 16, v40
	s_waitcnt lgkmcnt(2)
	v_lshl_or_b32 v5, v61, 16, v54
	global_store_dwordx4 v[6:7], v[2:5], off
	v_add_u32_e32 v6, s0, v90
	v_mad_i64_i32 v[6:7], s[20:21], v6, s1, v[0:1]
	v_lshl_or_b32 v2, v20, 16, v13
	v_lshl_or_b32 v3, v34, 16, v27
	v_lshl_or_b32 v4, v48, 16, v41
	s_waitcnt lgkmcnt(1)
	v_lshl_or_b32 v5, v62, 16, v55
	global_store_dwordx4 v[6:7], v[2:5], off
	v_add_u32_e32 v6, s0, v91
	v_mad_i64_i32 v[0:1], s[0:1], v6, s1, v[0:1]
	v_lshl_or_b32 v2, v21, 16, v14
	v_lshl_or_b32 v3, v35, 16, v28
	v_lshl_or_b32 v4, v49, 16, v42
	s_waitcnt lgkmcnt(0)
	v_lshl_or_b32 v5, v63, 16, v56
	global_store_dwordx4 v[0:1], v[2:5], off
	s_waitcnt lgkmcnt(0)

.LBB0_1213:
	s_waitcnt vmcnt(0)
	s_nop 0
	v_cvt_pk_bf16_f32 v60, v60, v60
	s_nop 0
	v_lshrrev_b32_e32 v60, 16, v60
	v_cvt_pk_bf16_f32 v61, v61, v61
	v_and_or_b32 v60, v61, s36, v60
	s_nop 0
	v_cvt_pk_bf16_f32 v61, v62, v62
	s_nop 0
	v_lshrrev_b32_e32 v61, 16, v61
	v_cvt_pk_bf16_f32 v62, v63, v63
	v_and_or_b32 v61, v62, s36, v61
	v_add_u32_e32 v62, v81, v82
	s_and_b64 vcc, exec, s[0:1]
	ds_write_b64 v62, v[60:61]
	s_cbranch_vccnz .LBB0_1215
	global_load_dword v60, v[76:77], off offset:16
	s_waitcnt vmcnt(0)
	v_pk_mul_f32 v[58:59], v[58:59], v[60:61] op_sel_hi:[1,0]
	v_pk_mul_f32 v[56:57], v[56:57], v[60:61] op_sel_hi:[1,0]
.LBB0_1215:
	s_nop 0
	s_nop 0
	v_cvt_pk_bf16_f32 v56, v56, v56
	s_nop 0
	v_lshrrev_b32_e32 v56, 16, v56
	v_cvt_pk_bf16_f32 v57, v57, v57
	v_and_or_b32 v60, v57, s36, v56
	s_nop 0
	v_cvt_pk_bf16_f32 v56, v58, v58
	s_nop 0
	v_lshrrev_b32_e32 v56, 16, v56
	v_cvt_pk_bf16_f32 v57, v59, v59
	v_and_or_b32 v61, v57, s36, v56
	v_add_u32_e32 v56, v81, v92
	s_and_b64 vcc, exec, s[0:1]
	ds_write_b64 v56, v[60:61]
	s_cbranch_vccnz .LBB0_1217
	global_load_dword v58, v[76:77], off offset:32
	s_waitcnt vmcnt(0)
	v_pk_mul_f32 v[54:55], v[54:55], v[58:59] op_sel_hi:[1,0]
	v_pk_mul_f32 v[52:53], v[52:53], v[58:59] op_sel_hi:[1,0]
.LBB0_1217:
	s_nop 0
	s_nop 0
	v_cvt_pk_bf16_f32 v52, v52, v52
	s_nop 0
	v_lshrrev_b32_e32 v52, 16, v52
	v_cvt_pk_bf16_f32 v53, v53, v53
	v_and_or_b32 v52, v53, s36, v52
	s_nop 0
	v_cvt_pk_bf16_f32 v53, v54, v54
	v_bfe_u32 v54, v55, 16, 1
	v_lshrrev_b32_e32 v53, 16, v53
	v_add3_u32 v54, v55, v54, s48
	v_and_or_b32 v53, v54, s36, v53
	s_and_b64 vcc, exec, s[0:1]
	ds_write_b64 v56, v[52:53] offset:528
	s_cbranch_vccnz .LBB0_1219
	global_load_dword v52, v[76:77], off offset:48
	s_waitcnt vmcnt(0)
	v_pk_mul_f32 v[50:51], v[50:51], v[52:53] op_sel_hi:[1,0]
	v_pk_mul_f32 v[48:49], v[48:49], v[52:53] op_sel_hi:[1,0]
.LBB0_1219:
	s_nop 0
	s_nop 0
	v_cvt_pk_bf16_f32 v48, v48, v48
	s_nop 0
	v_lshrrev_b32_e32 v48, 16, v48
	v_cvt_pk_bf16_f32 v49, v49, v49
	v_and_or_b32 v48, v49, s36, v48
	s_nop 0
	v_cvt_pk_bf16_f32 v49, v50, v50
	v_bfe_u32 v50, v51, 16, 1
	v_lshrrev_b32_e32 v49, 16, v49
	v_add3_u32 v50, v51, v50, s48
	v_and_or_b32 v49, v50, s36, v49
	s_and_b64 vcc, exec, s[0:1]
	ds_write_b64 v56, v[48:49] offset:1056
	s_cbranch_vccnz .LBB0_1221
	global_load_dword v48, v[76:77], off offset:64
	s_waitcnt vmcnt(0)
	v_pk_mul_f32 v[46:47], v[46:47], v[48:49] op_sel_hi:[1,0]
	v_pk_mul_f32 v[44:45], v[44:45], v[48:49] op_sel_hi:[1,0]
.LBB0_1221:
	s_nop 0
	s_nop 0
	v_cvt_pk_bf16_f32 v44, v44, v44
	s_nop 0
	v_lshrrev_b32_e32 v44, 16, v44
	v_cvt_pk_bf16_f32 v45, v45, v45
	v_and_or_b32 v44, v45, s36, v44
	s_nop 0
	v_cvt_pk_bf16_f32 v45, v46, v46
	v_bfe_u32 v46, v47, 16, 1
	v_lshrrev_b32_e32 v45, 16, v45
	v_add3_u32 v46, v47, v46, s48
	v_and_or_b32 v45, v46, s36, v45
	s_and_b64 vcc, exec, s[0:1]
	ds_write_b64 v56, v[44:45] offset:1584
	s_cbranch_vccnz .LBB0_1223
	global_load_dword v44, v[76:77], off offset:80
	s_waitcnt vmcnt(0)
	v_pk_mul_f32 v[42:43], v[42:43], v[44:45] op_sel_hi:[1,0]
	v_pk_mul_f32 v[40:41], v[40:41], v[44:45] op_sel_hi:[1,0]
.LBB0_1223:
	s_nop 0
	s_nop 0
	v_cvt_pk_bf16_f32 v40, v40, v40
	s_nop 0
	v_lshrrev_b32_e32 v40, 16, v40
	v_cvt_pk_bf16_f32 v41, v41, v41
	v_and_or_b32 v40, v41, s36, v40
	s_nop 0
	v_cvt_pk_bf16_f32 v41, v42, v42
	v_bfe_u32 v42, v43, 16, 1
	v_lshrrev_b32_e32 v41, 16, v41
	v_add3_u32 v42, v43, v42, s48
	v_and_or_b32 v41, v42, s36, v41
	s_and_b64 vcc, exec, s[0:1]
	ds_write_b64 v56, v[40:41] offset:2112
	s_cbranch_vccnz .LBB0_1225
	global_load_dword v40, v[76:77], off offset:96
	s_waitcnt vmcnt(0)
	v_pk_mul_f32 v[38:39], v[38:39], v[40:41] op_sel_hi:[1,0]
	v_pk_mul_f32 v[36:37], v[36:37], v[40:41] op_sel_hi:[1,0]
.LBB0_1225:
	s_nop 0
	s_nop 0
	v_cvt_pk_bf16_f32 v36, v36, v36
	s_nop 0
	v_lshrrev_b32_e32 v36, 16, v36
	v_cvt_pk_bf16_f32 v37, v37, v37
	v_and_or_b32 v36, v37, s36, v36
	s_nop 0
	v_cvt_pk_bf16_f32 v37, v38, v38
	v_bfe_u32 v38, v39, 16, 1
	v_lshrrev_b32_e32 v37, 16, v37
	v_add3_u32 v38, v39, v38, s48
	v_and_or_b32 v37, v38, s36, v37
	s_and_b64 vcc, exec, s[0:1]
	ds_write_b64 v56, v[36:37] offset:2640
	s_cbranch_vccnz .LBB0_1227
	global_load_dword v36, v[76:77], off offset:112
	s_waitcnt vmcnt(0)
	v_pk_mul_f32 v[34:35], v[34:35], v[36:37] op_sel_hi:[1,0]
	v_pk_mul_f32 v[32:33], v[32:33], v[36:37] op_sel_hi:[1,0]
.LBB0_1227:
	s_nop 0
	s_nop 0
	v_cvt_pk_bf16_f32 v32, v32, v32
	s_nop 0
	v_lshrrev_b32_e32 v32, 16, v32
	v_cvt_pk_bf16_f32 v33, v33, v33
	v_and_or_b32 v32, v33, s36, v32
	s_nop 0
	v_cvt_pk_bf16_f32 v33, v34, v34
	v_bfe_u32 v34, v35, 16, 1
	v_lshrrev_b32_e32 v33, 16, v33
	v_add3_u32 v34, v35, v34, s48
	v_and_or_b32 v33, v34, s36, v33
	s_and_b64 vcc, exec, s[0:1]
	ds_write_b64 v56, v[32:33] offset:3168
	s_cbranch_vccnz .LBB0_1229
	global_load_dword v32, v[76:77], off offset:128
	s_waitcnt vmcnt(0)
	v_pk_mul_f32 v[30:31], v[30:31], v[32:33] op_sel_hi:[1,0]
	v_pk_mul_f32 v[28:29], v[28:29], v[32:33] op_sel_hi:[1,0]
.LBB0_1229:
	s_nop 0
	s_nop 0
	v_cvt_pk_bf16_f32 v28, v28, v28
	s_nop 0
	v_lshrrev_b32_e32 v28, 16, v28
	v_cvt_pk_bf16_f32 v29, v29, v29
	v_and_or_b32 v28, v29, s36, v28
	s_nop 0
	v_cvt_pk_bf16_f32 v29, v30, v30
	v_bfe_u32 v30, v31, 16, 1
	v_lshrrev_b32_e32 v29, 16, v29
	v_add3_u32 v30, v31, v30, s48
	v_and_or_b32 v29, v30, s36, v29
	s_and_b64 vcc, exec, s[0:1]
	ds_write_b64 v56, v[28:29] offset:3696
	s_cbranch_vccnz .LBB0_1231
	global_load_dword v28, v[76:77], off offset:144
	s_waitcnt vmcnt(0)
	v_pk_mul_f32 v[26:27], v[26:27], v[28:29] op_sel_hi:[1,0]
	v_pk_mul_f32 v[24:25], v[24:25], v[28:29] op_sel_hi:[1,0]
.LBB0_1231:
	s_nop 0
	s_nop 0
	v_cvt_pk_bf16_f32 v24, v24, v24
	s_nop 0
	v_lshrrev_b32_e32 v24, 16, v24
	v_cvt_pk_bf16_f32 v25, v25, v25
	v_and_or_b32 v24, v25, s36, v24
	s_nop 0
	v_cvt_pk_bf16_f32 v25, v26, v26
	v_bfe_u32 v26, v27, 16, 1
	v_lshrrev_b32_e32 v25, 16, v25
	v_add3_u32 v26, v27, v26, s48
	v_and_or_b32 v25, v26, s36, v25
	s_and_b64 vcc, exec, s[0:1]
	ds_write_b64 v56, v[24:25] offset:4224
	s_cbranch_vccnz .LBB0_1233
	global_load_dword v24, v[76:77], off offset:160
	s_waitcnt vmcnt(0)
	v_pk_mul_f32 v[22:23], v[22:23], v[24:25] op_sel_hi:[1,0]
	v_pk_mul_f32 v[20:21], v[20:21], v[24:25] op_sel_hi:[1,0]
.LBB0_1233:
	s_nop 0
	s_nop 0
	v_cvt_pk_bf16_f32 v20, v20, v20
	s_nop 0
	v_lshrrev_b32_e32 v20, 16, v20
	v_cvt_pk_bf16_f32 v21, v21, v21
	v_and_or_b32 v20, v21, s36, v20
	s_nop 0
	v_cvt_pk_bf16_f32 v21, v22, v22
	v_bfe_u32 v22, v23, 16, 1
	v_lshrrev_b32_e32 v21, 16, v21
	v_add3_u32 v22, v23, v22, s48
	v_and_or_b32 v21, v22, s36, v21
	s_and_b64 vcc, exec, s[0:1]
	ds_write_b64 v56, v[20:21] offset:4752
	s_cbranch_vccnz .LBB0_1235
	global_load_dword v20, v[76:77], off offset:176
	s_waitcnt vmcnt(0)
	v_pk_mul_f32 v[18:19], v[18:19], v[20:21] op_sel_hi:[1,0]
	v_pk_mul_f32 v[16:17], v[16:17], v[20:21] op_sel_hi:[1,0]
.LBB0_1235:
	s_nop 0
	s_nop 0
	v_cvt_pk_bf16_f32 v16, v16, v16
	s_nop 0
	v_lshrrev_b32_e32 v16, 16, v16
	v_cvt_pk_bf16_f32 v17, v17, v17
	v_and_or_b32 v16, v17, s36, v16
	s_nop 0
	v_cvt_pk_bf16_f32 v17, v18, v18
	v_bfe_u32 v18, v19, 16, 1
	v_lshrrev_b32_e32 v17, 16, v17
	v_add3_u32 v18, v19, v18, s48
	v_and_or_b32 v17, v18, s36, v17
	s_and_b64 vcc, exec, s[0:1]
	ds_write_b64 v56, v[16:17] offset:5280
	s_cbranch_vccnz .LBB0_1237
	global_load_dword v16, v[76:77], off offset:192
	s_waitcnt vmcnt(0)
	v_pk_mul_f32 v[14:15], v[14:15], v[16:17] op_sel_hi:[1,0]
	v_pk_mul_f32 v[12:13], v[12:13], v[16:17] op_sel_hi:[1,0]
.LBB0_1237:
	s_nop 0
	s_nop 0
	v_cvt_pk_bf16_f32 v12, v12, v12
	s_nop 0
	v_lshrrev_b32_e32 v12, 16, v12
	v_cvt_pk_bf16_f32 v13, v13, v13
	v_and_or_b32 v12, v13, s36, v12
	s_nop 0
	v_cvt_pk_bf16_f32 v13, v14, v14
	v_bfe_u32 v14, v15, 16, 1
	v_lshrrev_b32_e32 v13, 16, v13
	v_add3_u32 v14, v15, v14, s48
	v_and_or_b32 v13, v14, s36, v13
	s_and_b64 vcc, exec, s[0:1]
	ds_write_b64 v56, v[12:13] offset:5808
	s_cbranch_vccnz .LBB0_1239
	global_load_dword v12, v[76:77], off offset:208
	s_waitcnt vmcnt(0)
	v_pk_mul_f32 v[10:11], v[10:11], v[12:13] op_sel_hi:[1,0]
	v_pk_mul_f32 v[8:9], v[8:9], v[12:13] op_sel_hi:[1,0]
.LBB0_1239:
	s_nop 0
	s_nop 0
	v_cvt_pk_bf16_f32 v8, v8, v8
	s_nop 0
	v_lshrrev_b32_e32 v8, 16, v8
	v_cvt_pk_bf16_f32 v9, v9, v9
	v_and_or_b32 v8, v9, s36, v8
	s_nop 0
	v_cvt_pk_bf16_f32 v9, v10, v10
	v_bfe_u32 v10, v11, 16, 1
	v_lshrrev_b32_e32 v9, 16, v9
	v_add3_u32 v10, v11, v10, s48
	v_and_or_b32 v9, v10, s36, v9
	s_and_b64 vcc, exec, s[0:1]
	ds_write_b64 v56, v[8:9] offset:6336
	s_cbranch_vccnz .LBB0_1241
	global_load_dword v8, v[76:77], off offset:224
	s_waitcnt vmcnt(0)
	v_pk_mul_f32 v[6:7], v[6:7], v[8:9] op_sel_hi:[1,0]
	v_pk_mul_f32 v[4:5], v[4:5], v[8:9] op_sel_hi:[1,0]
.LBB0_1241:
	s_nop 0
	s_nop 0
	v_cvt_pk_bf16_f32 v4, v4, v4
	s_nop 0
	v_lshrrev_b32_e32 v4, 16, v4
	v_cvt_pk_bf16_f32 v5, v5, v5
	v_and_or_b32 v4, v5, s36, v4
	s_nop 0
	v_cvt_pk_bf16_f32 v5, v6, v6
	s_nop 0
	v_lshrrev_b32_e32 v5, 16, v5
	v_cvt_pk_bf16_f32 v6, v7, v7
	v_and_or_b32 v5, v6, s36, v5
	s_and_b64 vcc, exec, s[0:1]
	ds_write_b64 v56, v[4:5] offset:6864
	s_cbranch_vccnz .LBB0_1243
	global_load_dword v4, v[76:77], off offset:240
	s_waitcnt vmcnt(0)
	v_pk_mul_f32 v[2:3], v[2:3], v[4:5] op_sel_hi:[1,0]
	v_pk_mul_f32 v[0:1], v[0:1], v[4:5] op_sel_hi:[1,0]
.LBB0_1243:
	s_nop 0
	s_nop 0
	v_cvt_pk_bf16_f32 v0, v0, v0
	s_nop 0
	v_lshrrev_b32_e32 v0, 16, v0
	v_cvt_pk_bf16_f32 v1, v1, v1
	v_and_or_b32 v0, v1, s36, v0
	s_nop 0
	v_cvt_pk_bf16_f32 v1, v2, v2
	s_nop 0
	v_lshrrev_b32_e32 v1, 16, v1
	v_cvt_pk_bf16_f32 v2, v3, v3
	v_and_or_b32 v1, v2, s36, v1
	ds_write_b64 v56, v[0:1] offset:7392
	s_waitcnt lgkmcnt(0)
	ds_read_u16 v0, v84 offset:132
	ds_read_u16 v1, v84
	ds_read_u16 v8, v84 offset:16
	s_lshl_b32 s0, s28, 7
	s_or_b32 s1, s0, 0x80
	s_addk_i32 s1, 0xd500
	s_waitcnt lgkmcnt(1)
	v_lshl_or_b32 v0, v0, 16, v1
	ds_read_u16 v1, v84 offset:264
	ds_read_u16 v2, v84 offset:396
	s_and_b32 s0, s0, 0x3f00
	s_cmpk_lt_u32 s28, 0x56
	s_cselect_b32 s0, s0, s1
	s_and_b32 s1, s21, 64
	s_waitcnt lgkmcnt(0)
	v_lshl_or_b32 v1, v2, 16, v1
	ds_read_u16 v2, v84 offset:528
	ds_read_u16 v3, v84 offset:660
	s_or_b32 s0, s0, s1
	s_and_b32 s1, 0xffff, s20
	s_lshl_b32 s38, s1, 1
	v_lshl_add_u64 v[4:5], v[70:71], 0, s[38:39]
	s_waitcnt lgkmcnt(0)
	v_lshl_or_b32 v2, v3, 16, v2
	ds_read_u16 v3, v84 offset:792
	ds_read_u16 v6, v84 offset:924
	s_waitcnt lgkmcnt(0)
	v_lshl_or_b32 v3, v6, 16, v3
	v_add_u32_e32 v6, s0, v83
	v_ashrrev_i32_e32 v7, 31, v6
	v_lshlrev_b64 v[6:7], 12, v[6:7]
	v_lshl_add_u64 v[6:7], v[4:5], 0, v[6:7]
	global_store_dwordx4 v[6:7], v[0:3], off
	ds_read_u16 v0, v84 offset:148
	ds_read_u16 v1, v84 offset:280
	ds_read_u16 v2, v84 offset:412
	s_waitcnt lgkmcnt(2)
	v_lshl_or_b32 v0, v0, 16, v8
	s_waitcnt lgkmcnt(0)
	v_lshl_or_b32 v1, v2, 16, v1
	ds_read_u16 v2, v84 offset:544
	ds_read_u16 v3, v84 offset:676
	s_waitcnt lgkmcnt(0)
	v_lshl_or_b32 v2, v3, 16, v2
	ds_read_u16 v3, v84 offset:808
	ds_read_u16 v6, v84 offset:940
	s_waitcnt lgkmcnt(0)
	v_lshl_or_b32 v3, v6, 16, v3
	v_add_u32_e32 v6, s0, v85
	v_ashrrev_i32_e32 v7, 31, v6
	v_lshlrev_b64 v[6:7], 12, v[6:7]
	v_lshl_add_u64 v[6:7], v[4:5], 0, v[6:7]
	global_store_dwordx4 v[6:7], v[0:3], off
	ds_read_u16 v0, v84 offset:164
	ds_read_u16 v1, v84 offset:32
	ds_read_u16 v8, v84 offset:48
	s_waitcnt lgkmcnt(1)
	v_lshl_or_b32 v0, v0, 16, v1
	ds_read_u16 v1, v84 offset:296
	ds_read_u16 v2, v84 offset:428
	s_waitcnt lgkmcnt(0)
	v_lshl_or_b32 v1, v2, 16, v1
	ds_read_u16 v2, v84 offset:560
	ds_read_u16 v3, v84 offset:692
	s_waitcnt lgkmcnt(0)
	v_lshl_or_b32 v2, v3, 16, v2
	ds_read_u16 v3, v84 offset:824
	ds_read_u16 v6, v84 offset:956
	s_waitcnt lgkmcnt(0)
	v_lshl_or_b32 v3, v6, 16, v3
	v_add_u32_e32 v6, s0, v86
	v_ashrrev_i32_e32 v7, 31, v6
	v_lshlrev_b64 v[6:7], 12, v[6:7]
	v_lshl_add_u64 v[6:7], v[4:5], 0, v[6:7]
	global_store_dwordx4 v[6:7], v[0:3], off
	ds_read_u16 v0, v84 offset:180
	ds_read_u16 v1, v84 offset:312
	ds_read_u16 v2, v84 offset:444
	s_waitcnt lgkmcnt(2)
	v_lshl_or_b32 v0, v0, 16, v8
	s_waitcnt lgkmcnt(0)
	v_lshl_or_b32 v1, v2, 16, v1
	ds_read_u16 v2, v84 offset:576
	ds_read_u16 v3, v84 offset:708
	s_waitcnt lgkmcnt(0)
	v_lshl_or_b32 v2, v3, 16, v2
	ds_read_u16 v3, v84 offset:840
	ds_read_u16 v6, v84 offset:972
	s_waitcnt lgkmcnt(0)
	v_lshl_or_b32 v3, v6, 16, v3
	v_add_u32_e32 v6, s0, v87
	v_ashrrev_i32_e32 v7, 31, v6
	v_lshlrev_b64 v[6:7], 12, v[6:7]
	v_lshl_add_u64 v[6:7], v[4:5], 0, v[6:7]
	global_store_dwordx4 v[6:7], v[0:3], off
	ds_read_u16 v0, v84 offset:64
	ds_read_u16 v1, v84 offset:196
	s_waitcnt lgkmcnt(0)
	v_lshl_or_b32 v0, v1, 16, v0
	ds_read_u16 v1, v84 offset:328
	ds_read_u16 v2, v84 offset:460
	s_waitcnt lgkmcnt(0)
	v_lshl_or_b32 v1, v2, 16, v1
	ds_read_u16 v2, v84 offset:592
	ds_read_u16 v3, v84 offset:724
	s_waitcnt lgkmcnt(0)
	v_lshl_or_b32 v2, v3, 16, v2
	ds_read_u16 v3, v84 offset:856
	ds_read_u16 v6, v84 offset:988
	s_waitcnt lgkmcnt(0)
	v_lshl_or_b32 v3, v6, 16, v3
	v_add_u32_e32 v6, s0, v88
	v_ashrrev_i32_e32 v7, 31, v6
	v_lshlrev_b64 v[6:7], 12, v[6:7]
	v_lshl_add_u64 v[6:7], v[4:5], 0, v[6:7]
	global_store_dwordx4 v[6:7], v[0:3], off
	ds_read_u16 v0, v84 offset:80
	ds_read_u16 v1, v84 offset:212
	s_waitcnt lgkmcnt(0)
	v_lshl_or_b32 v0, v1, 16, v0
	ds_read_u16 v1, v84 offset:344
	ds_read_u16 v2, v84 offset:476
	s_waitcnt lgkmcnt(0)
	v_lshl_or_b32 v1, v2, 16, v1
	ds_read_u16 v2, v84 offset:608
	ds_read_u16 v3, v84 offset:740
	s_waitcnt lgkmcnt(0)
	v_lshl_or_b32 v2, v3, 16, v2
	ds_read_u16 v3, v84 offset:872
	ds_read_u16 v6, v84 offset:1004
	s_waitcnt lgkmcnt(0)
	v_lshl_or_b32 v3, v6, 16, v3
	v_add_u32_e32 v6, s0, v89
	v_ashrrev_i32_e32 v7, 31, v6
	v_lshlrev_b64 v[6:7], 12, v[6:7]
	v_lshl_add_u64 v[6:7], v[4:5], 0, v[6:7]
	global_store_dwordx4 v[6:7], v[0:3], off
	ds_read_u16 v0, v84 offset:96
	ds_read_u16 v1, v84 offset:228
	s_waitcnt lgkmcnt(0)
	v_lshl_or_b32 v0, v1, 16, v0
	ds_read_u16 v1, v84 offset:360
	ds_read_u16 v2, v84 offset:492
	s_waitcnt lgkmcnt(0)
	v_lshl_or_b32 v1, v2, 16, v1
	ds_read_u16 v2, v84 offset:624
	ds_read_u16 v3, v84 offset:756
	s_waitcnt lgkmcnt(0)
	v_lshl_or_b32 v2, v3, 16, v2
	ds_read_u16 v3, v84 offset:888
	ds_read_u16 v6, v84 offset:1020
	s_waitcnt lgkmcnt(0)
	v_lshl_or_b32 v3, v6, 16, v3
	v_add_u32_e32 v6, s0, v90
	v_ashrrev_i32_e32 v7, 31, v6
	v_lshlrev_b64 v[6:7], 12, v[6:7]
	v_lshl_add_u64 v[6:7], v[4:5], 0, v[6:7]
	global_store_dwordx4 v[6:7], v[0:3], off
	ds_read_u16 v0, v84 offset:112
	ds_read_u16 v1, v84 offset:244
	s_waitcnt lgkmcnt(0)
	v_lshl_or_b32 v0, v1, 16, v0
	ds_read_u16 v1, v84 offset:376
	ds_read_u16 v2, v84 offset:508
	s_waitcnt lgkmcnt(0)
	v_lshl_or_b32 v1, v2, 16, v1
	ds_read_u16 v2, v84 offset:640
	ds_read_u16 v3, v84 offset:772
	s_waitcnt lgkmcnt(0)
	v_lshl_or_b32 v2, v3, 16, v2
	ds_read_u16 v3, v84 offset:904
	ds_read_u16 v6, v84 offset:1036
	s_waitcnt lgkmcnt(0)
	v_lshl_or_b32 v3, v6, 16, v3
	v_add_u32_e32 v6, s0, v91
	v_ashrrev_i32_e32 v7, 31, v6
	v_lshlrev_b64 v[6:7], 12, v[6:7]
	v_lshl_add_u64 v[4:5], v[4:5], 0, v[6:7]
	global_store_dwordx4 v[4:5], v[0:3], off
	s_waitcnt lgkmcnt(0)

.LBB0_1245:
	s_andn2_b64 vcc, exec, s[0:1]
	s_cbranch_vccnz .LBB0_1247
	s_and_b32 s0, s26, 0x1fc0
	s_add_i32 s38, s0, 0xffffe800
	s_and_b32 s0, s22, 0x7c0
	v_or_b32_e32 v1, s0, v80
	v_add_u32_e32 v0, s38, v66
	v_lshlrev_b32_e32 v96, 2, v1
	v_ashrrev_i32_e32 v1, 31, v0
	v_lshl_add_u64 v[2:3], s[14:15], 0, v[96:97]
	v_lshlrev_b64 v[0:1], 13, v[0:1]
	v_lshl_add_u64 v[56:57], v[2:3], 0, v[0:1]
	v_add_co_u32_e32 v4, vcc, 0x8000, v56
	s_mov_b32 s1, 0x18000
	s_nop 0
	v_addc_co_u32_e32 v5, vcc, 0, v57, vcc
	global_load_dwordx4 v[0:3], v[56:57], off
	s_nop 0
	global_load_dwordx4 v[4:7], v[4:5], off
	v_add_co_u32_e32 v8, vcc, s75, v56
	s_waitcnt vmcnt(0)
	s_nop 0
	v_addc_co_u32_e32 v9, vcc, 0, v57, vcc
	v_add_co_u32_e32 v12, vcc, s1, v56
	s_mov_b32 s1, 0x40000
	s_nop 0
	v_addc_co_u32_e32 v13, vcc, 0, v57, vcc
	global_load_dwordx4 v[8:11], v[8:9], off
	s_nop 0
	global_load_dwordx4 v[12:15], v[12:13], off
	v_add_co_u32_e32 v16, vcc, 0x20000, v56
	v_cvt_pk_bf16_f32 v0, v0, v0
	s_nop 0
	v_addc_co_u32_e32 v17, vcc, 0, v57, vcc
	v_add_co_u32_e32 v20, vcc, 0x28000, v56
	s_nop 0
	s_nop 0
	v_addc_co_u32_e32 v21, vcc, 0, v57, vcc
	global_load_dwordx4 v[16:19], v[16:17], off
	s_nop 0
	global_load_dwordx4 v[20:23], v[20:21], off
	v_add_co_u32_e32 v24, vcc, 0x30000, v56
	v_lshrrev_b32_e32 v0, 16, v0
	s_nop 0
	v_addc_co_u32_e32 v25, vcc, 0, v57, vcc
	v_add_co_u32_e32 v28, vcc, 0x38000, v56
	v_cvt_pk_bf16_f32 v1, v1, v1
	s_nop 0
	v_addc_co_u32_e32 v29, vcc, 0, v57, vcc
	global_load_dwordx4 v[24:27], v[24:25], off
	s_nop 0
	global_load_dwordx4 v[28:31], v[28:29], off
	v_add_co_u32_e32 v32, vcc, s1, v56
	v_and_or_b32 v0, v1, s36, v0
	s_nop 0
	v_addc_co_u32_e32 v33, vcc, 0, v57, vcc
	v_add_co_u32_e32 v36, vcc, 0x48000, v56
	s_nop 0
	s_nop 0
	v_addc_co_u32_e32 v37, vcc, 0, v57, vcc
	global_load_dwordx4 v[32:35], v[32:33], off
	s_nop 0
	global_load_dwordx4 v[36:39], v[36:37], off
	v_add_co_u32_e32 v40, vcc, 0x50000, v56
	v_cvt_pk_bf16_f32 v1, v2, v2
	s_nop 0
	v_addc_co_u32_e32 v41, vcc, 0, v57, vcc
	v_add_co_u32_e32 v44, vcc, 0x58000, v56
	s_nop 0
	s_nop 0
	v_addc_co_u32_e32 v45, vcc, 0, v57, vcc
	global_load_dwordx4 v[40:43], v[40:41], off
	s_nop 0
	global_load_dwordx4 v[44:47], v[44:45], off
	v_add_co_u32_e32 v48, vcc, 0x60000, v56
	v_lshrrev_b32_e32 v1, 16, v1
	s_nop 0
	v_addc_co_u32_e32 v49, vcc, 0, v57, vcc
	v_add_co_u32_e32 v52, vcc, 0x68000, v56
	v_cvt_pk_bf16_f32 v2, v3, v3
	s_nop 0
	v_addc_co_u32_e32 v53, vcc, 0, v57, vcc
	global_load_dwordx4 v[48:51], v[48:49], off
	s_nop 0
	global_load_dwordx4 v[52:55], v[52:53], off
	v_and_or_b32 v1, v2, s36, v1
	s_nop 0
	v_cvt_pk_bf16_f32 v2, v4, v4
	s_nop 0
	v_add_co_u32_e32 v58, vcc, 0x70000, v56
	v_lshrrev_b32_e32 v2, 16, v2
	v_cvt_pk_bf16_f32 v3, v5, v5
	v_addc_co_u32_e32 v59, vcc, 0, v57, vcc
	v_and_or_b32 v2, v3, s36, v2
	s_nop 0
	v_add_co_u32_e32 v60, vcc, 0x78000, v56
	v_cvt_pk_bf16_f32 v3, v6, v6
	s_nop 0
	v_addc_co_u32_e32 v61, vcc, 0, v57, vcc
	v_lshrrev_b32_e32 v3, 16, v3
	v_cvt_pk_bf16_f32 v4, v7, v7
	global_load_dwordx4 v[56:59], v[58:59], off
	s_nop 0
	global_load_dwordx4 v[60:63], v[60:61], off
	v_add_u32_e32 v76, v81, v82
	v_and_or_b32 v3, v4, s36, v3
	ds_write2_b64 v76, v[0:1], v[2:3] offset1:66
	s_waitcnt vmcnt(13)
	s_nop 0
	v_cvt_pk_bf16_f32 v0, v8, v8
	s_nop 0
	v_lshrrev_b32_e32 v0, 16, v0
	v_cvt_pk_bf16_f32 v1, v9, v9
	v_and_or_b32 v0, v1, s36, v0
	s_nop 0
	v_cvt_pk_bf16_f32 v1, v10, v10
	s_nop 0
	v_lshrrev_b32_e32 v1, 16, v1
	v_cvt_pk_bf16_f32 v2, v11, v11
	v_and_or_b32 v1, v2, s36, v1
	s_waitcnt vmcnt(12)
	s_nop 0
	v_cvt_pk_bf16_f32 v2, v12, v12
	s_nop 0
	v_lshrrev_b32_e32 v2, 16, v2
	v_cvt_pk_bf16_f32 v3, v13, v13
	v_and_or_b32 v2, v3, s36, v2
	s_nop 0
	v_cvt_pk_bf16_f32 v3, v14, v14
	s_nop 0
	v_lshrrev_b32_e32 v3, 16, v3
	v_cvt_pk_bf16_f32 v4, v15, v15
	v_and_or_b32 v3, v4, s36, v3
	ds_write2_b64 v76, v[0:1], v[2:3] offset0:132 offset1:198
	s_waitcnt vmcnt(11)
	s_nop 0
	v_cvt_pk_bf16_f32 v0, v16, v16
	s_nop 0
	v_lshrrev_b32_e32 v0, 16, v0
	v_cvt_pk_bf16_f32 v1, v17, v17
	v_and_or_b32 v0, v1, s36, v0
	s_nop 0
	v_cvt_pk_bf16_f32 v1, v18, v18
	s_nop 0
	v_lshrrev_b32_e32 v1, 16, v1
	v_cvt_pk_bf16_f32 v2, v19, v19
	v_and_or_b32 v1, v2, s36, v1
	s_waitcnt vmcnt(10)
	s_nop 0
	v_cvt_pk_bf16_f32 v2, v20, v20
	s_nop 0
	v_lshrrev_b32_e32 v2, 16, v2
	v_cvt_pk_bf16_f32 v3, v21, v21
	v_and_or_b32 v2, v3, s36, v2
	s_nop 0
	v_cvt_pk_bf16_f32 v3, v22, v22
	s_nop 0
	v_lshrrev_b32_e32 v3, 16, v3
	v_cvt_pk_bf16_f32 v4, v23, v23
	v_and_or_b32 v3, v4, s36, v3
	v_add_u32_e32 v4, 0x800, v76
	ds_write2_b64 v4, v[0:1], v[2:3] offset0:8 offset1:74
	s_waitcnt vmcnt(9)
	s_nop 0
	v_cvt_pk_bf16_f32 v0, v24, v24
	s_nop 0
	v_lshrrev_b32_e32 v0, 16, v0
	v_cvt_pk_bf16_f32 v1, v25, v25
	v_and_or_b32 v0, v1, s36, v0
	s_nop 0
	v_cvt_pk_bf16_f32 v1, v26, v26
	s_nop 0
	v_lshrrev_b32_e32 v1, 16, v1
	v_cvt_pk_bf16_f32 v2, v27, v27
	v_and_or_b32 v1, v2, s36, v1
	s_waitcnt vmcnt(8)
	s_nop 0
	v_cvt_pk_bf16_f32 v2, v28, v28
	s_nop 0
	v_lshrrev_b32_e32 v2, 16, v2
	v_cvt_pk_bf16_f32 v3, v29, v29
	v_and_or_b32 v2, v3, s36, v2
	s_nop 0
	v_cvt_pk_bf16_f32 v3, v30, v30
	s_nop 0
	v_lshrrev_b32_e32 v3, 16, v3
	v_cvt_pk_bf16_f32 v5, v31, v31
	v_and_or_b32 v3, v5, s36, v3
	ds_write2_b64 v4, v[0:1], v[2:3] offset0:140 offset1:206
	s_waitcnt vmcnt(7)
	s_nop 0
	v_cvt_pk_bf16_f32 v0, v32, v32
	s_nop 0
	v_lshrrev_b32_e32 v0, 16, v0
	v_cvt_pk_bf16_f32 v1, v33, v33
	v_and_or_b32 v0, v1, s36, v0
	s_nop 0
	v_cvt_pk_bf16_f32 v1, v34, v34
	s_nop 0
	v_lshrrev_b32_e32 v1, 16, v1
	v_cvt_pk_bf16_f32 v2, v35, v35
	v_and_or_b32 v1, v2, s36, v1
	s_waitcnt vmcnt(6)
	s_nop 0
	v_cvt_pk_bf16_f32 v2, v36, v36
	s_nop 0
	v_lshrrev_b32_e32 v2, 16, v2
	v_cvt_pk_bf16_f32 v3, v37, v37
	v_and_or_b32 v2, v3, s36, v2
	s_nop 0
	v_cvt_pk_bf16_f32 v3, v38, v38
	s_nop 0
	v_lshrrev_b32_e32 v3, 16, v3
	v_cvt_pk_bf16_f32 v4, v39, v39
	v_and_or_b32 v3, v4, s36, v3
	v_add_u32_e32 v4, 0x1000, v76
	ds_write2_b64 v4, v[0:1], v[2:3] offset0:16 offset1:82
	s_waitcnt vmcnt(5)
	s_nop 0
	v_cvt_pk_bf16_f32 v0, v40, v40
	s_nop 0
	v_lshrrev_b32_e32 v0, 16, v0
	v_cvt_pk_bf16_f32 v1, v41, v41
	v_and_or_b32 v0, v1, s36, v0
	s_nop 0
	v_cvt_pk_bf16_f32 v1, v42, v42
	s_nop 0
	v_lshrrev_b32_e32 v1, 16, v1
	v_cvt_pk_bf16_f32 v2, v43, v43
	v_and_or_b32 v1, v2, s36, v1
	s_waitcnt vmcnt(4)
	s_nop 0
	v_cvt_pk_bf16_f32 v2, v44, v44
	s_nop 0
	v_lshrrev_b32_e32 v2, 16, v2
	v_cvt_pk_bf16_f32 v3, v45, v45
	v_and_or_b32 v2, v3, s36, v2
	s_nop 0
	v_cvt_pk_bf16_f32 v3, v46, v46
	s_nop 0
	v_lshrrev_b32_e32 v3, 16, v3
	v_cvt_pk_bf16_f32 v5, v47, v47
	v_and_or_b32 v3, v5, s36, v3
	ds_write2_b64 v4, v[0:1], v[2:3] offset0:148 offset1:214
	s_waitcnt vmcnt(3)
	s_nop 0
	v_cvt_pk_bf16_f32 v0, v48, v48
	s_nop 0
	v_lshrrev_b32_e32 v0, 16, v0
	v_cvt_pk_bf16_f32 v1, v49, v49
	v_and_or_b32 v0, v1, s36, v0
	s_nop 0
	v_cvt_pk_bf16_f32 v1, v50, v50
	s_nop 0
	v_lshrrev_b32_e32 v1, 16, v1
	v_cvt_pk_bf16_f32 v2, v51, v51
	v_and_or_b32 v1, v2, s36, v1
	s_waitcnt vmcnt(2)
	s_nop 0
	v_cvt_pk_bf16_f32 v2, v52, v52
	s_nop 0
	v_lshrrev_b32_e32 v2, 16, v2
	v_cvt_pk_bf16_f32 v3, v53, v53
	v_and_or_b32 v2, v3, s36, v2
	s_nop 0
	v_cvt_pk_bf16_f32 v3, v54, v54
	s_nop 0
	v_lshrrev_b32_e32 v3, 16, v3
	v_cvt_pk_bf16_f32 v4, v55, v55
	v_and_or_b32 v3, v4, s36, v3
	v_add_u32_e32 v4, 0x1800, v76
	ds_write2_b64 v4, v[0:1], v[2:3] offset0:24 offset1:90
	s_waitcnt vmcnt(1)
	s_nop 0
	v_cvt_pk_bf16_f32 v0, v56, v56
	s_nop 0
	v_lshrrev_b32_e32 v0, 16, v0
	v_cvt_pk_bf16_f32 v1, v57, v57
	v_and_or_b32 v0, v1, s36, v0
	s_nop 0
	v_cvt_pk_bf16_f32 v1, v58, v58
	s_nop 0
	v_lshrrev_b32_e32 v1, 16, v1
	v_cvt_pk_bf16_f32 v2, v59, v59
	v_and_or_b32 v1, v2, s36, v1
	s_waitcnt vmcnt(0)
	s_nop 0
	v_cvt_pk_bf16_f32 v2, v60, v60
	s_nop 0
	v_lshrrev_b32_e32 v2, 16, v2
	v_cvt_pk_bf16_f32 v3, v61, v61
	v_and_or_b32 v2, v3, s36, v2
	s_nop 0
	v_cvt_pk_bf16_f32 v3, v62, v62
	s_nop 0
	v_lshrrev_b32_e32 v3, 16, v3
	v_cvt_pk_bf16_f32 v5, v63, v63
	v_and_or_b32 v3, v5, s36, v3
	ds_write2_b64 v4, v[0:1], v[2:3] offset0:156 offset1:222
	s_waitcnt lgkmcnt(0)
	ds_read_u16 v2, v84
	ds_read_u16 v8, v84 offset:16
	ds_read_u16 v9, v84 offset:32
	ds_read_u16 v10, v84 offset:48
	ds_read_u16 v11, v84 offset:64
	ds_read_u16 v12, v84 offset:80
	ds_read_u16 v13, v84 offset:96
	ds_read_u16 v14, v84 offset:112
	ds_read_u16 v3, v84 offset:132
	ds_read_u16 v15, v84 offset:148
	ds_read_u16 v16, v84 offset:164
	ds_read_u16 v17, v84 offset:180
	ds_read_u16 v18, v84 offset:196
	ds_read_u16 v19, v84 offset:212
	ds_read_u16 v20, v84 offset:228
	ds_read_u16 v21, v84 offset:244
	s_waitcnt lgkmcnt(7)
	v_lshl_or_b32 v2, v3, 16, v2
	ds_read_u16 v3, v84 offset:264
	ds_read_u16 v22, v84 offset:280
	ds_read_u16 v23, v84 offset:296
	ds_read_u16 v24, v84 offset:312
	ds_read_u16 v25, v84 offset:328
	ds_read_u16 v26, v84 offset:344
	ds_read_u16 v27, v84 offset:360
	ds_read_u16 v28, v84 offset:376
	ds_read_u16 v4, v84 offset:396
	ds_read_u16 v29, v84 offset:412
	ds_read_u16 v30, v84 offset:428
	ds_read_u16 v31, v84 offset:444
	ds_read_u16 v32, v84 offset:460
	ds_read_u16 v33, v84 offset:476
	ds_read_u16 v34, v84 offset:492
	ds_read_u16 v35, v84 offset:508
	s_waitcnt lgkmcnt(7)
	v_lshl_or_b32 v3, v4, 16, v3
	ds_read_u16 v4, v84 offset:528
	ds_read_u16 v36, v84 offset:544
	ds_read_u16 v37, v84 offset:560
	ds_read_u16 v38, v84 offset:576
	ds_read_u16 v39, v84 offset:592
	ds_read_u16 v40, v84 offset:608
	ds_read_u16 v41, v84 offset:624
	ds_read_u16 v42, v84 offset:640
	ds_read_u16 v5, v84 offset:660
	ds_read_u16 v43, v84 offset:676
	ds_read_u16 v44, v84 offset:692
	ds_read_u16 v45, v84 offset:708
	ds_read_u16 v46, v84 offset:724
	ds_read_u16 v47, v84 offset:740
	ds_read_u16 v48, v84 offset:756
	ds_read_u16 v49, v84 offset:772
	s_waitcnt lgkmcnt(7)
	v_lshl_or_b32 v4, v5, 16, v4
	ds_read_u16 v5, v84 offset:792
	ds_read_u16 v50, v84 offset:808
	ds_read_u16 v51, v84 offset:824
	ds_read_u16 v52, v84 offset:840
	ds_read_u16 v53, v84 offset:856
	ds_read_u16 v54, v84 offset:872
	ds_read_u16 v55, v84 offset:888
	ds_read_u16 v56, v84 offset:904
	ds_read_u16 v6, v84 offset:924
	ds_read_u16 v57, v84 offset:940
	ds_read_u16 v58, v84 offset:956
	ds_read_u16 v59, v84 offset:972
	ds_read_u16 v60, v84 offset:988
	ds_read_u16 v61, v84 offset:1004
	ds_read_u16 v62, v84 offset:1020
	ds_read_u16 v63, v84 offset:1036
	s_waitcnt lgkmcnt(7)
	v_lshl_or_b32 v5, v6, 16, v5
	v_add_u32_e32 v6, s0, v83
	v_ashrrev_i32_e32 v7, 31, v6
	v_lshl_add_u64 v[0:1], s[38:39], 1, v[72:73]
	v_lshlrev_b64 v[6:7], 12, v[6:7]
	v_lshl_add_u64 v[6:7], v[0:1], 0, v[6:7]
	global_store_dwordx4 v[6:7], v[2:5], off
	v_add_u32_e32 v6, s0, v85
	v_ashrrev_i32_e32 v7, 31, v6
	v_lshlrev_b64 v[6:7], 12, v[6:7]
	v_lshl_or_b32 v2, v15, 16, v8
	v_lshl_or_b32 v3, v29, 16, v22
	v_lshl_or_b32 v4, v43, 16, v36
	s_waitcnt lgkmcnt(6)
	v_lshl_or_b32 v5, v57, 16, v50
	v_lshl_add_u64 v[6:7], v[0:1], 0, v[6:7]
	global_store_dwordx4 v[6:7], v[2:5], off
	v_add_u32_e32 v6, s0, v86
	v_ashrrev_i32_e32 v7, 31, v6
	v_lshlrev_b64 v[6:7], 12, v[6:7]
	v_lshl_or_b32 v2, v16, 16, v9
	v_lshl_or_b32 v3, v30, 16, v23
	v_lshl_or_b32 v4, v44, 16, v37
	s_waitcnt lgkmcnt(5)
	v_lshl_or_b32 v5, v58, 16, v51
	v_lshl_add_u64 v[6:7], v[0:1], 0, v[6:7]
	global_store_dwordx4 v[6:7], v[2:5], off
	v_add_u32_e32 v6, s0, v87
	v_ashrrev_i32_e32 v7, 31, v6
	v_lshlrev_b64 v[6:7], 12, v[6:7]
	v_lshl_or_b32 v2, v17, 16, v10
	v_lshl_or_b32 v3, v31, 16, v24
	v_lshl_or_b32 v4, v45, 16, v38
	s_waitcnt lgkmcnt(4)
	v_lshl_or_b32 v5, v59, 16, v52
	v_lshl_add_u64 v[6:7], v[0:1], 0, v[6:7]
	global_store_dwordx4 v[6:7], v[2:5], off
	v_add_u32_e32 v6, s0, v88
	v_ashrrev_i32_e32 v7, 31, v6
	v_lshlrev_b64 v[6:7], 12, v[6:7]
	v_lshl_or_b32 v2, v18, 16, v11
	v_lshl_or_b32 v3, v32, 16, v25
	v_lshl_or_b32 v4, v46, 16, v39
	s_waitcnt lgkmcnt(3)
	v_lshl_or_b32 v5, v60, 16, v53
	v_lshl_add_u64 v[6:7], v[0:1], 0, v[6:7]
	global_store_dwordx4 v[6:7], v[2:5], off
	v_add_u32_e32 v6, s0, v89
	v_ashrrev_i32_e32 v7, 31, v6
	v_lshlrev_b64 v[6:7], 12, v[6:7]
	v_lshl_or_b32 v2, v19, 16, v12
	v_lshl_or_b32 v3, v33, 16, v26
	v_lshl_or_b32 v4, v47, 16, v40
	s_waitcnt lgkmcnt(2)
	v_lshl_or_b32 v5, v61, 16, v54
	v_lshl_add_u64 v[6:7], v[0:1], 0, v[6:7]
	global_store_dwordx4 v[6:7], v[2:5], off
	v_add_u32_e32 v6, s0, v90
	v_ashrrev_i32_e32 v7, 31, v6
	v_lshlrev_b64 v[6:7], 12, v[6:7]
	v_lshl_or_b32 v2, v20, 16, v13
	v_lshl_or_b32 v3, v34, 16, v27
	v_lshl_or_b32 v4, v48, 16, v41
	s_waitcnt lgkmcnt(1)
	v_lshl_or_b32 v5, v62, 16, v55
	v_lshl_add_u64 v[6:7], v[0:1], 0, v[6:7]
	global_store_dwordx4 v[6:7], v[2:5], off
	v_add_u32_e32 v6, s0, v91
	v_ashrrev_i32_e32 v7, 31, v6
	v_lshlrev_b64 v[6:7], 12, v[6:7]
	v_lshl_or_b32 v2, v21, 16, v14
	v_lshl_or_b32 v3, v35, 16, v28
	v_lshl_or_b32 v4, v49, 16, v42
	s_waitcnt lgkmcnt(0)
	v_lshl_or_b32 v5, v63, 16, v56
	v_lshl_add_u64 v[0:1], v[0:1], 0, v[6:7]
	global_store_dwordx4 v[0:1], v[2:5], off
	s_waitcnt lgkmcnt(0)

.LBB0_1283:
	s_nop 0
	s_nop 0
	v_cvt_pk_bf16_f32 v60, v60, v60
	s_nop 0
	v_lshrrev_b32_e32 v60, 16, v60
	v_cvt_pk_bf16_f32 v61, v61, v61
	v_and_or_b32 v60, v61, s36, v60
	s_nop 0
	v_cvt_pk_bf16_f32 v61, v62, v62
	s_nop 0
	v_lshrrev_b32_e32 v61, 16, v61
	v_cvt_pk_bf16_f32 v62, v63, v63
	v_and_or_b32 v61, v62, s36, v61
	v_add_u32_e32 v62, v81, v82
	s_and_b64 vcc, exec, s[0:1]
	ds_write_b64 v62, v[60:61]
	s_cbranch_vccnz .LBB0_1285
	s_ashr_i32 s21, s20, 31
	v_lshl_add_u64 v[60:61], s[20:21], 0, v[66:67]
	v_lshl_add_u64 v[60:61], v[60:61], 2, s[18:19]
	global_load_dword v60, v[60:61], off offset:16
	s_waitcnt vmcnt(0)
	v_pk_mul_f32 v[58:59], v[58:59], v[60:61] op_sel_hi:[1,0]
	v_pk_mul_f32 v[56:57], v[56:57], v[60:61] op_sel_hi:[1,0]
.LBB0_1285:
	s_nop 0
	s_nop 0
	v_cvt_pk_bf16_f32 v56, v56, v56
	s_nop 0
	v_lshrrev_b32_e32 v56, 16, v56
	v_cvt_pk_bf16_f32 v57, v57, v57
	v_and_or_b32 v60, v57, s36, v56
	s_nop 0
	v_cvt_pk_bf16_f32 v56, v58, v58
	s_nop 0
	v_lshrrev_b32_e32 v56, 16, v56
	v_cvt_pk_bf16_f32 v57, v59, v59
	v_and_or_b32 v61, v57, s36, v56
	v_add_u32_e32 v56, v81, v92
	s_and_b64 vcc, exec, s[0:1]
	ds_write_b64 v56, v[60:61]
	s_cbranch_vccnz .LBB0_1287
	s_ashr_i32 s21, s20, 31
	v_lshl_add_u64 v[58:59], s[20:21], 0, v[66:67]
	v_lshl_add_u64 v[58:59], v[58:59], 2, s[18:19]
	global_load_dword v58, v[58:59], off offset:32
	s_waitcnt vmcnt(0)
	v_pk_mul_f32 v[54:55], v[54:55], v[58:59] op_sel_hi:[1,0]
	v_pk_mul_f32 v[52:53], v[52:53], v[58:59] op_sel_hi:[1,0]
.LBB0_1287:
	s_nop 0
	s_nop 0
	v_cvt_pk_bf16_f32 v52, v52, v52
	s_nop 0
	v_lshrrev_b32_e32 v52, 16, v52
	v_cvt_pk_bf16_f32 v53, v53, v53
	v_and_or_b32 v52, v53, s36, v52
	s_nop 0
	v_cvt_pk_bf16_f32 v53, v54, v54
	v_bfe_u32 v54, v55, 16, 1
	v_lshrrev_b32_e32 v53, 16, v53
	v_add3_u32 v54, v55, v54, s48
	v_and_or_b32 v53, v54, s36, v53
	s_and_b64 vcc, exec, s[0:1]
	ds_write_b64 v56, v[52:53] offset:528
	s_cbranch_vccnz .LBB0_1289
	s_ashr_i32 s21, s20, 31
	v_lshl_add_u64 v[52:53], s[20:21], 0, v[66:67]
	v_lshl_add_u64 v[52:53], v[52:53], 2, s[18:19]
	global_load_dword v52, v[52:53], off offset:48
	s_waitcnt vmcnt(0)
	v_pk_mul_f32 v[50:51], v[50:51], v[52:53] op_sel_hi:[1,0]
	v_pk_mul_f32 v[48:49], v[48:49], v[52:53] op_sel_hi:[1,0]
.LBB0_1289:
	s_nop 0
	s_nop 0
	v_cvt_pk_bf16_f32 v48, v48, v48
	s_nop 0
	v_lshrrev_b32_e32 v48, 16, v48
	v_cvt_pk_bf16_f32 v49, v49, v49
	v_and_or_b32 v48, v49, s36, v48
	s_nop 0
	v_cvt_pk_bf16_f32 v49, v50, v50
	v_bfe_u32 v50, v51, 16, 1
	v_lshrrev_b32_e32 v49, 16, v49
	v_add3_u32 v50, v51, v50, s48
	v_and_or_b32 v49, v50, s36, v49
	s_and_b64 vcc, exec, s[0:1]
	ds_write_b64 v56, v[48:49] offset:1056
	s_cbranch_vccnz .LBB0_1291
	s_ashr_i32 s21, s20, 31
	v_lshl_add_u64 v[48:49], s[20:21], 0, v[66:67]
	v_lshl_add_u64 v[48:49], v[48:49], 2, s[18:19]
	global_load_dword v48, v[48:49], off offset:64
	s_waitcnt vmcnt(0)
	v_pk_mul_f32 v[46:47], v[46:47], v[48:49] op_sel_hi:[1,0]
	v_pk_mul_f32 v[44:45], v[44:45], v[48:49] op_sel_hi:[1,0]
.LBB0_1291:
	s_nop 0
	s_nop 0
	v_cvt_pk_bf16_f32 v44, v44, v44
	s_nop 0
	v_lshrrev_b32_e32 v44, 16, v44
	v_cvt_pk_bf16_f32 v45, v45, v45
	v_and_or_b32 v44, v45, s36, v44
	s_nop 0
	v_cvt_pk_bf16_f32 v45, v46, v46
	v_bfe_u32 v46, v47, 16, 1
	v_lshrrev_b32_e32 v45, 16, v45
	v_add3_u32 v46, v47, v46, s48
	v_and_or_b32 v45, v46, s36, v45
	s_and_b64 vcc, exec, s[0:1]
	ds_write_b64 v56, v[44:45] offset:1584
	s_cbranch_vccnz .LBB0_1293
	s_ashr_i32 s21, s20, 31
	v_lshl_add_u64 v[44:45], s[20:21], 0, v[66:67]
	v_lshl_add_u64 v[44:45], v[44:45], 2, s[18:19]
	global_load_dword v44, v[44:45], off offset:80
	s_waitcnt vmcnt(0)
	v_pk_mul_f32 v[42:43], v[42:43], v[44:45] op_sel_hi:[1,0]
	v_pk_mul_f32 v[40:41], v[40:41], v[44:45] op_sel_hi:[1,0]
.LBB0_1293:
	s_nop 0
	s_nop 0
	v_cvt_pk_bf16_f32 v40, v40, v40
	s_nop 0
	v_lshrrev_b32_e32 v40, 16, v40
	v_cvt_pk_bf16_f32 v41, v41, v41
	v_and_or_b32 v40, v41, s36, v40
	s_nop 0
	v_cvt_pk_bf16_f32 v41, v42, v42
	v_bfe_u32 v42, v43, 16, 1
	v_lshrrev_b32_e32 v41, 16, v41
	v_add3_u32 v42, v43, v42, s48
	v_and_or_b32 v41, v42, s36, v41
	s_and_b64 vcc, exec, s[0:1]
	ds_write_b64 v56, v[40:41] offset:2112
	s_cbranch_vccnz .LBB0_1295
	s_ashr_i32 s21, s20, 31
	v_lshl_add_u64 v[40:41], s[20:21], 0, v[66:67]
	v_lshl_add_u64 v[40:41], v[40:41], 2, s[18:19]
	global_load_dword v40, v[40:41], off offset:96
	s_waitcnt vmcnt(0)
	v_pk_mul_f32 v[38:39], v[38:39], v[40:41] op_sel_hi:[1,0]
	v_pk_mul_f32 v[36:37], v[36:37], v[40:41] op_sel_hi:[1,0]
.LBB0_1295:
	s_nop 0
	s_nop 0
	v_cvt_pk_bf16_f32 v36, v36, v36
	s_nop 0
	v_lshrrev_b32_e32 v36, 16, v36
	v_cvt_pk_bf16_f32 v37, v37, v37
	v_and_or_b32 v36, v37, s36, v36
	s_nop 0
	v_cvt_pk_bf16_f32 v37, v38, v38
	v_bfe_u32 v38, v39, 16, 1
	v_lshrrev_b32_e32 v37, 16, v37
	v_add3_u32 v38, v39, v38, s48
	v_and_or_b32 v37, v38, s36, v37
	s_and_b64 vcc, exec, s[0:1]
	ds_write_b64 v56, v[36:37] offset:2640
	s_cbranch_vccnz .LBB0_1297
	s_ashr_i32 s21, s20, 31
	v_lshl_add_u64 v[36:37], s[20:21], 0, v[66:67]
	v_lshl_add_u64 v[36:37], v[36:37], 2, s[18:19]
	global_load_dword v36, v[36:37], off offset:112
	s_waitcnt vmcnt(0)
	v_pk_mul_f32 v[34:35], v[34:35], v[36:37] op_sel_hi:[1,0]
	v_pk_mul_f32 v[32:33], v[32:33], v[36:37] op_sel_hi:[1,0]
.LBB0_1297:
	s_nop 0
	s_nop 0
	v_cvt_pk_bf16_f32 v32, v32, v32
	s_nop 0
	v_lshrrev_b32_e32 v32, 16, v32
	v_cvt_pk_bf16_f32 v33, v33, v33
	v_and_or_b32 v32, v33, s36, v32
	s_nop 0
	v_cvt_pk_bf16_f32 v33, v34, v34
	v_bfe_u32 v34, v35, 16, 1
	v_lshrrev_b32_e32 v33, 16, v33
	v_add3_u32 v34, v35, v34, s48
	v_and_or_b32 v33, v34, s36, v33
	s_and_b64 vcc, exec, s[0:1]
	ds_write_b64 v56, v[32:33] offset:3168
	s_cbranch_vccnz .LBB0_1299
	s_ashr_i32 s21, s20, 31
	v_lshl_add_u64 v[32:33], s[20:21], 0, v[66:67]
	v_lshl_add_u64 v[32:33], v[32:33], 2, s[18:19]
	global_load_dword v32, v[32:33], off offset:128
	s_waitcnt vmcnt(0)
	v_pk_mul_f32 v[30:31], v[30:31], v[32:33] op_sel_hi:[1,0]
	v_pk_mul_f32 v[28:29], v[28:29], v[32:33] op_sel_hi:[1,0]
.LBB0_1299:
	s_nop 0
	s_nop 0
	v_cvt_pk_bf16_f32 v28, v28, v28
	s_nop 0
	v_lshrrev_b32_e32 v28, 16, v28
	v_cvt_pk_bf16_f32 v29, v29, v29
	v_and_or_b32 v28, v29, s36, v28
	s_nop 0
	v_cvt_pk_bf16_f32 v29, v30, v30
	v_bfe_u32 v30, v31, 16, 1
	v_lshrrev_b32_e32 v29, 16, v29
	v_add3_u32 v30, v31, v30, s48
	v_and_or_b32 v29, v30, s36, v29
	s_and_b64 vcc, exec, s[0:1]
	ds_write_b64 v56, v[28:29] offset:3696
	s_cbranch_vccnz .LBB0_1301
	s_ashr_i32 s21, s20, 31
	v_lshl_add_u64 v[28:29], s[20:21], 0, v[66:67]
	v_lshl_add_u64 v[28:29], v[28:29], 2, s[18:19]
	global_load_dword v28, v[28:29], off offset:144
	s_waitcnt vmcnt(0)
	v_pk_mul_f32 v[26:27], v[26:27], v[28:29] op_sel_hi:[1,0]
	v_pk_mul_f32 v[24:25], v[24:25], v[28:29] op_sel_hi:[1,0]
.LBB0_1301:
	s_nop 0
	s_nop 0
	v_cvt_pk_bf16_f32 v24, v24, v24
	s_nop 0
	v_lshrrev_b32_e32 v24, 16, v24
	v_cvt_pk_bf16_f32 v25, v25, v25
	v_and_or_b32 v24, v25, s36, v24
	s_nop 0
	v_cvt_pk_bf16_f32 v25, v26, v26
	v_bfe_u32 v26, v27, 16, 1
	v_lshrrev_b32_e32 v25, 16, v25
	v_add3_u32 v26, v27, v26, s48
	v_and_or_b32 v25, v26, s36, v25
	s_and_b64 vcc, exec, s[0:1]
	ds_write_b64 v56, v[24:25] offset:4224
	s_cbranch_vccnz .LBB0_1303
	s_ashr_i32 s21, s20, 31
	v_lshl_add_u64 v[24:25], s[20:21], 0, v[66:67]
	v_lshl_add_u64 v[24:25], v[24:25], 2, s[18:19]
	global_load_dword v24, v[24:25], off offset:160
	s_waitcnt vmcnt(0)
	v_pk_mul_f32 v[22:23], v[22:23], v[24:25] op_sel_hi:[1,0]
	v_pk_mul_f32 v[20:21], v[20:21], v[24:25] op_sel_hi:[1,0]
.LBB0_1303:
	s_nop 0
	s_nop 0
	v_cvt_pk_bf16_f32 v20, v20, v20
	s_nop 0
	v_lshrrev_b32_e32 v20, 16, v20
	v_cvt_pk_bf16_f32 v21, v21, v21
	v_and_or_b32 v20, v21, s36, v20
	s_nop 0
	v_cvt_pk_bf16_f32 v21, v22, v22
	v_bfe_u32 v22, v23, 16, 1
	v_lshrrev_b32_e32 v21, 16, v21
	v_add3_u32 v22, v23, v22, s48
	v_and_or_b32 v21, v22, s36, v21
	s_and_b64 vcc, exec, s[0:1]
	ds_write_b64 v56, v[20:21] offset:4752
	s_cbranch_vccnz .LBB0_1305
	s_ashr_i32 s21, s20, 31
	v_lshl_add_u64 v[20:21], s[20:21], 0, v[66:67]
	v_lshl_add_u64 v[20:21], v[20:21], 2, s[18:19]
	global_load_dword v20, v[20:21], off offset:176
	s_waitcnt vmcnt(0)
	v_pk_mul_f32 v[18:19], v[18:19], v[20:21] op_sel_hi:[1,0]
	v_pk_mul_f32 v[16:17], v[16:17], v[20:21] op_sel_hi:[1,0]
.LBB0_1305:
	s_nop 0
	s_nop 0
	v_cvt_pk_bf16_f32 v16, v16, v16
	s_nop 0
	v_lshrrev_b32_e32 v16, 16, v16
	v_cvt_pk_bf16_f32 v17, v17, v17
	v_and_or_b32 v16, v17, s36, v16
	s_nop 0
	v_cvt_pk_bf16_f32 v17, v18, v18
	v_bfe_u32 v18, v19, 16, 1
	v_lshrrev_b32_e32 v17, 16, v17
	v_add3_u32 v18, v19, v18, s48
	v_and_or_b32 v17, v18, s36, v17
	s_and_b64 vcc, exec, s[0:1]
	ds_write_b64 v56, v[16:17] offset:5280
	s_cbranch_vccnz .LBB0_1307
	s_ashr_i32 s21, s20, 31
	v_lshl_add_u64 v[16:17], s[20:21], 0, v[66:67]
	v_lshl_add_u64 v[16:17], v[16:17], 2, s[18:19]
	global_load_dword v16, v[16:17], off offset:192
	s_waitcnt vmcnt(0)
	v_pk_mul_f32 v[14:15], v[14:15], v[16:17] op_sel_hi:[1,0]
	v_pk_mul_f32 v[12:13], v[12:13], v[16:17] op_sel_hi:[1,0]
.LBB0_1307:
	s_waitcnt vmcnt(0)
	s_nop 0
	v_cvt_pk_bf16_f32 v12, v12, v12
	s_nop 0
	v_lshrrev_b32_e32 v12, 16, v12
	v_cvt_pk_bf16_f32 v13, v13, v13
	v_and_or_b32 v12, v13, s36, v12
	s_nop 0
	v_cvt_pk_bf16_f32 v13, v14, v14
	v_bfe_u32 v14, v15, 16, 1
	v_lshrrev_b32_e32 v13, 16, v13
	v_add3_u32 v14, v15, v14, s48
	v_and_or_b32 v13, v14, s36, v13
	s_and_b64 vcc, exec, s[0:1]
	ds_write_b64 v56, v[12:13] offset:5808
	s_cbranch_vccnz .LBB0_1309
	s_ashr_i32 s21, s20, 31
	v_lshl_add_u64 v[12:13], s[20:21], 0, v[66:67]
	v_lshl_add_u64 v[12:13], v[12:13], 2, s[18:19]
	global_load_dword v12, v[12:13], off offset:208
	s_waitcnt vmcnt(0)
	v_pk_mul_f32 v[10:11], v[10:11], v[12:13] op_sel_hi:[1,0]
	v_pk_mul_f32 v[8:9], v[8:9], v[12:13] op_sel_hi:[1,0]
.LBB0_1309:
	s_nop 0
	s_nop 0
	v_cvt_pk_bf16_f32 v8, v8, v8
	s_nop 0
	v_lshrrev_b32_e32 v8, 16, v8
	v_cvt_pk_bf16_f32 v9, v9, v9
	v_and_or_b32 v8, v9, s36, v8
	s_nop 0
	v_cvt_pk_bf16_f32 v9, v10, v10
	s_nop 0
	v_lshrrev_b32_e32 v9, 16, v9
	v_cvt_pk_bf16_f32 v10, v11, v11
	v_and_or_b32 v9, v10, s36, v9
	s_and_b64 vcc, exec, s[0:1]
	ds_write_b64 v56, v[8:9] offset:6336
	s_cbranch_vccnz .LBB0_1311
	s_ashr_i32 s21, s20, 31
	v_lshl_add_u64 v[8:9], s[20:21], 0, v[66:67]
	v_lshl_add_u64 v[8:9], v[8:9], 2, s[18:19]
	global_load_dword v8, v[8:9], off offset:224
	s_waitcnt vmcnt(0)
	v_pk_mul_f32 v[6:7], v[6:7], v[8:9] op_sel_hi:[1,0]
	v_pk_mul_f32 v[4:5], v[4:5], v[8:9] op_sel_hi:[1,0]
.LBB0_1311:
	s_nop 0
	s_nop 0
	v_cvt_pk_bf16_f32 v4, v4, v4
	s_nop 0
	v_lshrrev_b32_e32 v4, 16, v4
	v_cvt_pk_bf16_f32 v5, v5, v5
	v_and_or_b32 v4, v5, s36, v4
	s_nop 0
	v_cvt_pk_bf16_f32 v5, v6, v6
	s_nop 0
	v_readlane_b32 s0, v255, 22
	v_lshrrev_b32_e32 v5, 16, v5
	v_cvt_pk_bf16_f32 v6, v7, v7
	v_readlane_b32 s1, v255, 23
	v_and_or_b32 v5, v6, s36, v5
	s_and_b64 vcc, exec, s[0:1]
	ds_write_b64 v56, v[4:5] offset:6864
	s_cbranch_vccz .LBB0_1313
	s_ashr_i32 s21, s20, 31
	v_lshl_add_u64 v[4:5], s[20:21], 0, v[66:67]
	v_lshl_add_u64 v[4:5], v[4:5], 2, s[18:19]
	global_load_dword v4, v[4:5], off offset:240
	s_waitcnt vmcnt(0)
	v_pk_mul_f32 v[6:7], v[2:3], v[4:5] op_sel_hi:[1,0]
	v_pk_mul_f32 v[4:5], v[0:1], v[4:5] op_sel_hi:[1,0]
	s_cbranch_execnz .LBB0_1200
	s_branch .LBB0_1199

.LBB0_1528:
	s_or_b64 exec, exec, s[16:17]
	v_bfi_b32 v1, s49, v2, v1
	v_mul_f32_e32 v0, 0.5, v0
	v_add_f32_e32 v1, 1.0, v1
	v_mul_f32_e32 v0, v0, v1
	s_add_u32 s14, s14, 0x4000
	s_nop 0
	s_addc_u32 s15, s15, 0
	v_cvt_pk_bf16_f32 v2, v0, v0
	v_lshl_add_u64 v[0:1], s[6:7], 0, v[58:59]
	v_lshl_add_u64 v[62:63], v[62:63], 0, s[50:51]
	v_lshl_add_u64 v[60:61], v[60:61], 0, s[40:41]
	v_lshl_add_u64 v[58:59], v[58:59], 0, s[40:41]
	s_cmp_eq_u32 s14, 0x20000
	v_lshl_add_u64 v[56:57], v[56:57], 0, s[96:97]
	global_store_short_d16_hi v[0:1], v2, off
	s_cbranch_scc1 .LBB0_1526

.LBB0_1535:
	v_lshl_add_u64 v[100:101], s[14:15], 0, v[96:97]
	v_add_co_u32_e32 v98, vcc, 0x33812000, v100
	s_mov_b32 s0, 0x2d772000
	s_nop 1
	v_addc_co_u32_e32 v99, vcc, 0, v101, vcc
	v_add_co_u32_e32 v102, vcc, 0x326f2000, v100
	global_load_dwordx4 v[108:111], v[98:99], off
	s_nop 1
	v_addc_co_u32_e32 v103, vcc, 0, v101, vcc
	global_load_dwordx4 v[112:115], v[102:103], off
	v_add_co_u32_e32 v104, vcc, s5, v100
	s_nop 1
	v_addc_co_u32_e32 v105, vcc, 0, v101, vcc
	global_load_dwordx4 v[116:119], v[104:105], off
	global_load_dwordx4 v[120:123], v[4:5], off offset:16
	global_load_dwordx4 v[124:127], v[4:5], off
	v_add_co_u32_e32 v98, vcc, s3, v100
	s_nop 1
	v_addc_co_u32_e32 v99, vcc, 0, v101, vcc
	global_load_dwordx4 v[128:131], v[98:99], off
	v_add_co_u32_e32 v98, vcc, s0, v100
	s_nop 1
	v_addc_co_u32_e32 v99, vcc, 0, v101, vcc
	global_load_dwordx4 v[132:135], v[98:99], off
	s_mov_b32 s0, 0x2c652000
	v_add_co_u32_e32 v98, vcc, s0, v100
	s_nop 1
	v_addc_co_u32_e32 v99, vcc, 0, v101, vcc
	v_lshl_add_u64 v[100:101], s[6:7], 0, v[96:97]
	s_mov_b32 s0, 0x1ec01000
	v_add_co_u32_e32 v104, vcc, s0, v100
	global_load_dwordx4 v[138:141], v[98:99], off
	s_nop 1
	v_addc_co_u32_e32 v105, vcc, 0, v101, vcc
	s_mov_b32 s0, 0x1ec02000
	v_add_co_u32_e32 v100, vcc, s0, v100
	global_load_dwordx4 v[142:145], v[104:105], off offset:3584
	s_nop 1
	v_addc_co_u32_e32 v101, vcc, 0, v101, vcc
	global_load_dwordx4 v[146:149], v[100:101], off offset:2592
	global_load_dwordx4 v[150:153], v[6:7], off offset:16
	global_load_dwordx4 v[154:157], v[6:7], off
	global_load_dwordx4 v[158:161], v[8:9], off offset:16
	global_load_dwordx4 v[162:165], v[8:9], off
	v_lshl_add_u64 v[10:11], s[14:15], 0, v[96:97]
	v_add_co_u32_e32 v0, vcc, 0x33812000, v10
	s_mov_b32 s0, 0x2d772000
	s_nop 0
	v_addc_co_u32_e32 v1, vcc, 0, v11, vcc
	v_add_co_u32_e32 v12, vcc, 0x326f2000, v10
	s_waitcnt vmcnt(0)
	v_mov_b64_e32 v[0:1], v[108:109]
	v_mov_b64_e32 v[2:3], v[110:111]
	s_nop 0
	v_addc_co_u32_e32 v13, vcc, 0, v11, vcc
	v_mov_b64_e32 v[18:19], v[112:113]
	v_mov_b64_e32 v[20:21], v[114:115]
	s_add_i32 s4, s4, s2
	s_waitcnt vmcnt(1)
	v_lshlrev_b32_e32 v37, 16, v2
	v_lshlrev_b32_e32 v36, 16, v0
	v_and_b32_e32 v39, 0xffff0000, v2
	s_waitcnt vmcnt(0)
	v_lshlrev_b32_e32 v12, 16, v18
	v_and_b32_e32 v13, 0xffff0000, v18
	v_add_co_u32_e32 v18, vcc, s5, v10
	v_lshlrev_b32_e32 v30, 16, v19
	v_and_b32_e32 v31, 0xffff0000, v19
	v_addc_co_u32_e32 v19, vcc, 0, v11, vcc
	v_lshlrev_b32_e32 v32, 16, v20
	v_and_b32_e32 v33, 0xffff0000, v20
	v_lshlrev_b32_e32 v34, 16, v21
	v_and_b32_e32 v35, 0xffff0000, v21
	v_mov_b64_e32 v[18:19], v[116:117]
	v_mov_b64_e32 v[20:21], v[118:119]
	s_nop 0
	v_mov_b64_e32 v[22:23], v[120:121]
	v_mov_b64_e32 v[24:25], v[122:123]
	v_mov_b64_e32 v[26:27], v[124:125]
	v_mov_b64_e32 v[28:29], v[126:127]
	v_and_b32_e32 v38, 0xffff0000, v0
	v_lshlrev_b32_e32 v41, 16, v3
	v_lshlrev_b32_e32 v40, 16, v1
	v_and_b32_e32 v2, 0xffff0000, v1
	v_pk_add_f32 v[0:1], v[36:37], v[38:39]
	v_and_b32_e32 v3, 0xffff0000, v3
	v_pk_add_f32 v[0:1], v[0:1], v[40:41]
	s_nop 0
	v_pk_add_f32 v[0:1], v[0:1], v[2:3]
	s_nop 0
	v_add_f32_e32 v0, v0, v1
	ds_bpermute_b32 v1, v14, v0
	s_waitcnt lgkmcnt(0)
	v_add_f32_e32 v0, v0, v1
	ds_bpermute_b32 v1, v15, v0
	s_waitcnt lgkmcnt(0)
	v_add_f32_e32 v0, v0, v1
	ds_bpermute_b32 v1, v16, v0
	s_waitcnt lgkmcnt(0)
	v_add_f32_e32 v0, v0, v1
	v_fmac_f32_e32 v38, 0xbc800000, v0
	v_fmac_f32_e32 v39, 0xbc800000, v0
	v_fmac_f32_e32 v36, 0xbc800000, v0
	v_fmac_f32_e32 v37, 0xbc800000, v0
	v_mov_b32_e32 v1, v39
	v_mov_b32_e32 v43, v38
	v_pk_mul_f32 v[38:39], v[38:39], v[38:39]
	v_fmac_f32_e32 v2, 0xbc800000, v0
	v_fmac_f32_e32 v40, 0xbc800000, v0
	v_fmac_f32_e32 v3, 0xbc800000, v0
	v_fmac_f32_e32 v41, 0xbc800000, v0
	v_mov_b32_e32 v0, v37
	v_mov_b32_e32 v42, v36
	v_pk_fma_f32 v[36:37], v[36:37], v[36:37], v[38:39]
	v_mov_b32_e32 v39, v3
	v_pk_fma_f32 v[36:37], v[40:41], v[40:41], v[36:37]
	v_mov_b32_e32 v45, v2
	v_pk_fma_f32 v[2:3], v[2:3], v[2:3], v[36:37]
	v_mov_b32_e32 v44, v40
	v_add_f32_e32 v2, v2, v3
	ds_bpermute_b32 v3, v14, v2
	v_mov_b32_e32 v38, v41
	s_waitcnt lgkmcnt(0)
	v_add_f32_e32 v2, v2, v3
	ds_bpermute_b32 v3, v15, v2
	s_waitcnt lgkmcnt(0)
	v_add_f32_e32 v2, v2, v3
	ds_bpermute_b32 v3, v16, v2
	s_waitcnt lgkmcnt(0)
	v_add_f32_e32 v2, v2, v3
	v_fmamk_f32 v2, v2, 0x3c800000, v231
	v_cmp_gt_f32_e32 vcc, s45, v2
	v_mul_f32_e32 v3, 0x4b800000, v2
	s_nop 0
	v_cndmask_b32_e32 v2, v2, v3, vcc
	v_rsq_f32_e32 v2, v2
	s_nop 0
	v_mul_f32_e32 v3, 0x45800000, v2
	v_cndmask_b32_e32 v2, v2, v3, vcc
	v_pk_mul_f32 v[36:37], v[44:45], v[2:3] op_sel_hi:[1,0]
	v_pk_mul_f32 v[40:41], v[42:43], v[2:3] op_sel_hi:[1,0]
	v_pk_mul_f32 v[0:1], v[0:1], v[2:3] op_sel_hi:[1,0]
	s_waitcnt vmcnt(0)
	v_pk_fma_f32 v[12:13], v[26:27], v[40:41], v[12:13]
	v_pk_fma_f32 v[26:27], v[28:29], v[36:37], v[30:31]
	v_pk_mul_f32 v[28:29], v[38:39], v[2:3] op_sel_hi:[1,0]
	v_pk_fma_f32 v[0:1], v[22:23], v[0:1], v[32:33]
	v_pk_fma_f32 v[2:3], v[24:25], v[28:29], v[34:35]
	v_lshlrev_b32_e32 v23, 16, v19
	v_lshlrev_b32_e32 v22, 16, v18
	v_mov_b32_e32 v24, v12
	v_mov_b32_e32 v25, v26
	v_and_b32_e32 v19, 0xffff0000, v19
	v_and_b32_e32 v18, 0xffff0000, v18
	v_mov_b32_e32 v26, v13
	v_pk_mul_f32 v[22:23], v[24:25], v[22:23]
	v_pk_mul_f32 v[12:13], v[26:27], v[18:19]
	v_lshlrev_b32_e32 v19, 16, v21
	v_lshlrev_b32_e32 v18, 16, v20
	v_mov_b32_e32 v25, v2
	v_and_b32_e32 v21, 0xffff0000, v21
	v_and_b32_e32 v20, 0xffff0000, v20
	v_mov_b32_e32 v2, v1
	v_mov_b32_e32 v24, v0
	v_pk_mul_f32 v[0:1], v[2:3], v[20:21]
	v_pk_mul_f32 v[18:19], v[24:25], v[18:19]
	s_nop 0
	s_nop 0
	s_nop 0
	s_nop 0
	v_cvt_pk_bf16_f32 v12, v12, v12
	v_cvt_pk_bf16_f32 v13, v13, v13
	v_cvt_pk_bf16_f32 v0, v0, v0
	v_cvt_pk_bf16_f32 v1, v1, v1
	s_nop 0
	s_nop 0
	s_nop 0
	s_nop 0
	v_cvt_pk_bf16_f32 v19, v19, v19
	v_cvt_pk_bf16_f32 v18, v18, v18
	v_cvt_pk_bf16_f32 v3, v23, v23
	v_cvt_pk_bf16_f32 v2, v22, v22
	v_lshrrev_b32_e32 v20, 16, v2
	v_lshrrev_b32_e32 v21, 16, v3
	v_lshrrev_b32_e32 v2, 16, v18
	v_lshrrev_b32_e32 v3, 16, v19
	v_and_or_b32 v3, v1, s36, v3
	v_and_or_b32 v2, v0, s36, v2
	v_and_or_b32 v1, v13, s36, v21
	v_and_or_b32 v0, v12, s36, v20
	v_lshl_add_u64 v[12:13], s[10:11], 0, v[96:97]
	v_add_co_u32_e32 v12, vcc, s18, v12
	s_add_u32 s10, s10, s12
	s_nop 0
	v_addc_co_u32_e32 v13, vcc, 0, v13, vcc
	global_store_dwordx4 v[12:13], v[0:3], off
	s_addc_u32 s11, s11, s13
	s_add_u32 s14, s14, s16
	v_add_co_u32_e32 v0, vcc, s3, v10
	s_addc_u32 s15, s15, s17
	s_nop 0
	v_addc_co_u32_e32 v1, vcc, 0, v11, vcc
	v_mov_b64_e32 v[0:1], v[128:129]
	v_mov_b64_e32 v[2:3], v[130:131]
	s_waitcnt vmcnt(0)
	v_lshlrev_b32_e32 v42, 16, v0
	v_and_b32_e32 v44, 0xffff0000, v0
	v_add_co_u32_e32 v0, vcc, s0, v10
	v_lshlrev_b32_e32 v43, 16, v1
	v_and_b32_e32 v45, 0xffff0000, v1
	v_addc_co_u32_e32 v1, vcc, 0, v11, vcc
	v_lshlrev_b32_e32 v46, 16, v2
	v_and_b32_e32 v48, 0xffff0000, v2
	v_lshlrev_b32_e32 v47, 16, v3
	v_and_b32_e32 v49, 0xffff0000, v3
	v_mov_b64_e32 v[0:1], v[132:133]
	v_mov_b64_e32 v[2:3], v[134:135]
	s_mov_b32 s0, 0x2c652000
	s_waitcnt vmcnt(0)
	v_lshlrev_b32_e32 v50, 16, v0
	v_and_b32_e32 v52, 0xffff0000, v0
	v_add_co_u32_e32 v0, vcc, s0, v10
	v_lshlrev_b32_e32 v51, 16, v1
	v_and_b32_e32 v53, 0xffff0000, v1
	v_addc_co_u32_e32 v1, vcc, 0, v11, vcc
	v_lshl_add_u64 v[10:11], s[6:7], 0, v[96:97]
	s_mov_b32 s0, 0x1ec01000
	v_add_co_u32_e32 v18, vcc, s0, v10
	v_lshlrev_b32_e32 v54, 16, v2
	v_and_b32_e32 v56, 0xffff0000, v2
	v_lshlrev_b32_e32 v55, 16, v3
	v_and_b32_e32 v57, 0xffff0000, v3
	v_mov_b64_e32 v[0:1], v[138:139]
	v_mov_b64_e32 v[2:3], v[140:141]
	v_addc_co_u32_e32 v19, vcc, 0, v11, vcc
	s_mov_b32 s0, 0x1ec02000
	v_add_co_u32_e32 v10, vcc, s0, v10
	v_mov_b64_e32 v[18:19], v[142:143]
	v_mov_b64_e32 v[20:21], v[144:145]
	s_nop 0
	v_addc_co_u32_e32 v11, vcc, 0, v11, vcc
	v_mov_b64_e32 v[22:23], v[146:147]
	v_mov_b64_e32 v[24:25], v[148:149]
	v_mov_b64_e32 v[26:27], v[150:151]
	v_mov_b64_e32 v[28:29], v[152:153]
	v_mov_b64_e32 v[30:31], v[154:155]
	v_mov_b64_e32 v[32:33], v[156:157]
	v_mov_b64_e32 v[34:35], v[158:159]
	v_mov_b64_e32 v[36:37], v[160:161]
	v_mov_b64_e32 v[38:39], v[162:163]
	v_mov_b64_e32 v[40:41], v[164:165]
	v_pk_add_f32 v[10:11], v[42:43], v[50:51]
	v_pk_add_f32 v[42:43], v[44:45], v[52:53]
	v_mov_b32_e32 v73, v10
	v_mov_b32_e32 v75, v42
	v_mov_b32_e32 v50, v43
	v_mov_b32_e32 v51, v11
	v_pk_mul_f32 v[50:51], v[50:51], v[50:51]
	s_add_u32 s6, s6, s8
	s_addc_u32 s7, s7, s9
	s_cmpk_lt_i32 s4, 0xc00
	s_waitcnt vmcnt(6)
	v_and_b32_e32 v69, 0xffff0000, v1
	v_and_b32_e32 v68, 0xffff0000, v0
	v_mov_b32_e32 v74, v68
	v_pk_mul_f32 v[74:75], v[74:75], v[74:75]
	v_and_b32_e32 v80, 0xffff0000, v2
	s_waitcnt vmcnt(4)
	v_lshlrev_b32_e32 v70, 16, v22
	s_waitcnt vmcnt(3)
	v_mov_b32_e32 v67, v28
	v_mov_b32_e32 v28, v27
	v_lshlrev_b32_e32 v27, 16, v1
	v_mov_b32_e32 v66, v26
	v_lshlrev_b32_e32 v26, 16, v0
	v_mov_b32_e32 v0, v69
	v_mov_b32_e32 v1, v27
	v_pk_mul_f32 v[0:1], v[0:1], v[0:1]
	v_mov_b32_e32 v72, v26
	v_pk_fma_f32 v[72:73], v[72:73], v[72:73], v[74:75]
	v_mov_b32_e32 v74, v1
	v_mul_f32_e32 v1, 0xbfb8aa3b, v70
	v_exp_f32_e32 v1, v1
	v_and_b32_e32 v22, 0xffff0000, v22
	v_mov_b32_e32 v75, v51
	v_pk_add_f32 v[72:73], v[74:75], v[72:73]
	v_add_f32_e32 v1, 1.0, v1
	v_rcp_f32_e32 v74, v1
	v_mul_f32_e32 v1, 0xbfb8aa3b, v22
	v_exp_f32_e32 v1, v1
	v_lshlrev_b32_e32 v71, 16, v23
	v_and_b32_e32 v23, 0xffff0000, v23
	v_lshlrev_b32_e32 v82, 16, v24
	v_add_f32_e32 v1, 1.0, v1
	v_rcp_f32_e32 v76, v1
	v_mul_f32_e32 v1, 0xbfb8aa3b, v71
	v_exp_f32_e32 v1, v1
	v_and_b32_e32 v24, 0xffff0000, v24
	v_lshlrev_b32_e32 v45, 16, v19
	v_lshlrev_b32_e32 v44, 16, v18
	v_add_f32_e32 v1, 1.0, v1
	v_rcp_f32_e32 v75, v1
	v_mul_f32_e32 v1, 0xbfb8aa3b, v23
	v_exp_f32_e32 v1, v1
	v_and_b32_e32 v18, 0xffff0000, v18
	v_mul_f32_e32 v53, 0xbfb8aa3b, v18
	s_waitcnt vmcnt(2)
	v_mov_b32_e32 v60, v30
	v_add_f32_e32 v1, 1.0, v1
	v_rcp_f32_e32 v77, v1
	v_mul_f32_e32 v1, 0xbfb8aa3b, v82
	v_exp_f32_e32 v1, v1
	v_mul_f32_e32 v30, 0xbfb8aa3b, v45
	v_exp_f32_e32 v53, v53
	v_exp_f32_e32 v30, v30
	v_add_f32_e32 v1, 1.0, v1
	v_rcp_f32_e32 v86, v1
	v_mul_f32_e32 v1, 0xbfb8aa3b, v24
	v_exp_f32_e32 v1, v1
	v_lshlrev_b32_e32 v83, 16, v25
	v_and_b32_e32 v19, 0xffff0000, v19
	v_add_f32_e32 v53, 1.0, v53
	v_add_f32_e32 v1, 1.0, v1
	v_rcp_f32_e32 v88, v1
	v_mul_f32_e32 v1, 0xbfb8aa3b, v83
	v_exp_f32_e32 v1, v1
	v_add_f32_e32 v30, 1.0, v30
	v_rcp_f32_e32 v58, v53
	v_rcp_f32_e32 v53, v30
	v_mul_f32_e32 v30, 0xbfb8aa3b, v19
	v_exp_f32_e32 v30, v30
	v_and_b32_e32 v25, 0xffff0000, v25
	v_add_f32_e32 v1, 1.0, v1
	v_rcp_f32_e32 v87, v1
	v_mul_f32_e32 v1, 0xbfb8aa3b, v25
	v_exp_f32_e32 v1, v1
	v_add_f32_e32 v30, 1.0, v30
	v_mov_b32_e32 v61, v32
	v_mov_b32_e32 v32, v31
	v_rcp_f32_e32 v59, v30
	v_pk_add_f32 v[30:31], v[46:47], v[54:55]
	v_pk_add_f32 v[46:47], v[48:49], v[56:57]
	s_waitcnt vmcnt(0)
	v_mov_b32_e32 v78, v38
	v_lshlrev_b32_e32 v38, 16, v2
	v_mov_b32_e32 v54, v46
	v_mov_b32_e32 v55, v30
	v_mov_b32_e32 v79, v40
	v_mov_b32_e32 v40, v39
	v_lshlrev_b32_e32 v39, 16, v3
	v_and_b32_e32 v81, 0xffff0000, v3
	v_mov_b32_e32 v2, v80
	v_mov_b32_e32 v3, v38
	v_add_f32_e32 v1, 1.0, v1
	v_pk_mul_f32 v[54:55], v[54:55], v[54:55]
	v_pk_mul_f32 v[2:3], v[2:3], v[2:3]
	v_rcp_f32_e32 v89, v1
	v_mov_b32_e32 v1, v50
	v_mov_b32_e32 v56, v47
	v_mov_b32_e32 v57, v31
	v_mov_b32_e32 v84, v81
	v_mov_b32_e32 v85, v39
	v_pk_add_f32 v[0:1], v[0:1], v[72:73]
	v_mov_b32_e32 v50, v3
	v_mov_b32_e32 v51, v55
	v_pk_mul_f32 v[56:57], v[56:57], v[56:57]
	v_pk_mul_f32 v[84:85], v[84:85], v[84:85]
	v_pk_add_f32 v[0:1], v[50:51], v[0:1]
	v_mov_b32_e32 v3, v54
	v_pk_add_f32 v[0:1], v[2:3], v[0:1]
	v_mov_b32_e32 v2, v85
	v_mov_b32_e32 v3, v57
	v_pk_add_f32 v[0:1], v[2:3], v[0:1]
	v_mov_b32_e32 v85, v56
	v_pk_add_f32 v[0:1], v[84:85], v[0:1]
	ds_bpermute_b32 v3, v14, v1
	ds_bpermute_b32 v2, v14, v0
	v_lshlrev_b32_e32 v48, 16, v20
	v_and_b32_e32 v20, 0xffff0000, v20
	v_mul_f32_e32 v63, 0xbfb8aa3b, v20
	v_exp_f32_e32 v63, v63
	s_waitcnt lgkmcnt(0)
	v_pk_add_f32 v[0:1], v[0:1], v[2:3]
	ds_bpermute_b32 v3, v15, v1
	ds_bpermute_b32 v2, v15, v0
	v_lshlrev_b32_e32 v49, 16, v21
	v_and_b32_e32 v21, 0xffff0000, v21
	v_add_f32_e32 v63, 1.0, v63
	v_mul_f32_e32 v65, 0xbfb8aa3b, v21
	s_waitcnt lgkmcnt(0)
	v_pk_add_f32 v[0:1], v[0:1], v[2:3]
	ds_bpermute_b32 v3, v16, v1
	ds_bpermute_b32 v2, v16, v0
	v_mul_f32_e32 v52, 0xbfb8aa3b, v44
	v_mul_f32_e32 v62, 0xbfb8aa3b, v48
	v_rcp_f32_e32 v64, v63
	v_mul_f32_e32 v63, 0xbfb8aa3b, v49
	s_waitcnt lgkmcnt(0)
	v_pk_add_f32 v[0:1], v[0:1], v[2:3]
	ds_bpermute_b32 v3, v17, v1
	ds_bpermute_b32 v2, v17, v0
	v_exp_f32_e32 v65, v65
	v_exp_f32_e32 v52, v52
	v_exp_f32_e32 v62, v62
	v_exp_f32_e32 v63, v63
	s_waitcnt lgkmcnt(0)
	v_pk_add_f32 v[0:1], v[0:1], v[2:3]
	v_add_f32_e32 v65, 1.0, v65
	v_pk_fma_f32 v[50:51], v[0:1], s[20:21], v[242:243] op_sel_hi:[1,0,0]
	v_add_f32_e32 v52, 1.0, v52
	v_mul_f32_e32 v0, 0x4b800000, v51
	v_cmp_gt_f32_e64 s[0:1], s45, v51
	v_add_f32_e32 v62, 1.0, v62
	v_add_f32_e32 v63, 1.0, v63
	v_cndmask_b32_e64 v0, v51, v0, s[0:1]
	v_rsq_f32_e32 v0, v0
	v_rcp_f32_e32 v65, v65
	v_rcp_f32_e32 v52, v52
	v_rcp_f32_e32 v62, v62
	v_mul_f32_e32 v1, 0x45800000, v0
	v_cndmask_b32_e64 v0, v0, v1, s[0:1]
	v_pk_mul_f32 v[2:3], v[10:11], v[0:1] op_sel_hi:[1,0]
	v_pk_mul_f32 v[10:11], v[42:43], v[0:1] op_sel_hi:[1,0]
	v_rcp_f32_e32 v63, v63
	v_pk_mul_f32 v[10:11], v[32:33], v[10:11]
	v_pk_mul_f32 v[2:3], v[60:61], v[2:3]
	v_pk_mul_f32 v[10:11], v[10:11], v[18:19]
	v_pk_mul_f32 v[18:19], v[30:31], v[0:1] op_sel_hi:[1,0]
	v_pk_mul_f32 v[0:1], v[46:47], v[0:1] op_sel_hi:[1,0]
	v_pk_mul_f32 v[18:19], v[66:67], v[18:19]
	v_pk_mul_f32 v[0:1], v[28:29], v[0:1]
	v_pk_mul_f32 v[2:3], v[2:3], v[44:45]
	v_pk_mul_f32 v[0:1], v[0:1], v[20:21]
	v_pk_mul_f32 v[10:11], v[58:59], v[10:11]
	v_pk_mul_f32 v[18:19], v[18:19], v[48:49]
	v_pk_mul_f32 v[0:1], v[64:65], v[0:1]
	v_pk_mul_f32 v[2:3], v[52:53], v[2:3]
	v_pk_mul_f32 v[18:19], v[62:63], v[18:19]
	s_nop 0
	s_nop 0
	s_nop 0
	s_nop 0
	v_cvt_pk_bf16_f32 v10, v10, v10
	v_cvt_pk_bf16_f32 v11, v11, v11
	v_cvt_pk_bf16_f32 v0, v0, v0
	v_cvt_pk_bf16_f32 v1, v1, v1
	s_nop 0
	s_nop 0
	s_nop 0
	s_nop 0
	v_cvt_pk_bf16_f32 v19, v19, v19
	v_cvt_pk_bf16_f32 v18, v18, v18
	v_cvt_pk_bf16_f32 v3, v3, v3
	v_cvt_pk_bf16_f32 v2, v2, v2
	v_lshrrev_b32_e32 v20, 16, v2
	v_lshrrev_b32_e32 v21, 16, v3
	v_lshrrev_b32_e32 v2, 16, v18
	v_lshrrev_b32_e32 v3, 16, v19
	v_and_or_b32 v3, v1, s36, v3
	v_and_or_b32 v2, v0, s36, v2
	v_and_or_b32 v1, v11, s36, v21
	v_and_or_b32 v0, v10, s36, v20
	v_cmp_gt_f32_e32 vcc, s45, v50
	global_store_dwordx4 v[12:13], v[0:3], off offset:2048
	v_mov_b32_e32 v21, v36
	v_mov_b32_e32 v36, v35
	v_mul_f32_e32 v0, 0x4b800000, v50
	v_cndmask_b32_e32 v0, v50, v0, vcc
	v_rsq_f32_e32 v0, v0
	v_mov_b32_e32 v20, v34
	v_mul_f32_e32 v1, 0x45800000, v0
	v_cndmask_b32_e32 v0, v0, v1, vcc
	v_pk_mul_f32 v[2:3], v[0:1], v[26:27] op_sel_hi:[0,1]
	v_pk_mul_f32 v[10:11], v[0:1], v[68:69] op_sel_hi:[0,1]
	v_pk_mul_f32 v[18:19], v[0:1], v[38:39] op_sel_hi:[0,1]
	v_pk_mul_f32 v[0:1], v[0:1], v[80:81] op_sel_hi:[0,1]
	v_pk_mul_f32 v[10:11], v[40:41], v[10:11]
	v_pk_mul_f32 v[0:1], v[36:37], v[0:1]
	v_pk_mul_f32 v[2:3], v[78:79], v[2:3]
	v_pk_mul_f32 v[10:11], v[10:11], v[22:23]
	v_pk_mul_f32 v[18:19], v[20:21], v[18:19]
	v_pk_mul_f32 v[0:1], v[0:1], v[24:25]
	v_pk_mul_f32 v[2:3], v[2:3], v[70:71]
	v_pk_mul_f32 v[10:11], v[76:77], v[10:11]
	v_pk_mul_f32 v[18:19], v[18:19], v[82:83]
	v_pk_mul_f32 v[0:1], v[88:89], v[0:1]
	v_pk_mul_f32 v[2:3], v[74:75], v[2:3]
	v_pk_mul_f32 v[18:19], v[86:87], v[18:19]
	s_nop 0
	s_nop 0
	v_bfe_u32 v22, v11, 16, 1
	v_bfe_u32 v23, v10, 16, 1
	v_add3_u32 v10, v10, v23, s48
	v_add3_u32 v11, v11, v22, s48
	v_cvt_pk_bf16_f32 v0, v0, v0
	v_cvt_pk_bf16_f32 v1, v1, v1
	s_nop 0
	s_nop 0
	v_bfe_u32 v22, v18, 16, 1
	v_bfe_u32 v23, v19, 16, 1
	v_add3_u32 v19, v19, v23, s48
	v_add3_u32 v18, v18, v22, s48
	v_cvt_pk_bf16_f32 v3, v3, v3
	v_cvt_pk_bf16_f32 v2, v2, v2
	v_lshrrev_b32_e32 v20, 16, v2
	v_lshrrev_b32_e32 v21, 16, v3
	v_lshrrev_b32_e32 v2, 16, v18
	v_lshrrev_b32_e32 v3, 16, v19
	v_and_or_b32 v3, v1, s36, v3
	v_and_or_b32 v2, v0, s36, v2
	v_and_or_b32 v1, v11, s36, v21
	v_and_or_b32 v0, v10, s36, v20
	global_store_dwordx4 v[12:13], v[0:3], off offset:3072
	s_cbranch_scc1 .LBB0_1535

.LBB0_1608:
	v_add_co_u32_e32 v0, vcc, 0x2c652000, v4
	global_load_dwordx4 v[8:11], v[24:25], off offset:16
	global_load_dwordx4 v[12:15], v[24:25], off
	v_addc_co_u32_e32 v1, vcc, 0, v5, vcc
	global_load_dwordx4 v[20:23], v[0:1], off
	v_lshl_add_u64 v[0:1], s[2:3], 0, v[96:97]
	v_add_co_u32_e32 v2, vcc, 0x1ec01000, v0
	v_pk_mul_f32 v[38:39], v[32:33], v[32:33]
	s_nop 0
	v_addc_co_u32_e32 v3, vcc, 0, v1, vcc
	v_add_co_u32_e32 v0, vcc, 0x1ec02000, v0
	global_load_dwordx4 v[54:57], v[2:3], off offset:3584
	s_nop 0
	v_addc_co_u32_e32 v1, vcc, 0, v1, vcc
	global_load_dwordx4 v[16:19], v[0:1], off offset:2592
	s_nop 0
	global_load_dwordx4 v[0:3], v[26:27], off offset:16
	global_load_dwordx4 v[4:7], v[26:27], off
	v_pk_mul_f32 v[44:45], v[48:49], v[48:49]
	v_pk_mul_f32 v[46:47], v[34:35], v[34:35]
	v_mov_b32_e32 v37, v34
	v_mov_b32_e32 v34, v41
	v_mov_b32_e32 v42, v48
	v_mov_b32_e32 v43, v32
	v_mov_b32_e32 v32, v49
	v_mov_b32_e32 v49, v36
	s_brev_b32 s0, 60
	s_add_i32 s6, s6, s4
	s_add_u32 s8, s8, s10
	s_addc_u32 s9, s9, s11
	s_add_u32 s12, s12, s14
	s_addc_u32 s13, s13, s15
	s_waitcnt vmcnt(0)
	v_mov_b32_e32 v60, v8
	v_mov_b32_e32 v59, v14
	v_mov_b32_e32 v14, v13
	v_mov_b32_e32 v61, v10
	v_mov_b32_e32 v10, v9
	v_lshlrev_b32_e32 v13, 16, v21
	v_and_b32_e32 v9, 0xffff0000, v21
	v_and_b32_e32 v8, 0xffff0000, v20
	v_mov_b32_e32 v58, v12
	v_lshlrev_b32_e32 v12, 16, v20
	v_mov_b32_e32 v66, v9
	v_mov_b32_e32 v67, v13
	v_mov_b32_e32 v40, v8
	v_mov_b32_e32 v48, v12
	v_pk_mul_f32 v[66:67], v[66:67], v[66:67]
	v_pk_mul_f32 v[40:41], v[40:41], v[40:41]
	v_lshlrev_b32_e32 v20, 16, v16
	v_lshlrev_b32_e32 v63, 16, v55
	v_lshlrev_b32_e32 v62, 16, v54
	v_and_b32_e32 v54, 0xffff0000, v54
	v_and_b32_e32 v16, 0xffff0000, v16
	v_pk_fma_f32 v[40:41], v[48:49], v[48:49], v[40:41]
	v_pk_mov_b32 v[48:49], v[66:67], v[46:47] op_sel:[1,0]
	v_mul_f32_e32 v46, 0xbfb8aa3b, v20
	v_mul_f32_e32 v69, 0xbfb8aa3b, v54
	v_mul_f32_e32 v70, 0xbfb8aa3b, v63
	v_exp_f32_e32 v46, v46
	v_mul_f32_e32 v67, 0xbfb8aa3b, v16
	v_exp_f32_e32 v69, v69
	v_exp_f32_e32 v70, v70
	v_exp_f32_e32 v67, v67
	v_lshlrev_b32_e32 v21, 16, v17
	v_lshlrev_b32_e32 v65, 16, v57
	v_lshlrev_b32_e32 v64, 16, v56
	v_and_b32_e32 v56, 0xffff0000, v56
	v_and_b32_e32 v17, 0xffff0000, v17
	v_add_f32_e32 v46, 1.0, v46
	v_mov_b32_e32 v78, v4
	v_mul_f32_e32 v4, 0xbfb8aa3b, v21
	v_mul_f32_e32 v73, 0xbfb8aa3b, v56
	v_mul_f32_e32 v74, 0xbfb8aa3b, v65
	v_add_f32_e32 v69, 1.0, v69
	v_add_f32_e32 v76, 1.0, v70
	v_pk_add_f32 v[40:41], v[48:49], v[40:41]
	v_rcp_f32_e32 v48, v46
	v_add_f32_e32 v46, 1.0, v67
	v_exp_f32_e32 v4, v4
	v_mov_b32_e32 v79, v6
	v_mul_f32_e32 v6, 0xbfb8aa3b, v17
	v_exp_f32_e32 v73, v73
	v_exp_f32_e32 v74, v74
	v_rcp_f32_e32 v70, v69
	v_rcp_f32_e32 v69, v76
	v_rcp_f32_e32 v76, v46
	v_exp_f32_e32 v46, v6
	v_add_f32_e32 v4, 1.0, v4
	v_add_f32_e32 v73, 1.0, v73
	v_add_f32_e32 v77, 1.0, v74
	v_rcp_f32_e32 v49, v4
	v_add_f32_e32 v4, 1.0, v46
	v_rcp_f32_e32 v74, v73
	v_rcp_f32_e32 v73, v77
	v_rcp_f32_e32 v77, v4
	v_lshlrev_b32_e32 v4, 16, v22
	v_and_b32_e32 v22, 0xffff0000, v22
	v_mov_b32_e32 v82, v22
	v_mov_b32_e32 v83, v4
	v_mov_b32_e32 v6, v5
	v_lshlrev_b32_e32 v5, 16, v23
	v_and_b32_e32 v23, 0xffff0000, v23
	v_pk_mul_f32 v[82:83], v[82:83], v[82:83]
	v_mov_b32_e32 v67, v47
	v_mov_b32_e32 v84, v23
	v_mov_b32_e32 v85, v5
	v_pk_add_f32 v[40:41], v[66:67], v[40:41]
	v_pk_mov_b32 v[46:47], v[82:83], v[44:45] op_sel:[1,0]
	v_pk_mul_f32 v[84:85], v[84:85], v[84:85]
	v_pk_add_f32 v[40:41], v[46:47], v[40:41]
	v_mov_b32_e32 v83, v45
	v_pk_add_f32 v[40:41], v[82:83], v[40:41]
	v_pk_mov_b32 v[44:45], v[84:85], v[38:39] op_sel:[1,0]
	v_mov_b32_e32 v85, v39
	v_pk_add_f32 v[40:41], v[44:45], v[40:41]
	v_lshlrev_b32_e32 v80, 16, v18
	v_pk_add_f32 v[38:39], v[84:85], v[40:41]
	ds_bpermute_b32 v41, v50, v39
	ds_bpermute_b32 v40, v50, v38
	v_and_b32_e32 v18, 0xffff0000, v18
	v_lshlrev_b32_e32 v81, 16, v19
	v_mul_f32_e32 v45, 0xbfb8aa3b, v18
	v_exp_f32_e32 v45, v45
	s_waitcnt lgkmcnt(0)
	v_pk_add_f32 v[38:39], v[38:39], v[40:41]
	ds_bpermute_b32 v41, v51, v39
	ds_bpermute_b32 v40, v51, v38
	v_mul_f32_e32 v46, 0xbfb8aa3b, v81
	v_exp_f32_e32 v47, v46
	v_and_b32_e32 v19, 0xffff0000, v19
	v_add_f32_e32 v45, 1.0, v45
	s_waitcnt lgkmcnt(0)
	v_pk_add_f32 v[38:39], v[38:39], v[40:41]
	ds_bpermute_b32 v41, v52, v39
	ds_bpermute_b32 v40, v52, v38
	v_and_b32_e32 v55, 0xffff0000, v55
	v_rcp_f32_e32 v46, v45
	v_add_f32_e32 v45, 1.0, v47
	v_mul_f32_e32 v47, 0xbfb8aa3b, v19
	s_waitcnt lgkmcnt(0)
	v_pk_add_f32 v[38:39], v[38:39], v[40:41]
	ds_bpermute_b32 v41, v53, v39
	ds_bpermute_b32 v40, v53, v38
	v_mul_f32_e32 v71, 0xbfb8aa3b, v55
	v_exp_f32_e32 v47, v47
	v_and_b32_e32 v57, 0xffff0000, v57
	v_mul_f32_e32 v72, 0xbfb8aa3b, v64
	s_waitcnt lgkmcnt(0)
	v_pk_add_f32 v[38:39], v[38:39], v[40:41]
	v_exp_f32_e32 v71, v71
	v_pk_fma_f32 v[38:39], v[38:39], s[0:1], v[242:243] op_sel_hi:[1,0,0]
	v_mul_f32_e32 v75, 0xbfb8aa3b, v57
	v_mul_f32_e32 v40, 0x4b800000, v39
	v_cmp_gt_f32_e32 vcc, s45, v39
	v_exp_f32_e32 v72, v72
	v_mul_f32_e32 v68, 0xbfb8aa3b, v62
	v_cndmask_b32_e32 v39, v39, v40, vcc
	v_rsq_f32_e32 v39, v39
	v_exp_f32_e32 v75, v75
	v_exp_f32_e32 v68, v68
	v_add_f32_e32 v40, 1.0, v47
	v_add_f32_e32 v71, 1.0, v71
	v_rcp_f32_e32 v47, v40
	v_mul_f32_e32 v40, 0x45800000, v39
	v_add_f32_e32 v72, 1.0, v72
	v_rcp_f32_e32 v71, v71
	v_cndmask_b32_e32 v40, v39, v40, vcc
	v_add_f32_e32 v75, 1.0, v75
	v_rcp_f32_e32 v72, v72
	v_pk_mul_f32 v[34:35], v[34:35], v[40:41] op_sel_hi:[1,0]
	v_add_f32_e32 v68, 1.0, v68
	v_rcp_f32_e32 v75, v75
	v_pk_mul_f32 v[14:15], v[14:15], v[34:35]
	v_pk_mul_f32 v[34:35], v[42:43], v[40:41] op_sel_hi:[1,0]
	v_rcp_f32_e32 v68, v68
	v_pk_mul_f32 v[14:15], v[14:15], v[54:55]
	v_pk_mul_f32 v[34:35], v[60:61], v[34:35]
	v_pk_mul_f32 v[32:33], v[32:33], v[40:41] op_sel_hi:[1,0]
	v_pk_mul_f32 v[36:37], v[36:37], v[40:41] op_sel_hi:[1,0]
	v_pk_mul_f32 v[14:15], v[70:71], v[14:15]
	v_pk_mul_f32 v[34:35], v[34:35], v[64:65]
	v_pk_mul_f32 v[10:11], v[10:11], v[32:33]
	v_pk_mul_f32 v[36:37], v[58:59], v[36:37]
	v_pk_mul_f32 v[34:35], v[72:73], v[34:35]
	v_pk_mul_f32 v[10:11], v[10:11], v[56:57]
	s_nop 0
	v_pk_mul_f32 v[36:37], v[36:37], v[62:63]
	v_pk_mul_f32 v[10:11], v[74:75], v[10:11]
	v_cvt_pk_bf16_f32 v15, v15, v15
	s_nop 0
	v_pk_mul_f32 v[36:37], v[68:69], v[36:37]
	s_nop 0
	s_nop 0
	v_cvt_pk_bf16_f32 v34, v34, v34
	v_cvt_pk_bf16_f32 v10, v10, v10
	v_cvt_pk_bf16_f32 v11, v11, v11
	s_nop 0
	v_lshrrev_b32_e32 v34, 16, v34
	s_nop 0
	v_cvt_pk_bf16_f32 v32, v36, v36
	v_and_or_b32 v34, v10, s36, v34
	v_mul_f32_e32 v10, 0x4b800000, v38
	v_cmp_gt_f32_e32 vcc, s45, v38
	v_cvt_pk_bf16_f32 v14, v14, v14
	v_lshrrev_b32_e32 v32, 16, v32
	v_cndmask_b32_e32 v10, v38, v10, vcc
	v_and_or_b32 v32, v14, s36, v32
	v_rsq_f32_e32 v14, v10
	s_nop 0
	v_mul_f32_e32 v44, 0xbfb8aa3b, v80
	v_cvt_pk_bf16_f32 v33, v37, v37
	v_exp_f32_e32 v44, v44
	v_lshrrev_b32_e32 v33, 16, v33
	v_and_or_b32 v33, v15, s36, v33
	v_mul_f32_e32 v15, 0x45800000, v14
	v_cndmask_b32_e32 v14, v14, v15, vcc
	v_pk_mul_f32 v[8:9], v[14:15], v[8:9] op_sel_hi:[0,1]
	v_add_f32_e32 v44, 1.0, v44
	v_pk_mul_f32 v[6:7], v[6:7], v[8:9]
	v_pk_mul_f32 v[4:5], v[14:15], v[4:5] op_sel_hi:[0,1]
	v_mov_b32_e32 v8, v0
	v_mov_b32_e32 v9, v2
	v_rcp_f32_e32 v44, v44
	v_rcp_f32_e32 v45, v45
	v_pk_mul_f32 v[4:5], v[8:9], v[4:5]
	v_pk_mul_f32 v[8:9], v[14:15], v[22:23] op_sel_hi:[0,1]
	v_mov_b32_e32 v2, v1
	s_nop 0
	v_pk_mul_f32 v[12:13], v[14:15], v[12:13] op_sel_hi:[0,1]
	v_pk_mul_f32 v[0:1], v[2:3], v[8:9]
	v_cvt_pk_bf16_f32 v35, v35, v35
	v_pk_mul_f32 v[12:13], v[78:79], v[12:13]
	v_pk_mul_f32 v[6:7], v[6:7], v[16:17]
	v_pk_mul_f32 v[0:1], v[0:1], v[18:19]
	v_lshrrev_b32_e32 v35, 16, v35
	v_add_co_u32_e64 v10, s[0:1], s7, v30
	v_pk_mul_f32 v[12:13], v[12:13], v[20:21]
	v_pk_mul_f32 v[6:7], v[76:77], v[6:7]
	v_pk_mul_f32 v[4:5], v[4:5], v[80:81]
	v_pk_mul_f32 v[0:1], v[46:47], v[0:1]
	v_and_or_b32 v35, v11, s36, v35
	v_addc_co_u32_e64 v11, s[0:1], 0, v31, s[0:1]
	v_pk_mul_f32 v[12:13], v[48:49], v[12:13]
	v_pk_mul_f32 v[4:5], v[44:45], v[4:5]
	s_nop 0
	s_nop 0
	v_bfe_u32 v8, v7, 16, 1
	v_bfe_u32 v9, v6, 16, 1
	v_add3_u32 v6, v6, v9, s48
	v_add3_u32 v7, v7, v8, s48
	v_cvt_pk_bf16_f32 v0, v0, v0
	v_cvt_pk_bf16_f32 v1, v1, v1
	s_nop 0
	s_nop 0
	v_bfe_u32 v8, v4, 16, 1
	v_bfe_u32 v9, v5, 16, 1
	s_mul_i32 s0, s4, 0x3000
	v_add3_u32 v5, v5, v9, s48
	v_add3_u32 v4, v4, v8, s48
	v_cvt_pk_bf16_f32 v3, v13, v13
	v_cvt_pk_bf16_f32 v2, v12, v12
	s_add_u32 s2, s2, s0
	s_mul_hi_i32 s0, s4, 0x3000
	v_lshrrev_b32_e32 v8, 16, v2
	v_lshrrev_b32_e32 v9, 16, v3
	v_lshrrev_b32_e32 v2, 16, v4
	v_lshrrev_b32_e32 v3, 16, v5
	s_addc_u32 s3, s3, s0
	v_and_or_b32 v3, v1, s36, v3
	v_and_or_b32 v2, v0, s36, v2
	v_and_or_b32 v1, v7, s36, v9
	v_and_or_b32 v0, v6, s36, v8
	s_cmpk_lt_i32 s6, 0x2240
	global_store_dwordx4 v[10:11], v[32:35], off offset:2048
	global_store_dwordx4 v[10:11], v[0:3], off offset:3072
	s_cbranch_scc0 .LBB0_1613
.LBB0_1609:
	s_cmpk_lt_i32 s6, 0x2040
	s_cselect_b64 s[0:1], -1, 0
	s_cmpk_gt_i32 s6, 0x203f
	v_lshl_add_u64 v[4:5], s[12:13], 0, v[96:97]
	v_lshl_add_u64 v[30:31], s[8:9], 0, v[96:97]
	s_cbranch_scc1 .LBB0_1611
	v_add_co_u32_e32 v98, vcc, 0x33812000, v4
	s_nop 1
	v_addc_co_u32_e32 v99, vcc, 0, v5, vcc
	v_add_co_u32_e32 v100, vcc, 0x326f2000, v4
	global_load_dwordx4 v[102:105], v[98:99], off
	s_nop 1
	v_addc_co_u32_e32 v101, vcc, 0, v5, vcc
	global_load_dwordx4 v[106:109], v[100:101], off
	v_add_co_u32_e32 v100, vcc, s5, v4
	s_nop 1
	v_addc_co_u32_e32 v101, vcc, 0, v5, vcc
	global_load_dwordx4 v[110:113], v[100:101], off
	global_load_dwordx4 v[114:117], v[28:29], off offset:16
	global_load_dwordx4 v[118:121], v[28:29], off
	v_add_co_u32_e32 v0, vcc, 0x33812000, v4
	s_nop 1
	v_addc_co_u32_e32 v1, vcc, 0, v5, vcc
	v_add_co_u32_e32 v6, vcc, 0x326f2000, v4
	s_waitcnt vmcnt(0)
	v_mov_b64_e32 v[0:1], v[102:103]
	v_mov_b64_e32 v[2:3], v[104:105]
	s_nop 0
	v_addc_co_u32_e32 v7, vcc, 0, v5, vcc
	v_mov_b64_e32 v[6:7], v[106:107]
	v_mov_b64_e32 v[8:9], v[108:109]
	s_waitcnt vmcnt(0)
	v_lshlrev_b32_e32 v35, 16, v2
	v_lshlrev_b32_e32 v34, 16, v0
	v_and_b32_e32 v37, 0xffff0000, v2
	v_lshlrev_b32_e32 v18, 16, v6
	v_and_b32_e32 v19, 0xffff0000, v6
	v_add_co_u32_e32 v6, vcc, s5, v4
	v_lshlrev_b32_e32 v20, 16, v7
	v_and_b32_e32 v21, 0xffff0000, v7
	v_addc_co_u32_e32 v7, vcc, 0, v5, vcc
	v_lshlrev_b32_e32 v22, 16, v8
	v_and_b32_e32 v23, 0xffff0000, v8
	v_lshlrev_b32_e32 v32, 16, v9
	v_and_b32_e32 v33, 0xffff0000, v9
	v_mov_b64_e32 v[6:7], v[110:111]
	v_mov_b64_e32 v[8:9], v[112:113]
	s_nop 0
	v_mov_b64_e32 v[10:11], v[114:115]
	v_mov_b64_e32 v[12:13], v[116:117]
	v_mov_b64_e32 v[14:15], v[118:119]
	v_mov_b64_e32 v[16:17], v[120:121]
	v_and_b32_e32 v36, 0xffff0000, v0
	v_lshlrev_b32_e32 v39, 16, v3
	v_lshlrev_b32_e32 v38, 16, v1
	v_and_b32_e32 v2, 0xffff0000, v1
	v_pk_add_f32 v[0:1], v[34:35], v[36:37]
	v_and_b32_e32 v3, 0xffff0000, v3
	v_pk_add_f32 v[0:1], v[0:1], v[38:39]
	s_nop 0
	v_pk_add_f32 v[0:1], v[0:1], v[2:3]
	s_nop 0
	v_add_f32_e32 v0, v0, v1
	ds_bpermute_b32 v1, v50, v0
	s_waitcnt lgkmcnt(0)
	v_add_f32_e32 v0, v0, v1
	ds_bpermute_b32 v1, v51, v0
	s_waitcnt lgkmcnt(0)
	v_add_f32_e32 v0, v0, v1
	ds_bpermute_b32 v1, v52, v0
	s_waitcnt lgkmcnt(0)
	v_add_f32_e32 v0, v0, v1
	v_fmac_f32_e32 v36, 0xbc800000, v0
	v_fmac_f32_e32 v37, 0xbc800000, v0
	v_fmac_f32_e32 v34, 0xbc800000, v0
	v_fmac_f32_e32 v35, 0xbc800000, v0
	v_mov_b32_e32 v1, v37
	v_mov_b32_e32 v41, v36
	v_pk_mul_f32 v[36:37], v[36:37], v[36:37]
	v_fmac_f32_e32 v2, 0xbc800000, v0
	v_fmac_f32_e32 v38, 0xbc800000, v0
	v_fmac_f32_e32 v3, 0xbc800000, v0
	v_fmac_f32_e32 v39, 0xbc800000, v0
	v_mov_b32_e32 v0, v35
	v_mov_b32_e32 v40, v34
	v_pk_fma_f32 v[34:35], v[34:35], v[34:35], v[36:37]
	v_mov_b32_e32 v37, v3
	v_pk_fma_f32 v[34:35], v[38:39], v[38:39], v[34:35]
	v_mov_b32_e32 v43, v2
	v_pk_fma_f32 v[2:3], v[2:3], v[2:3], v[34:35]
	v_mov_b32_e32 v42, v38
	v_add_f32_e32 v2, v2, v3
	ds_bpermute_b32 v3, v50, v2
	v_mov_b32_e32 v36, v39
	s_waitcnt lgkmcnt(0)
	v_add_f32_e32 v2, v2, v3
	ds_bpermute_b32 v3, v51, v2
	s_waitcnt lgkmcnt(0)
	v_add_f32_e32 v2, v2, v3
	ds_bpermute_b32 v3, v52, v2
	s_waitcnt lgkmcnt(0)
	v_add_f32_e32 v2, v2, v3
	v_fmamk_f32 v2, v2, 0x3c800000, v231
	v_cmp_gt_f32_e32 vcc, s45, v2
	v_mul_f32_e32 v3, 0x4b800000, v2
	s_nop 0
	v_cndmask_b32_e32 v2, v2, v3, vcc
	v_rsq_f32_e32 v2, v2
	s_nop 0
	v_mul_f32_e32 v3, 0x45800000, v2
	v_cndmask_b32_e32 v2, v2, v3, vcc
	v_pk_mul_f32 v[34:35], v[42:43], v[2:3] op_sel_hi:[1,0]
	v_pk_mul_f32 v[38:39], v[40:41], v[2:3] op_sel_hi:[1,0]
	s_waitcnt vmcnt(0)
	v_pk_fma_f32 v[16:17], v[16:17], v[34:35], v[20:21]
	v_pk_fma_f32 v[14:15], v[14:15], v[38:39], v[18:19]
	v_pk_mul_f32 v[18:19], v[36:37], v[2:3] op_sel_hi:[1,0]
	v_pk_mul_f32 v[0:1], v[0:1], v[2:3] op_sel_hi:[1,0]
	v_pk_fma_f32 v[2:3], v[12:13], v[18:19], v[32:33]
	v_pk_fma_f32 v[0:1], v[10:11], v[0:1], v[22:23]
	v_lshlrev_b32_e32 v11, 16, v7
	v_lshlrev_b32_e32 v10, 16, v6
	v_mov_b32_e32 v12, v14
	v_mov_b32_e32 v13, v16
	v_pk_mul_f32 v[10:11], v[12:13], v[10:11]
	v_and_b32_e32 v7, 0xffff0000, v7
	v_and_b32_e32 v6, 0xffff0000, v6
	v_mov_b32_e32 v16, v15
	v_lshlrev_b32_e32 v13, 16, v9
	v_lshlrev_b32_e32 v12, 16, v8
	v_mov_b32_e32 v15, v2
	v_and_b32_e32 v9, 0xffff0000, v9
	v_and_b32_e32 v8, 0xffff0000, v8
	v_mov_b32_e32 v2, v1
	v_pk_mul_f32 v[6:7], v[16:17], v[6:7]
	v_mov_b32_e32 v14, v0
	v_pk_mul_f32 v[0:1], v[2:3], v[8:9]
	v_pk_mul_f32 v[12:13], v[14:15], v[12:13]
	s_nop 0
	s_nop 0
	s_nop 0
	s_nop 0
	v_cvt_pk_bf16_f32 v7, v7, v7
	v_cvt_pk_bf16_f32 v1, v1, v1
	s_nop 0
	s_nop 0
	v_cvt_pk_bf16_f32 v6, v6, v6
	v_cvt_pk_bf16_f32 v0, v0, v0
	s_nop 0
	s_nop 0
	v_cvt_pk_bf16_f32 v8, v12, v12
	v_cvt_pk_bf16_f32 v2, v10, v10
	v_cvt_pk_bf16_f32 v9, v13, v13
	v_cvt_pk_bf16_f32 v3, v11, v11
	v_lshrrev_b32_e32 v10, 16, v2
	v_lshrrev_b32_e32 v2, 16, v8
	v_lshrrev_b32_e32 v11, 16, v3
	v_lshrrev_b32_e32 v3, 16, v9
	v_and_or_b32 v2, v0, s36, v2
	v_and_or_b32 v0, v6, s36, v10
	v_add_co_u32_e32 v6, vcc, 0x25500000, v30
	v_and_or_b32 v3, v1, s36, v3
	v_and_or_b32 v1, v7, s36, v11
	v_addc_co_u32_e32 v7, vcc, 0, v31, vcc
	global_store_dwordx4 v[6:7], v[0:3], off

.LBB0_2000:
	v_lshlrev_b64 v[8:9], 2, v[68:69]
	v_lshl_add_u64 v[12:13], s[56:57], 0, v[8:9]
	v_lshl_add_u64 v[16:17], s[4:5], 0, v[8:9]
	v_lshl_add_u64 v[20:21], s[6:7], 0, v[8:9]
	v_lshl_add_u64 v[36:37], s[58:59], 0, v[8:9]
	global_load_dwordx4 v[8:11], v[12:13], off offset:16
	global_load_dwordx4 v[24:27], v[12:13], off
	s_nop 0
	global_load_dwordx4 v[12:15], v[16:17], off offset:16
	global_load_dwordx4 v[28:31], v[16:17], off
	s_nop 0
	global_load_dwordx4 v[16:19], v[20:21], off offset:16
	global_load_dwordx4 v[32:35], v[20:21], off
	s_nop 0
	global_load_dwordx4 v[20:23], v[36:37], off offset:16
	s_nop 0
	global_load_dwordx4 v[36:39], v[36:37], off
	s_waitcnt vmcnt(0)
	v_lshlrev_b32_e32 v60, 16, v52
	v_and_b32_e32 v58, 0xffff0000, v52
	v_lshlrev_b32_e32 v61, 16, v53
	v_and_b32_e32 v59, 0xffff0000, v53
	v_lshlrev_b32_e32 v56, 16, v54
	v_and_b32_e32 v52, 0xffff0000, v54
	v_lshlrev_b32_e32 v57, 16, v55
	v_and_b32_e32 v53, 0xffff0000, v55
	v_lshlrev_b32_e32 v63, 16, v49
	v_lshlrev_b32_e32 v62, 16, v48
	v_and_b32_e32 v73, 0xffff0000, v49
	v_and_b32_e32 v72, 0xffff0000, v48
	v_lshl_add_u64 v[48:49], v[68:69], 1, s[8:9]
	v_lshlrev_b32_e32 v69, 16, v41
	v_lshlrev_b32_e32 v68, 16, v40
	v_and_b32_e32 v75, 0xffff0000, v41
	v_and_b32_e32 v74, 0xffff0000, v40
	v_lshlrev_b32_e32 v71, 16, v51
	v_lshlrev_b32_e32 v70, 16, v50
	v_and_b32_e32 v67, 0xffff0000, v51
	v_and_b32_e32 v66, 0xffff0000, v50
	v_lshlrev_b32_e32 v51, 16, v45
	v_lshlrev_b32_e32 v50, 16, v44
	v_and_b32_e32 v45, 0xffff0000, v45
	v_and_b32_e32 v44, 0xffff0000, v44
	v_mov_b32_e32 v40, v24
	v_mov_b32_e32 v41, v26
	v_mov_b32_e32 v26, v25
	v_mov_b32_e32 v64, v28
	v_mov_b32_e32 v65, v30
	v_mov_b32_e32 v30, v29
	v_mov_b32_e32 v54, v36
	v_mov_b32_e32 v55, v38
	v_mov_b32_e32 v38, v37
	v_pk_fma_f32 v[62:63], v[40:41], v[62:63], v[54:55]
	v_pk_fma_f32 v[36:37], v[26:27], v[72:73], v[38:39]
	v_pk_fma_f32 v[76:77], v[64:65], v[60:61], v[62:63]
	v_mov_b32_e32 v63, v34
	v_pk_fma_f32 v[28:29], v[30:31], v[58:59], v[36:37]
	v_mov_b32_e32 v34, v33
	v_pk_fma_f32 v[28:29], v[34:35], v[44:45], v[28:29]
	v_mov_b32_e32 v62, v32
	v_mul_f32_e32 v25, 0x3d372713, v28
	v_mul_f32_e32 v25, v28, v25
	v_fma_f32 v25, v28, v25, v28
	v_mul_f32_e32 v25, 0xbfcc422a, v25
	v_mul_f32_e32 v25, 0x3fb8aa3b, v25
	v_exp_f32_e32 v25, v25
	v_pk_fma_f32 v[76:77], v[62:63], v[50:51], v[76:77]
	v_mul_f32_e32 v33, 0x3d372713, v29
	v_mul_f32_e32 v24, 0x3d372713, v76
	v_add_f32_e32 v25, 1.0, v25
	v_rcp_f32_e32 v32, v25
	v_mul_f32_e32 v25, 0x3d372713, v77
	v_mul_f32_e32 v24, v76, v24
	v_mul_f32_e32 v25, v77, v25
	v_mul_f32_e32 v33, v29, v33
	v_fma_f32 v24, v76, v24, v76
	v_fma_f32 v25, v77, v25, v77
	v_fma_f32 v33, v29, v33, v29
	v_mul_f32_e32 v24, 0xbfcc422a, v24
	v_mul_f32_e32 v25, 0xbfcc422a, v25
	v_mul_f32_e32 v33, 0xbfcc422a, v33
	v_mul_f32_e32 v24, 0x3fb8aa3b, v24
	v_mul_f32_e32 v25, 0x3fb8aa3b, v25
	v_mul_f32_e32 v33, 0x3fb8aa3b, v33
	v_exp_f32_e32 v24, v24
	v_exp_f32_e32 v25, v25
	v_exp_f32_e32 v33, v33
	v_lshlrev_b32_e32 v37, 16, v47
	v_add_f32_e32 v24, 1.0, v24
	v_add_f32_e32 v25, 1.0, v25
	v_add_f32_e32 v33, 1.0, v33
	v_rcp_f32_e32 v24, v24
	v_rcp_f32_e32 v25, v25
	v_rcp_f32_e32 v33, v33
	v_lshlrev_b32_e32 v36, 16, v46
	v_pk_mul_f32 v[24:25], v[76:77], v[24:25]
	v_pk_mul_f32 v[28:29], v[28:29], v[32:33]
	v_pk_mul_f32 v[24:25], v[24:25], v[68:69]
	v_pk_mul_f32 v[28:29], v[28:29], v[74:75]
	v_and_b32_e32 v33, 0xffff0000, v47
	v_and_b32_e32 v32, 0xffff0000, v46
	v_lshlrev_b32_e32 v75, 16, v43
	v_lshlrev_b32_e32 v74, 16, v42
	v_and_b32_e32 v47, 0xffff0000, v43
	v_and_b32_e32 v46, 0xffff0000, v42
	v_mov_b32_e32 v42, v8
	v_mov_b32_e32 v43, v10
	v_mov_b32_e32 v68, v20
	v_mov_b32_e32 v69, v22
	v_mov_b32_e32 v10, v9
	v_mov_b32_e32 v22, v21
	v_pk_fma_f32 v[72:73], v[42:43], v[70:71], v[68:69]
	v_mov_b32_e32 v70, v12
	v_mov_b32_e32 v71, v14
	v_pk_fma_f32 v[20:21], v[10:11], v[66:67], v[22:23]
	v_mov_b32_e32 v14, v13
	v_pk_fma_f32 v[76:77], v[70:71], v[56:57], v[72:73]
	v_mov_b32_e32 v73, v18
	v_pk_fma_f32 v[12:13], v[14:15], v[52:53], v[20:21]
	v_mov_b32_e32 v18, v17
	v_pk_fma_f32 v[12:13], v[18:19], v[32:33], v[12:13]
	v_mov_b32_e32 v72, v16
	v_mul_f32_e32 v9, 0x3d372713, v12
	v_mul_f32_e32 v9, v12, v9
	v_fma_f32 v9, v12, v9, v12
	v_mul_f32_e32 v9, 0xbfcc422a, v9
	v_mul_f32_e32 v9, 0x3fb8aa3b, v9
	v_exp_f32_e32 v9, v9
	v_pk_fma_f32 v[76:77], v[72:73], v[36:37], v[76:77]
	v_mul_f32_e32 v17, 0x3d372713, v13
	v_mul_f32_e32 v8, 0x3d372713, v76
	v_add_f32_e32 v9, 1.0, v9
	v_rcp_f32_e32 v16, v9
	v_mul_f32_e32 v9, 0x3d372713, v77
	v_mul_f32_e32 v17, v13, v17
	v_mul_f32_e32 v8, v76, v8
	v_mul_f32_e32 v9, v77, v9
	v_fma_f32 v17, v13, v17, v13
	v_fma_f32 v8, v76, v8, v76
	v_fma_f32 v9, v77, v9, v77
	v_mul_f32_e32 v17, 0xbfcc422a, v17
	v_mul_f32_e32 v8, 0xbfcc422a, v8
	v_mul_f32_e32 v9, 0xbfcc422a, v9
	v_mul_f32_e32 v17, 0x3fb8aa3b, v17
	v_mul_f32_e32 v8, 0x3fb8aa3b, v8
	v_mul_f32_e32 v9, 0x3fb8aa3b, v9
	v_exp_f32_e32 v17, v17
	v_exp_f32_e32 v8, v8
	v_exp_f32_e32 v9, v9
	v_bfe_u32 v20, v29, 16, 1
	v_add_f32_e32 v17, 1.0, v17
	v_add_f32_e32 v8, 1.0, v8
	v_add_f32_e32 v9, 1.0, v9
	v_rcp_f32_e32 v17, v17
	v_rcp_f32_e32 v8, v8
	v_rcp_f32_e32 v9, v9
	s_nop 0
	v_pk_mul_f32 v[12:13], v[12:13], v[16:17]
	v_cvt_pk_bf16_f32 v21, v28, v28
	v_pk_mul_f32 v[8:9], v[76:77], v[8:9]
	v_pk_mul_f32 v[12:13], v[12:13], v[46:47]
	v_pk_mul_f32 v[8:9], v[8:9], v[74:75]
	s_nop 0
	s_nop 0
	v_add3_u32 v20, v29, v20, s48
	v_cvt_pk_bf16_f32 v12, v12, v12
	v_cvt_pk_bf16_f32 v13, v13, v13
	s_nop 0
	s_nop 0
	s_nop 0
	s_nop 0
	v_cvt_pk_bf16_f32 v9, v9, v9
	v_cvt_pk_bf16_f32 v8, v8, v8
	v_cvt_pk_bf16_f32 v17, v25, v25
	v_cvt_pk_bf16_f32 v16, v24, v24
	v_lshrrev_b32_e32 v16, 16, v16
	v_lshrrev_b32_e32 v17, 16, v17
	v_lshrrev_b32_e32 v8, 16, v8
	v_lshrrev_b32_e32 v9, 16, v9
	v_mov_b32_e32 v24, 0x2b00
	v_and_or_b32 v77, v13, s36, v9
	v_and_or_b32 v76, v12, s36, v8
	v_and_or_b32 v75, v20, s36, v17
	v_and_or_b32 v74, v21, s36, v16
	v_mad_i64_i32 v[8:9], s[24:25], s12, v24, v[48:49]
	v_pk_fma_f32 v[20:21], v[26:27], v[58:59], v[38:39]
	global_store_dwordx4 v[8:9], v[74:77], off
	v_lshlrev_b32_e32 v9, 16, v5
	v_lshlrev_b32_e32 v8, 16, v4
	v_and_b32_e32 v5, 0xffff0000, v5
	v_and_b32_e32 v4, 0xffff0000, v4
	v_pk_fma_f32 v[16:17], v[40:41], v[60:61], v[54:55]
	v_pk_fma_f32 v[20:21], v[30:31], v[44:45], v[20:21]
	v_pk_fma_f32 v[16:17], v[64:65], v[50:51], v[16:17]
	v_pk_fma_f32 v[4:5], v[34:35], v[4:5], v[20:21]
	v_pk_fma_f32 v[8:9], v[62:63], v[8:9], v[16:17]
	v_mul_f32_e32 v17, 0x3d372713, v4
	v_mul_f32_e32 v17, v4, v17
	v_fma_f32 v17, v4, v17, v4
	v_mul_f32_e32 v17, 0xbfcc422a, v17
	v_mul_f32_e32 v17, 0x3fb8aa3b, v17
	v_exp_f32_e32 v17, v17
	v_mul_f32_e32 v16, 0x3d372713, v8
	v_mul_f32_e32 v16, v8, v16
	v_fma_f32 v16, v8, v16, v8
	v_add_f32_e32 v17, 1.0, v17
	v_rcp_f32_e32 v20, v17
	v_mul_f32_e32 v17, 0x3d372713, v9
	v_mul_f32_e32 v17, v9, v17
	v_fma_f32 v17, v9, v17, v9
	v_mul_f32_e32 v16, 0xbfcc422a, v16
	v_mul_f32_e32 v17, 0xbfcc422a, v17
	v_mul_f32_e32 v16, 0x3fb8aa3b, v16
	v_mul_f32_e32 v17, 0x3fb8aa3b, v17
	v_exp_f32_e32 v16, v16
	v_exp_f32_e32 v17, v17
	v_lshlrev_b32_e32 v13, 16, v1
	v_lshlrev_b32_e32 v12, 16, v0
	v_add_f32_e32 v16, 1.0, v16
	v_add_f32_e32 v17, 1.0, v17
	v_rcp_f32_e32 v16, v16
	v_rcp_f32_e32 v17, v17
	v_and_b32_e32 v1, 0xffff0000, v1
	v_and_b32_e32 v0, 0xffff0000, v0
	v_pk_fma_f32 v[10:11], v[10:11], v[52:53], v[22:23]
	v_pk_mul_f32 v[8:9], v[8:9], v[16:17]
	v_pk_fma_f32 v[16:17], v[42:43], v[56:57], v[68:69]
	v_pk_mul_f32 v[8:9], v[8:9], v[12:13]
	v_mul_f32_e32 v12, 0x3d372713, v5
	v_mul_f32_e32 v12, v5, v12
	v_fma_f32 v12, v5, v12, v5
	v_mul_f32_e32 v12, 0xbfcc422a, v12
	v_mul_f32_e32 v12, 0x3fb8aa3b, v12
	v_exp_f32_e32 v12, v12
	v_pk_fma_f32 v[16:17], v[70:71], v[36:37], v[16:17]
	v_pk_fma_f32 v[10:11], v[14:15], v[32:33], v[10:11]
	v_lshlrev_b32_e32 v13, 16, v3
	v_add_f32_e32 v12, 1.0, v12
	v_rcp_f32_e32 v21, v12
	v_lshlrev_b32_e32 v12, 16, v2
	v_and_b32_e32 v3, 0xffff0000, v3
	v_and_b32_e32 v2, 0xffff0000, v2
	v_pk_mul_f32 v[4:5], v[4:5], v[20:21]
	s_or_b32 s12, s12, 1
	v_pk_mul_f32 v[0:1], v[4:5], v[0:1]
	v_lshlrev_b32_e32 v5, 16, v7
	v_lshlrev_b32_e32 v4, 16, v6
	v_and_b32_e32 v7, 0xffff0000, v7
	v_and_b32_e32 v6, 0xffff0000, v6
	v_pk_fma_f32 v[4:5], v[72:73], v[4:5], v[16:17]
	v_pk_fma_f32 v[6:7], v[18:19], v[6:7], v[10:11]
	v_mul_f32_e32 v11, 0x3d372713, v5
	v_mul_f32_e32 v11, v5, v11
	v_fma_f32 v11, v5, v11, v5
	v_mul_f32_e32 v11, 0xbfcc422a, v11
	v_mul_f32_e32 v11, 0x3fb8aa3b, v11
	v_exp_f32_e32 v11, v11
	v_mul_f32_e32 v10, 0x3d372713, v6
	v_mul_f32_e32 v16, 0x3d372713, v4
	v_mul_f32_e32 v10, v6, v10
	v_add_f32_e32 v11, 1.0, v11
	v_rcp_f32_e32 v17, v11
	v_mul_f32_e32 v11, 0x3d372713, v7
	v_mul_f32_e32 v11, v7, v11
	v_mul_f32_e32 v16, v4, v16
	v_fma_f32 v10, v6, v10, v6
	v_fma_f32 v11, v7, v11, v7
	v_fma_f32 v16, v4, v16, v4
	v_mul_f32_e32 v10, 0xbfcc422a, v10
	v_mul_f32_e32 v11, 0xbfcc422a, v11
	v_mul_f32_e32 v16, 0xbfcc422a, v16
	v_mul_f32_e32 v10, 0x3fb8aa3b, v10
	v_mul_f32_e32 v11, 0x3fb8aa3b, v11
	v_mul_f32_e32 v16, 0x3fb8aa3b, v16
	v_exp_f32_e32 v10, v10
	v_exp_f32_e32 v11, v11
	v_exp_f32_e32 v16, v16
	v_add_f32_e32 v10, 1.0, v10
	v_add_f32_e32 v11, 1.0, v11
	v_add_f32_e32 v16, 1.0, v16
	v_rcp_f32_e32 v10, v10
	v_rcp_f32_e32 v11, v11
	v_rcp_f32_e32 v16, v16
	v_pk_mul_f32 v[6:7], v[6:7], v[10:11]
	v_pk_mul_f32 v[4:5], v[4:5], v[16:17]
	v_pk_mul_f32 v[2:3], v[6:7], v[2:3]
	v_pk_mul_f32 v[4:5], v[4:5], v[12:13]
	s_nop 0
	s_nop 0
	s_nop 0
	s_nop 0
	v_cvt_pk_bf16_f32 v0, v0, v0
	v_cvt_pk_bf16_f32 v1, v1, v1
	v_cvt_pk_bf16_f32 v2, v2, v2
	v_cvt_pk_bf16_f32 v3, v3, v3
	s_nop 0
	s_nop 0
	s_nop 0
	s_nop 0
	v_cvt_pk_bf16_f32 v5, v5, v5
	v_cvt_pk_bf16_f32 v4, v4, v4
	v_cvt_pk_bf16_f32 v7, v9, v9
	v_cvt_pk_bf16_f32 v6, v8, v8
	v_lshrrev_b32_e32 v6, 16, v6
	v_lshrrev_b32_e32 v7, 16, v7
	v_lshrrev_b32_e32 v4, 16, v4
	v_lshrrev_b32_e32 v5, 16, v5
	v_and_or_b32 v3, v3, s36, v5
	v_and_or_b32 v2, v2, s36, v4
	v_and_or_b32 v1, v1, s36, v7
	v_and_or_b32 v0, v0, s36, v6
	v_mad_i64_i32 v[4:5], s[12:13], s12, v24, v[48:49]
	global_store_dwordx4 v[4:5], v[0:3], off

.LBB0_2002:
	s_mul_hi_i32 s10, s0, 0x2e8ba2e9
	v_mov_b32_e32 v0, v96
	s_lshr_b32 s11, s10, 31
	s_ashr_i32 s24, s10, 1
	s_add_i32 s24, s24, s11
	v_lshlrev_b32_e32 v0, 3, v0
	s_mul_i32 s10, s24, 0x1600
	v_subrev_u32_e32 v0, s10, v0
	v_add_u32_e32 v68, s22, v0
	v_cmp_gt_i32_e32 vcc, s49, v68
	s_and_saveexec_b64 s[10:11], vcc
	s_cbranch_execz .LBB0_2001
	s_mov_b64 s[12:13], -1
	s_cmpk_gt_i32 s0, 0x58a
	v_ashrrev_i32_e32 v69, 31, v68
	s_cbranch_scc0 .LBB0_2009
	v_lshlrev_b64 v[80:81], 1, v[68:69]
	v_lshlrev_b64 v[82:83], 2, v[68:69]
	s_cmpk_gt_u32 s0, 0x5ab
	v_lshl_add_u64 v[78:79], s[56:57], 0, v[82:83]
	v_lshl_add_u64 v[76:77], s[4:5], 0, v[82:83]
	v_lshl_add_u64 v[74:75], s[6:7], 0, v[82:83]
	v_lshl_add_u64 v[72:73], s[58:59], 0, v[82:83]
	v_lshl_add_u64 v[70:71], s[8:9], 0, v[80:81]
	s_cbranch_scc0 .LBB0_2006
	s_lshl_b32 s25, s24, 2
	s_addk_i32 s25, 0x1e30
	s_mul_i32 s38, s25, 0x2b00
	s_lshl_b64 s[12:13], s[38:39], 1
	s_add_u32 s12, s16, s12
	s_addc_u32 s13, s17, s13
	s_add_i32 s26, s24, 0xffffff7c
	v_lshl_add_u64 v[6:7], s[2:3], 0, v[82:83]
	v_mov_b32_e32 v8, 0xac00
	v_lshl_add_u64 v[40:41], s[12:13], 0, v[80:81]
	v_mad_u64_u32 v[16:17], s[12:13], s26, v8, v[6:7]
	global_load_dwordx4 v[0:3], v[78:79], off
	global_load_dwordx4 v[24:27], v[72:73], off
	global_load_dwordx4 v[98:101], v[16:17], off
	global_load_dwordx4 v[64:67], v[40:41], off
	v_add_co_u32_e32 v4, vcc, s74, v40
	s_movk_i32 s29, 0x5000
	s_nop 0
	v_addc_co_u32_e32 v5, vcc, 0, v41, vcc
	v_add_co_u32_e32 v6, vcc, s29, v16
	s_mov_b32 s12, 0x12000
	s_nop 0
	v_addc_co_u32_e32 v7, vcc, 0, v17, vcc
	global_load_dwordx4 v[56:59], v[6:7], off offset:1536
	global_load_dwordx4 v[102:105], v[4:5], off offset:2816
	global_load_dwordx4 v[32:35], v[76:77], off
	global_load_dwordx4 v[36:39], v[74:75], off
	s_nop 0
	global_load_dwordx4 v[4:7], v[78:79], off offset:16
	global_load_dwordx4 v[8:11], v[76:77], off offset:16
	global_load_dwordx4 v[12:15], v[74:75], off offset:16
	global_load_dwordx4 v[20:23], v[72:73], off offset:16
	v_add_co_u32_e32 v18, vcc, s75, v40
	global_load_dwordx4 v[106:109], v[16:17], off offset:16
	s_nop 0
	v_addc_co_u32_e32 v19, vcc, 0, v41, vcc
	v_add_co_u32_e32 v42, vcc, s12, v40
	s_mov_b64 s[12:13], 0x5600
	s_nop 0
	v_addc_co_u32_e32 v43, vcc, 0, v41, vcc
	v_lshl_add_u64 v[44:45], v[16:17], 0, s[12:13]
	global_load_dwordx4 v[28:31], v[18:19], off offset:512
	s_nop 0
	global_load_dwordx4 v[16:19], v[42:43], off offset:3328
	global_load_dwordx4 v[52:55], v[44:45], off offset:16
	v_add_co_u32_e32 v46, vcc, s29, v40
	s_mov_b32 s28, 0x8000
	s_nop 0
	v_addc_co_u32_e32 v47, vcc, 0, v41, vcc
	v_add_co_u32_e32 v42, vcc, s28, v40
	s_mul_hi_u32 s27, s26, 0xac00
	s_nop 0
	v_addc_co_u32_e32 v43, vcc, 0, v41, vcc
	global_load_dwordx4 v[60:63], v[46:47], off offset:1536
	global_load_dwordx4 v[48:51], v[42:43], off offset:256
	s_mul_i32 s26, s26, 0xac00
	v_add_co_u32_e32 v44, vcc, s79, v40
	s_add_u32 s12, s26, s14
	s_nop 0
	v_addc_co_u32_e32 v45, vcc, 0, v41, vcc
	s_mov_b32 s26, 0xd000
	v_add_co_u32_e32 v40, vcc, s26, v40
	s_mul_i32 s38, s25, 0x1580
	s_nop 0
	v_addc_co_u32_e32 v41, vcc, 0, v41, vcc
	global_load_dwordx4 v[44:47], v[44:45], off offset:3072
	s_nop 0
	global_load_dwordx4 v[40:43], v[40:41], off offset:1792
	s_addc_u32 s13, s27, s1
	s_add_u32 s26, s18, s12
	s_addc_u32 s27, s19, s13
	s_add_u32 s12, s20, s12
	s_addc_u32 s13, s21, s13
	s_waitcnt vmcnt(0)
	v_mov_b32_e32 v85, v2
	v_mov_b32_e32 v86, v24
	v_pk_fma_f32 v[94:95], v[100:101], v[2:3], v[26:27]
	v_pk_fma_f32 v[98:99], v[98:99], v[0:1], v[24:25]
	v_lshlrev_b32_e32 v93, 16, v65
	v_lshlrev_b32_e32 v92, 16, v64
	v_and_b32_e32 v91, 0xffff0000, v65
	v_and_b32_e32 v90, 0xffff0000, v64
	v_mov_b32_e32 v88, v98
	v_mov_b32_e32 v89, v94
	v_mov_b32_e32 v110, v56
	v_mov_b32_e32 v111, v58
	v_mov_b32_e32 v64, v32
	v_mov_b32_e32 v65, v34
	v_mov_b32_e32 v94, v99
	v_mov_b32_e32 v58, v57
	v_mov_b32_e32 v34, v33
	v_pk_fma_f32 v[112:113], v[110:111], v[64:65], v[88:89]
	v_mov_b32_e32 v89, v38
	v_pk_fma_f32 v[32:33], v[58:59], v[34:35], v[94:95]
	v_mov_b32_e32 v38, v37
	v_pk_fma_f32 v[32:33], v[38:39], v[90:91], v[32:33]
	v_mov_b32_e32 v88, v36
	v_mul_f32_e32 v2, 0x3d372713, v32
	v_mul_f32_e32 v2, v32, v2
	v_fma_f32 v2, v32, v2, v32
	v_mul_f32_e32 v2, 0xbfcc422a, v2
	v_mul_f32_e32 v2, 0x3fb8aa3b, v2
	v_exp_f32_e32 v24, v2
	v_pk_fma_f32 v[112:113], v[88:89], v[92:93], v[112:113]
	v_mov_b32_e32 v84, v0
	v_mul_f32_e32 v0, 0x3d372713, v112
	v_mov_b32_e32 v2, v1
	v_add_f32_e32 v1, 1.0, v24
	v_mul_f32_e32 v24, 0x3d372713, v113
	v_mov_b32_e32 v87, v26
	v_mul_f32_e32 v0, v112, v0
	v_mul_f32_e32 v24, v113, v24
	v_mul_f32_e32 v26, 0x3d372713, v33
	v_fma_f32 v0, v112, v0, v112
	v_fma_f32 v24, v113, v24, v113
	v_mul_f32_e32 v26, v33, v26
	v_mul_f32_e32 v0, 0xbfcc422a, v0
	v_mul_f32_e32 v24, 0xbfcc422a, v24
	v_fma_f32 v26, v33, v26, v33
	v_mul_f32_e32 v0, 0x3fb8aa3b, v0
	v_mul_f32_e32 v24, 0x3fb8aa3b, v24
	v_mul_f32_e32 v26, 0xbfcc422a, v26
	v_exp_f32_e32 v0, v0
	v_exp_f32_e32 v24, v24
	v_mul_f32_e32 v26, 0x3fb8aa3b, v26
	v_exp_f32_e32 v26, v26
	v_add_f32_e32 v0, 1.0, v0
	v_rcp_f32_e32 v36, v1
	v_add_f32_e32 v1, 1.0, v24
	v_rcp_f32_e32 v0, v0
	v_rcp_f32_e32 v1, v1
	v_add_f32_e32 v24, 1.0, v26
	v_rcp_f32_e32 v37, v24
	v_lshlrev_b32_e32 v101, 16, v103
	v_lshlrev_b32_e32 v100, 16, v102
	v_pk_mul_f32 v[0:1], v[112:113], v[0:1]
	v_and_b32_e32 v103, 0xffff0000, v103
	v_and_b32_e32 v102, 0xffff0000, v102
	v_pk_mul_f32 v[98:99], v[0:1], v[100:101]
	v_pk_mul_f32 v[0:1], v[32:33], v[36:37]
	v_lshlrev_b32_e32 v95, 16, v67
	v_pk_mul_f32 v[100:101], v[0:1], v[102:103]
	v_lshlrev_b32_e32 v94, 16, v66
	v_and_b32_e32 v57, 0xffff0000, v67
	v_and_b32_e32 v56, 0xffff0000, v66
	v_lshlrev_b32_e32 v67, 16, v105
	v_lshlrev_b32_e32 v66, 16, v104
	v_and_b32_e32 v103, 0xffff0000, v105
	v_and_b32_e32 v102, 0xffff0000, v104
	v_pk_fma_f32 v[104:105], v[108:109], v[6:7], v[22:23]
	v_pk_fma_f32 v[106:107], v[106:107], v[4:5], v[20:21]
	v_mov_b32_e32 v37, v104
	v_mov_b32_e32 v36, v106
	v_mov_b32_e32 v108, v52
	v_mov_b32_e32 v109, v54
	v_mov_b32_e32 v32, v8
	v_mov_b32_e32 v33, v10
	v_mov_b32_e32 v104, v107
	v_mov_b32_e32 v54, v53
	v_mov_b32_e32 v10, v9
	v_pk_fma_f32 v[112:113], v[108:109], v[32:33], v[36:37]
	v_mov_b32_e32 v37, v14
	v_pk_fma_f32 v[8:9], v[54:55], v[10:11], v[104:105]
	v_mov_b32_e32 v14, v13
	v_pk_fma_f32 v[8:9], v[14:15], v[56:57], v[8:9]
	v_mov_b32_e32 v1, v6
	v_mul_f32_e32 v6, 0x3d372713, v8
	v_mul_f32_e32 v6, v8, v6
	v_fma_f32 v6, v8, v6, v8
	v_mul_f32_e32 v6, 0xbfcc422a, v6
	v_mul_f32_e32 v6, 0x3fb8aa3b, v6
	v_mov_b32_e32 v36, v12
	v_exp_f32_e32 v12, v6
	v_pk_fma_f32 v[112:113], v[36:37], v[94:95], v[112:113]
	v_mov_b32_e32 v6, v5
	v_mov_b32_e32 v0, v4
	v_add_f32_e32 v5, 1.0, v12
	v_mul_f32_e32 v12, 0x3d372713, v113
	v_mul_f32_e32 v12, v113, v12
	v_fma_f32 v12, v113, v12, v113
	v_mul_f32_e32 v12, 0xbfcc422a, v12
	v_mul_f32_e32 v12, 0x3fb8aa3b, v12
	v_exp_f32_e32 v13, v12
	v_mul_f32_e32 v12, 0x3d372713, v9
	v_mul_f32_e32 v12, v9, v12
	v_fma_f32 v12, v9, v12, v9
	v_mul_f32_e32 v12, 0xbfcc422a, v12
	v_mul_f32_e32 v4, 0x3d372713, v112
	v_mul_f32_e32 v12, 0x3fb8aa3b, v12
	v_mov_b32_e32 v24, v20
	v_mul_f32_e32 v4, v112, v4
	v_exp_f32_e32 v20, v12
	v_fma_f32 v4, v112, v4, v112
	v_mul_f32_e32 v4, 0xbfcc422a, v4
	v_mul_f32_e32 v4, 0x3fb8aa3b, v4
	v_exp_f32_e32 v4, v4
	v_rcp_f32_e32 v12, v5
	v_add_f32_e32 v5, 1.0, v13
	v_add_f32_e32 v13, 1.0, v20
	v_rcp_f32_e32 v13, v13
	v_add_f32_e32 v4, 1.0, v4
	v_rcp_f32_e32 v4, v4
	v_rcp_f32_e32 v5, v5
	v_pk_mul_f32 v[8:9], v[8:9], v[12:13]
	v_mov_b32_e32 v26, v25
	v_pk_mul_f32 v[8:9], v[8:9], v[102:103]
	v_mov_b32_e32 v25, v22
	s_nop 0
	s_nop 0
	v_cvt_pk_bf16_f32 v8, v8, v8
	v_cvt_pk_bf16_f32 v9, v9, v9
	s_nop 0
	s_nop 0
	v_mov_b32_e32 v22, v21
	v_pk_mul_f32 v[4:5], v[112:113], v[4:5]
	s_nop 0
	s_nop 0
	v_cvt_pk_bf16_f32 v13, v99, v99
	v_cvt_pk_bf16_f32 v12, v98, v98
	v_pk_mul_f32 v[4:5], v[4:5], v[66:67]
	v_cvt_pk_bf16_f32 v21, v100, v100
	v_cvt_pk_bf16_f32 v20, v101, v101
	v_lshrrev_b32_e32 v12, 16, v12
	v_lshrrev_b32_e32 v13, 16, v13
	s_nop 0
	s_nop 0
	v_and_or_b32 v99, v20, s36, v13
	v_and_or_b32 v98, v21, s36, v12
	v_pk_fma_f32 v[20:21], v[110:111], v[84:85], v[86:87]
	v_cvt_pk_bf16_f32 v5, v5, v5
	v_cvt_pk_bf16_f32 v4, v4, v4
	v_lshlrev_b32_e32 v53, 16, v61
	v_lshlrev_b32_e32 v52, 16, v60
	v_pk_fma_f32 v[20:21], v[64:65], v[92:93], v[20:21]
	v_lshrrev_b32_e32 v4, 16, v4
	v_pk_fma_f32 v[20:21], v[88:89], v[52:53], v[20:21]
	v_lshrrev_b32_e32 v5, 16, v5
	v_pk_fma_f32 v[58:59], v[58:59], v[2:3], v[26:27]
	v_mul_f32_e32 v66, 0x3d372713, v21
	v_and_or_b32 v101, v9, s36, v5
	v_and_or_b32 v100, v8, s36, v4
	v_and_b32_e32 v9, 0xffff0000, v61
	v_and_b32_e32 v8, 0xffff0000, v60
	v_pk_fma_f32 v[58:59], v[34:35], v[90:91], v[58:59]
	v_mul_f32_e32 v66, v21, v66
	v_pk_fma_f32 v[58:59], v[38:39], v[8:9], v[58:59]
	v_fma_f32 v66, v21, v66, v21
	v_mul_f32_e32 v61, 0x3d372713, v58
	v_mul_f32_e32 v66, 0xbfcc422a, v66
	v_mul_f32_e32 v60, 0x3d372713, v20
	v_mul_f32_e32 v61, v58, v61
	v_mul_f32_e32 v66, 0x3fb8aa3b, v66
	v_mul_f32_e32 v60, v20, v60
	v_fma_f32 v61, v58, v61, v58
	v_exp_f32_e32 v67, v66
	v_mul_f32_e32 v66, 0x3d372713, v59
	v_fma_f32 v60, v20, v60, v20
	v_mul_f32_e32 v61, 0xbfcc422a, v61
	v_mul_f32_e32 v66, v59, v66
	v_mul_f32_e32 v60, 0xbfcc422a, v60
	v_mul_f32_e32 v61, 0x3fb8aa3b, v61
	v_fma_f32 v66, v59, v66, v59
	v_mul_f32_e32 v60, 0x3fb8aa3b, v60
	v_exp_f32_e32 v61, v61
	v_mul_f32_e32 v66, 0xbfcc422a, v66
	v_lshl_add_u64 v[4:5], s[38:39], 1, v[70:71]
	v_exp_f32_e32 v60, v60
	v_mul_f32_e32 v66, 0x3fb8aa3b, v66
	global_store_dwordx4 v[4:5], v[98:101], off
	v_add_f32_e32 v61, 1.0, v61
	v_add_f32_e32 v60, 1.0, v60
	v_exp_f32_e32 v98, v66
	v_rcp_f32_e32 v66, v61
	v_add_f32_e32 v61, 1.0, v67
	v_rcp_f32_e32 v60, v60
	v_rcp_f32_e32 v61, v61
	v_add_f32_e32 v67, 1.0, v98
	v_rcp_f32_e32 v67, v67
	v_lshlrev_b32_e32 v13, 16, v49
	v_lshlrev_b32_e32 v12, 16, v48
	v_pk_mul_f32 v[20:21], v[20:21], v[60:61]
	v_and_b32_e32 v49, 0xffff0000, v49
	v_and_b32_e32 v48, 0xffff0000, v48
	v_pk_mul_f32 v[60:61], v[20:21], v[12:13]
	v_pk_mul_f32 v[12:13], v[58:59], v[66:67]
	v_lshlrev_b32_e32 v21, 16, v63
	v_pk_mul_f32 v[48:49], v[12:13], v[48:49]
	v_lshlrev_b32_e32 v20, 16, v62
	v_and_b32_e32 v13, 0xffff0000, v63
	v_and_b32_e32 v12, 0xffff0000, v62
	v_pk_fma_f32 v[62:63], v[108:109], v[0:1], v[24:25]
	v_pk_fma_f32 v[54:55], v[54:55], v[6:7], v[22:23]
	v_pk_fma_f32 v[62:63], v[32:33], v[94:95], v[62:63]
	v_pk_fma_f32 v[54:55], v[10:11], v[56:57], v[54:55]
	v_pk_fma_f32 v[62:63], v[36:37], v[20:21], v[62:63]
	v_pk_fma_f32 v[54:55], v[14:15], v[12:13], v[54:55]
	v_mul_f32_e32 v98, 0x3d372713, v63
	v_mul_f32_e32 v98, v63, v98
	v_fma_f32 v98, v63, v98, v63
	v_mul_f32_e32 v98, 0xbfcc422a, v98
	v_mul_f32_e32 v67, 0x3d372713, v54
	v_mul_f32_e32 v98, 0x3fb8aa3b, v98
	v_mul_f32_e32 v67, v54, v67
	v_exp_f32_e32 v99, v98
	v_mul_f32_e32 v98, 0x3d372713, v55
	v_mul_f32_e32 v66, 0x3d372713, v62
	v_fma_f32 v67, v54, v67, v54
	v_mul_f32_e32 v98, v55, v98
	v_mul_f32_e32 v66, v62, v66
	v_mul_f32_e32 v67, 0xbfcc422a, v67
	v_fma_f32 v98, v55, v98, v55
	v_fma_f32 v66, v62, v66, v62
	v_mul_f32_e32 v67, 0x3fb8aa3b, v67
	v_mul_f32_e32 v98, 0xbfcc422a, v98
	v_mul_f32_e32 v66, 0xbfcc422a, v66
	v_exp_f32_e32 v67, v67
	v_mul_f32_e32 v98, 0x3fb8aa3b, v98
	v_mul_f32_e32 v66, 0x3fb8aa3b, v66
	v_exp_f32_e32 v100, v98
	v_exp_f32_e32 v66, v66
	v_add_f32_e32 v67, 1.0, v67
	v_rcp_f32_e32 v98, v67
	v_add_f32_e32 v67, 1.0, v99
	v_add_f32_e32 v99, 1.0, v100
	v_add_f32_e32 v66, 1.0, v66
	v_rcp_f32_e32 v99, v99
	v_rcp_f32_e32 v66, v66
	v_rcp_f32_e32 v67, v67
	v_lshlrev_b32_e32 v59, 16, v51
	v_lshlrev_b32_e32 v58, 16, v50
	v_and_b32_e32 v51, 0xffff0000, v51
	v_and_b32_e32 v50, 0xffff0000, v50
	v_pk_mul_f32 v[54:55], v[54:55], v[98:99]
	v_pk_mul_f32 v[62:63], v[62:63], v[66:67]
	v_pk_mul_f32 v[50:51], v[54:55], v[50:51]
	s_nop 0
	v_pk_mul_f32 v[58:59], v[62:63], v[58:59]
	s_nop 0
	s_nop 0
	s_nop 0
	v_cvt_pk_bf16_f32 v49, v49, v49
	s_nop 0
	v_cvt_pk_bf16_f32 v48, v48, v48
	v_cvt_pk_bf16_f32 v50, v50, v50
	v_cvt_pk_bf16_f32 v51, v51, v51
	s_nop 0
	s_nop 0
	s_nop 0
	v_cvt_pk_bf16_f32 v54, v60, v60
	v_cvt_pk_bf16_f32 v59, v59, v59
	v_cvt_pk_bf16_f32 v58, v58, v58
	v_cvt_pk_bf16_f32 v55, v61, v61
	v_lshrrev_b32_e32 v54, 16, v54
	v_lshrrev_b32_e32 v55, 16, v55
	v_lshrrev_b32_e32 v58, 16, v58
	v_lshrrev_b32_e32 v59, 16, v59
	v_and_or_b32 v48, v48, s36, v54
	v_add_co_u32_e32 v54, vcc, s74, v4
	v_and_or_b32 v51, v51, s36, v59
	v_and_or_b32 v50, v50, s36, v58
	v_and_or_b32 v49, v49, s36, v55
	v_addc_co_u32_e32 v55, vcc, 0, v5, vcc
	global_store_dwordx4 v[54:55], v[48:51], off offset:2816
	v_pk_fma_f32 v[54:55], v[84:85], v[92:93], v[86:87]
	v_pk_fma_f32 v[56:57], v[6:7], v[56:57], v[22:23]
	v_lshlrev_b32_e32 v49, 16, v45
	v_lshlrev_b32_e32 v48, 16, v44
	v_pk_fma_f32 v[54:55], v[64:65], v[52:53], v[54:55]
	v_and_b32_e32 v45, 0xffff0000, v45
	v_pk_fma_f32 v[54:55], v[88:89], v[48:49], v[54:55]
	v_and_b32_e32 v44, 0xffff0000, v44
	v_mul_f32_e32 v58, 0x3d372713, v54
	v_mul_f32_e32 v58, v54, v58
	v_fma_f32 v58, v54, v58, v54
	v_mul_f32_e32 v58, 0xbfcc422a, v58
	v_mul_f32_e32 v58, 0x3fb8aa3b, v58
	v_exp_f32_e32 v60, v58
	v_pk_fma_f32 v[58:59], v[2:3], v[90:91], v[26:27]
	v_mul_f32_e32 v62, 0x3d372713, v55
	v_pk_fma_f32 v[58:59], v[34:35], v[8:9], v[58:59]
	v_mul_f32_e32 v62, v55, v62
	v_pk_fma_f32 v[58:59], v[38:39], v[44:45], v[58:59]
	v_fma_f32 v62, v55, v62, v55
	v_mul_f32_e32 v61, 0x3d372713, v58
	v_mul_f32_e32 v62, 0xbfcc422a, v62
	v_mul_f32_e32 v61, v58, v61
	v_mul_f32_e32 v62, 0x3fb8aa3b, v62
	v_fma_f32 v61, v58, v61, v58
	v_exp_f32_e32 v63, v62
	v_mul_f32_e32 v62, 0x3d372713, v59
	v_mul_f32_e32 v61, 0xbfcc422a, v61
	v_mul_f32_e32 v62, v59, v62
	v_mul_f32_e32 v61, 0x3fb8aa3b, v61
	v_fma_f32 v62, v59, v62, v59
	v_exp_f32_e32 v61, v61
	v_mul_f32_e32 v62, 0xbfcc422a, v62
	v_mul_f32_e32 v62, 0x3fb8aa3b, v62
	v_exp_f32_e32 v66, v62
	v_add_f32_e32 v61, 1.0, v61
	v_add_f32_e32 v60, 1.0, v60
	v_rcp_f32_e32 v62, v61
	v_add_f32_e32 v61, 1.0, v63
	v_rcp_f32_e32 v60, v60
	v_rcp_f32_e32 v61, v61
	v_add_f32_e32 v63, 1.0, v66
	v_rcp_f32_e32 v63, v63
	v_lshlrev_b32_e32 v51, 16, v41
	v_lshlrev_b32_e32 v50, 16, v40
	v_pk_mul_f32 v[54:55], v[54:55], v[60:61]
	v_and_b32_e32 v41, 0xffff0000, v41
	v_and_b32_e32 v40, 0xffff0000, v40
	v_pk_mul_f32 v[50:51], v[54:55], v[50:51]
	v_pk_mul_f32 v[54:55], v[58:59], v[62:63]
	v_pk_fma_f32 v[60:61], v[0:1], v[94:95], v[24:25]
	v_pk_mul_f32 v[40:41], v[54:55], v[40:41]
	v_lshlrev_b32_e32 v55, 16, v47
	v_lshlrev_b32_e32 v54, 16, v46
	v_pk_fma_f32 v[60:61], v[32:33], v[20:21], v[60:61]
	v_and_b32_e32 v47, 0xffff0000, v47
	v_pk_fma_f32 v[60:61], v[36:37], v[54:55], v[60:61]
	v_and_b32_e32 v46, 0xffff0000, v46
	v_mul_f32_e32 v66, 0x3d372713, v61
	v_mul_f32_e32 v66, v61, v66
	v_pk_fma_f32 v[56:57], v[10:11], v[12:13], v[56:57]
	v_fma_f32 v66, v61, v66, v61
	v_pk_fma_f32 v[56:57], v[14:15], v[46:47], v[56:57]
	v_mul_f32_e32 v66, 0xbfcc422a, v66
	v_mul_f32_e32 v63, 0x3d372713, v56
	v_mul_f32_e32 v66, 0x3fb8aa3b, v66
	v_mul_f32_e32 v63, v56, v63
	v_exp_f32_e32 v67, v66
	v_mul_f32_e32 v66, 0x3d372713, v57
	v_fma_f32 v63, v56, v63, v56
	v_mul_f32_e32 v66, v57, v66
	v_mul_f32_e32 v62, 0x3d372713, v60
	v_mul_f32_e32 v63, 0xbfcc422a, v63
	v_fma_f32 v66, v57, v66, v57
	v_mul_f32_e32 v62, v60, v62
	v_mul_f32_e32 v63, 0x3fb8aa3b, v63
	v_mul_f32_e32 v66, 0xbfcc422a, v66
	v_fma_f32 v62, v60, v62, v60
	v_exp_f32_e32 v63, v63
	v_mul_f32_e32 v66, 0x3fb8aa3b, v66
	v_mul_f32_e32 v62, 0xbfcc422a, v62
	v_exp_f32_e32 v90, v66
	v_mul_f32_e32 v62, 0x3fb8aa3b, v62
	v_exp_f32_e32 v62, v62
	v_add_f32_e32 v63, 1.0, v63
	v_rcp_f32_e32 v66, v63
	v_add_f32_e32 v63, 1.0, v67
	v_add_f32_e32 v67, 1.0, v90
	v_rcp_f32_e32 v67, v67
	v_add_f32_e32 v62, 1.0, v62
	v_rcp_f32_e32 v62, v62
	v_rcp_f32_e32 v63, v63
	v_lshlrev_b32_e32 v59, 16, v43
	v_lshlrev_b32_e32 v58, 16, v42
	v_and_b32_e32 v43, 0xffff0000, v43
	v_and_b32_e32 v42, 0xffff0000, v42
	v_pk_mul_f32 v[56:57], v[56:57], v[66:67]
	v_pk_mul_f32 v[60:61], v[60:61], v[62:63]
	v_pk_mul_f32 v[42:43], v[56:57], v[42:43]
	v_pk_mul_f32 v[58:59], v[60:61], v[58:59]
	s_nop 0
	s_nop 0
	s_nop 0
	s_nop 0
	v_cvt_pk_bf16_f32 v43, v43, v43
	s_nop 0
	v_cvt_pk_bf16_f32 v40, v40, v40
	v_cvt_pk_bf16_f32 v41, v41, v41
	v_cvt_pk_bf16_f32 v42, v42, v42
	s_nop 0
	v_bfe_u32 v60, v58, 16, 1
	v_bfe_u32 v61, v59, 16, 1
	v_cvt_pk_bf16_f32 v50, v50, v50
	v_add3_u32 v59, v59, v61, s48
	v_add3_u32 v58, v58, v60, s48
	v_cvt_pk_bf16_f32 v51, v51, v51
	v_lshrrev_b32_e32 v50, 16, v50
	v_lshrrev_b32_e32 v51, 16, v51
	v_lshrrev_b32_e32 v56, 16, v58
	v_lshrrev_b32_e32 v57, 16, v59
	v_and_or_b32 v40, v40, s36, v50
	v_add_co_u32_e32 v50, vcc, s29, v4
	v_and_or_b32 v43, v43, s36, v57
	v_and_or_b32 v42, v42, s36, v56
	v_and_or_b32 v41, v41, s36, v51
	v_addc_co_u32_e32 v51, vcc, 0, v5, vcc
	global_store_dwordx4 v[50:51], v[40:43], off offset:1536
	v_lshl_add_u64 v[50:51], s[26:27], 0, v[82:83]
	v_pk_fma_f32 v[2:3], v[2:3], v[8:9], v[26:27]
	v_mov_b32_e32 v40, v48
	v_mov_b32_e32 v41, v44
	v_mov_b32_e32 v42, v49
	v_mov_b32_e32 v43, v45
	global_store_dwordx4 v[50:51], v[40:43], off
	v_pk_fma_f32 v[2:3], v[34:35], v[44:45], v[2:3]
	v_and_b32_e32 v9, 0xffff0000, v17
	v_mov_b32_e32 v40, v54
	v_mov_b32_e32 v41, v46
	v_mov_b32_e32 v42, v55
	v_mov_b32_e32 v43, v47
	global_store_dwordx4 v[50:51], v[40:43], off offset:16
	v_pk_fma_f32 v[50:51], v[84:85], v[52:53], v[86:87]
	v_pk_fma_f32 v[6:7], v[6:7], v[12:13], v[22:23]
	v_lshlrev_b32_e32 v41, 16, v29
	v_lshlrev_b32_e32 v40, 16, v28
	v_pk_fma_f32 v[48:49], v[64:65], v[48:49], v[50:51]
	v_and_b32_e32 v29, 0xffff0000, v29
	v_pk_fma_f32 v[48:49], v[88:89], v[40:41], v[48:49]
	v_and_b32_e32 v28, 0xffff0000, v28
	v_mul_f32_e32 v50, 0x3d372713, v48
	v_mul_f32_e32 v50, v48, v50
	v_fma_f32 v50, v48, v50, v48
	v_mul_f32_e32 v50, 0xbfcc422a, v50
	v_mul_f32_e32 v50, 0x3fb8aa3b, v50
	v_exp_f32_e32 v50, v50
	v_pk_fma_f32 v[2:3], v[38:39], v[28:29], v[2:3]
	v_lshlrev_b32_e32 v43, 16, v17
	v_mul_f32_e32 v8, 0x3d372713, v2
	v_add_f32_e32 v17, 1.0, v50
	v_mul_f32_e32 v8, v2, v8
	v_rcp_f32_e32 v26, v17
	v_mul_f32_e32 v17, 0x3d372713, v49
	v_fma_f32 v8, v2, v8, v2
	v_mul_f32_e32 v17, v49, v17
	v_mul_f32_e32 v27, 0x3d372713, v3
	v_mul_f32_e32 v8, 0xbfcc422a, v8
	v_fma_f32 v17, v49, v17, v49
	v_mul_f32_e32 v27, v3, v27
	v_mul_f32_e32 v8, 0x3fb8aa3b, v8
	v_mul_f32_e32 v17, 0xbfcc422a, v17
	v_fma_f32 v27, v3, v27, v3
	v_exp_f32_e32 v8, v8
	v_mul_f32_e32 v17, 0x3fb8aa3b, v17
	v_mul_f32_e32 v27, 0xbfcc422a, v27
	v_exp_f32_e32 v17, v17
	v_mul_f32_e32 v27, 0x3fb8aa3b, v27
	v_exp_f32_e32 v35, v27
	v_add_f32_e32 v8, 1.0, v8
	v_rcp_f32_e32 v34, v8
	v_add_f32_e32 v8, 1.0, v17
	v_rcp_f32_e32 v27, v8
	v_add_f32_e32 v8, 1.0, v35
	v_rcp_f32_e32 v35, v8
	v_and_b32_e32 v8, 0xffff0000, v16
	v_pk_fma_f32 v[0:1], v[0:1], v[20:21], v[24:25]
	v_pk_fma_f32 v[6:7], v[10:11], v[46:47], v[6:7]
	v_pk_mul_f32 v[2:3], v[2:3], v[34:35]
	v_lshlrev_b32_e32 v35, 16, v31
	v_pk_mul_f32 v[8:9], v[2:3], v[8:9]
	v_and_b32_e32 v3, 0xffff0000, v31
	v_and_b32_e32 v2, 0xffff0000, v30
	v_lshlrev_b32_e32 v34, 16, v30
	v_pk_fma_f32 v[0:1], v[32:33], v[54:55], v[0:1]
	v_pk_fma_f32 v[6:7], v[14:15], v[2:3], v[6:7]
	v_pk_fma_f32 v[0:1], v[36:37], v[34:35], v[0:1]
	v_mul_f32_e32 v10, 0x3d372713, v6
	v_mul_f32_e32 v10, v6, v10
	v_mul_f32_e32 v13, 0x3d372713, v1
	v_fma_f32 v10, v6, v10, v6
	v_mul_f32_e32 v13, v1, v13
	v_mul_f32_e32 v14, 0x3d372713, v7
	v_mul_f32_e32 v20, 0x3d372713, v0
	v_mul_f32_e32 v10, 0xbfcc422a, v10
	v_fma_f32 v13, v1, v13, v1
	v_mul_f32_e32 v14, v7, v14
	v_mul_f32_e32 v20, v0, v20
	v_mul_f32_e32 v10, 0x3fb8aa3b, v10
	v_mul_f32_e32 v13, 0xbfcc422a, v13
	v_fma_f32 v14, v7, v14, v7
	v_fma_f32 v20, v0, v20, v0
	v_exp_f32_e32 v10, v10
	v_mul_f32_e32 v13, 0x3fb8aa3b, v13
	v_mul_f32_e32 v14, 0xbfcc422a, v14
	v_mul_f32_e32 v20, 0xbfcc422a, v20
	v_exp_f32_e32 v13, v13
	v_mul_f32_e32 v14, 0x3fb8aa3b, v14
	v_mul_f32_e32 v20, 0x3fb8aa3b, v20
	v_exp_f32_e32 v15, v14
	v_exp_f32_e32 v20, v20
	v_add_f32_e32 v10, 1.0, v10
	v_rcp_f32_e32 v14, v10
	v_add_f32_e32 v10, 1.0, v13
	v_rcp_f32_e32 v13, v10
	v_add_f32_e32 v10, 1.0, v15
	v_add_f32_e32 v12, 1.0, v20
	v_rcp_f32_e32 v15, v10
	v_rcp_f32_e32 v12, v12
	v_and_b32_e32 v11, 0xffff0000, v19
	v_and_b32_e32 v10, 0xffff0000, v18
	v_pk_mul_f32 v[6:7], v[6:7], v[14:15]
	v_lshlrev_b32_e32 v42, 16, v16
	v_pk_mul_f32 v[16:17], v[48:49], v[26:27]
	v_lshlrev_b32_e32 v27, 16, v19
	v_lshlrev_b32_e32 v26, 16, v18
	v_pk_mul_f32 v[0:1], v[0:1], v[12:13]
	v_pk_mul_f32 v[6:7], v[6:7], v[10:11]
	v_pk_mul_f32 v[0:1], v[0:1], v[26:27]
	s_nop 0
	v_pk_mul_f32 v[16:17], v[16:17], v[42:43]
	s_nop 0
	v_bfe_u32 v12, v9, 16, 1
	v_bfe_u32 v13, v8, 16, 1
	v_cvt_pk_bf16_f32 v7, v7, v7
	s_nop 0
	v_add3_u32 v13, v8, v13, s48
	v_add3_u32 v12, v9, v12, s48
	v_cvt_pk_bf16_f32 v6, v6, v6
	s_nop 0
	s_nop 0
	s_nop 0
	v_cvt_pk_bf16_f32 v0, v0, v0
	v_cvt_pk_bf16_f32 v1, v1, v1
	v_cvt_pk_bf16_f32 v9, v17, v17
	v_cvt_pk_bf16_f32 v8, v16, v16
	v_lshrrev_b32_e32 v0, 16, v0
	v_lshrrev_b32_e32 v10, 16, v8
	v_lshrrev_b32_e32 v11, 16, v9
	v_lshrrev_b32_e32 v1, 16, v1
	v_and_or_b32 v8, v6, s36, v0
	v_add_co_u32_e32 v0, vcc, s28, v4
	v_and_or_b32 v9, v7, s36, v1
	v_and_or_b32 v7, v12, s36, v11
	v_and_or_b32 v6, v13, s36, v10
	v_addc_co_u32_e32 v1, vcc, 0, v5, vcc
	global_store_dwordx4 v[0:1], v[6:9], off offset:256
	v_lshl_add_u64 v[4:5], s[12:13], 0, v[82:83]
	v_mov_b32_e32 v26, v40
	v_mov_b32_e32 v27, v28
	v_mov_b32_e32 v28, v41
	v_mov_b32_e32 v0, v34
	v_mov_b32_e32 v1, v2
	v_mov_b32_e32 v2, v35
	global_store_dwordx4 v[4:5], v[26:29], off
	global_store_dwordx4 v[4:5], v[0:3], off offset:16
	s_mov_b64 s[12:13], 0
.LBB0_2006:
	s_andn2_b64 vcc, exec, s[12:13]
	s_cbranch_vccnz .LBB0_2008
	s_mul_i32 s12, s24, 0x810
	s_add_i32 s13, s12, 0xfffbf800
	s_mul_i32 s26, s13, 0x5600
	s_mul_hi_u32 s25, s13, 0x5600
	s_add_u32 s26, s16, s26
	s_addc_u32 s27, s17, s25
	v_lshl_add_u64 v[0:1], s[26:27], 0, v[80:81]
	v_add_co_u32_e32 v2, vcc, s74, v0
	s_movk_i32 s25, 0x5000
	s_nop 0
	v_addc_co_u32_e32 v3, vcc, 0, v1, vcc
	global_load_dwordx4 v[36:39], v[2:3], off offset:2816
	v_add_co_u32_e32 v2, vcc, s25, v0
	s_mov_b32 s25, 0x8000
	s_nop 0
	v_addc_co_u32_e32 v3, vcc, 0, v1, vcc
	global_load_dwordx4 v[32:35], v[0:1], off
	global_load_dwordx4 v[4:7], v[2:3], off offset:1536
	v_add_co_u32_e32 v0, vcc, s25, v0
	s_add_i32 s12, s12, 0xfffbf801
	s_nop 0
	v_addc_co_u32_e32 v1, vcc, 0, v1, vcc
	global_load_dwordx4 v[0:3], v[0:1], off offset:256
	s_nop 0
	global_load_dwordx4 v[24:27], v[78:79], off offset:16
	global_load_dwordx4 v[40:43], v[78:79], off
	global_load_dwordx4 v[8:11], v[76:77], off offset:16
	global_load_dwordx4 v[16:19], v[76:77], off
	global_load_dwordx4 v[12:15], v[74:75], off offset:16
	global_load_dwordx4 v[20:23], v[74:75], off
	global_load_dwordx4 v[28:31], v[72:73], off offset:16
	global_load_dwordx4 v[52:55], v[72:73], off
	s_waitcnt vmcnt(0)
	v_lshlrev_b32_e32 v57, 16, v37
	v_lshlrev_b32_e32 v56, 16, v36
	v_and_b32_e32 v51, 0xffff0000, v37
	v_and_b32_e32 v50, 0xffff0000, v36
	v_lshlrev_b32_e32 v45, 16, v33
	v_mov_b32_e32 v36, v40
	v_mov_b32_e32 v37, v42
	v_mov_b32_e32 v42, v41
	v_lshlrev_b32_e32 v44, 16, v32
	v_and_b32_e32 v33, 0xffff0000, v33
	v_and_b32_e32 v32, 0xffff0000, v32
	v_mov_b32_e32 v46, v52
	v_mov_b32_e32 v47, v54
	v_mov_b32_e32 v54, v53
	v_pk_fma_f32 v[36:37], v[36:37], 0, v[46:47] op_sel_hi:[1,0,1]
	v_mov_b32_e32 v47, v18
	v_pk_fma_f32 v[40:41], v[42:43], 0, v[54:55] op_sel_hi:[1,0,1]
	v_mov_b32_e32 v18, v17
	v_mov_b32_e32 v49, v22
	v_pk_fma_f32 v[42:43], v[18:19], 0, v[40:41] op_sel_hi:[1,0,1]
	v_mov_b32_e32 v22, v21
	v_mov_b32_e32 v48, v20
	v_pk_fma_f32 v[20:21], v[22:23], v[32:33], v[42:43]
	v_mov_b32_e32 v46, v16
	v_mul_f32_e32 v17, 0x3d372713, v20
	v_mul_f32_e32 v17, v20, v17
	v_fma_f32 v17, v20, v17, v20
	v_mul_f32_e32 v17, 0xbfcc422a, v17
	v_mul_f32_e32 v17, 0x3fb8aa3b, v17
	v_exp_f32_e32 v17, v17
	v_pk_fma_f32 v[58:59], v[46:47], 0, v[36:37] op_sel_hi:[1,0,1]
	v_mov_b32_e32 v54, v28
	v_pk_fma_f32 v[58:59], v[48:49], v[44:45], v[58:59]
	v_add_f32_e32 v17, 1.0, v17
	v_mul_f32_e32 v16, 0x3d372713, v58
	v_rcp_f32_e32 v52, v17
	v_mul_f32_e32 v17, 0x3d372713, v59
	v_mul_f32_e32 v16, v58, v16
	v_mul_f32_e32 v17, v59, v17
	v_fma_f32 v16, v58, v16, v58
	v_fma_f32 v17, v59, v17, v59
	v_mul_f32_e32 v16, 0xbfcc422a, v16
	v_mul_f32_e32 v17, 0xbfcc422a, v17
	v_mul_f32_e32 v16, 0x3fb8aa3b, v16
	v_mul_f32_e32 v17, 0x3fb8aa3b, v17
	v_exp_f32_e32 v16, v16
	v_exp_f32_e32 v17, v17
	v_mov_b32_e32 v55, v30
	v_mov_b32_e32 v30, v29
	v_add_f32_e32 v16, 1.0, v16
	v_add_f32_e32 v17, 1.0, v17
	v_rcp_f32_e32 v16, v16
	v_rcp_f32_e32 v17, v17
	v_pk_fma_f32 v[18:19], v[18:19], v[32:33], v[40:41]
	v_pk_mul_f32 v[16:17], v[58:59], v[16:17]
	s_nop 0
	v_pk_mul_f32 v[42:43], v[16:17], v[56:57]
	v_mul_f32_e32 v16, 0x3d372713, v21
	v_mul_f32_e32 v16, v21, v16
	v_fma_f32 v16, v21, v16, v21
	v_mul_f32_e32 v16, 0xbfcc422a, v16
	v_mul_f32_e32 v16, 0x3fb8aa3b, v16
	v_exp_f32_e32 v16, v16
	v_mov_b32_e32 v57, v14
	v_mov_b32_e32 v14, v13
	v_mov_b32_e32 v56, v12
	v_add_f32_e32 v16, 1.0, v16
	v_rcp_f32_e32 v53, v16
	s_nop 0
	v_pk_mul_f32 v[16:17], v[20:21], v[52:53]
	s_nop 0
	v_pk_mul_f32 v[50:51], v[16:17], v[50:51]
	v_lshlrev_b32_e32 v21, 16, v35
	v_lshlrev_b32_e32 v20, 16, v34
	v_and_b32_e32 v17, 0xffff0000, v35
	v_and_b32_e32 v16, 0xffff0000, v34
	v_lshlrev_b32_e32 v53, 16, v39
	v_lshlrev_b32_e32 v52, 16, v38
	v_and_b32_e32 v35, 0xffff0000, v39
	v_and_b32_e32 v34, 0xffff0000, v38
	v_mov_b32_e32 v38, v24
	v_mov_b32_e32 v39, v26
	v_mov_b32_e32 v26, v25
	v_pk_fma_f32 v[38:39], v[38:39], 0, v[54:55] op_sel_hi:[1,0,1]
	v_mov_b32_e32 v55, v10
	v_pk_fma_f32 v[24:25], v[26:27], 0, v[30:31] op_sel_hi:[1,0,1]
	v_mov_b32_e32 v10, v9
	v_pk_fma_f32 v[26:27], v[10:11], 0, v[24:25] op_sel_hi:[1,0,1]
	v_mov_b32_e32 v54, v8
	v_pk_fma_f32 v[12:13], v[14:15], v[16:17], v[26:27]
	v_pk_fma_f32 v[58:59], v[54:55], 0, v[38:39] op_sel_hi:[1,0,1]
	v_mul_f32_e32 v9, 0x3d372713, v12
	v_mul_f32_e32 v9, v12, v9
	v_fma_f32 v9, v12, v9, v12
	v_mul_f32_e32 v9, 0xbfcc422a, v9
	v_mul_f32_e32 v9, 0x3fb8aa3b, v9
	v_exp_f32_e32 v9, v9
	v_mul_f32_e32 v27, 0x3d372713, v13
	v_pk_fma_f32 v[58:59], v[56:57], v[20:21], v[58:59]
	v_mul_f32_e32 v27, v13, v27
	v_add_f32_e32 v9, 1.0, v9
	v_mul_f32_e32 v8, 0x3d372713, v58
	v_rcp_f32_e32 v26, v9
	v_mul_f32_e32 v9, 0x3d372713, v59
	v_fma_f32 v27, v13, v27, v13
	v_mul_f32_e32 v8, v58, v8
	v_mul_f32_e32 v9, v59, v9
	v_mul_f32_e32 v27, 0xbfcc422a, v27
	v_fma_f32 v8, v58, v8, v58
	v_fma_f32 v9, v59, v9, v59
	v_mul_f32_e32 v27, 0x3fb8aa3b, v27
	v_mul_f32_e32 v8, 0xbfcc422a, v8
	v_mul_f32_e32 v9, 0xbfcc422a, v9
	v_exp_f32_e32 v27, v27
	v_mul_f32_e32 v8, 0x3fb8aa3b, v8
	v_mul_f32_e32 v9, 0x3fb8aa3b, v9
	v_exp_f32_e32 v8, v8
	v_exp_f32_e32 v9, v9
	v_add_f32_e32 v27, 1.0, v27
	v_rcp_f32_e32 v27, v27
	v_add_f32_e32 v8, 1.0, v8
	v_add_f32_e32 v9, 1.0, v9
	v_rcp_f32_e32 v8, v8
	v_rcp_f32_e32 v9, v9
	v_pk_mul_f32 v[12:13], v[12:13], v[26:27]
	v_bfe_u32 v28, v51, 16, 1
	v_pk_mul_f32 v[12:13], v[12:13], v[34:35]
	v_pk_mul_f32 v[8:9], v[58:59], v[8:9]
	s_nop 0
	v_pk_mul_f32 v[8:9], v[8:9], v[52:53]
	s_nop 0
	s_nop 0
	v_cvt_pk_bf16_f32 v13, v13, v13
	s_nop 0
	v_cvt_pk_bf16_f32 v30, v50, v50
	v_add3_u32 v31, v51, v28, s48
	v_cvt_pk_bf16_f32 v12, v12, v12
	s_nop 0
	s_nop 0
	s_nop 0
	v_cvt_pk_bf16_f32 v26, v42, v42
	v_cvt_pk_bf16_f32 v9, v9, v9
	v_cvt_pk_bf16_f32 v8, v8, v8
	v_cvt_pk_bf16_f32 v27, v43, v43
	v_lshrrev_b32_e32 v26, 16, v26
	v_lshrrev_b32_e32 v27, 16, v27
	v_lshrrev_b32_e32 v8, 16, v8
	v_lshrrev_b32_e32 v9, 16, v9
	v_and_or_b32 v26, v30, s36, v26
	v_mov_b32_e32 v30, 0x2b00
	v_and_or_b32 v29, v13, s36, v9
	v_and_or_b32 v28, v12, s36, v8
	v_and_or_b32 v27, v31, s36, v27
	v_mad_u64_u32 v[8:9], s[26:27], s13, v30, v[70:71]
	global_store_dwordx4 v[8:9], v[26:29], off
	v_lshlrev_b32_e32 v9, 16, v5
	v_lshlrev_b32_e32 v8, 16, v4
	v_pk_fma_f32 v[26:27], v[46:47], v[44:45], v[36:37]
	v_and_b32_e32 v5, 0xffff0000, v5
	v_and_b32_e32 v4, 0xffff0000, v4
	v_pk_fma_f32 v[8:9], v[48:49], v[8:9], v[26:27]
	v_pk_fma_f32 v[4:5], v[22:23], v[4:5], v[18:19]
	v_mul_f32_e32 v26, 0x3d372713, v8
	v_mul_f32_e32 v19, 0x3d372713, v9
	v_mul_f32_e32 v26, v8, v26
	v_mul_f32_e32 v19, v9, v19
	v_fma_f32 v26, v8, v26, v8
	v_fma_f32 v19, v9, v19, v9
	v_mul_f32_e32 v26, 0xbfcc422a, v26
	v_mul_f32_e32 v19, 0xbfcc422a, v19
	v_mul_f32_e32 v26, 0x3fb8aa3b, v26
	v_mul_f32_e32 v19, 0x3fb8aa3b, v19
	v_exp_f32_e32 v26, v26
	v_exp_f32_e32 v19, v19
	v_lshlrev_b32_e32 v13, 16, v1
	v_lshlrev_b32_e32 v12, 16, v0
	v_add_f32_e32 v26, 1.0, v26
	v_add_f32_e32 v19, 1.0, v19
	v_rcp_f32_e32 v26, v26
	v_rcp_f32_e32 v27, v19
	v_mul_f32_e32 v18, 0x3d372713, v4
	v_mul_f32_e32 v18, v4, v18
	v_fma_f32 v18, v4, v18, v4
	v_pk_mul_f32 v[8:9], v[8:9], v[26:27]
	v_mul_f32_e32 v18, 0xbfcc422a, v18
	v_pk_mul_f32 v[8:9], v[8:9], v[12:13]
	v_mul_f32_e32 v12, 0x3d372713, v5
	v_mul_f32_e32 v12, v5, v12
	v_fma_f32 v12, v5, v12, v5
	v_mul_f32_e32 v12, 0xbfcc422a, v12
	v_mul_f32_e32 v18, 0x3fb8aa3b, v18
	v_mul_f32_e32 v12, 0x3fb8aa3b, v12
	v_exp_f32_e32 v18, v18
	v_exp_f32_e32 v12, v12
	v_and_b32_e32 v1, 0xffff0000, v1
	v_and_b32_e32 v0, 0xffff0000, v0
	v_add_f32_e32 v18, 1.0, v18
	v_add_f32_e32 v12, 1.0, v12
	v_rcp_f32_e32 v18, v18
	v_rcp_f32_e32 v19, v12
	v_pk_fma_f32 v[10:11], v[10:11], v[16:17], v[24:25]
	v_lshlrev_b32_e32 v13, 16, v3
	v_lshlrev_b32_e32 v12, 16, v2
	v_pk_mul_f32 v[4:5], v[4:5], v[18:19]
	v_pk_fma_f32 v[18:19], v[54:55], v[20:21], v[38:39]
	v_pk_mul_f32 v[0:1], v[4:5], v[0:1]
	v_lshlrev_b32_e32 v5, 16, v7
	v_lshlrev_b32_e32 v4, 16, v6
	v_and_b32_e32 v7, 0xffff0000, v7
	v_and_b32_e32 v6, 0xffff0000, v6
	v_pk_fma_f32 v[4:5], v[56:57], v[4:5], v[18:19]
	v_pk_fma_f32 v[6:7], v[14:15], v[6:7], v[10:11]
	v_mul_f32_e32 v11, 0x3d372713, v5
	v_mul_f32_e32 v11, v5, v11
	v_fma_f32 v11, v5, v11, v5
	v_mul_f32_e32 v11, 0xbfcc422a, v11
	v_mul_f32_e32 v11, 0x3fb8aa3b, v11
	v_exp_f32_e32 v11, v11
	v_mul_f32_e32 v10, 0x3d372713, v6
	v_mul_f32_e32 v18, 0x3d372713, v4
	v_mul_f32_e32 v10, v6, v10
	v_add_f32_e32 v11, 1.0, v11
	v_rcp_f32_e32 v19, v11
	v_mul_f32_e32 v11, 0x3d372713, v7
	v_mul_f32_e32 v11, v7, v11
	v_mul_f32_e32 v18, v4, v18
	v_fma_f32 v10, v6, v10, v6
	v_fma_f32 v11, v7, v11, v7
	v_fma_f32 v18, v4, v18, v4
	v_mul_f32_e32 v10, 0xbfcc422a, v10
	v_mul_f32_e32 v11, 0xbfcc422a, v11
	v_mul_f32_e32 v18, 0xbfcc422a, v18
	v_mul_f32_e32 v10, 0x3fb8aa3b, v10
	v_mul_f32_e32 v11, 0x3fb8aa3b, v11
	v_mul_f32_e32 v18, 0x3fb8aa3b, v18
	v_exp_f32_e32 v10, v10
	v_exp_f32_e32 v11, v11
	v_exp_f32_e32 v18, v18
	v_and_b32_e32 v3, 0xffff0000, v3
	v_add_f32_e32 v10, 1.0, v10
	v_add_f32_e32 v11, 1.0, v11
	v_add_f32_e32 v18, 1.0, v18
	v_rcp_f32_e32 v10, v10
	v_rcp_f32_e32 v11, v11
	v_rcp_f32_e32 v18, v18
	v_and_b32_e32 v2, 0xffff0000, v2
	v_pk_mul_f32 v[6:7], v[6:7], v[10:11]
	v_pk_mul_f32 v[4:5], v[4:5], v[18:19]
	v_pk_mul_f32 v[2:3], v[6:7], v[2:3]
	v_pk_mul_f32 v[4:5], v[4:5], v[12:13]
	s_nop 0
	s_nop 0
	s_nop 0
	s_nop 0
	v_cvt_pk_bf16_f32 v0, v0, v0
	v_cvt_pk_bf16_f32 v1, v1, v1
	v_cvt_pk_bf16_f32 v2, v2, v2
	v_cvt_pk_bf16_f32 v3, v3, v3
	s_nop 0
	s_nop 0
	s_nop 0
	s_nop 0
	v_cvt_pk_bf16_f32 v5, v5, v5
	v_cvt_pk_bf16_f32 v4, v4, v4
	v_cvt_pk_bf16_f32 v7, v9, v9
	v_cvt_pk_bf16_f32 v6, v8, v8
	v_lshrrev_b32_e32 v6, 16, v6
	v_lshrrev_b32_e32 v7, 16, v7
	v_lshrrev_b32_e32 v4, 16, v4
	v_lshrrev_b32_e32 v5, 16, v5
	v_and_or_b32 v3, v3, s36, v5
	v_and_or_b32 v2, v2, s36, v4
	v_and_or_b32 v1, v1, s36, v7
	v_and_or_b32 v0, v0, s36, v6
	v_mad_u64_u32 v[4:5], s[12:13], s12, v30, v[70:71]
	global_store_dwordx4 v[4:5], v[0:3], off
